# staggered wave halves in all three N=1024 GEMMs (branch, out-projection, down)
# baseline (speedup 1.0000x reference)
.Lop_tile:
	s_and_b32 s0, s78, 3
	s_or_b32 s0, s0, s77
	s_lshr_b32 s1, s78, 2
	s_lshl_b32 s1, s1, 7
	s_lshl_b32 s2, s0, 8
	s_mul_i32 s3, s2, 0x800
	s_add_u32 s68, s18, s3
	s_addc_u32 s69, s19, 0
	s_mul_i32 s3, s1, 0x800
	s_add_u32 s70, s80, s3
	s_addc_u32 s71, s81, 0
	s_lshl_b32 s3, s2, 11
	s_lshl_b32 s12, s1, 1
	s_add_u32 s3, s3, s12
	s_add_u32 s74, s24, s3
	s_addc_u32 s75, s25, 0
	s_add_i32 s12, s0, -12
	s_lshr_b32 s12, s12, 2
	s_cmp_lt_u32 s0, 16
	s_cselect_b32 s12, 0, s12
	s_cselect_b32 s14, s52, s54
	s_cselect_b32 s15, s53, s55
	s_mul_i32 s13, s82, 5
	s_add_i32 s12, s12, s13
	s_mul_i32 s12, s12, 0x6000
	s_add_u32 s12, s12, 0x2000
	s_lshl_b32 s13, s1, 2
	s_add_u32 s12, s12, s13
	s_add_u32 s72, s30, s12
	s_addc_u32 s73, s31, 0
	s_and_b32 s12, s0, 15
	s_lshl_b32 s12, s12, 20
	s_add_u32 s12, s12, s13
	s_add_u32 s14, s14, s12
	s_addc_u32 s15, s15, 0
	s_cmp_eq_u32 s82, 0
	s_cselect_b32 s14, s14, s74
	s_cselect_b32 s15, s15, s75
	s_cselect_b32 s38, 64, 32
	s_cselect_b64 vcc, -1, 0
	s_lshl_b32 s39, s38, 1
	s_add_u32 s40, s39, s38
	v_cndmask_b32_e32 v191, v206, v210, vcc
	v_cndmask_b32_e32 v192, v207, v211, vcc
	v_cndmask_b32_e32 v193, v208, v168, vcc
	v_cndmask_b32_e32 v244, v209, v169, vcc
	s_add_u32 m0, s76, 0x0
	s_nop 0
	global_load_lds_dwordx4 v196, s[68:69]
	s_add_u32 m0, s76, 0x2000
	s_nop 0
	global_load_lds_dwordx4 v197, s[68:69]
	s_add_u32 m0, s76, 0x4000
	s_nop 0
	global_load_lds_dwordx4 v198, s[68:69]
	s_add_u32 m0, s76, 0x6000
	s_nop 0
	global_load_lds_dwordx4 v199, s[68:69]
	s_add_u32 m0, s76, 0x8000
	s_nop 0
	global_load_lds_dwordx4 v196, s[70:71]
	s_add_u32 m0, s76, 0xa000
	s_nop 0
	global_load_lds_dwordx4 v197, s[70:71]
	s_add_u32 s68, s68, 0x80
	s_addc_u32 s69, s69, 0
	s_add_u32 s70, s70, 0x80
	s_addc_u32 s71, s71, 0
	s_add_u32 m0, s76, 0xc000
	s_nop 0
	global_load_lds_dwordx4 v196, s[68:69]
	s_add_u32 m0, s76, 0xe000
	s_nop 0
	global_load_lds_dwordx4 v197, s[68:69]
	s_add_u32 m0, s76, 0x10000
	s_nop 0
	global_load_lds_dwordx4 v198, s[68:69]
	s_add_u32 m0, s76, 0x12000
	s_nop 0
	global_load_lds_dwordx4 v199, s[68:69]
	s_add_u32 m0, s76, 0x14000
	s_nop 0
	global_load_lds_dwordx4 v196, s[70:71]
	s_add_u32 m0, s76, 0x16000
	s_nop 0
	global_load_lds_dwordx4 v197, s[70:71]
	s_add_u32 s68, s68, 0x80
	s_addc_u32 s69, s69, 0
	s_add_u32 s70, s70, 0x80
	s_addc_u32 s71, s71, 0
	s_waitcnt vmcnt(6)
	s_barrier
	s_cmp_ge_u32 s76, 0x1000
	s_cbranch_scc1 .Lop_streamB
	v_add_u32_e32 v204, 0x0, v200
	v_add_u32_e32 v205, 0x0, v202
	ds_read_b128 v[130:133], v204 offset:0
	ds_read_b128 v[134:137], v204 offset:2048
	ds_read_b128 v[138:141], v204 offset:4096
	ds_read_b128 v[142:145], v204 offset:6144
	ds_read_b128 v[146:149], v205 offset:0
	ds_read_b128 v[150:153], v205 offset:2048
	ds_read_b128 v[154:157], v205 offset:4096
	ds_read_b128 v[158:161], v205 offset:6144
	v_add_u32_e32 v204, 0x0, v201
	v_add_u32_e32 v205, 0x0, v203
	ds_read_b128 v[212:215], v204 offset:0
	ds_read_b128 v[216:219], v204 offset:2048
	ds_read_b128 v[220:223], v204 offset:4096
	ds_read_b128 v[224:227], v204 offset:6144
	ds_read_b128 v[228:231], v205 offset:0
	ds_read_b128 v[232:235], v205 offset:2048
	ds_read_b128 v[236:239], v205 offset:4096
	ds_read_b128 v[240:243], v205 offset:6144
	s_add_u32 m0, s76, 0x18000
	s_nop 0
	global_load_lds_dwordx4 v196, s[68:69]
	s_add_u32 m0, s76, 0x1a000
	s_nop 0
	global_load_lds_dwordx4 v197, s[68:69]
	s_add_u32 m0, s76, 0x1c000
	s_nop 0
	global_load_lds_dwordx4 v198, s[68:69]
	s_add_u32 m0, s76, 0x1e000
	s_nop 0
	global_load_lds_dwordx4 v199, s[68:69]
	s_add_u32 m0, s76, 0x20000
	s_nop 0
	global_load_lds_dwordx4 v196, s[70:71]
	s_add_u32 m0, s76, 0x22000
	s_nop 0
	global_load_lds_dwordx4 v197, s[70:71]
	s_add_u32 s68, s68, 0x80
	s_addc_u32 s69, s69, 0
	s_add_u32 s70, s70, 0x80
	s_addc_u32 s71, s71, 0
	global_load_dwordx4 v[174:177], v190, s[72:73] offset:0
	global_load_dwordx4 v[178:181], v190, s[72:73] offset:64
	s_waitcnt lgkmcnt(0)
	s_barrier
	v_mfma_f32_16x16x32_bf16 v[2:5], v[146:149], v[130:133], 0
	v_mfma_f32_16x16x32_bf16 v[6:9], v[150:153], v[130:133], 0
	v_mfma_f32_16x16x32_bf16 v[10:13], v[154:157], v[130:133], 0
	v_mfma_f32_16x16x32_bf16 v[14:17], v[158:161], v[130:133], 0
	v_mfma_f32_16x16x32_bf16 v[18:21], v[146:149], v[134:137], 0
	v_mfma_f32_16x16x32_bf16 v[22:25], v[150:153], v[134:137], 0
	v_mfma_f32_16x16x32_bf16 v[26:29], v[154:157], v[134:137], 0
	v_mfma_f32_16x16x32_bf16 v[30:33], v[158:161], v[134:137], 0
	v_mfma_f32_16x16x32_bf16 v[34:37], v[146:149], v[138:141], 0
	v_mfma_f32_16x16x32_bf16 v[38:41], v[150:153], v[138:141], 0
	v_mfma_f32_16x16x32_bf16 v[42:45], v[154:157], v[138:141], 0
	v_mfma_f32_16x16x32_bf16 v[46:49], v[158:161], v[138:141], 0
	v_mfma_f32_16x16x32_bf16 v[50:53], v[146:149], v[142:145], 0
	v_mfma_f32_16x16x32_bf16 v[54:57], v[150:153], v[142:145], 0
	v_mfma_f32_16x16x32_bf16 v[58:61], v[154:157], v[142:145], 0
	v_mfma_f32_16x16x32_bf16 v[62:65], v[158:161], v[142:145], 0
	v_mfma_f32_16x16x32_bf16 v[2:5], v[228:231], v[212:215], v[2:5]
	v_mfma_f32_16x16x32_bf16 v[6:9], v[232:235], v[212:215], v[6:9]
	v_mfma_f32_16x16x32_bf16 v[10:13], v[236:239], v[212:215], v[10:13]
	v_mfma_f32_16x16x32_bf16 v[14:17], v[240:243], v[212:215], v[14:17]
	v_mfma_f32_16x16x32_bf16 v[18:21], v[228:231], v[216:219], v[18:21]
	v_mfma_f32_16x16x32_bf16 v[22:25], v[232:235], v[216:219], v[22:25]
	v_mfma_f32_16x16x32_bf16 v[26:29], v[236:239], v[216:219], v[26:29]
	v_mfma_f32_16x16x32_bf16 v[30:33], v[240:243], v[216:219], v[30:33]
	v_mfma_f32_16x16x32_bf16 v[34:37], v[228:231], v[220:223], v[34:37]
	v_mfma_f32_16x16x32_bf16 v[38:41], v[232:235], v[220:223], v[38:41]
	v_mfma_f32_16x16x32_bf16 v[42:45], v[236:239], v[220:223], v[42:45]
	v_mfma_f32_16x16x32_bf16 v[46:49], v[240:243], v[220:223], v[46:49]
	v_mfma_f32_16x16x32_bf16 v[50:53], v[228:231], v[224:227], v[50:53]
	v_mfma_f32_16x16x32_bf16 v[54:57], v[232:235], v[224:227], v[54:57]
	v_mfma_f32_16x16x32_bf16 v[58:61], v[236:239], v[224:227], v[58:61]
	v_mfma_f32_16x16x32_bf16 v[62:65], v[240:243], v[224:227], v[62:65]
	s_waitcnt vmcnt(8)
	s_barrier
	v_add_u32_e32 v204, 0xc000, v200
	v_add_u32_e32 v205, 0xc000, v202
	ds_read_b128 v[130:133], v204 offset:0
	ds_read_b128 v[134:137], v204 offset:2048
	ds_read_b128 v[138:141], v204 offset:4096
	ds_read_b128 v[142:145], v204 offset:6144
	ds_read_b128 v[146:149], v205 offset:0
	ds_read_b128 v[150:153], v205 offset:2048
	ds_read_b128 v[154:157], v205 offset:4096
	ds_read_b128 v[158:161], v205 offset:6144
	v_add_u32_e32 v204, 0xc000, v201
	v_add_u32_e32 v205, 0xc000, v203
	ds_read_b128 v[212:215], v204 offset:0
	ds_read_b128 v[216:219], v204 offset:2048
	ds_read_b128 v[220:223], v204 offset:4096
	ds_read_b128 v[224:227], v204 offset:6144
	ds_read_b128 v[228:231], v205 offset:0
	ds_read_b128 v[232:235], v205 offset:2048
	ds_read_b128 v[236:239], v205 offset:4096
	ds_read_b128 v[240:243], v205 offset:6144
	s_add_u32 m0, s76, 0x0
	s_nop 0
	global_load_lds_dwordx4 v196, s[68:69]
	s_add_u32 m0, s76, 0x2000
	s_nop 0
	global_load_lds_dwordx4 v197, s[68:69]
	s_add_u32 m0, s76, 0x4000
	s_nop 0
	global_load_lds_dwordx4 v198, s[68:69]
	s_add_u32 m0, s76, 0x6000
	s_nop 0
	global_load_lds_dwordx4 v199, s[68:69]
	s_add_u32 m0, s76, 0x8000
	s_nop 0
	global_load_lds_dwordx4 v196, s[70:71]
	s_add_u32 m0, s76, 0xa000
	s_nop 0
	global_load_lds_dwordx4 v197, s[70:71]
	s_add_u32 s68, s68, 0x80
	s_addc_u32 s69, s69, 0
	s_add_u32 s70, s70, 0x80
	s_addc_u32 s71, s71, 0
	global_load_dwordx4 v[182:185], v190, s[72:73] offset:128
	global_load_dwordx4 v[186:189], v190, s[72:73] offset:192
	s_waitcnt lgkmcnt(0)
	s_barrier
	v_mfma_f32_16x16x32_bf16 v[2:5], v[146:149], v[130:133], v[2:5]
	v_mfma_f32_16x16x32_bf16 v[6:9], v[150:153], v[130:133], v[6:9]
	v_mfma_f32_16x16x32_bf16 v[10:13], v[154:157], v[130:133], v[10:13]
	v_mfma_f32_16x16x32_bf16 v[14:17], v[158:161], v[130:133], v[14:17]
	v_mfma_f32_16x16x32_bf16 v[18:21], v[146:149], v[134:137], v[18:21]
	v_mfma_f32_16x16x32_bf16 v[22:25], v[150:153], v[134:137], v[22:25]
	v_mfma_f32_16x16x32_bf16 v[26:29], v[154:157], v[134:137], v[26:29]
	v_mfma_f32_16x16x32_bf16 v[30:33], v[158:161], v[134:137], v[30:33]
	v_mfma_f32_16x16x32_bf16 v[34:37], v[146:149], v[138:141], v[34:37]
	v_mfma_f32_16x16x32_bf16 v[38:41], v[150:153], v[138:141], v[38:41]
	v_mfma_f32_16x16x32_bf16 v[42:45], v[154:157], v[138:141], v[42:45]
	v_mfma_f32_16x16x32_bf16 v[46:49], v[158:161], v[138:141], v[46:49]
	v_mfma_f32_16x16x32_bf16 v[50:53], v[146:149], v[142:145], v[50:53]
	v_mfma_f32_16x16x32_bf16 v[54:57], v[150:153], v[142:145], v[54:57]
	v_mfma_f32_16x16x32_bf16 v[58:61], v[154:157], v[142:145], v[58:61]
	v_mfma_f32_16x16x32_bf16 v[62:65], v[158:161], v[142:145], v[62:65]
	v_mfma_f32_16x16x32_bf16 v[2:5], v[228:231], v[212:215], v[2:5]
	v_mfma_f32_16x16x32_bf16 v[6:9], v[232:235], v[212:215], v[6:9]
	v_mfma_f32_16x16x32_bf16 v[10:13], v[236:239], v[212:215], v[10:13]
	v_mfma_f32_16x16x32_bf16 v[14:17], v[240:243], v[212:215], v[14:17]
	v_mfma_f32_16x16x32_bf16 v[18:21], v[228:231], v[216:219], v[18:21]
	v_mfma_f32_16x16x32_bf16 v[22:25], v[232:235], v[216:219], v[22:25]
	v_mfma_f32_16x16x32_bf16 v[26:29], v[236:239], v[216:219], v[26:29]
	v_mfma_f32_16x16x32_bf16 v[30:33], v[240:243], v[216:219], v[30:33]
	v_mfma_f32_16x16x32_bf16 v[34:37], v[228:231], v[220:223], v[34:37]
	v_mfma_f32_16x16x32_bf16 v[38:41], v[232:235], v[220:223], v[38:41]
	v_mfma_f32_16x16x32_bf16 v[42:45], v[236:239], v[220:223], v[42:45]
	v_mfma_f32_16x16x32_bf16 v[46:49], v[240:243], v[220:223], v[46:49]
	v_mfma_f32_16x16x32_bf16 v[50:53], v[228:231], v[224:227], v[50:53]
	v_mfma_f32_16x16x32_bf16 v[54:57], v[232:235], v[224:227], v[54:57]
	v_mfma_f32_16x16x32_bf16 v[58:61], v[236:239], v[224:227], v[58:61]
	v_mfma_f32_16x16x32_bf16 v[62:65], v[240:243], v[224:227], v[62:65]
	s_waitcnt vmcnt(10)
	s_barrier
	v_add_u32_e32 v204, 0x18000, v200
	v_add_u32_e32 v205, 0x18000, v202
	ds_read_b128 v[130:133], v204 offset:0
	ds_read_b128 v[134:137], v204 offset:2048
	ds_read_b128 v[138:141], v204 offset:4096
	ds_read_b128 v[142:145], v204 offset:6144
	ds_read_b128 v[146:149], v205 offset:0
	ds_read_b128 v[150:153], v205 offset:2048
	ds_read_b128 v[154:157], v205 offset:4096
	ds_read_b128 v[158:161], v205 offset:6144
	v_add_u32_e32 v204, 0x18000, v201
	v_add_u32_e32 v205, 0x18000, v203
	ds_read_b128 v[212:215], v204 offset:0
	ds_read_b128 v[216:219], v204 offset:2048
	ds_read_b128 v[220:223], v204 offset:4096
	ds_read_b128 v[224:227], v204 offset:6144
	ds_read_b128 v[228:231], v205 offset:0
	ds_read_b128 v[232:235], v205 offset:2048
	ds_read_b128 v[236:239], v205 offset:4096
	ds_read_b128 v[240:243], v205 offset:6144
	s_add_u32 m0, s76, 0xc000
	s_nop 0
	global_load_lds_dwordx4 v196, s[68:69]
	s_add_u32 m0, s76, 0xe000
	s_nop 0
	global_load_lds_dwordx4 v197, s[68:69]
	s_add_u32 m0, s76, 0x10000
	s_nop 0
	global_load_lds_dwordx4 v198, s[68:69]
	s_add_u32 m0, s76, 0x12000
	s_nop 0
	global_load_lds_dwordx4 v199, s[68:69]
	s_add_u32 m0, s76, 0x14000
	s_nop 0
	global_load_lds_dwordx4 v196, s[70:71]
	s_add_u32 m0, s76, 0x16000
	s_nop 0
	global_load_lds_dwordx4 v197, s[70:71]
	s_add_u32 s68, s68, 0x80
	s_addc_u32 s69, s69, 0
	s_add_u32 s70, s70, 0x80
	s_addc_u32 s71, s71, 0
	global_load_dwordx4 v[66:69], v191, s[14:15]
	v_add_u32_e32 v170, s38, v191
	global_load_dwordx4 v[70:73], v170, s[14:15]
	s_waitcnt lgkmcnt(0)
	s_barrier
	v_mfma_f32_16x16x32_bf16 v[2:5], v[146:149], v[130:133], v[2:5]
	v_mfma_f32_16x16x32_bf16 v[6:9], v[150:153], v[130:133], v[6:9]
	v_mfma_f32_16x16x32_bf16 v[10:13], v[154:157], v[130:133], v[10:13]
	v_mfma_f32_16x16x32_bf16 v[14:17], v[158:161], v[130:133], v[14:17]
	v_mfma_f32_16x16x32_bf16 v[18:21], v[146:149], v[134:137], v[18:21]
	v_mfma_f32_16x16x32_bf16 v[22:25], v[150:153], v[134:137], v[22:25]
	v_mfma_f32_16x16x32_bf16 v[26:29], v[154:157], v[134:137], v[26:29]
	v_mfma_f32_16x16x32_bf16 v[30:33], v[158:161], v[134:137], v[30:33]
	v_mfma_f32_16x16x32_bf16 v[34:37], v[146:149], v[138:141], v[34:37]
	v_mfma_f32_16x16x32_bf16 v[38:41], v[150:153], v[138:141], v[38:41]
	v_mfma_f32_16x16x32_bf16 v[42:45], v[154:157], v[138:141], v[42:45]
	v_mfma_f32_16x16x32_bf16 v[46:49], v[158:161], v[138:141], v[46:49]
	v_mfma_f32_16x16x32_bf16 v[50:53], v[146:149], v[142:145], v[50:53]
	v_mfma_f32_16x16x32_bf16 v[54:57], v[150:153], v[142:145], v[54:57]
	v_mfma_f32_16x16x32_bf16 v[58:61], v[154:157], v[142:145], v[58:61]
	v_mfma_f32_16x16x32_bf16 v[62:65], v[158:161], v[142:145], v[62:65]
	v_mfma_f32_16x16x32_bf16 v[2:5], v[228:231], v[212:215], v[2:5]
	v_mfma_f32_16x16x32_bf16 v[6:9], v[232:235], v[212:215], v[6:9]
	v_mfma_f32_16x16x32_bf16 v[10:13], v[236:239], v[212:215], v[10:13]
	v_mfma_f32_16x16x32_bf16 v[14:17], v[240:243], v[212:215], v[14:17]
	v_mfma_f32_16x16x32_bf16 v[18:21], v[228:231], v[216:219], v[18:21]
	v_mfma_f32_16x16x32_bf16 v[22:25], v[232:235], v[216:219], v[22:25]
	v_mfma_f32_16x16x32_bf16 v[26:29], v[236:239], v[216:219], v[26:29]
	v_mfma_f32_16x16x32_bf16 v[30:33], v[240:243], v[216:219], v[30:33]
	v_mfma_f32_16x16x32_bf16 v[34:37], v[228:231], v[220:223], v[34:37]
	v_mfma_f32_16x16x32_bf16 v[38:41], v[232:235], v[220:223], v[38:41]
	v_mfma_f32_16x16x32_bf16 v[42:45], v[236:239], v[220:223], v[42:45]
	v_mfma_f32_16x16x32_bf16 v[46:49], v[240:243], v[220:223], v[46:49]
	v_mfma_f32_16x16x32_bf16 v[50:53], v[228:231], v[224:227], v[50:53]
	v_mfma_f32_16x16x32_bf16 v[54:57], v[232:235], v[224:227], v[54:57]
	v_mfma_f32_16x16x32_bf16 v[58:61], v[236:239], v[224:227], v[58:61]
	v_mfma_f32_16x16x32_bf16 v[62:65], v[240:243], v[224:227], v[62:65]
	s_waitcnt vmcnt(10)
	s_barrier
	v_add_u32_e32 v204, 0x0, v200
	v_add_u32_e32 v205, 0x0, v202
	ds_read_b128 v[130:133], v204 offset:0
	ds_read_b128 v[134:137], v204 offset:2048
	ds_read_b128 v[138:141], v204 offset:4096
	ds_read_b128 v[142:145], v204 offset:6144
	ds_read_b128 v[146:149], v205 offset:0
	ds_read_b128 v[150:153], v205 offset:2048
	ds_read_b128 v[154:157], v205 offset:4096
	ds_read_b128 v[158:161], v205 offset:6144
	v_add_u32_e32 v204, 0x0, v201
	v_add_u32_e32 v205, 0x0, v203
	ds_read_b128 v[212:215], v204 offset:0
	ds_read_b128 v[216:219], v204 offset:2048
	ds_read_b128 v[220:223], v204 offset:4096
	ds_read_b128 v[224:227], v204 offset:6144
	ds_read_b128 v[228:231], v205 offset:0
	ds_read_b128 v[232:235], v205 offset:2048
	ds_read_b128 v[236:239], v205 offset:4096
	ds_read_b128 v[240:243], v205 offset:6144
	s_add_u32 m0, s76, 0x18000
	s_nop 0
	global_load_lds_dwordx4 v196, s[68:69]
	s_add_u32 m0, s76, 0x1a000
	s_nop 0
	global_load_lds_dwordx4 v197, s[68:69]
	s_add_u32 m0, s76, 0x1c000
	s_nop 0
	global_load_lds_dwordx4 v198, s[68:69]
	s_add_u32 m0, s76, 0x1e000
	s_nop 0
	global_load_lds_dwordx4 v199, s[68:69]
	s_add_u32 m0, s76, 0x20000
	s_nop 0
	global_load_lds_dwordx4 v196, s[70:71]
	s_add_u32 m0, s76, 0x22000
	s_nop 0
	global_load_lds_dwordx4 v197, s[70:71]
	s_add_u32 s68, s68, 0x80
	s_addc_u32 s69, s69, 0
	s_add_u32 s70, s70, 0x80
	s_addc_u32 s71, s71, 0
	v_add_u32_e32 v170, s39, v191
	global_load_dwordx4 v[74:77], v170, s[14:15]
	v_add_u32_e32 v170, s40, v191
	global_load_dwordx4 v[78:81], v170, s[14:15]
	s_waitcnt lgkmcnt(0)
	s_barrier
	v_mfma_f32_16x16x32_bf16 v[2:5], v[146:149], v[130:133], v[2:5]
	v_mfma_f32_16x16x32_bf16 v[6:9], v[150:153], v[130:133], v[6:9]
	v_mfma_f32_16x16x32_bf16 v[10:13], v[154:157], v[130:133], v[10:13]
	v_mfma_f32_16x16x32_bf16 v[14:17], v[158:161], v[130:133], v[14:17]
	v_mfma_f32_16x16x32_bf16 v[18:21], v[146:149], v[134:137], v[18:21]
	v_mfma_f32_16x16x32_bf16 v[22:25], v[150:153], v[134:137], v[22:25]
	v_mfma_f32_16x16x32_bf16 v[26:29], v[154:157], v[134:137], v[26:29]
	v_mfma_f32_16x16x32_bf16 v[30:33], v[158:161], v[134:137], v[30:33]
	v_mfma_f32_16x16x32_bf16 v[34:37], v[146:149], v[138:141], v[34:37]
	v_mfma_f32_16x16x32_bf16 v[38:41], v[150:153], v[138:141], v[38:41]
	v_mfma_f32_16x16x32_bf16 v[42:45], v[154:157], v[138:141], v[42:45]
	v_mfma_f32_16x16x32_bf16 v[46:49], v[158:161], v[138:141], v[46:49]
	v_mfma_f32_16x16x32_bf16 v[50:53], v[146:149], v[142:145], v[50:53]
	v_mfma_f32_16x16x32_bf16 v[54:57], v[150:153], v[142:145], v[54:57]
	v_mfma_f32_16x16x32_bf16 v[58:61], v[154:157], v[142:145], v[58:61]
	v_mfma_f32_16x16x32_bf16 v[62:65], v[158:161], v[142:145], v[62:65]
	v_mfma_f32_16x16x32_bf16 v[2:5], v[228:231], v[212:215], v[2:5]
	v_mfma_f32_16x16x32_bf16 v[6:9], v[232:235], v[212:215], v[6:9]
	v_mfma_f32_16x16x32_bf16 v[10:13], v[236:239], v[212:215], v[10:13]
	v_mfma_f32_16x16x32_bf16 v[14:17], v[240:243], v[212:215], v[14:17]
	v_mfma_f32_16x16x32_bf16 v[18:21], v[228:231], v[216:219], v[18:21]
	v_mfma_f32_16x16x32_bf16 v[22:25], v[232:235], v[216:219], v[22:25]
	v_mfma_f32_16x16x32_bf16 v[26:29], v[236:239], v[216:219], v[26:29]
	v_mfma_f32_16x16x32_bf16 v[30:33], v[240:243], v[216:219], v[30:33]
	v_mfma_f32_16x16x32_bf16 v[34:37], v[228:231], v[220:223], v[34:37]
	v_mfma_f32_16x16x32_bf16 v[38:41], v[232:235], v[220:223], v[38:41]
	v_mfma_f32_16x16x32_bf16 v[42:45], v[236:239], v[220:223], v[42:45]
	v_mfma_f32_16x16x32_bf16 v[46:49], v[240:243], v[220:223], v[46:49]
	v_mfma_f32_16x16x32_bf16 v[50:53], v[228:231], v[224:227], v[50:53]
	v_mfma_f32_16x16x32_bf16 v[54:57], v[232:235], v[224:227], v[54:57]
	v_mfma_f32_16x16x32_bf16 v[58:61], v[236:239], v[224:227], v[58:61]
	v_mfma_f32_16x16x32_bf16 v[62:65], v[240:243], v[224:227], v[62:65]
	s_waitcnt vmcnt(10)
	s_barrier
	v_add_u32_e32 v204, 0xc000, v200
	v_add_u32_e32 v205, 0xc000, v202
	ds_read_b128 v[130:133], v204 offset:0
	ds_read_b128 v[134:137], v204 offset:2048
	ds_read_b128 v[138:141], v204 offset:4096
	ds_read_b128 v[142:145], v204 offset:6144
	ds_read_b128 v[146:149], v205 offset:0
	ds_read_b128 v[150:153], v205 offset:2048
	ds_read_b128 v[154:157], v205 offset:4096
	ds_read_b128 v[158:161], v205 offset:6144
	v_add_u32_e32 v204, 0xc000, v201
	v_add_u32_e32 v205, 0xc000, v203
	ds_read_b128 v[212:215], v204 offset:0
	ds_read_b128 v[216:219], v204 offset:2048
	ds_read_b128 v[220:223], v204 offset:4096
	ds_read_b128 v[224:227], v204 offset:6144
	ds_read_b128 v[228:231], v205 offset:0
	ds_read_b128 v[232:235], v205 offset:2048
	ds_read_b128 v[236:239], v205 offset:4096
	ds_read_b128 v[240:243], v205 offset:6144
	s_add_u32 m0, s76, 0x0
	s_nop 0
	global_load_lds_dwordx4 v196, s[68:69]
	s_add_u32 m0, s76, 0x2000
	s_nop 0
	global_load_lds_dwordx4 v197, s[68:69]
	s_add_u32 m0, s76, 0x4000
	s_nop 0
	global_load_lds_dwordx4 v198, s[68:69]
	s_add_u32 m0, s76, 0x6000
	s_nop 0
	global_load_lds_dwordx4 v199, s[68:69]
	s_add_u32 m0, s76, 0x8000
	s_nop 0
	global_load_lds_dwordx4 v196, s[70:71]
	s_add_u32 m0, s76, 0xa000
	s_nop 0
	global_load_lds_dwordx4 v197, s[70:71]
	s_add_u32 s68, s68, 0x80
	s_addc_u32 s69, s69, 0
	s_add_u32 s70, s70, 0x80
	s_addc_u32 s71, s71, 0
	global_load_dwordx4 v[82:85], v192, s[14:15]
	v_add_u32_e32 v170, s38, v192
	global_load_dwordx4 v[86:89], v170, s[14:15]
	s_waitcnt lgkmcnt(0)
	s_barrier
	v_mfma_f32_16x16x32_bf16 v[2:5], v[146:149], v[130:133], v[2:5]
	v_mfma_f32_16x16x32_bf16 v[6:9], v[150:153], v[130:133], v[6:9]
	v_mfma_f32_16x16x32_bf16 v[10:13], v[154:157], v[130:133], v[10:13]
	v_mfma_f32_16x16x32_bf16 v[14:17], v[158:161], v[130:133], v[14:17]
	v_mfma_f32_16x16x32_bf16 v[18:21], v[146:149], v[134:137], v[18:21]
	v_mfma_f32_16x16x32_bf16 v[22:25], v[150:153], v[134:137], v[22:25]
	v_mfma_f32_16x16x32_bf16 v[26:29], v[154:157], v[134:137], v[26:29]
	v_mfma_f32_16x16x32_bf16 v[30:33], v[158:161], v[134:137], v[30:33]
	v_mfma_f32_16x16x32_bf16 v[34:37], v[146:149], v[138:141], v[34:37]
	v_mfma_f32_16x16x32_bf16 v[38:41], v[150:153], v[138:141], v[38:41]
	v_mfma_f32_16x16x32_bf16 v[42:45], v[154:157], v[138:141], v[42:45]
	v_mfma_f32_16x16x32_bf16 v[46:49], v[158:161], v[138:141], v[46:49]
	v_mfma_f32_16x16x32_bf16 v[50:53], v[146:149], v[142:145], v[50:53]
	v_mfma_f32_16x16x32_bf16 v[54:57], v[150:153], v[142:145], v[54:57]
	v_mfma_f32_16x16x32_bf16 v[58:61], v[154:157], v[142:145], v[58:61]
	v_mfma_f32_16x16x32_bf16 v[62:65], v[158:161], v[142:145], v[62:65]
	v_mfma_f32_16x16x32_bf16 v[2:5], v[228:231], v[212:215], v[2:5]
	v_mfma_f32_16x16x32_bf16 v[6:9], v[232:235], v[212:215], v[6:9]
	v_mfma_f32_16x16x32_bf16 v[10:13], v[236:239], v[212:215], v[10:13]
	v_mfma_f32_16x16x32_bf16 v[14:17], v[240:243], v[212:215], v[14:17]
	v_mfma_f32_16x16x32_bf16 v[18:21], v[228:231], v[216:219], v[18:21]
	v_mfma_f32_16x16x32_bf16 v[22:25], v[232:235], v[216:219], v[22:25]
	v_mfma_f32_16x16x32_bf16 v[26:29], v[236:239], v[216:219], v[26:29]
	v_mfma_f32_16x16x32_bf16 v[30:33], v[240:243], v[216:219], v[30:33]
	v_mfma_f32_16x16x32_bf16 v[34:37], v[228:231], v[220:223], v[34:37]
	v_mfma_f32_16x16x32_bf16 v[38:41], v[232:235], v[220:223], v[38:41]
	v_mfma_f32_16x16x32_bf16 v[42:45], v[236:239], v[220:223], v[42:45]
	v_mfma_f32_16x16x32_bf16 v[46:49], v[240:243], v[220:223], v[46:49]
	v_mfma_f32_16x16x32_bf16 v[50:53], v[228:231], v[224:227], v[50:53]
	v_mfma_f32_16x16x32_bf16 v[54:57], v[232:235], v[224:227], v[54:57]
	v_mfma_f32_16x16x32_bf16 v[58:61], v[236:239], v[224:227], v[58:61]
	v_mfma_f32_16x16x32_bf16 v[62:65], v[240:243], v[224:227], v[62:65]
	s_waitcnt vmcnt(10)
	s_barrier
	v_add_u32_e32 v204, 0x18000, v200
	v_add_u32_e32 v205, 0x18000, v202
	ds_read_b128 v[130:133], v204 offset:0
	ds_read_b128 v[134:137], v204 offset:2048
	ds_read_b128 v[138:141], v204 offset:4096
	ds_read_b128 v[142:145], v204 offset:6144
	ds_read_b128 v[146:149], v205 offset:0
	ds_read_b128 v[150:153], v205 offset:2048
	ds_read_b128 v[154:157], v205 offset:4096
	ds_read_b128 v[158:161], v205 offset:6144
	v_add_u32_e32 v204, 0x18000, v201
	v_add_u32_e32 v205, 0x18000, v203
	ds_read_b128 v[212:215], v204 offset:0
	ds_read_b128 v[216:219], v204 offset:2048
	ds_read_b128 v[220:223], v204 offset:4096
	ds_read_b128 v[224:227], v204 offset:6144
	ds_read_b128 v[228:231], v205 offset:0
	ds_read_b128 v[232:235], v205 offset:2048
	ds_read_b128 v[236:239], v205 offset:4096
	ds_read_b128 v[240:243], v205 offset:6144
	s_add_u32 m0, s76, 0xc000
	s_nop 0
	global_load_lds_dwordx4 v196, s[68:69]
	s_add_u32 m0, s76, 0xe000
	s_nop 0
	global_load_lds_dwordx4 v197, s[68:69]
	s_add_u32 m0, s76, 0x10000
	s_nop 0
	global_load_lds_dwordx4 v198, s[68:69]
	s_add_u32 m0, s76, 0x12000
	s_nop 0
	global_load_lds_dwordx4 v199, s[68:69]
	s_add_u32 m0, s76, 0x14000
	s_nop 0
	global_load_lds_dwordx4 v196, s[70:71]
	s_add_u32 m0, s76, 0x16000
	s_nop 0
	global_load_lds_dwordx4 v197, s[70:71]
	s_add_u32 s68, s68, 0x80
	s_addc_u32 s69, s69, 0
	s_add_u32 s70, s70, 0x80
	s_addc_u32 s71, s71, 0
	v_add_u32_e32 v170, s39, v192
	global_load_dwordx4 v[90:93], v170, s[14:15]
	v_add_u32_e32 v170, s40, v192
	global_load_dwordx4 v[94:97], v170, s[14:15]
	s_waitcnt lgkmcnt(0)
	s_barrier
	v_mfma_f32_16x16x32_bf16 v[2:5], v[146:149], v[130:133], v[2:5]
	v_mfma_f32_16x16x32_bf16 v[6:9], v[150:153], v[130:133], v[6:9]
	v_mfma_f32_16x16x32_bf16 v[10:13], v[154:157], v[130:133], v[10:13]
	v_mfma_f32_16x16x32_bf16 v[14:17], v[158:161], v[130:133], v[14:17]
	v_mfma_f32_16x16x32_bf16 v[18:21], v[146:149], v[134:137], v[18:21]
	v_mfma_f32_16x16x32_bf16 v[22:25], v[150:153], v[134:137], v[22:25]
	v_mfma_f32_16x16x32_bf16 v[26:29], v[154:157], v[134:137], v[26:29]
	v_mfma_f32_16x16x32_bf16 v[30:33], v[158:161], v[134:137], v[30:33]
	v_mfma_f32_16x16x32_bf16 v[34:37], v[146:149], v[138:141], v[34:37]
	v_mfma_f32_16x16x32_bf16 v[38:41], v[150:153], v[138:141], v[38:41]
	v_mfma_f32_16x16x32_bf16 v[42:45], v[154:157], v[138:141], v[42:45]
	v_mfma_f32_16x16x32_bf16 v[46:49], v[158:161], v[138:141], v[46:49]
	v_mfma_f32_16x16x32_bf16 v[50:53], v[146:149], v[142:145], v[50:53]
	v_mfma_f32_16x16x32_bf16 v[54:57], v[150:153], v[142:145], v[54:57]
	v_mfma_f32_16x16x32_bf16 v[58:61], v[154:157], v[142:145], v[58:61]
	v_mfma_f32_16x16x32_bf16 v[62:65], v[158:161], v[142:145], v[62:65]
	v_mfma_f32_16x16x32_bf16 v[2:5], v[228:231], v[212:215], v[2:5]
	v_mfma_f32_16x16x32_bf16 v[6:9], v[232:235], v[212:215], v[6:9]
	v_mfma_f32_16x16x32_bf16 v[10:13], v[236:239], v[212:215], v[10:13]
	v_mfma_f32_16x16x32_bf16 v[14:17], v[240:243], v[212:215], v[14:17]
	v_mfma_f32_16x16x32_bf16 v[18:21], v[228:231], v[216:219], v[18:21]
	v_mfma_f32_16x16x32_bf16 v[22:25], v[232:235], v[216:219], v[22:25]
	v_mfma_f32_16x16x32_bf16 v[26:29], v[236:239], v[216:219], v[26:29]
	v_mfma_f32_16x16x32_bf16 v[30:33], v[240:243], v[216:219], v[30:33]
	v_mfma_f32_16x16x32_bf16 v[34:37], v[228:231], v[220:223], v[34:37]
	v_mfma_f32_16x16x32_bf16 v[38:41], v[232:235], v[220:223], v[38:41]
	v_mfma_f32_16x16x32_bf16 v[42:45], v[236:239], v[220:223], v[42:45]
	v_mfma_f32_16x16x32_bf16 v[46:49], v[240:243], v[220:223], v[46:49]
	v_mfma_f32_16x16x32_bf16 v[50:53], v[228:231], v[224:227], v[50:53]
	v_mfma_f32_16x16x32_bf16 v[54:57], v[232:235], v[224:227], v[54:57]
	v_mfma_f32_16x16x32_bf16 v[58:61], v[236:239], v[224:227], v[58:61]
	v_mfma_f32_16x16x32_bf16 v[62:65], v[240:243], v[224:227], v[62:65]
	s_waitcnt vmcnt(10)
	s_barrier
	v_add_u32_e32 v204, 0x0, v200
	v_add_u32_e32 v205, 0x0, v202
	ds_read_b128 v[130:133], v204 offset:0
	ds_read_b128 v[134:137], v204 offset:2048
	ds_read_b128 v[138:141], v204 offset:4096
	ds_read_b128 v[142:145], v204 offset:6144
	ds_read_b128 v[146:149], v205 offset:0
	ds_read_b128 v[150:153], v205 offset:2048
	ds_read_b128 v[154:157], v205 offset:4096
	ds_read_b128 v[158:161], v205 offset:6144
	v_add_u32_e32 v204, 0x0, v201
	v_add_u32_e32 v205, 0x0, v203
	ds_read_b128 v[212:215], v204 offset:0
	ds_read_b128 v[216:219], v204 offset:2048
	ds_read_b128 v[220:223], v204 offset:4096
	ds_read_b128 v[224:227], v204 offset:6144
	ds_read_b128 v[228:231], v205 offset:0
	ds_read_b128 v[232:235], v205 offset:2048
	ds_read_b128 v[236:239], v205 offset:4096
	ds_read_b128 v[240:243], v205 offset:6144
	s_add_u32 m0, s76, 0x18000
	s_nop 0
	global_load_lds_dwordx4 v196, s[68:69]
	s_add_u32 m0, s76, 0x1a000
	s_nop 0
	global_load_lds_dwordx4 v197, s[68:69]
	s_add_u32 m0, s76, 0x1c000
	s_nop 0
	global_load_lds_dwordx4 v198, s[68:69]
	s_add_u32 m0, s76, 0x1e000
	s_nop 0
	global_load_lds_dwordx4 v199, s[68:69]
	s_add_u32 m0, s76, 0x20000
	s_nop 0
	global_load_lds_dwordx4 v196, s[70:71]
	s_add_u32 m0, s76, 0x22000
	s_nop 0
	global_load_lds_dwordx4 v197, s[70:71]
	s_add_u32 s68, s68, 0x80
	s_addc_u32 s69, s69, 0
	s_add_u32 s70, s70, 0x80
	s_addc_u32 s71, s71, 0
	global_load_dwordx4 v[98:101], v193, s[14:15]
	v_add_u32_e32 v170, s38, v193
	global_load_dwordx4 v[102:105], v170, s[14:15]
	s_waitcnt lgkmcnt(0)
	s_barrier
	v_mfma_f32_16x16x32_bf16 v[2:5], v[146:149], v[130:133], v[2:5]
	v_mfma_f32_16x16x32_bf16 v[6:9], v[150:153], v[130:133], v[6:9]
	v_mfma_f32_16x16x32_bf16 v[10:13], v[154:157], v[130:133], v[10:13]
	v_mfma_f32_16x16x32_bf16 v[14:17], v[158:161], v[130:133], v[14:17]
	v_mfma_f32_16x16x32_bf16 v[18:21], v[146:149], v[134:137], v[18:21]
	v_mfma_f32_16x16x32_bf16 v[22:25], v[150:153], v[134:137], v[22:25]
	v_mfma_f32_16x16x32_bf16 v[26:29], v[154:157], v[134:137], v[26:29]
	v_mfma_f32_16x16x32_bf16 v[30:33], v[158:161], v[134:137], v[30:33]
	v_mfma_f32_16x16x32_bf16 v[34:37], v[146:149], v[138:141], v[34:37]
	v_mfma_f32_16x16x32_bf16 v[38:41], v[150:153], v[138:141], v[38:41]
	v_mfma_f32_16x16x32_bf16 v[42:45], v[154:157], v[138:141], v[42:45]
	v_mfma_f32_16x16x32_bf16 v[46:49], v[158:161], v[138:141], v[46:49]
	v_mfma_f32_16x16x32_bf16 v[50:53], v[146:149], v[142:145], v[50:53]
	v_mfma_f32_16x16x32_bf16 v[54:57], v[150:153], v[142:145], v[54:57]
	v_mfma_f32_16x16x32_bf16 v[58:61], v[154:157], v[142:145], v[58:61]
	v_mfma_f32_16x16x32_bf16 v[62:65], v[158:161], v[142:145], v[62:65]
	v_mfma_f32_16x16x32_bf16 v[2:5], v[228:231], v[212:215], v[2:5]
	v_mfma_f32_16x16x32_bf16 v[6:9], v[232:235], v[212:215], v[6:9]
	v_mfma_f32_16x16x32_bf16 v[10:13], v[236:239], v[212:215], v[10:13]
	v_mfma_f32_16x16x32_bf16 v[14:17], v[240:243], v[212:215], v[14:17]
	v_mfma_f32_16x16x32_bf16 v[18:21], v[228:231], v[216:219], v[18:21]
	v_mfma_f32_16x16x32_bf16 v[22:25], v[232:235], v[216:219], v[22:25]
	v_mfma_f32_16x16x32_bf16 v[26:29], v[236:239], v[216:219], v[26:29]
	v_mfma_f32_16x16x32_bf16 v[30:33], v[240:243], v[216:219], v[30:33]
	v_mfma_f32_16x16x32_bf16 v[34:37], v[228:231], v[220:223], v[34:37]
	v_mfma_f32_16x16x32_bf16 v[38:41], v[232:235], v[220:223], v[38:41]
	v_mfma_f32_16x16x32_bf16 v[42:45], v[236:239], v[220:223], v[42:45]
	v_mfma_f32_16x16x32_bf16 v[46:49], v[240:243], v[220:223], v[46:49]
	v_mfma_f32_16x16x32_bf16 v[50:53], v[228:231], v[224:227], v[50:53]
	v_mfma_f32_16x16x32_bf16 v[54:57], v[232:235], v[224:227], v[54:57]
	v_mfma_f32_16x16x32_bf16 v[58:61], v[236:239], v[224:227], v[58:61]
	v_mfma_f32_16x16x32_bf16 v[62:65], v[240:243], v[224:227], v[62:65]
	s_waitcnt vmcnt(10)
	s_barrier
	v_add_u32_e32 v204, 0xc000, v200
	v_add_u32_e32 v205, 0xc000, v202
	ds_read_b128 v[130:133], v204 offset:0
	ds_read_b128 v[134:137], v204 offset:2048
	ds_read_b128 v[138:141], v204 offset:4096
	ds_read_b128 v[142:145], v204 offset:6144
	ds_read_b128 v[146:149], v205 offset:0
	ds_read_b128 v[150:153], v205 offset:2048
	ds_read_b128 v[154:157], v205 offset:4096
	ds_read_b128 v[158:161], v205 offset:6144
	v_add_u32_e32 v204, 0xc000, v201
	v_add_u32_e32 v205, 0xc000, v203
	ds_read_b128 v[212:215], v204 offset:0
	ds_read_b128 v[216:219], v204 offset:2048
	ds_read_b128 v[220:223], v204 offset:4096
	ds_read_b128 v[224:227], v204 offset:6144
	ds_read_b128 v[228:231], v205 offset:0
	ds_read_b128 v[232:235], v205 offset:2048
	ds_read_b128 v[236:239], v205 offset:4096
	ds_read_b128 v[240:243], v205 offset:6144
	s_add_u32 m0, s76, 0x0
	s_nop 0
	global_load_lds_dwordx4 v196, s[68:69]
	s_add_u32 m0, s76, 0x2000
	s_nop 0
	global_load_lds_dwordx4 v197, s[68:69]
	s_add_u32 m0, s76, 0x4000
	s_nop 0
	global_load_lds_dwordx4 v198, s[68:69]
	s_add_u32 m0, s76, 0x6000
	s_nop 0
	global_load_lds_dwordx4 v199, s[68:69]
	s_add_u32 m0, s76, 0x8000
	s_nop 0
	global_load_lds_dwordx4 v196, s[70:71]
	s_add_u32 m0, s76, 0xa000
	s_nop 0
	global_load_lds_dwordx4 v197, s[70:71]
	s_add_u32 s68, s68, 0x80
	s_addc_u32 s69, s69, 0
	s_add_u32 s70, s70, 0x80
	s_addc_u32 s71, s71, 0
	v_add_u32_e32 v170, s39, v193
	global_load_dwordx4 v[106:109], v170, s[14:15]
	v_add_u32_e32 v170, s40, v193
	global_load_dwordx4 v[110:113], v170, s[14:15]
	s_waitcnt lgkmcnt(0)
	s_barrier
	v_mfma_f32_16x16x32_bf16 v[2:5], v[146:149], v[130:133], v[2:5]
	v_mfma_f32_16x16x32_bf16 v[6:9], v[150:153], v[130:133], v[6:9]
	v_mfma_f32_16x16x32_bf16 v[10:13], v[154:157], v[130:133], v[10:13]
	v_mfma_f32_16x16x32_bf16 v[14:17], v[158:161], v[130:133], v[14:17]
	v_mfma_f32_16x16x32_bf16 v[18:21], v[146:149], v[134:137], v[18:21]
	v_mfma_f32_16x16x32_bf16 v[22:25], v[150:153], v[134:137], v[22:25]
	v_mfma_f32_16x16x32_bf16 v[26:29], v[154:157], v[134:137], v[26:29]
	v_mfma_f32_16x16x32_bf16 v[30:33], v[158:161], v[134:137], v[30:33]
	v_mfma_f32_16x16x32_bf16 v[34:37], v[146:149], v[138:141], v[34:37]
	v_mfma_f32_16x16x32_bf16 v[38:41], v[150:153], v[138:141], v[38:41]
	v_mfma_f32_16x16x32_bf16 v[42:45], v[154:157], v[138:141], v[42:45]
	v_mfma_f32_16x16x32_bf16 v[46:49], v[158:161], v[138:141], v[46:49]
	v_mfma_f32_16x16x32_bf16 v[50:53], v[146:149], v[142:145], v[50:53]
	v_mfma_f32_16x16x32_bf16 v[54:57], v[150:153], v[142:145], v[54:57]
	v_mfma_f32_16x16x32_bf16 v[58:61], v[154:157], v[142:145], v[58:61]
	v_mfma_f32_16x16x32_bf16 v[62:65], v[158:161], v[142:145], v[62:65]
	v_mfma_f32_16x16x32_bf16 v[2:5], v[228:231], v[212:215], v[2:5]
	v_mfma_f32_16x16x32_bf16 v[6:9], v[232:235], v[212:215], v[6:9]
	v_mfma_f32_16x16x32_bf16 v[10:13], v[236:239], v[212:215], v[10:13]
	v_mfma_f32_16x16x32_bf16 v[14:17], v[240:243], v[212:215], v[14:17]
	v_mfma_f32_16x16x32_bf16 v[18:21], v[228:231], v[216:219], v[18:21]
	v_mfma_f32_16x16x32_bf16 v[22:25], v[232:235], v[216:219], v[22:25]
	v_mfma_f32_16x16x32_bf16 v[26:29], v[236:239], v[216:219], v[26:29]
	v_mfma_f32_16x16x32_bf16 v[30:33], v[240:243], v[216:219], v[30:33]
	v_mfma_f32_16x16x32_bf16 v[34:37], v[228:231], v[220:223], v[34:37]
	v_mfma_f32_16x16x32_bf16 v[38:41], v[232:235], v[220:223], v[38:41]
	v_mfma_f32_16x16x32_bf16 v[42:45], v[236:239], v[220:223], v[42:45]
	v_mfma_f32_16x16x32_bf16 v[46:49], v[240:243], v[220:223], v[46:49]
	v_mfma_f32_16x16x32_bf16 v[50:53], v[228:231], v[224:227], v[50:53]
	v_mfma_f32_16x16x32_bf16 v[54:57], v[232:235], v[224:227], v[54:57]
	v_mfma_f32_16x16x32_bf16 v[58:61], v[236:239], v[224:227], v[58:61]
	v_mfma_f32_16x16x32_bf16 v[62:65], v[240:243], v[224:227], v[62:65]
	s_waitcnt vmcnt(10)
	s_barrier
	v_add_u32_e32 v204, 0x18000, v200
	v_add_u32_e32 v205, 0x18000, v202
	ds_read_b128 v[130:133], v204 offset:0
	ds_read_b128 v[134:137], v204 offset:2048
	ds_read_b128 v[138:141], v204 offset:4096
	ds_read_b128 v[142:145], v204 offset:6144
	ds_read_b128 v[146:149], v205 offset:0
	ds_read_b128 v[150:153], v205 offset:2048
	ds_read_b128 v[154:157], v205 offset:4096
	ds_read_b128 v[158:161], v205 offset:6144
	v_add_u32_e32 v204, 0x18000, v201
	v_add_u32_e32 v205, 0x18000, v203
	ds_read_b128 v[212:215], v204 offset:0
	ds_read_b128 v[216:219], v204 offset:2048
	ds_read_b128 v[220:223], v204 offset:4096
	ds_read_b128 v[224:227], v204 offset:6144
	ds_read_b128 v[228:231], v205 offset:0
	ds_read_b128 v[232:235], v205 offset:2048
	ds_read_b128 v[236:239], v205 offset:4096
	ds_read_b128 v[240:243], v205 offset:6144
	s_add_u32 m0, s76, 0xc000
	s_nop 0
	global_load_lds_dwordx4 v196, s[68:69]
	s_add_u32 m0, s76, 0xe000
	s_nop 0
	global_load_lds_dwordx4 v197, s[68:69]
	s_add_u32 m0, s76, 0x10000
	s_nop 0
	global_load_lds_dwordx4 v198, s[68:69]
	s_add_u32 m0, s76, 0x12000
	s_nop 0
	global_load_lds_dwordx4 v199, s[68:69]
	s_add_u32 m0, s76, 0x14000
	s_nop 0
	global_load_lds_dwordx4 v196, s[70:71]
	s_add_u32 m0, s76, 0x16000
	s_nop 0
	global_load_lds_dwordx4 v197, s[70:71]
	s_add_u32 s68, s68, 0x80
	s_addc_u32 s69, s69, 0
	s_add_u32 s70, s70, 0x80
	s_addc_u32 s71, s71, 0
	global_load_dwordx4 v[114:117], v244, s[14:15]
	v_add_u32_e32 v170, s38, v244
	global_load_dwordx4 v[118:121], v170, s[14:15]
	s_waitcnt lgkmcnt(0)
	s_barrier
	v_mfma_f32_16x16x32_bf16 v[2:5], v[146:149], v[130:133], v[2:5]
	v_mfma_f32_16x16x32_bf16 v[6:9], v[150:153], v[130:133], v[6:9]
	v_mfma_f32_16x16x32_bf16 v[10:13], v[154:157], v[130:133], v[10:13]
	v_mfma_f32_16x16x32_bf16 v[14:17], v[158:161], v[130:133], v[14:17]
	v_mfma_f32_16x16x32_bf16 v[18:21], v[146:149], v[134:137], v[18:21]
	v_mfma_f32_16x16x32_bf16 v[22:25], v[150:153], v[134:137], v[22:25]
	v_mfma_f32_16x16x32_bf16 v[26:29], v[154:157], v[134:137], v[26:29]
	v_mfma_f32_16x16x32_bf16 v[30:33], v[158:161], v[134:137], v[30:33]
	v_mfma_f32_16x16x32_bf16 v[34:37], v[146:149], v[138:141], v[34:37]
	v_mfma_f32_16x16x32_bf16 v[38:41], v[150:153], v[138:141], v[38:41]
	v_mfma_f32_16x16x32_bf16 v[42:45], v[154:157], v[138:141], v[42:45]
	v_mfma_f32_16x16x32_bf16 v[46:49], v[158:161], v[138:141], v[46:49]
	v_mfma_f32_16x16x32_bf16 v[50:53], v[146:149], v[142:145], v[50:53]
	v_mfma_f32_16x16x32_bf16 v[54:57], v[150:153], v[142:145], v[54:57]
	v_mfma_f32_16x16x32_bf16 v[58:61], v[154:157], v[142:145], v[58:61]
	v_mfma_f32_16x16x32_bf16 v[62:65], v[158:161], v[142:145], v[62:65]
	v_mfma_f32_16x16x32_bf16 v[2:5], v[228:231], v[212:215], v[2:5]
	v_mfma_f32_16x16x32_bf16 v[6:9], v[232:235], v[212:215], v[6:9]
	v_mfma_f32_16x16x32_bf16 v[10:13], v[236:239], v[212:215], v[10:13]
	v_mfma_f32_16x16x32_bf16 v[14:17], v[240:243], v[212:215], v[14:17]
	v_mfma_f32_16x16x32_bf16 v[18:21], v[228:231], v[216:219], v[18:21]
	v_mfma_f32_16x16x32_bf16 v[22:25], v[232:235], v[216:219], v[22:25]
	v_mfma_f32_16x16x32_bf16 v[26:29], v[236:239], v[216:219], v[26:29]
	v_mfma_f32_16x16x32_bf16 v[30:33], v[240:243], v[216:219], v[30:33]
	v_mfma_f32_16x16x32_bf16 v[34:37], v[228:231], v[220:223], v[34:37]
	v_mfma_f32_16x16x32_bf16 v[38:41], v[232:235], v[220:223], v[38:41]
	v_mfma_f32_16x16x32_bf16 v[42:45], v[236:239], v[220:223], v[42:45]
	v_mfma_f32_16x16x32_bf16 v[46:49], v[240:243], v[220:223], v[46:49]
	v_mfma_f32_16x16x32_bf16 v[50:53], v[228:231], v[224:227], v[50:53]
	v_mfma_f32_16x16x32_bf16 v[54:57], v[232:235], v[224:227], v[54:57]
	v_mfma_f32_16x16x32_bf16 v[58:61], v[236:239], v[224:227], v[58:61]
	v_mfma_f32_16x16x32_bf16 v[62:65], v[240:243], v[224:227], v[62:65]
	s_waitcnt vmcnt(10)
	s_barrier
	v_add_u32_e32 v204, 0x0, v200
	v_add_u32_e32 v205, 0x0, v202
	ds_read_b128 v[130:133], v204 offset:0
	ds_read_b128 v[134:137], v204 offset:2048
	ds_read_b128 v[138:141], v204 offset:4096
	ds_read_b128 v[142:145], v204 offset:6144
	ds_read_b128 v[146:149], v205 offset:0
	ds_read_b128 v[150:153], v205 offset:2048
	ds_read_b128 v[154:157], v205 offset:4096
	ds_read_b128 v[158:161], v205 offset:6144
	v_add_u32_e32 v204, 0x0, v201
	v_add_u32_e32 v205, 0x0, v203
	ds_read_b128 v[212:215], v204 offset:0
	ds_read_b128 v[216:219], v204 offset:2048
	ds_read_b128 v[220:223], v204 offset:4096
	ds_read_b128 v[224:227], v204 offset:6144
	ds_read_b128 v[228:231], v205 offset:0
	ds_read_b128 v[232:235], v205 offset:2048
	ds_read_b128 v[236:239], v205 offset:4096
	ds_read_b128 v[240:243], v205 offset:6144
	s_add_u32 m0, s76, 0x18000
	s_nop 0
	global_load_lds_dwordx4 v196, s[68:69]
	s_add_u32 m0, s76, 0x1a000
	s_nop 0
	global_load_lds_dwordx4 v197, s[68:69]
	s_add_u32 m0, s76, 0x1c000
	s_nop 0
	global_load_lds_dwordx4 v198, s[68:69]
	s_add_u32 m0, s76, 0x1e000
	s_nop 0
	global_load_lds_dwordx4 v199, s[68:69]
	s_add_u32 m0, s76, 0x20000
	s_nop 0
	global_load_lds_dwordx4 v196, s[70:71]
	s_add_u32 m0, s76, 0x22000
	s_nop 0
	global_load_lds_dwordx4 v197, s[70:71]
	s_add_u32 s68, s68, 0x80
	s_addc_u32 s69, s69, 0
	s_add_u32 s70, s70, 0x80
	s_addc_u32 s71, s71, 0
	v_add_u32_e32 v170, s39, v244
	global_load_dwordx4 v[122:125], v170, s[14:15]
	v_add_u32_e32 v170, s40, v244
	global_load_dwordx4 v[126:129], v170, s[14:15]
	s_waitcnt lgkmcnt(0)
	s_barrier
	v_mfma_f32_16x16x32_bf16 v[2:5], v[146:149], v[130:133], v[2:5]
	v_mfma_f32_16x16x32_bf16 v[6:9], v[150:153], v[130:133], v[6:9]
	v_mfma_f32_16x16x32_bf16 v[10:13], v[154:157], v[130:133], v[10:13]
	v_mfma_f32_16x16x32_bf16 v[14:17], v[158:161], v[130:133], v[14:17]
	v_mfma_f32_16x16x32_bf16 v[18:21], v[146:149], v[134:137], v[18:21]
	v_mfma_f32_16x16x32_bf16 v[22:25], v[150:153], v[134:137], v[22:25]
	v_mfma_f32_16x16x32_bf16 v[26:29], v[154:157], v[134:137], v[26:29]
	v_mfma_f32_16x16x32_bf16 v[30:33], v[158:161], v[134:137], v[30:33]
	v_mfma_f32_16x16x32_bf16 v[34:37], v[146:149], v[138:141], v[34:37]
	v_mfma_f32_16x16x32_bf16 v[38:41], v[150:153], v[138:141], v[38:41]
	v_mfma_f32_16x16x32_bf16 v[42:45], v[154:157], v[138:141], v[42:45]
	v_mfma_f32_16x16x32_bf16 v[46:49], v[158:161], v[138:141], v[46:49]
	v_mfma_f32_16x16x32_bf16 v[50:53], v[146:149], v[142:145], v[50:53]
	v_mfma_f32_16x16x32_bf16 v[54:57], v[150:153], v[142:145], v[54:57]
	v_mfma_f32_16x16x32_bf16 v[58:61], v[154:157], v[142:145], v[58:61]
	v_mfma_f32_16x16x32_bf16 v[62:65], v[158:161], v[142:145], v[62:65]
	v_mfma_f32_16x16x32_bf16 v[2:5], v[228:231], v[212:215], v[2:5]
	v_mfma_f32_16x16x32_bf16 v[6:9], v[232:235], v[212:215], v[6:9]
	v_mfma_f32_16x16x32_bf16 v[10:13], v[236:239], v[212:215], v[10:13]
	v_mfma_f32_16x16x32_bf16 v[14:17], v[240:243], v[212:215], v[14:17]
	v_mfma_f32_16x16x32_bf16 v[18:21], v[228:231], v[216:219], v[18:21]
	v_mfma_f32_16x16x32_bf16 v[22:25], v[232:235], v[216:219], v[22:25]
	v_mfma_f32_16x16x32_bf16 v[26:29], v[236:239], v[216:219], v[26:29]
	v_mfma_f32_16x16x32_bf16 v[30:33], v[240:243], v[216:219], v[30:33]
	v_mfma_f32_16x16x32_bf16 v[34:37], v[228:231], v[220:223], v[34:37]
	v_mfma_f32_16x16x32_bf16 v[38:41], v[232:235], v[220:223], v[38:41]
	v_mfma_f32_16x16x32_bf16 v[42:45], v[236:239], v[220:223], v[42:45]
	v_mfma_f32_16x16x32_bf16 v[46:49], v[240:243], v[220:223], v[46:49]
	v_mfma_f32_16x16x32_bf16 v[50:53], v[228:231], v[224:227], v[50:53]
	v_mfma_f32_16x16x32_bf16 v[54:57], v[232:235], v[224:227], v[54:57]
	v_mfma_f32_16x16x32_bf16 v[58:61], v[236:239], v[224:227], v[58:61]
	v_mfma_f32_16x16x32_bf16 v[62:65], v[240:243], v[224:227], v[62:65]
	s_waitcnt vmcnt(10)
	s_barrier
	v_add_u32_e32 v204, 0xc000, v200
	v_add_u32_e32 v205, 0xc000, v202
	ds_read_b128 v[130:133], v204 offset:0
	ds_read_b128 v[134:137], v204 offset:2048
	ds_read_b128 v[138:141], v204 offset:4096
	ds_read_b128 v[142:145], v204 offset:6144
	ds_read_b128 v[146:149], v205 offset:0
	ds_read_b128 v[150:153], v205 offset:2048
	ds_read_b128 v[154:157], v205 offset:4096
	ds_read_b128 v[158:161], v205 offset:6144
	v_add_u32_e32 v204, 0xc000, v201
	v_add_u32_e32 v205, 0xc000, v203
	ds_read_b128 v[212:215], v204 offset:0
	ds_read_b128 v[216:219], v204 offset:2048
	ds_read_b128 v[220:223], v204 offset:4096
	ds_read_b128 v[224:227], v204 offset:6144
	ds_read_b128 v[228:231], v205 offset:0
	ds_read_b128 v[232:235], v205 offset:2048
	ds_read_b128 v[236:239], v205 offset:4096
	ds_read_b128 v[240:243], v205 offset:6144
	s_add_u32 m0, s76, 0x0
	s_nop 0
	global_load_lds_dwordx4 v196, s[68:69]
	s_add_u32 m0, s76, 0x2000
	s_nop 0
	global_load_lds_dwordx4 v197, s[68:69]
	s_add_u32 m0, s76, 0x4000
	s_nop 0
	global_load_lds_dwordx4 v198, s[68:69]
	s_add_u32 m0, s76, 0x6000
	s_nop 0
	global_load_lds_dwordx4 v199, s[68:69]
	s_add_u32 m0, s76, 0x8000
	s_nop 0
	global_load_lds_dwordx4 v196, s[70:71]
	s_add_u32 m0, s76, 0xa000
	s_nop 0
	global_load_lds_dwordx4 v197, s[70:71]
	s_add_u32 s68, s68, 0x80
	s_addc_u32 s69, s69, 0
	s_add_u32 s70, s70, 0x80
	s_addc_u32 s71, s71, 0
	s_waitcnt lgkmcnt(0)
	s_barrier
	v_mfma_f32_16x16x32_bf16 v[2:5], v[146:149], v[130:133], v[2:5]
	v_mfma_f32_16x16x32_bf16 v[6:9], v[150:153], v[130:133], v[6:9]
	v_mfma_f32_16x16x32_bf16 v[10:13], v[154:157], v[130:133], v[10:13]
	v_mfma_f32_16x16x32_bf16 v[14:17], v[158:161], v[130:133], v[14:17]
	v_mfma_f32_16x16x32_bf16 v[18:21], v[146:149], v[134:137], v[18:21]
	v_mfma_f32_16x16x32_bf16 v[22:25], v[150:153], v[134:137], v[22:25]
	v_mfma_f32_16x16x32_bf16 v[26:29], v[154:157], v[134:137], v[26:29]
	v_mfma_f32_16x16x32_bf16 v[30:33], v[158:161], v[134:137], v[30:33]
	v_mfma_f32_16x16x32_bf16 v[34:37], v[146:149], v[138:141], v[34:37]
	v_mfma_f32_16x16x32_bf16 v[38:41], v[150:153], v[138:141], v[38:41]
	v_mfma_f32_16x16x32_bf16 v[42:45], v[154:157], v[138:141], v[42:45]
	v_mfma_f32_16x16x32_bf16 v[46:49], v[158:161], v[138:141], v[46:49]
	v_mfma_f32_16x16x32_bf16 v[50:53], v[146:149], v[142:145], v[50:53]
	v_mfma_f32_16x16x32_bf16 v[54:57], v[150:153], v[142:145], v[54:57]
	v_mfma_f32_16x16x32_bf16 v[58:61], v[154:157], v[142:145], v[58:61]
	v_mfma_f32_16x16x32_bf16 v[62:65], v[158:161], v[142:145], v[62:65]
	v_mfma_f32_16x16x32_bf16 v[2:5], v[228:231], v[212:215], v[2:5]
	v_mfma_f32_16x16x32_bf16 v[6:9], v[232:235], v[212:215], v[6:9]
	v_mfma_f32_16x16x32_bf16 v[10:13], v[236:239], v[212:215], v[10:13]
	v_mfma_f32_16x16x32_bf16 v[14:17], v[240:243], v[212:215], v[14:17]
	v_mfma_f32_16x16x32_bf16 v[18:21], v[228:231], v[216:219], v[18:21]
	v_mfma_f32_16x16x32_bf16 v[22:25], v[232:235], v[216:219], v[22:25]
	v_mfma_f32_16x16x32_bf16 v[26:29], v[236:239], v[216:219], v[26:29]
	v_mfma_f32_16x16x32_bf16 v[30:33], v[240:243], v[216:219], v[30:33]
	v_mfma_f32_16x16x32_bf16 v[34:37], v[228:231], v[220:223], v[34:37]
	v_mfma_f32_16x16x32_bf16 v[38:41], v[232:235], v[220:223], v[38:41]
	v_mfma_f32_16x16x32_bf16 v[42:45], v[236:239], v[220:223], v[42:45]
	v_mfma_f32_16x16x32_bf16 v[46:49], v[240:243], v[220:223], v[46:49]
	v_mfma_f32_16x16x32_bf16 v[50:53], v[228:231], v[224:227], v[50:53]
	v_mfma_f32_16x16x32_bf16 v[54:57], v[232:235], v[224:227], v[54:57]
	v_mfma_f32_16x16x32_bf16 v[58:61], v[236:239], v[224:227], v[58:61]
	v_mfma_f32_16x16x32_bf16 v[62:65], v[240:243], v[224:227], v[62:65]
	s_waitcnt vmcnt(8)
	s_barrier
	v_add_u32_e32 v204, 0x18000, v200
	v_add_u32_e32 v205, 0x18000, v202
	ds_read_b128 v[130:133], v204 offset:0
	ds_read_b128 v[134:137], v204 offset:2048
	ds_read_b128 v[138:141], v204 offset:4096
	ds_read_b128 v[142:145], v204 offset:6144
	ds_read_b128 v[146:149], v205 offset:0
	ds_read_b128 v[150:153], v205 offset:2048
	ds_read_b128 v[154:157], v205 offset:4096
	ds_read_b128 v[158:161], v205 offset:6144
	v_add_u32_e32 v204, 0x18000, v201
	v_add_u32_e32 v205, 0x18000, v203
	ds_read_b128 v[212:215], v204 offset:0
	ds_read_b128 v[216:219], v204 offset:2048
	ds_read_b128 v[220:223], v204 offset:4096
	ds_read_b128 v[224:227], v204 offset:6144
	ds_read_b128 v[228:231], v205 offset:0
	ds_read_b128 v[232:235], v205 offset:2048
	ds_read_b128 v[236:239], v205 offset:4096
	ds_read_b128 v[240:243], v205 offset:6144
	s_add_u32 m0, s76, 0xc000
	s_nop 0
	global_load_lds_dwordx4 v196, s[68:69]
	s_add_u32 m0, s76, 0xe000
	s_nop 0
	global_load_lds_dwordx4 v197, s[68:69]
	s_add_u32 m0, s76, 0x10000
	s_nop 0
	global_load_lds_dwordx4 v198, s[68:69]
	s_add_u32 m0, s76, 0x12000
	s_nop 0
	global_load_lds_dwordx4 v199, s[68:69]
	s_add_u32 m0, s76, 0x14000
	s_nop 0
	global_load_lds_dwordx4 v196, s[70:71]
	s_add_u32 m0, s76, 0x16000
	s_nop 0
	global_load_lds_dwordx4 v197, s[70:71]
	s_add_u32 s68, s68, 0x80
	s_addc_u32 s69, s69, 0
	s_add_u32 s70, s70, 0x80
	s_addc_u32 s71, s71, 0
	s_waitcnt lgkmcnt(0)
	s_barrier
	v_mfma_f32_16x16x32_bf16 v[2:5], v[146:149], v[130:133], v[2:5]
	v_mfma_f32_16x16x32_bf16 v[6:9], v[150:153], v[130:133], v[6:9]
	v_mfma_f32_16x16x32_bf16 v[10:13], v[154:157], v[130:133], v[10:13]
	v_mfma_f32_16x16x32_bf16 v[14:17], v[158:161], v[130:133], v[14:17]
	v_mfma_f32_16x16x32_bf16 v[18:21], v[146:149], v[134:137], v[18:21]
	v_mfma_f32_16x16x32_bf16 v[22:25], v[150:153], v[134:137], v[22:25]
	v_mfma_f32_16x16x32_bf16 v[26:29], v[154:157], v[134:137], v[26:29]
	v_mfma_f32_16x16x32_bf16 v[30:33], v[158:161], v[134:137], v[30:33]
	v_mfma_f32_16x16x32_bf16 v[34:37], v[146:149], v[138:141], v[34:37]
	v_mfma_f32_16x16x32_bf16 v[38:41], v[150:153], v[138:141], v[38:41]
	v_mfma_f32_16x16x32_bf16 v[42:45], v[154:157], v[138:141], v[42:45]
	v_mfma_f32_16x16x32_bf16 v[46:49], v[158:161], v[138:141], v[46:49]
	v_mfma_f32_16x16x32_bf16 v[50:53], v[146:149], v[142:145], v[50:53]
	v_mfma_f32_16x16x32_bf16 v[54:57], v[150:153], v[142:145], v[54:57]
	v_mfma_f32_16x16x32_bf16 v[58:61], v[154:157], v[142:145], v[58:61]
	v_mfma_f32_16x16x32_bf16 v[62:65], v[158:161], v[142:145], v[62:65]
	v_mfma_f32_16x16x32_bf16 v[2:5], v[228:231], v[212:215], v[2:5]
	v_mfma_f32_16x16x32_bf16 v[6:9], v[232:235], v[212:215], v[6:9]
	v_mfma_f32_16x16x32_bf16 v[10:13], v[236:239], v[212:215], v[10:13]
	v_mfma_f32_16x16x32_bf16 v[14:17], v[240:243], v[212:215], v[14:17]
	v_mfma_f32_16x16x32_bf16 v[18:21], v[228:231], v[216:219], v[18:21]
	v_mfma_f32_16x16x32_bf16 v[22:25], v[232:235], v[216:219], v[22:25]
	v_mfma_f32_16x16x32_bf16 v[26:29], v[236:239], v[216:219], v[26:29]
	v_mfma_f32_16x16x32_bf16 v[30:33], v[240:243], v[216:219], v[30:33]
	v_mfma_f32_16x16x32_bf16 v[34:37], v[228:231], v[220:223], v[34:37]
	v_mfma_f32_16x16x32_bf16 v[38:41], v[232:235], v[220:223], v[38:41]
	v_mfma_f32_16x16x32_bf16 v[42:45], v[236:239], v[220:223], v[42:45]
	v_mfma_f32_16x16x32_bf16 v[46:49], v[240:243], v[220:223], v[46:49]
	v_mfma_f32_16x16x32_bf16 v[50:53], v[228:231], v[224:227], v[50:53]
	v_mfma_f32_16x16x32_bf16 v[54:57], v[232:235], v[224:227], v[54:57]
	v_mfma_f32_16x16x32_bf16 v[58:61], v[236:239], v[224:227], v[58:61]
	v_mfma_f32_16x16x32_bf16 v[62:65], v[240:243], v[224:227], v[62:65]
	s_waitcnt vmcnt(6)
	s_barrier
	v_add_u32_e32 v204, 0x0, v200
	v_add_u32_e32 v205, 0x0, v202
	ds_read_b128 v[130:133], v204 offset:0
	ds_read_b128 v[134:137], v204 offset:2048
	ds_read_b128 v[138:141], v204 offset:4096
	ds_read_b128 v[142:145], v204 offset:6144
	ds_read_b128 v[146:149], v205 offset:0
	ds_read_b128 v[150:153], v205 offset:2048
	ds_read_b128 v[154:157], v205 offset:4096
	ds_read_b128 v[158:161], v205 offset:6144
	v_add_u32_e32 v204, 0x0, v201
	v_add_u32_e32 v205, 0x0, v203
	ds_read_b128 v[212:215], v204 offset:0
	ds_read_b128 v[216:219], v204 offset:2048
	ds_read_b128 v[220:223], v204 offset:4096
	ds_read_b128 v[224:227], v204 offset:6144
	ds_read_b128 v[228:231], v205 offset:0
	ds_read_b128 v[232:235], v205 offset:2048
	ds_read_b128 v[236:239], v205 offset:4096
	ds_read_b128 v[240:243], v205 offset:6144
	s_add_u32 m0, s76, 0x18000
	s_nop 0
	global_load_lds_dwordx4 v196, s[68:69]
	s_add_u32 m0, s76, 0x1a000
	s_nop 0
	global_load_lds_dwordx4 v197, s[68:69]
	s_add_u32 m0, s76, 0x1c000
	s_nop 0
	global_load_lds_dwordx4 v198, s[68:69]
	s_add_u32 m0, s76, 0x1e000
	s_nop 0
	global_load_lds_dwordx4 v199, s[68:69]
	s_add_u32 m0, s76, 0x20000
	s_nop 0
	global_load_lds_dwordx4 v196, s[70:71]
	s_add_u32 m0, s76, 0x22000
	s_nop 0
	global_load_lds_dwordx4 v197, s[70:71]
	s_add_u32 s68, s68, 0x80
	s_addc_u32 s69, s69, 0
	s_add_u32 s70, s70, 0x80
	s_addc_u32 s71, s71, 0
	s_waitcnt lgkmcnt(0)
	s_barrier
	v_mfma_f32_16x16x32_bf16 v[2:5], v[146:149], v[130:133], v[2:5]
	v_mfma_f32_16x16x32_bf16 v[6:9], v[150:153], v[130:133], v[6:9]
	v_mfma_f32_16x16x32_bf16 v[10:13], v[154:157], v[130:133], v[10:13]
	v_mfma_f32_16x16x32_bf16 v[14:17], v[158:161], v[130:133], v[14:17]
	v_mfma_f32_16x16x32_bf16 v[18:21], v[146:149], v[134:137], v[18:21]
	v_mfma_f32_16x16x32_bf16 v[22:25], v[150:153], v[134:137], v[22:25]
	v_mfma_f32_16x16x32_bf16 v[26:29], v[154:157], v[134:137], v[26:29]
	v_mfma_f32_16x16x32_bf16 v[30:33], v[158:161], v[134:137], v[30:33]
	v_mfma_f32_16x16x32_bf16 v[34:37], v[146:149], v[138:141], v[34:37]
	v_mfma_f32_16x16x32_bf16 v[38:41], v[150:153], v[138:141], v[38:41]
	v_mfma_f32_16x16x32_bf16 v[42:45], v[154:157], v[138:141], v[42:45]
	v_mfma_f32_16x16x32_bf16 v[46:49], v[158:161], v[138:141], v[46:49]
	v_mfma_f32_16x16x32_bf16 v[50:53], v[146:149], v[142:145], v[50:53]
	v_mfma_f32_16x16x32_bf16 v[54:57], v[150:153], v[142:145], v[54:57]
	v_mfma_f32_16x16x32_bf16 v[58:61], v[154:157], v[142:145], v[58:61]
	v_mfma_f32_16x16x32_bf16 v[62:65], v[158:161], v[142:145], v[62:65]
	v_mfma_f32_16x16x32_bf16 v[2:5], v[228:231], v[212:215], v[2:5]
	v_mfma_f32_16x16x32_bf16 v[6:9], v[232:235], v[212:215], v[6:9]
	v_mfma_f32_16x16x32_bf16 v[10:13], v[236:239], v[212:215], v[10:13]
	v_mfma_f32_16x16x32_bf16 v[14:17], v[240:243], v[212:215], v[14:17]
	v_mfma_f32_16x16x32_bf16 v[18:21], v[228:231], v[216:219], v[18:21]
	v_mfma_f32_16x16x32_bf16 v[22:25], v[232:235], v[216:219], v[22:25]
	v_mfma_f32_16x16x32_bf16 v[26:29], v[236:239], v[216:219], v[26:29]
	v_mfma_f32_16x16x32_bf16 v[30:33], v[240:243], v[216:219], v[30:33]
	v_mfma_f32_16x16x32_bf16 v[34:37], v[228:231], v[220:223], v[34:37]
	v_mfma_f32_16x16x32_bf16 v[38:41], v[232:235], v[220:223], v[38:41]
	v_mfma_f32_16x16x32_bf16 v[42:45], v[236:239], v[220:223], v[42:45]
	v_mfma_f32_16x16x32_bf16 v[46:49], v[240:243], v[220:223], v[46:49]
	v_mfma_f32_16x16x32_bf16 v[50:53], v[228:231], v[224:227], v[50:53]
	v_mfma_f32_16x16x32_bf16 v[54:57], v[232:235], v[224:227], v[54:57]
	v_mfma_f32_16x16x32_bf16 v[58:61], v[236:239], v[224:227], v[58:61]
	v_mfma_f32_16x16x32_bf16 v[62:65], v[240:243], v[224:227], v[62:65]
	s_waitcnt vmcnt(6)
	s_barrier
	v_add_u32_e32 v204, 0xc000, v200
	v_add_u32_e32 v205, 0xc000, v202
	ds_read_b128 v[130:133], v204 offset:0
	ds_read_b128 v[134:137], v204 offset:2048
	ds_read_b128 v[138:141], v204 offset:4096
	ds_read_b128 v[142:145], v204 offset:6144
	ds_read_b128 v[146:149], v205 offset:0
	ds_read_b128 v[150:153], v205 offset:2048
	ds_read_b128 v[154:157], v205 offset:4096
	ds_read_b128 v[158:161], v205 offset:6144
	v_add_u32_e32 v204, 0xc000, v201
	v_add_u32_e32 v205, 0xc000, v203
	ds_read_b128 v[212:215], v204 offset:0
	ds_read_b128 v[216:219], v204 offset:2048
	ds_read_b128 v[220:223], v204 offset:4096
	ds_read_b128 v[224:227], v204 offset:6144
	ds_read_b128 v[228:231], v205 offset:0
	ds_read_b128 v[232:235], v205 offset:2048
	ds_read_b128 v[236:239], v205 offset:4096
	ds_read_b128 v[240:243], v205 offset:6144
	s_add_u32 m0, s76, 0x0
	s_nop 0
	global_load_lds_dwordx4 v196, s[68:69]
	s_add_u32 m0, s76, 0x2000
	s_nop 0
	global_load_lds_dwordx4 v197, s[68:69]
	s_add_u32 m0, s76, 0x4000
	s_nop 0
	global_load_lds_dwordx4 v198, s[68:69]
	s_add_u32 m0, s76, 0x6000
	s_nop 0
	global_load_lds_dwordx4 v199, s[68:69]
	s_add_u32 m0, s76, 0x8000
	s_nop 0
	global_load_lds_dwordx4 v196, s[70:71]
	s_add_u32 m0, s76, 0xa000
	s_nop 0
	global_load_lds_dwordx4 v197, s[70:71]
	s_add_u32 s68, s68, 0x80
	s_addc_u32 s69, s69, 0
	s_add_u32 s70, s70, 0x80
	s_addc_u32 s71, s71, 0
	s_waitcnt lgkmcnt(0)
	s_barrier
	v_mfma_f32_16x16x32_bf16 v[2:5], v[146:149], v[130:133], v[2:5]
	v_mfma_f32_16x16x32_bf16 v[6:9], v[150:153], v[130:133], v[6:9]
	v_mfma_f32_16x16x32_bf16 v[10:13], v[154:157], v[130:133], v[10:13]
	v_mfma_f32_16x16x32_bf16 v[14:17], v[158:161], v[130:133], v[14:17]
	v_mfma_f32_16x16x32_bf16 v[18:21], v[146:149], v[134:137], v[18:21]
	v_mfma_f32_16x16x32_bf16 v[22:25], v[150:153], v[134:137], v[22:25]
	v_mfma_f32_16x16x32_bf16 v[26:29], v[154:157], v[134:137], v[26:29]
	v_mfma_f32_16x16x32_bf16 v[30:33], v[158:161], v[134:137], v[30:33]
	v_mfma_f32_16x16x32_bf16 v[34:37], v[146:149], v[138:141], v[34:37]
	v_mfma_f32_16x16x32_bf16 v[38:41], v[150:153], v[138:141], v[38:41]
	v_mfma_f32_16x16x32_bf16 v[42:45], v[154:157], v[138:141], v[42:45]
	v_mfma_f32_16x16x32_bf16 v[46:49], v[158:161], v[138:141], v[46:49]
	v_mfma_f32_16x16x32_bf16 v[50:53], v[146:149], v[142:145], v[50:53]
	v_mfma_f32_16x16x32_bf16 v[54:57], v[150:153], v[142:145], v[54:57]
	v_mfma_f32_16x16x32_bf16 v[58:61], v[154:157], v[142:145], v[58:61]
	v_mfma_f32_16x16x32_bf16 v[62:65], v[158:161], v[142:145], v[62:65]
	v_mfma_f32_16x16x32_bf16 v[2:5], v[228:231], v[212:215], v[2:5]
	v_mfma_f32_16x16x32_bf16 v[6:9], v[232:235], v[212:215], v[6:9]
	v_mfma_f32_16x16x32_bf16 v[10:13], v[236:239], v[212:215], v[10:13]
	v_mfma_f32_16x16x32_bf16 v[14:17], v[240:243], v[212:215], v[14:17]
	v_mfma_f32_16x16x32_bf16 v[18:21], v[228:231], v[216:219], v[18:21]
	v_mfma_f32_16x16x32_bf16 v[22:25], v[232:235], v[216:219], v[22:25]
	v_mfma_f32_16x16x32_bf16 v[26:29], v[236:239], v[216:219], v[26:29]
	v_mfma_f32_16x16x32_bf16 v[30:33], v[240:243], v[216:219], v[30:33]
	v_mfma_f32_16x16x32_bf16 v[34:37], v[228:231], v[220:223], v[34:37]
	v_mfma_f32_16x16x32_bf16 v[38:41], v[232:235], v[220:223], v[38:41]
	v_mfma_f32_16x16x32_bf16 v[42:45], v[236:239], v[220:223], v[42:45]
	v_mfma_f32_16x16x32_bf16 v[46:49], v[240:243], v[220:223], v[46:49]
	v_mfma_f32_16x16x32_bf16 v[50:53], v[228:231], v[224:227], v[50:53]
	v_mfma_f32_16x16x32_bf16 v[54:57], v[232:235], v[224:227], v[54:57]
	v_mfma_f32_16x16x32_bf16 v[58:61], v[236:239], v[224:227], v[58:61]
	v_mfma_f32_16x16x32_bf16 v[62:65], v[240:243], v[224:227], v[62:65]
	s_waitcnt vmcnt(6)
	s_barrier
	v_add_u32_e32 v204, 0x18000, v200
	v_add_u32_e32 v205, 0x18000, v202
	ds_read_b128 v[130:133], v204 offset:0
	ds_read_b128 v[134:137], v204 offset:2048
	ds_read_b128 v[138:141], v204 offset:4096
	ds_read_b128 v[142:145], v204 offset:6144
	ds_read_b128 v[146:149], v205 offset:0
	ds_read_b128 v[150:153], v205 offset:2048
	ds_read_b128 v[154:157], v205 offset:4096
	ds_read_b128 v[158:161], v205 offset:6144
	v_add_u32_e32 v204, 0x18000, v201
	v_add_u32_e32 v205, 0x18000, v203
	ds_read_b128 v[212:215], v204 offset:0
	ds_read_b128 v[216:219], v204 offset:2048
	ds_read_b128 v[220:223], v204 offset:4096
	ds_read_b128 v[224:227], v204 offset:6144
	ds_read_b128 v[228:231], v205 offset:0
	ds_read_b128 v[232:235], v205 offset:2048
	ds_read_b128 v[236:239], v205 offset:4096
	ds_read_b128 v[240:243], v205 offset:6144
	s_waitcnt lgkmcnt(0)
	s_barrier
	v_mfma_f32_16x16x32_bf16 v[2:5], v[146:149], v[130:133], v[2:5]
	v_mfma_f32_16x16x32_bf16 v[6:9], v[150:153], v[130:133], v[6:9]
	v_mfma_f32_16x16x32_bf16 v[10:13], v[154:157], v[130:133], v[10:13]
	v_mfma_f32_16x16x32_bf16 v[14:17], v[158:161], v[130:133], v[14:17]
	v_mfma_f32_16x16x32_bf16 v[18:21], v[146:149], v[134:137], v[18:21]
	v_mfma_f32_16x16x32_bf16 v[22:25], v[150:153], v[134:137], v[22:25]
	v_mfma_f32_16x16x32_bf16 v[26:29], v[154:157], v[134:137], v[26:29]
	v_mfma_f32_16x16x32_bf16 v[30:33], v[158:161], v[134:137], v[30:33]
	v_mfma_f32_16x16x32_bf16 v[34:37], v[146:149], v[138:141], v[34:37]
	v_mfma_f32_16x16x32_bf16 v[38:41], v[150:153], v[138:141], v[38:41]
	v_mfma_f32_16x16x32_bf16 v[42:45], v[154:157], v[138:141], v[42:45]
	v_mfma_f32_16x16x32_bf16 v[46:49], v[158:161], v[138:141], v[46:49]
	v_mfma_f32_16x16x32_bf16 v[50:53], v[146:149], v[142:145], v[50:53]
	v_mfma_f32_16x16x32_bf16 v[54:57], v[150:153], v[142:145], v[54:57]
	v_mfma_f32_16x16x32_bf16 v[58:61], v[154:157], v[142:145], v[58:61]
	v_mfma_f32_16x16x32_bf16 v[62:65], v[158:161], v[142:145], v[62:65]
	v_mfma_f32_16x16x32_bf16 v[2:5], v[228:231], v[212:215], v[2:5]
	v_mfma_f32_16x16x32_bf16 v[6:9], v[232:235], v[212:215], v[6:9]
	v_mfma_f32_16x16x32_bf16 v[10:13], v[236:239], v[212:215], v[10:13]
	v_mfma_f32_16x16x32_bf16 v[14:17], v[240:243], v[212:215], v[14:17]
	v_mfma_f32_16x16x32_bf16 v[18:21], v[228:231], v[216:219], v[18:21]
	v_mfma_f32_16x16x32_bf16 v[22:25], v[232:235], v[216:219], v[22:25]
	v_mfma_f32_16x16x32_bf16 v[26:29], v[236:239], v[216:219], v[26:29]
	v_mfma_f32_16x16x32_bf16 v[30:33], v[240:243], v[216:219], v[30:33]
	v_mfma_f32_16x16x32_bf16 v[34:37], v[228:231], v[220:223], v[34:37]
	v_mfma_f32_16x16x32_bf16 v[38:41], v[232:235], v[220:223], v[38:41]
	v_mfma_f32_16x16x32_bf16 v[42:45], v[236:239], v[220:223], v[42:45]
	v_mfma_f32_16x16x32_bf16 v[46:49], v[240:243], v[220:223], v[46:49]
	v_mfma_f32_16x16x32_bf16 v[50:53], v[228:231], v[224:227], v[50:53]
	v_mfma_f32_16x16x32_bf16 v[54:57], v[232:235], v[224:227], v[54:57]
	v_mfma_f32_16x16x32_bf16 v[58:61], v[236:239], v[224:227], v[58:61]
	v_mfma_f32_16x16x32_bf16 v[62:65], v[240:243], v[224:227], v[62:65]
	s_waitcnt vmcnt(0)
	s_barrier
	v_add_u32_e32 v204, 0x0, v200
	v_add_u32_e32 v205, 0x0, v202
	ds_read_b128 v[130:133], v204 offset:0
	ds_read_b128 v[134:137], v204 offset:2048
	ds_read_b128 v[138:141], v204 offset:4096
	ds_read_b128 v[142:145], v204 offset:6144
	ds_read_b128 v[146:149], v205 offset:0
	ds_read_b128 v[150:153], v205 offset:2048
	ds_read_b128 v[154:157], v205 offset:4096
	ds_read_b128 v[158:161], v205 offset:6144
	v_add_u32_e32 v204, 0x0, v201
	v_add_u32_e32 v205, 0x0, v203
	ds_read_b128 v[212:215], v204 offset:0
	ds_read_b128 v[216:219], v204 offset:2048
	ds_read_b128 v[220:223], v204 offset:4096
	ds_read_b128 v[224:227], v204 offset:6144
	ds_read_b128 v[228:231], v205 offset:0
	ds_read_b128 v[232:235], v205 offset:2048
	ds_read_b128 v[236:239], v205 offset:4096
	ds_read_b128 v[240:243], v205 offset:6144
	s_waitcnt lgkmcnt(0)
	s_barrier
	v_mfma_f32_16x16x32_bf16 v[2:5], v[146:149], v[130:133], v[2:5]
	v_mfma_f32_16x16x32_bf16 v[6:9], v[150:153], v[130:133], v[6:9]
	v_mfma_f32_16x16x32_bf16 v[10:13], v[154:157], v[130:133], v[10:13]
	v_mfma_f32_16x16x32_bf16 v[14:17], v[158:161], v[130:133], v[14:17]
	v_mfma_f32_16x16x32_bf16 v[18:21], v[146:149], v[134:137], v[18:21]
	v_mfma_f32_16x16x32_bf16 v[22:25], v[150:153], v[134:137], v[22:25]
	v_mfma_f32_16x16x32_bf16 v[26:29], v[154:157], v[134:137], v[26:29]
	v_mfma_f32_16x16x32_bf16 v[30:33], v[158:161], v[134:137], v[30:33]
	v_mfma_f32_16x16x32_bf16 v[34:37], v[146:149], v[138:141], v[34:37]
	v_mfma_f32_16x16x32_bf16 v[38:41], v[150:153], v[138:141], v[38:41]
	v_mfma_f32_16x16x32_bf16 v[42:45], v[154:157], v[138:141], v[42:45]
	v_mfma_f32_16x16x32_bf16 v[46:49], v[158:161], v[138:141], v[46:49]
	v_mfma_f32_16x16x32_bf16 v[50:53], v[146:149], v[142:145], v[50:53]
	v_mfma_f32_16x16x32_bf16 v[54:57], v[150:153], v[142:145], v[54:57]
	v_mfma_f32_16x16x32_bf16 v[58:61], v[154:157], v[142:145], v[58:61]
	v_mfma_f32_16x16x32_bf16 v[62:65], v[158:161], v[142:145], v[62:65]
	v_mfma_f32_16x16x32_bf16 v[2:5], v[228:231], v[212:215], v[2:5]
	v_mfma_f32_16x16x32_bf16 v[6:9], v[232:235], v[212:215], v[6:9]
	v_mfma_f32_16x16x32_bf16 v[10:13], v[236:239], v[212:215], v[10:13]
	v_mfma_f32_16x16x32_bf16 v[14:17], v[240:243], v[212:215], v[14:17]
	v_mfma_f32_16x16x32_bf16 v[18:21], v[228:231], v[216:219], v[18:21]
	v_mfma_f32_16x16x32_bf16 v[22:25], v[232:235], v[216:219], v[22:25]
	v_mfma_f32_16x16x32_bf16 v[26:29], v[236:239], v[216:219], v[26:29]
	v_mfma_f32_16x16x32_bf16 v[30:33], v[240:243], v[216:219], v[30:33]
	v_mfma_f32_16x16x32_bf16 v[34:37], v[228:231], v[220:223], v[34:37]
	v_mfma_f32_16x16x32_bf16 v[38:41], v[232:235], v[220:223], v[38:41]
	v_mfma_f32_16x16x32_bf16 v[42:45], v[236:239], v[220:223], v[42:45]
	v_mfma_f32_16x16x32_bf16 v[46:49], v[240:243], v[220:223], v[46:49]
	v_mfma_f32_16x16x32_bf16 v[50:53], v[228:231], v[224:227], v[50:53]
	v_mfma_f32_16x16x32_bf16 v[54:57], v[232:235], v[224:227], v[54:57]
	v_mfma_f32_16x16x32_bf16 v[58:61], v[236:239], v[224:227], v[58:61]
	v_mfma_f32_16x16x32_bf16 v[62:65], v[240:243], v[224:227], v[62:65]
	s_barrier
	s_branch .Lop_join
.Lop_streamB:
	s_barrier
	v_add_u32_e32 v204, 0x0, v200
	v_add_u32_e32 v205, 0x0, v202
	ds_read_b128 v[130:133], v204 offset:0
	ds_read_b128 v[134:137], v204 offset:2048
	ds_read_b128 v[138:141], v204 offset:4096
	ds_read_b128 v[142:145], v204 offset:6144
	ds_read_b128 v[146:149], v205 offset:0
	ds_read_b128 v[150:153], v205 offset:2048
	ds_read_b128 v[154:157], v205 offset:4096
	ds_read_b128 v[158:161], v205 offset:6144
	v_add_u32_e32 v204, 0x0, v201
	v_add_u32_e32 v205, 0x0, v203
	ds_read_b128 v[212:215], v204 offset:0
	ds_read_b128 v[216:219], v204 offset:2048
	ds_read_b128 v[220:223], v204 offset:4096
	ds_read_b128 v[224:227], v204 offset:6144
	ds_read_b128 v[228:231], v205 offset:0
	ds_read_b128 v[232:235], v205 offset:2048
	ds_read_b128 v[236:239], v205 offset:4096
	ds_read_b128 v[240:243], v205 offset:6144
	s_add_u32 m0, s76, 0x18000
	s_nop 0
	global_load_lds_dwordx4 v196, s[68:69]
	s_add_u32 m0, s76, 0x1a000
	s_nop 0
	global_load_lds_dwordx4 v197, s[68:69]
	s_add_u32 m0, s76, 0x1c000
	s_nop 0
	global_load_lds_dwordx4 v198, s[68:69]
	s_add_u32 m0, s76, 0x1e000
	s_nop 0
	global_load_lds_dwordx4 v199, s[68:69]
	s_add_u32 m0, s76, 0x20000
	s_nop 0
	global_load_lds_dwordx4 v196, s[70:71]
	s_add_u32 m0, s76, 0x22000
	s_nop 0
	global_load_lds_dwordx4 v197, s[70:71]
	s_add_u32 s68, s68, 0x80
	s_addc_u32 s69, s69, 0
	s_add_u32 s70, s70, 0x80
	s_addc_u32 s71, s71, 0
	global_load_dwordx4 v[174:177], v190, s[72:73] offset:0
	global_load_dwordx4 v[178:181], v190, s[72:73] offset:64
	s_waitcnt vmcnt(8)
	s_waitcnt lgkmcnt(0)
	s_barrier
	v_mfma_f32_16x16x32_bf16 v[2:5], v[146:149], v[130:133], 0
	v_mfma_f32_16x16x32_bf16 v[6:9], v[150:153], v[130:133], 0
	v_mfma_f32_16x16x32_bf16 v[10:13], v[154:157], v[130:133], 0
	v_mfma_f32_16x16x32_bf16 v[14:17], v[158:161], v[130:133], 0
	v_mfma_f32_16x16x32_bf16 v[18:21], v[146:149], v[134:137], 0
	v_mfma_f32_16x16x32_bf16 v[22:25], v[150:153], v[134:137], 0
	v_mfma_f32_16x16x32_bf16 v[26:29], v[154:157], v[134:137], 0
	v_mfma_f32_16x16x32_bf16 v[30:33], v[158:161], v[134:137], 0
	v_mfma_f32_16x16x32_bf16 v[34:37], v[146:149], v[138:141], 0
	v_mfma_f32_16x16x32_bf16 v[38:41], v[150:153], v[138:141], 0
	v_mfma_f32_16x16x32_bf16 v[42:45], v[154:157], v[138:141], 0
	v_mfma_f32_16x16x32_bf16 v[46:49], v[158:161], v[138:141], 0
	v_mfma_f32_16x16x32_bf16 v[50:53], v[146:149], v[142:145], 0
	v_mfma_f32_16x16x32_bf16 v[54:57], v[150:153], v[142:145], 0
	v_mfma_f32_16x16x32_bf16 v[58:61], v[154:157], v[142:145], 0
	v_mfma_f32_16x16x32_bf16 v[62:65], v[158:161], v[142:145], 0
	v_mfma_f32_16x16x32_bf16 v[2:5], v[228:231], v[212:215], v[2:5]
	v_mfma_f32_16x16x32_bf16 v[6:9], v[232:235], v[212:215], v[6:9]
	v_mfma_f32_16x16x32_bf16 v[10:13], v[236:239], v[212:215], v[10:13]
	v_mfma_f32_16x16x32_bf16 v[14:17], v[240:243], v[212:215], v[14:17]
	v_mfma_f32_16x16x32_bf16 v[18:21], v[228:231], v[216:219], v[18:21]
	v_mfma_f32_16x16x32_bf16 v[22:25], v[232:235], v[216:219], v[22:25]
	v_mfma_f32_16x16x32_bf16 v[26:29], v[236:239], v[216:219], v[26:29]
	v_mfma_f32_16x16x32_bf16 v[30:33], v[240:243], v[216:219], v[30:33]
	v_mfma_f32_16x16x32_bf16 v[34:37], v[228:231], v[220:223], v[34:37]
	v_mfma_f32_16x16x32_bf16 v[38:41], v[232:235], v[220:223], v[38:41]
	v_mfma_f32_16x16x32_bf16 v[42:45], v[236:239], v[220:223], v[42:45]
	v_mfma_f32_16x16x32_bf16 v[46:49], v[240:243], v[220:223], v[46:49]
	v_mfma_f32_16x16x32_bf16 v[50:53], v[228:231], v[224:227], v[50:53]
	v_mfma_f32_16x16x32_bf16 v[54:57], v[232:235], v[224:227], v[54:57]
	v_mfma_f32_16x16x32_bf16 v[58:61], v[236:239], v[224:227], v[58:61]
	v_mfma_f32_16x16x32_bf16 v[62:65], v[240:243], v[224:227], v[62:65]
	s_barrier
	v_add_u32_e32 v204, 0xc000, v200
	v_add_u32_e32 v205, 0xc000, v202
	ds_read_b128 v[130:133], v204 offset:0
	ds_read_b128 v[134:137], v204 offset:2048
	ds_read_b128 v[138:141], v204 offset:4096
	ds_read_b128 v[142:145], v204 offset:6144
	ds_read_b128 v[146:149], v205 offset:0
	ds_read_b128 v[150:153], v205 offset:2048
	ds_read_b128 v[154:157], v205 offset:4096
	ds_read_b128 v[158:161], v205 offset:6144
	v_add_u32_e32 v204, 0xc000, v201
	v_add_u32_e32 v205, 0xc000, v203
	ds_read_b128 v[212:215], v204 offset:0
	ds_read_b128 v[216:219], v204 offset:2048
	ds_read_b128 v[220:223], v204 offset:4096
	ds_read_b128 v[224:227], v204 offset:6144
	ds_read_b128 v[228:231], v205 offset:0
	ds_read_b128 v[232:235], v205 offset:2048
	ds_read_b128 v[236:239], v205 offset:4096
	ds_read_b128 v[240:243], v205 offset:6144
	s_add_u32 m0, s76, 0x0
	s_nop 0
	global_load_lds_dwordx4 v196, s[68:69]
	s_add_u32 m0, s76, 0x2000
	s_nop 0
	global_load_lds_dwordx4 v197, s[68:69]
	s_add_u32 m0, s76, 0x4000
	s_nop 0
	global_load_lds_dwordx4 v198, s[68:69]
	s_add_u32 m0, s76, 0x6000
	s_nop 0
	global_load_lds_dwordx4 v199, s[68:69]
	s_add_u32 m0, s76, 0x8000
	s_nop 0
	global_load_lds_dwordx4 v196, s[70:71]
	s_add_u32 m0, s76, 0xa000
	s_nop 0
	global_load_lds_dwordx4 v197, s[70:71]
	s_add_u32 s68, s68, 0x80
	s_addc_u32 s69, s69, 0
	s_add_u32 s70, s70, 0x80
	s_addc_u32 s71, s71, 0
	global_load_dwordx4 v[182:185], v190, s[72:73] offset:128
	global_load_dwordx4 v[186:189], v190, s[72:73] offset:192
	s_waitcnt vmcnt(10)
	s_waitcnt lgkmcnt(0)
	s_barrier
	v_mfma_f32_16x16x32_bf16 v[2:5], v[146:149], v[130:133], v[2:5]
	v_mfma_f32_16x16x32_bf16 v[6:9], v[150:153], v[130:133], v[6:9]
	v_mfma_f32_16x16x32_bf16 v[10:13], v[154:157], v[130:133], v[10:13]
	v_mfma_f32_16x16x32_bf16 v[14:17], v[158:161], v[130:133], v[14:17]
	v_mfma_f32_16x16x32_bf16 v[18:21], v[146:149], v[134:137], v[18:21]
	v_mfma_f32_16x16x32_bf16 v[22:25], v[150:153], v[134:137], v[22:25]
	v_mfma_f32_16x16x32_bf16 v[26:29], v[154:157], v[134:137], v[26:29]
	v_mfma_f32_16x16x32_bf16 v[30:33], v[158:161], v[134:137], v[30:33]
	v_mfma_f32_16x16x32_bf16 v[34:37], v[146:149], v[138:141], v[34:37]
	v_mfma_f32_16x16x32_bf16 v[38:41], v[150:153], v[138:141], v[38:41]
	v_mfma_f32_16x16x32_bf16 v[42:45], v[154:157], v[138:141], v[42:45]
	v_mfma_f32_16x16x32_bf16 v[46:49], v[158:161], v[138:141], v[46:49]
	v_mfma_f32_16x16x32_bf16 v[50:53], v[146:149], v[142:145], v[50:53]
	v_mfma_f32_16x16x32_bf16 v[54:57], v[150:153], v[142:145], v[54:57]
	v_mfma_f32_16x16x32_bf16 v[58:61], v[154:157], v[142:145], v[58:61]
	v_mfma_f32_16x16x32_bf16 v[62:65], v[158:161], v[142:145], v[62:65]
	v_mfma_f32_16x16x32_bf16 v[2:5], v[228:231], v[212:215], v[2:5]
	v_mfma_f32_16x16x32_bf16 v[6:9], v[232:235], v[212:215], v[6:9]
	v_mfma_f32_16x16x32_bf16 v[10:13], v[236:239], v[212:215], v[10:13]
	v_mfma_f32_16x16x32_bf16 v[14:17], v[240:243], v[212:215], v[14:17]
	v_mfma_f32_16x16x32_bf16 v[18:21], v[228:231], v[216:219], v[18:21]
	v_mfma_f32_16x16x32_bf16 v[22:25], v[232:235], v[216:219], v[22:25]
	v_mfma_f32_16x16x32_bf16 v[26:29], v[236:239], v[216:219], v[26:29]
	v_mfma_f32_16x16x32_bf16 v[30:33], v[240:243], v[216:219], v[30:33]
	v_mfma_f32_16x16x32_bf16 v[34:37], v[228:231], v[220:223], v[34:37]
	v_mfma_f32_16x16x32_bf16 v[38:41], v[232:235], v[220:223], v[38:41]
	v_mfma_f32_16x16x32_bf16 v[42:45], v[236:239], v[220:223], v[42:45]
	v_mfma_f32_16x16x32_bf16 v[46:49], v[240:243], v[220:223], v[46:49]
	v_mfma_f32_16x16x32_bf16 v[50:53], v[228:231], v[224:227], v[50:53]
	v_mfma_f32_16x16x32_bf16 v[54:57], v[232:235], v[224:227], v[54:57]
	v_mfma_f32_16x16x32_bf16 v[58:61], v[236:239], v[224:227], v[58:61]
	v_mfma_f32_16x16x32_bf16 v[62:65], v[240:243], v[224:227], v[62:65]
	s_barrier
	v_add_u32_e32 v204, 0x18000, v200
	v_add_u32_e32 v205, 0x18000, v202
	ds_read_b128 v[130:133], v204 offset:0
	ds_read_b128 v[134:137], v204 offset:2048
	ds_read_b128 v[138:141], v204 offset:4096
	ds_read_b128 v[142:145], v204 offset:6144
	ds_read_b128 v[146:149], v205 offset:0
	ds_read_b128 v[150:153], v205 offset:2048
	ds_read_b128 v[154:157], v205 offset:4096
	ds_read_b128 v[158:161], v205 offset:6144
	v_add_u32_e32 v204, 0x18000, v201
	v_add_u32_e32 v205, 0x18000, v203
	ds_read_b128 v[212:215], v204 offset:0
	ds_read_b128 v[216:219], v204 offset:2048
	ds_read_b128 v[220:223], v204 offset:4096
	ds_read_b128 v[224:227], v204 offset:6144
	ds_read_b128 v[228:231], v205 offset:0
	ds_read_b128 v[232:235], v205 offset:2048
	ds_read_b128 v[236:239], v205 offset:4096
	ds_read_b128 v[240:243], v205 offset:6144
	s_add_u32 m0, s76, 0xc000
	s_nop 0
	global_load_lds_dwordx4 v196, s[68:69]
	s_add_u32 m0, s76, 0xe000
	s_nop 0
	global_load_lds_dwordx4 v197, s[68:69]
	s_add_u32 m0, s76, 0x10000
	s_nop 0
	global_load_lds_dwordx4 v198, s[68:69]
	s_add_u32 m0, s76, 0x12000
	s_nop 0
	global_load_lds_dwordx4 v199, s[68:69]
	s_add_u32 m0, s76, 0x14000
	s_nop 0
	global_load_lds_dwordx4 v196, s[70:71]
	s_add_u32 m0, s76, 0x16000
	s_nop 0
	global_load_lds_dwordx4 v197, s[70:71]
	s_add_u32 s68, s68, 0x80
	s_addc_u32 s69, s69, 0
	s_add_u32 s70, s70, 0x80
	s_addc_u32 s71, s71, 0
	global_load_dwordx4 v[66:69], v191, s[14:15]
	v_add_u32_e32 v170, s38, v191
	global_load_dwordx4 v[70:73], v170, s[14:15]
	s_waitcnt vmcnt(10)
	s_waitcnt lgkmcnt(0)
	s_barrier
	v_mfma_f32_16x16x32_bf16 v[2:5], v[146:149], v[130:133], v[2:5]
	v_mfma_f32_16x16x32_bf16 v[6:9], v[150:153], v[130:133], v[6:9]
	v_mfma_f32_16x16x32_bf16 v[10:13], v[154:157], v[130:133], v[10:13]
	v_mfma_f32_16x16x32_bf16 v[14:17], v[158:161], v[130:133], v[14:17]
	v_mfma_f32_16x16x32_bf16 v[18:21], v[146:149], v[134:137], v[18:21]
	v_mfma_f32_16x16x32_bf16 v[22:25], v[150:153], v[134:137], v[22:25]
	v_mfma_f32_16x16x32_bf16 v[26:29], v[154:157], v[134:137], v[26:29]
	v_mfma_f32_16x16x32_bf16 v[30:33], v[158:161], v[134:137], v[30:33]
	v_mfma_f32_16x16x32_bf16 v[34:37], v[146:149], v[138:141], v[34:37]
	v_mfma_f32_16x16x32_bf16 v[38:41], v[150:153], v[138:141], v[38:41]
	v_mfma_f32_16x16x32_bf16 v[42:45], v[154:157], v[138:141], v[42:45]
	v_mfma_f32_16x16x32_bf16 v[46:49], v[158:161], v[138:141], v[46:49]
	v_mfma_f32_16x16x32_bf16 v[50:53], v[146:149], v[142:145], v[50:53]
	v_mfma_f32_16x16x32_bf16 v[54:57], v[150:153], v[142:145], v[54:57]
	v_mfma_f32_16x16x32_bf16 v[58:61], v[154:157], v[142:145], v[58:61]
	v_mfma_f32_16x16x32_bf16 v[62:65], v[158:161], v[142:145], v[62:65]
	v_mfma_f32_16x16x32_bf16 v[2:5], v[228:231], v[212:215], v[2:5]
	v_mfma_f32_16x16x32_bf16 v[6:9], v[232:235], v[212:215], v[6:9]
	v_mfma_f32_16x16x32_bf16 v[10:13], v[236:239], v[212:215], v[10:13]
	v_mfma_f32_16x16x32_bf16 v[14:17], v[240:243], v[212:215], v[14:17]
	v_mfma_f32_16x16x32_bf16 v[18:21], v[228:231], v[216:219], v[18:21]
	v_mfma_f32_16x16x32_bf16 v[22:25], v[232:235], v[216:219], v[22:25]
	v_mfma_f32_16x16x32_bf16 v[26:29], v[236:239], v[216:219], v[26:29]
	v_mfma_f32_16x16x32_bf16 v[30:33], v[240:243], v[216:219], v[30:33]
	v_mfma_f32_16x16x32_bf16 v[34:37], v[228:231], v[220:223], v[34:37]
	v_mfma_f32_16x16x32_bf16 v[38:41], v[232:235], v[220:223], v[38:41]
	v_mfma_f32_16x16x32_bf16 v[42:45], v[236:239], v[220:223], v[42:45]
	v_mfma_f32_16x16x32_bf16 v[46:49], v[240:243], v[220:223], v[46:49]
	v_mfma_f32_16x16x32_bf16 v[50:53], v[228:231], v[224:227], v[50:53]
	v_mfma_f32_16x16x32_bf16 v[54:57], v[232:235], v[224:227], v[54:57]
	v_mfma_f32_16x16x32_bf16 v[58:61], v[236:239], v[224:227], v[58:61]
	v_mfma_f32_16x16x32_bf16 v[62:65], v[240:243], v[224:227], v[62:65]
	s_barrier
	v_add_u32_e32 v204, 0x0, v200
	v_add_u32_e32 v205, 0x0, v202
	ds_read_b128 v[130:133], v204 offset:0
	ds_read_b128 v[134:137], v204 offset:2048
	ds_read_b128 v[138:141], v204 offset:4096
	ds_read_b128 v[142:145], v204 offset:6144
	ds_read_b128 v[146:149], v205 offset:0
	ds_read_b128 v[150:153], v205 offset:2048
	ds_read_b128 v[154:157], v205 offset:4096
	ds_read_b128 v[158:161], v205 offset:6144
	v_add_u32_e32 v204, 0x0, v201
	v_add_u32_e32 v205, 0x0, v203
	ds_read_b128 v[212:215], v204 offset:0
	ds_read_b128 v[216:219], v204 offset:2048
	ds_read_b128 v[220:223], v204 offset:4096
	ds_read_b128 v[224:227], v204 offset:6144
	ds_read_b128 v[228:231], v205 offset:0
	ds_read_b128 v[232:235], v205 offset:2048
	ds_read_b128 v[236:239], v205 offset:4096
	ds_read_b128 v[240:243], v205 offset:6144
	s_add_u32 m0, s76, 0x18000
	s_nop 0
	global_load_lds_dwordx4 v196, s[68:69]
	s_add_u32 m0, s76, 0x1a000
	s_nop 0
	global_load_lds_dwordx4 v197, s[68:69]
	s_add_u32 m0, s76, 0x1c000
	s_nop 0
	global_load_lds_dwordx4 v198, s[68:69]
	s_add_u32 m0, s76, 0x1e000
	s_nop 0
	global_load_lds_dwordx4 v199, s[68:69]
	s_add_u32 m0, s76, 0x20000
	s_nop 0
	global_load_lds_dwordx4 v196, s[70:71]
	s_add_u32 m0, s76, 0x22000
	s_nop 0
	global_load_lds_dwordx4 v197, s[70:71]
	s_add_u32 s68, s68, 0x80
	s_addc_u32 s69, s69, 0
	s_add_u32 s70, s70, 0x80
	s_addc_u32 s71, s71, 0
	v_add_u32_e32 v170, s39, v191
	global_load_dwordx4 v[74:77], v170, s[14:15]
	v_add_u32_e32 v170, s40, v191
	global_load_dwordx4 v[78:81], v170, s[14:15]
	s_waitcnt vmcnt(10)
	s_waitcnt lgkmcnt(0)
	s_barrier
	v_mfma_f32_16x16x32_bf16 v[2:5], v[146:149], v[130:133], v[2:5]
	v_mfma_f32_16x16x32_bf16 v[6:9], v[150:153], v[130:133], v[6:9]
	v_mfma_f32_16x16x32_bf16 v[10:13], v[154:157], v[130:133], v[10:13]
	v_mfma_f32_16x16x32_bf16 v[14:17], v[158:161], v[130:133], v[14:17]
	v_mfma_f32_16x16x32_bf16 v[18:21], v[146:149], v[134:137], v[18:21]
	v_mfma_f32_16x16x32_bf16 v[22:25], v[150:153], v[134:137], v[22:25]
	v_mfma_f32_16x16x32_bf16 v[26:29], v[154:157], v[134:137], v[26:29]
	v_mfma_f32_16x16x32_bf16 v[30:33], v[158:161], v[134:137], v[30:33]
	v_mfma_f32_16x16x32_bf16 v[34:37], v[146:149], v[138:141], v[34:37]
	v_mfma_f32_16x16x32_bf16 v[38:41], v[150:153], v[138:141], v[38:41]
	v_mfma_f32_16x16x32_bf16 v[42:45], v[154:157], v[138:141], v[42:45]
	v_mfma_f32_16x16x32_bf16 v[46:49], v[158:161], v[138:141], v[46:49]
	v_mfma_f32_16x16x32_bf16 v[50:53], v[146:149], v[142:145], v[50:53]
	v_mfma_f32_16x16x32_bf16 v[54:57], v[150:153], v[142:145], v[54:57]
	v_mfma_f32_16x16x32_bf16 v[58:61], v[154:157], v[142:145], v[58:61]
	v_mfma_f32_16x16x32_bf16 v[62:65], v[158:161], v[142:145], v[62:65]
	v_mfma_f32_16x16x32_bf16 v[2:5], v[228:231], v[212:215], v[2:5]
	v_mfma_f32_16x16x32_bf16 v[6:9], v[232:235], v[212:215], v[6:9]
	v_mfma_f32_16x16x32_bf16 v[10:13], v[236:239], v[212:215], v[10:13]
	v_mfma_f32_16x16x32_bf16 v[14:17], v[240:243], v[212:215], v[14:17]
	v_mfma_f32_16x16x32_bf16 v[18:21], v[228:231], v[216:219], v[18:21]
	v_mfma_f32_16x16x32_bf16 v[22:25], v[232:235], v[216:219], v[22:25]
	v_mfma_f32_16x16x32_bf16 v[26:29], v[236:239], v[216:219], v[26:29]
	v_mfma_f32_16x16x32_bf16 v[30:33], v[240:243], v[216:219], v[30:33]
	v_mfma_f32_16x16x32_bf16 v[34:37], v[228:231], v[220:223], v[34:37]
	v_mfma_f32_16x16x32_bf16 v[38:41], v[232:235], v[220:223], v[38:41]
	v_mfma_f32_16x16x32_bf16 v[42:45], v[236:239], v[220:223], v[42:45]
	v_mfma_f32_16x16x32_bf16 v[46:49], v[240:243], v[220:223], v[46:49]
	v_mfma_f32_16x16x32_bf16 v[50:53], v[228:231], v[224:227], v[50:53]
	v_mfma_f32_16x16x32_bf16 v[54:57], v[232:235], v[224:227], v[54:57]
	v_mfma_f32_16x16x32_bf16 v[58:61], v[236:239], v[224:227], v[58:61]
	v_mfma_f32_16x16x32_bf16 v[62:65], v[240:243], v[224:227], v[62:65]
	s_barrier
	v_add_u32_e32 v204, 0xc000, v200
	v_add_u32_e32 v205, 0xc000, v202
	ds_read_b128 v[130:133], v204 offset:0
	ds_read_b128 v[134:137], v204 offset:2048
	ds_read_b128 v[138:141], v204 offset:4096
	ds_read_b128 v[142:145], v204 offset:6144
	ds_read_b128 v[146:149], v205 offset:0
	ds_read_b128 v[150:153], v205 offset:2048
	ds_read_b128 v[154:157], v205 offset:4096
	ds_read_b128 v[158:161], v205 offset:6144
	v_add_u32_e32 v204, 0xc000, v201
	v_add_u32_e32 v205, 0xc000, v203
	ds_read_b128 v[212:215], v204 offset:0
	ds_read_b128 v[216:219], v204 offset:2048
	ds_read_b128 v[220:223], v204 offset:4096
	ds_read_b128 v[224:227], v204 offset:6144
	ds_read_b128 v[228:231], v205 offset:0
	ds_read_b128 v[232:235], v205 offset:2048
	ds_read_b128 v[236:239], v205 offset:4096
	ds_read_b128 v[240:243], v205 offset:6144
	s_add_u32 m0, s76, 0x0
	s_nop 0
	global_load_lds_dwordx4 v196, s[68:69]
	s_add_u32 m0, s76, 0x2000
	s_nop 0
	global_load_lds_dwordx4 v197, s[68:69]
	s_add_u32 m0, s76, 0x4000
	s_nop 0
	global_load_lds_dwordx4 v198, s[68:69]
	s_add_u32 m0, s76, 0x6000
	s_nop 0
	global_load_lds_dwordx4 v199, s[68:69]
	s_add_u32 m0, s76, 0x8000
	s_nop 0
	global_load_lds_dwordx4 v196, s[70:71]
	s_add_u32 m0, s76, 0xa000
	s_nop 0
	global_load_lds_dwordx4 v197, s[70:71]
	s_add_u32 s68, s68, 0x80
	s_addc_u32 s69, s69, 0
	s_add_u32 s70, s70, 0x80
	s_addc_u32 s71, s71, 0
	global_load_dwordx4 v[82:85], v192, s[14:15]
	v_add_u32_e32 v170, s38, v192
	global_load_dwordx4 v[86:89], v170, s[14:15]
	s_waitcnt vmcnt(10)
	s_waitcnt lgkmcnt(0)
	s_barrier
	v_mfma_f32_16x16x32_bf16 v[2:5], v[146:149], v[130:133], v[2:5]
	v_mfma_f32_16x16x32_bf16 v[6:9], v[150:153], v[130:133], v[6:9]
	v_mfma_f32_16x16x32_bf16 v[10:13], v[154:157], v[130:133], v[10:13]
	v_mfma_f32_16x16x32_bf16 v[14:17], v[158:161], v[130:133], v[14:17]
	v_mfma_f32_16x16x32_bf16 v[18:21], v[146:149], v[134:137], v[18:21]
	v_mfma_f32_16x16x32_bf16 v[22:25], v[150:153], v[134:137], v[22:25]
	v_mfma_f32_16x16x32_bf16 v[26:29], v[154:157], v[134:137], v[26:29]
	v_mfma_f32_16x16x32_bf16 v[30:33], v[158:161], v[134:137], v[30:33]
	v_mfma_f32_16x16x32_bf16 v[34:37], v[146:149], v[138:141], v[34:37]
	v_mfma_f32_16x16x32_bf16 v[38:41], v[150:153], v[138:141], v[38:41]
	v_mfma_f32_16x16x32_bf16 v[42:45], v[154:157], v[138:141], v[42:45]
	v_mfma_f32_16x16x32_bf16 v[46:49], v[158:161], v[138:141], v[46:49]
	v_mfma_f32_16x16x32_bf16 v[50:53], v[146:149], v[142:145], v[50:53]
	v_mfma_f32_16x16x32_bf16 v[54:57], v[150:153], v[142:145], v[54:57]
	v_mfma_f32_16x16x32_bf16 v[58:61], v[154:157], v[142:145], v[58:61]
	v_mfma_f32_16x16x32_bf16 v[62:65], v[158:161], v[142:145], v[62:65]
	v_mfma_f32_16x16x32_bf16 v[2:5], v[228:231], v[212:215], v[2:5]
	v_mfma_f32_16x16x32_bf16 v[6:9], v[232:235], v[212:215], v[6:9]
	v_mfma_f32_16x16x32_bf16 v[10:13], v[236:239], v[212:215], v[10:13]
	v_mfma_f32_16x16x32_bf16 v[14:17], v[240:243], v[212:215], v[14:17]
	v_mfma_f32_16x16x32_bf16 v[18:21], v[228:231], v[216:219], v[18:21]
	v_mfma_f32_16x16x32_bf16 v[22:25], v[232:235], v[216:219], v[22:25]
	v_mfma_f32_16x16x32_bf16 v[26:29], v[236:239], v[216:219], v[26:29]
	v_mfma_f32_16x16x32_bf16 v[30:33], v[240:243], v[216:219], v[30:33]
	v_mfma_f32_16x16x32_bf16 v[34:37], v[228:231], v[220:223], v[34:37]
	v_mfma_f32_16x16x32_bf16 v[38:41], v[232:235], v[220:223], v[38:41]
	v_mfma_f32_16x16x32_bf16 v[42:45], v[236:239], v[220:223], v[42:45]
	v_mfma_f32_16x16x32_bf16 v[46:49], v[240:243], v[220:223], v[46:49]
	v_mfma_f32_16x16x32_bf16 v[50:53], v[228:231], v[224:227], v[50:53]
	v_mfma_f32_16x16x32_bf16 v[54:57], v[232:235], v[224:227], v[54:57]
	v_mfma_f32_16x16x32_bf16 v[58:61], v[236:239], v[224:227], v[58:61]
	v_mfma_f32_16x16x32_bf16 v[62:65], v[240:243], v[224:227], v[62:65]
	s_barrier
	v_add_u32_e32 v204, 0x18000, v200
	v_add_u32_e32 v205, 0x18000, v202
	ds_read_b128 v[130:133], v204 offset:0
	ds_read_b128 v[134:137], v204 offset:2048
	ds_read_b128 v[138:141], v204 offset:4096
	ds_read_b128 v[142:145], v204 offset:6144
	ds_read_b128 v[146:149], v205 offset:0
	ds_read_b128 v[150:153], v205 offset:2048
	ds_read_b128 v[154:157], v205 offset:4096
	ds_read_b128 v[158:161], v205 offset:6144
	v_add_u32_e32 v204, 0x18000, v201
	v_add_u32_e32 v205, 0x18000, v203
	ds_read_b128 v[212:215], v204 offset:0
	ds_read_b128 v[216:219], v204 offset:2048
	ds_read_b128 v[220:223], v204 offset:4096
	ds_read_b128 v[224:227], v204 offset:6144
	ds_read_b128 v[228:231], v205 offset:0
	ds_read_b128 v[232:235], v205 offset:2048
	ds_read_b128 v[236:239], v205 offset:4096
	ds_read_b128 v[240:243], v205 offset:6144
	s_add_u32 m0, s76, 0xc000
	s_nop 0
	global_load_lds_dwordx4 v196, s[68:69]
	s_add_u32 m0, s76, 0xe000
	s_nop 0
	global_load_lds_dwordx4 v197, s[68:69]
	s_add_u32 m0, s76, 0x10000
	s_nop 0
	global_load_lds_dwordx4 v198, s[68:69]
	s_add_u32 m0, s76, 0x12000
	s_nop 0
	global_load_lds_dwordx4 v199, s[68:69]
	s_add_u32 m0, s76, 0x14000
	s_nop 0
	global_load_lds_dwordx4 v196, s[70:71]
	s_add_u32 m0, s76, 0x16000
	s_nop 0
	global_load_lds_dwordx4 v197, s[70:71]
	s_add_u32 s68, s68, 0x80
	s_addc_u32 s69, s69, 0
	s_add_u32 s70, s70, 0x80
	s_addc_u32 s71, s71, 0
	v_add_u32_e32 v170, s39, v192
	global_load_dwordx4 v[90:93], v170, s[14:15]
	v_add_u32_e32 v170, s40, v192
	global_load_dwordx4 v[94:97], v170, s[14:15]
	s_waitcnt vmcnt(10)
	s_waitcnt lgkmcnt(0)
	s_barrier
	v_mfma_f32_16x16x32_bf16 v[2:5], v[146:149], v[130:133], v[2:5]
	v_mfma_f32_16x16x32_bf16 v[6:9], v[150:153], v[130:133], v[6:9]
	v_mfma_f32_16x16x32_bf16 v[10:13], v[154:157], v[130:133], v[10:13]
	v_mfma_f32_16x16x32_bf16 v[14:17], v[158:161], v[130:133], v[14:17]
	v_mfma_f32_16x16x32_bf16 v[18:21], v[146:149], v[134:137], v[18:21]
	v_mfma_f32_16x16x32_bf16 v[22:25], v[150:153], v[134:137], v[22:25]
	v_mfma_f32_16x16x32_bf16 v[26:29], v[154:157], v[134:137], v[26:29]
	v_mfma_f32_16x16x32_bf16 v[30:33], v[158:161], v[134:137], v[30:33]
	v_mfma_f32_16x16x32_bf16 v[34:37], v[146:149], v[138:141], v[34:37]
	v_mfma_f32_16x16x32_bf16 v[38:41], v[150:153], v[138:141], v[38:41]
	v_mfma_f32_16x16x32_bf16 v[42:45], v[154:157], v[138:141], v[42:45]
	v_mfma_f32_16x16x32_bf16 v[46:49], v[158:161], v[138:141], v[46:49]
	v_mfma_f32_16x16x32_bf16 v[50:53], v[146:149], v[142:145], v[50:53]
	v_mfma_f32_16x16x32_bf16 v[54:57], v[150:153], v[142:145], v[54:57]
	v_mfma_f32_16x16x32_bf16 v[58:61], v[154:157], v[142:145], v[58:61]
	v_mfma_f32_16x16x32_bf16 v[62:65], v[158:161], v[142:145], v[62:65]
	v_mfma_f32_16x16x32_bf16 v[2:5], v[228:231], v[212:215], v[2:5]
	v_mfma_f32_16x16x32_bf16 v[6:9], v[232:235], v[212:215], v[6:9]
	v_mfma_f32_16x16x32_bf16 v[10:13], v[236:239], v[212:215], v[10:13]
	v_mfma_f32_16x16x32_bf16 v[14:17], v[240:243], v[212:215], v[14:17]
	v_mfma_f32_16x16x32_bf16 v[18:21], v[228:231], v[216:219], v[18:21]
	v_mfma_f32_16x16x32_bf16 v[22:25], v[232:235], v[216:219], v[22:25]
	v_mfma_f32_16x16x32_bf16 v[26:29], v[236:239], v[216:219], v[26:29]
	v_mfma_f32_16x16x32_bf16 v[30:33], v[240:243], v[216:219], v[30:33]
	v_mfma_f32_16x16x32_bf16 v[34:37], v[228:231], v[220:223], v[34:37]
	v_mfma_f32_16x16x32_bf16 v[38:41], v[232:235], v[220:223], v[38:41]
	v_mfma_f32_16x16x32_bf16 v[42:45], v[236:239], v[220:223], v[42:45]
	v_mfma_f32_16x16x32_bf16 v[46:49], v[240:243], v[220:223], v[46:49]
	v_mfma_f32_16x16x32_bf16 v[50:53], v[228:231], v[224:227], v[50:53]
	v_mfma_f32_16x16x32_bf16 v[54:57], v[232:235], v[224:227], v[54:57]
	v_mfma_f32_16x16x32_bf16 v[58:61], v[236:239], v[224:227], v[58:61]
	v_mfma_f32_16x16x32_bf16 v[62:65], v[240:243], v[224:227], v[62:65]
	s_barrier
	v_add_u32_e32 v204, 0x0, v200
	v_add_u32_e32 v205, 0x0, v202
	ds_read_b128 v[130:133], v204 offset:0
	ds_read_b128 v[134:137], v204 offset:2048
	ds_read_b128 v[138:141], v204 offset:4096
	ds_read_b128 v[142:145], v204 offset:6144
	ds_read_b128 v[146:149], v205 offset:0
	ds_read_b128 v[150:153], v205 offset:2048
	ds_read_b128 v[154:157], v205 offset:4096
	ds_read_b128 v[158:161], v205 offset:6144
	v_add_u32_e32 v204, 0x0, v201
	v_add_u32_e32 v205, 0x0, v203
	ds_read_b128 v[212:215], v204 offset:0
	ds_read_b128 v[216:219], v204 offset:2048
	ds_read_b128 v[220:223], v204 offset:4096
	ds_read_b128 v[224:227], v204 offset:6144
	ds_read_b128 v[228:231], v205 offset:0
	ds_read_b128 v[232:235], v205 offset:2048
	ds_read_b128 v[236:239], v205 offset:4096
	ds_read_b128 v[240:243], v205 offset:6144
	s_add_u32 m0, s76, 0x18000
	s_nop 0
	global_load_lds_dwordx4 v196, s[68:69]
	s_add_u32 m0, s76, 0x1a000
	s_nop 0
	global_load_lds_dwordx4 v197, s[68:69]
	s_add_u32 m0, s76, 0x1c000
	s_nop 0
	global_load_lds_dwordx4 v198, s[68:69]
	s_add_u32 m0, s76, 0x1e000
	s_nop 0
	global_load_lds_dwordx4 v199, s[68:69]
	s_add_u32 m0, s76, 0x20000
	s_nop 0
	global_load_lds_dwordx4 v196, s[70:71]
	s_add_u32 m0, s76, 0x22000
	s_nop 0
	global_load_lds_dwordx4 v197, s[70:71]
	s_add_u32 s68, s68, 0x80
	s_addc_u32 s69, s69, 0
	s_add_u32 s70, s70, 0x80
	s_addc_u32 s71, s71, 0
	global_load_dwordx4 v[98:101], v193, s[14:15]
	v_add_u32_e32 v170, s38, v193
	global_load_dwordx4 v[102:105], v170, s[14:15]
	s_waitcnt vmcnt(10)
	s_waitcnt lgkmcnt(0)
	s_barrier
	v_mfma_f32_16x16x32_bf16 v[2:5], v[146:149], v[130:133], v[2:5]
	v_mfma_f32_16x16x32_bf16 v[6:9], v[150:153], v[130:133], v[6:9]
	v_mfma_f32_16x16x32_bf16 v[10:13], v[154:157], v[130:133], v[10:13]
	v_mfma_f32_16x16x32_bf16 v[14:17], v[158:161], v[130:133], v[14:17]
	v_mfma_f32_16x16x32_bf16 v[18:21], v[146:149], v[134:137], v[18:21]
	v_mfma_f32_16x16x32_bf16 v[22:25], v[150:153], v[134:137], v[22:25]
	v_mfma_f32_16x16x32_bf16 v[26:29], v[154:157], v[134:137], v[26:29]
	v_mfma_f32_16x16x32_bf16 v[30:33], v[158:161], v[134:137], v[30:33]
	v_mfma_f32_16x16x32_bf16 v[34:37], v[146:149], v[138:141], v[34:37]
	v_mfma_f32_16x16x32_bf16 v[38:41], v[150:153], v[138:141], v[38:41]
	v_mfma_f32_16x16x32_bf16 v[42:45], v[154:157], v[138:141], v[42:45]
	v_mfma_f32_16x16x32_bf16 v[46:49], v[158:161], v[138:141], v[46:49]
	v_mfma_f32_16x16x32_bf16 v[50:53], v[146:149], v[142:145], v[50:53]
	v_mfma_f32_16x16x32_bf16 v[54:57], v[150:153], v[142:145], v[54:57]
	v_mfma_f32_16x16x32_bf16 v[58:61], v[154:157], v[142:145], v[58:61]
	v_mfma_f32_16x16x32_bf16 v[62:65], v[158:161], v[142:145], v[62:65]
	v_mfma_f32_16x16x32_bf16 v[2:5], v[228:231], v[212:215], v[2:5]
	v_mfma_f32_16x16x32_bf16 v[6:9], v[232:235], v[212:215], v[6:9]
	v_mfma_f32_16x16x32_bf16 v[10:13], v[236:239], v[212:215], v[10:13]
	v_mfma_f32_16x16x32_bf16 v[14:17], v[240:243], v[212:215], v[14:17]
	v_mfma_f32_16x16x32_bf16 v[18:21], v[228:231], v[216:219], v[18:21]
	v_mfma_f32_16x16x32_bf16 v[22:25], v[232:235], v[216:219], v[22:25]
	v_mfma_f32_16x16x32_bf16 v[26:29], v[236:239], v[216:219], v[26:29]
	v_mfma_f32_16x16x32_bf16 v[30:33], v[240:243], v[216:219], v[30:33]
	v_mfma_f32_16x16x32_bf16 v[34:37], v[228:231], v[220:223], v[34:37]
	v_mfma_f32_16x16x32_bf16 v[38:41], v[232:235], v[220:223], v[38:41]
	v_mfma_f32_16x16x32_bf16 v[42:45], v[236:239], v[220:223], v[42:45]
	v_mfma_f32_16x16x32_bf16 v[46:49], v[240:243], v[220:223], v[46:49]
	v_mfma_f32_16x16x32_bf16 v[50:53], v[228:231], v[224:227], v[50:53]
	v_mfma_f32_16x16x32_bf16 v[54:57], v[232:235], v[224:227], v[54:57]
	v_mfma_f32_16x16x32_bf16 v[58:61], v[236:239], v[224:227], v[58:61]
	v_mfma_f32_16x16x32_bf16 v[62:65], v[240:243], v[224:227], v[62:65]
	s_barrier
	v_add_u32_e32 v204, 0xc000, v200
	v_add_u32_e32 v205, 0xc000, v202
	ds_read_b128 v[130:133], v204 offset:0
	ds_read_b128 v[134:137], v204 offset:2048
	ds_read_b128 v[138:141], v204 offset:4096
	ds_read_b128 v[142:145], v204 offset:6144
	ds_read_b128 v[146:149], v205 offset:0
	ds_read_b128 v[150:153], v205 offset:2048
	ds_read_b128 v[154:157], v205 offset:4096
	ds_read_b128 v[158:161], v205 offset:6144
	v_add_u32_e32 v204, 0xc000, v201
	v_add_u32_e32 v205, 0xc000, v203
	ds_read_b128 v[212:215], v204 offset:0
	ds_read_b128 v[216:219], v204 offset:2048
	ds_read_b128 v[220:223], v204 offset:4096
	ds_read_b128 v[224:227], v204 offset:6144
	ds_read_b128 v[228:231], v205 offset:0
	ds_read_b128 v[232:235], v205 offset:2048
	ds_read_b128 v[236:239], v205 offset:4096
	ds_read_b128 v[240:243], v205 offset:6144
	s_add_u32 m0, s76, 0x0
	s_nop 0
	global_load_lds_dwordx4 v196, s[68:69]
	s_add_u32 m0, s76, 0x2000
	s_nop 0
	global_load_lds_dwordx4 v197, s[68:69]
	s_add_u32 m0, s76, 0x4000
	s_nop 0
	global_load_lds_dwordx4 v198, s[68:69]
	s_add_u32 m0, s76, 0x6000
	s_nop 0
	global_load_lds_dwordx4 v199, s[68:69]
	s_add_u32 m0, s76, 0x8000
	s_nop 0
	global_load_lds_dwordx4 v196, s[70:71]
	s_add_u32 m0, s76, 0xa000
	s_nop 0
	global_load_lds_dwordx4 v197, s[70:71]
	s_add_u32 s68, s68, 0x80
	s_addc_u32 s69, s69, 0
	s_add_u32 s70, s70, 0x80
	s_addc_u32 s71, s71, 0
	v_add_u32_e32 v170, s39, v193
	global_load_dwordx4 v[106:109], v170, s[14:15]
	v_add_u32_e32 v170, s40, v193
	global_load_dwordx4 v[110:113], v170, s[14:15]
	s_waitcnt vmcnt(10)
	s_waitcnt lgkmcnt(0)
	s_barrier
	v_mfma_f32_16x16x32_bf16 v[2:5], v[146:149], v[130:133], v[2:5]
	v_mfma_f32_16x16x32_bf16 v[6:9], v[150:153], v[130:133], v[6:9]
	v_mfma_f32_16x16x32_bf16 v[10:13], v[154:157], v[130:133], v[10:13]
	v_mfma_f32_16x16x32_bf16 v[14:17], v[158:161], v[130:133], v[14:17]
	v_mfma_f32_16x16x32_bf16 v[18:21], v[146:149], v[134:137], v[18:21]
	v_mfma_f32_16x16x32_bf16 v[22:25], v[150:153], v[134:137], v[22:25]
	v_mfma_f32_16x16x32_bf16 v[26:29], v[154:157], v[134:137], v[26:29]
	v_mfma_f32_16x16x32_bf16 v[30:33], v[158:161], v[134:137], v[30:33]
	v_mfma_f32_16x16x32_bf16 v[34:37], v[146:149], v[138:141], v[34:37]
	v_mfma_f32_16x16x32_bf16 v[38:41], v[150:153], v[138:141], v[38:41]
	v_mfma_f32_16x16x32_bf16 v[42:45], v[154:157], v[138:141], v[42:45]
	v_mfma_f32_16x16x32_bf16 v[46:49], v[158:161], v[138:141], v[46:49]
	v_mfma_f32_16x16x32_bf16 v[50:53], v[146:149], v[142:145], v[50:53]
	v_mfma_f32_16x16x32_bf16 v[54:57], v[150:153], v[142:145], v[54:57]
	v_mfma_f32_16x16x32_bf16 v[58:61], v[154:157], v[142:145], v[58:61]
	v_mfma_f32_16x16x32_bf16 v[62:65], v[158:161], v[142:145], v[62:65]
	v_mfma_f32_16x16x32_bf16 v[2:5], v[228:231], v[212:215], v[2:5]
	v_mfma_f32_16x16x32_bf16 v[6:9], v[232:235], v[212:215], v[6:9]
	v_mfma_f32_16x16x32_bf16 v[10:13], v[236:239], v[212:215], v[10:13]
	v_mfma_f32_16x16x32_bf16 v[14:17], v[240:243], v[212:215], v[14:17]
	v_mfma_f32_16x16x32_bf16 v[18:21], v[228:231], v[216:219], v[18:21]
	v_mfma_f32_16x16x32_bf16 v[22:25], v[232:235], v[216:219], v[22:25]
	v_mfma_f32_16x16x32_bf16 v[26:29], v[236:239], v[216:219], v[26:29]
	v_mfma_f32_16x16x32_bf16 v[30:33], v[240:243], v[216:219], v[30:33]
	v_mfma_f32_16x16x32_bf16 v[34:37], v[228:231], v[220:223], v[34:37]
	v_mfma_f32_16x16x32_bf16 v[38:41], v[232:235], v[220:223], v[38:41]
	v_mfma_f32_16x16x32_bf16 v[42:45], v[236:239], v[220:223], v[42:45]
	v_mfma_f32_16x16x32_bf16 v[46:49], v[240:243], v[220:223], v[46:49]
	v_mfma_f32_16x16x32_bf16 v[50:53], v[228:231], v[224:227], v[50:53]
	v_mfma_f32_16x16x32_bf16 v[54:57], v[232:235], v[224:227], v[54:57]
	v_mfma_f32_16x16x32_bf16 v[58:61], v[236:239], v[224:227], v[58:61]
	v_mfma_f32_16x16x32_bf16 v[62:65], v[240:243], v[224:227], v[62:65]
	s_barrier
	v_add_u32_e32 v204, 0x18000, v200
	v_add_u32_e32 v205, 0x18000, v202
	ds_read_b128 v[130:133], v204 offset:0
	ds_read_b128 v[134:137], v204 offset:2048
	ds_read_b128 v[138:141], v204 offset:4096
	ds_read_b128 v[142:145], v204 offset:6144
	ds_read_b128 v[146:149], v205 offset:0
	ds_read_b128 v[150:153], v205 offset:2048
	ds_read_b128 v[154:157], v205 offset:4096
	ds_read_b128 v[158:161], v205 offset:6144
	v_add_u32_e32 v204, 0x18000, v201
	v_add_u32_e32 v205, 0x18000, v203
	ds_read_b128 v[212:215], v204 offset:0
	ds_read_b128 v[216:219], v204 offset:2048
	ds_read_b128 v[220:223], v204 offset:4096
	ds_read_b128 v[224:227], v204 offset:6144
	ds_read_b128 v[228:231], v205 offset:0
	ds_read_b128 v[232:235], v205 offset:2048
	ds_read_b128 v[236:239], v205 offset:4096
	ds_read_b128 v[240:243], v205 offset:6144
	s_add_u32 m0, s76, 0xc000
	s_nop 0
	global_load_lds_dwordx4 v196, s[68:69]
	s_add_u32 m0, s76, 0xe000
	s_nop 0
	global_load_lds_dwordx4 v197, s[68:69]
	s_add_u32 m0, s76, 0x10000
	s_nop 0
	global_load_lds_dwordx4 v198, s[68:69]
	s_add_u32 m0, s76, 0x12000
	s_nop 0
	global_load_lds_dwordx4 v199, s[68:69]
	s_add_u32 m0, s76, 0x14000
	s_nop 0
	global_load_lds_dwordx4 v196, s[70:71]
	s_add_u32 m0, s76, 0x16000
	s_nop 0
	global_load_lds_dwordx4 v197, s[70:71]
	s_add_u32 s68, s68, 0x80
	s_addc_u32 s69, s69, 0
	s_add_u32 s70, s70, 0x80
	s_addc_u32 s71, s71, 0
	global_load_dwordx4 v[114:117], v244, s[14:15]
	v_add_u32_e32 v170, s38, v244
	global_load_dwordx4 v[118:121], v170, s[14:15]
	s_waitcnt vmcnt(10)
	s_waitcnt lgkmcnt(0)
	s_barrier
	v_mfma_f32_16x16x32_bf16 v[2:5], v[146:149], v[130:133], v[2:5]
	v_mfma_f32_16x16x32_bf16 v[6:9], v[150:153], v[130:133], v[6:9]
	v_mfma_f32_16x16x32_bf16 v[10:13], v[154:157], v[130:133], v[10:13]
	v_mfma_f32_16x16x32_bf16 v[14:17], v[158:161], v[130:133], v[14:17]
	v_mfma_f32_16x16x32_bf16 v[18:21], v[146:149], v[134:137], v[18:21]
	v_mfma_f32_16x16x32_bf16 v[22:25], v[150:153], v[134:137], v[22:25]
	v_mfma_f32_16x16x32_bf16 v[26:29], v[154:157], v[134:137], v[26:29]
	v_mfma_f32_16x16x32_bf16 v[30:33], v[158:161], v[134:137], v[30:33]
	v_mfma_f32_16x16x32_bf16 v[34:37], v[146:149], v[138:141], v[34:37]
	v_mfma_f32_16x16x32_bf16 v[38:41], v[150:153], v[138:141], v[38:41]
	v_mfma_f32_16x16x32_bf16 v[42:45], v[154:157], v[138:141], v[42:45]
	v_mfma_f32_16x16x32_bf16 v[46:49], v[158:161], v[138:141], v[46:49]
	v_mfma_f32_16x16x32_bf16 v[50:53], v[146:149], v[142:145], v[50:53]
	v_mfma_f32_16x16x32_bf16 v[54:57], v[150:153], v[142:145], v[54:57]
	v_mfma_f32_16x16x32_bf16 v[58:61], v[154:157], v[142:145], v[58:61]
	v_mfma_f32_16x16x32_bf16 v[62:65], v[158:161], v[142:145], v[62:65]
	v_mfma_f32_16x16x32_bf16 v[2:5], v[228:231], v[212:215], v[2:5]
	v_mfma_f32_16x16x32_bf16 v[6:9], v[232:235], v[212:215], v[6:9]
	v_mfma_f32_16x16x32_bf16 v[10:13], v[236:239], v[212:215], v[10:13]
	v_mfma_f32_16x16x32_bf16 v[14:17], v[240:243], v[212:215], v[14:17]
	v_mfma_f32_16x16x32_bf16 v[18:21], v[228:231], v[216:219], v[18:21]
	v_mfma_f32_16x16x32_bf16 v[22:25], v[232:235], v[216:219], v[22:25]
	v_mfma_f32_16x16x32_bf16 v[26:29], v[236:239], v[216:219], v[26:29]
	v_mfma_f32_16x16x32_bf16 v[30:33], v[240:243], v[216:219], v[30:33]
	v_mfma_f32_16x16x32_bf16 v[34:37], v[228:231], v[220:223], v[34:37]
	v_mfma_f32_16x16x32_bf16 v[38:41], v[232:235], v[220:223], v[38:41]
	v_mfma_f32_16x16x32_bf16 v[42:45], v[236:239], v[220:223], v[42:45]
	v_mfma_f32_16x16x32_bf16 v[46:49], v[240:243], v[220:223], v[46:49]
	v_mfma_f32_16x16x32_bf16 v[50:53], v[228:231], v[224:227], v[50:53]
	v_mfma_f32_16x16x32_bf16 v[54:57], v[232:235], v[224:227], v[54:57]
	v_mfma_f32_16x16x32_bf16 v[58:61], v[236:239], v[224:227], v[58:61]
	v_mfma_f32_16x16x32_bf16 v[62:65], v[240:243], v[224:227], v[62:65]
	s_barrier
	v_add_u32_e32 v204, 0x0, v200
	v_add_u32_e32 v205, 0x0, v202
	ds_read_b128 v[130:133], v204 offset:0
	ds_read_b128 v[134:137], v204 offset:2048
	ds_read_b128 v[138:141], v204 offset:4096
	ds_read_b128 v[142:145], v204 offset:6144
	ds_read_b128 v[146:149], v205 offset:0
	ds_read_b128 v[150:153], v205 offset:2048
	ds_read_b128 v[154:157], v205 offset:4096
	ds_read_b128 v[158:161], v205 offset:6144
	v_add_u32_e32 v204, 0x0, v201
	v_add_u32_e32 v205, 0x0, v203
	ds_read_b128 v[212:215], v204 offset:0
	ds_read_b128 v[216:219], v204 offset:2048
	ds_read_b128 v[220:223], v204 offset:4096
	ds_read_b128 v[224:227], v204 offset:6144
	ds_read_b128 v[228:231], v205 offset:0
	ds_read_b128 v[232:235], v205 offset:2048
	ds_read_b128 v[236:239], v205 offset:4096
	ds_read_b128 v[240:243], v205 offset:6144
	s_add_u32 m0, s76, 0x18000
	s_nop 0
	global_load_lds_dwordx4 v196, s[68:69]
	s_add_u32 m0, s76, 0x1a000
	s_nop 0
	global_load_lds_dwordx4 v197, s[68:69]
	s_add_u32 m0, s76, 0x1c000
	s_nop 0
	global_load_lds_dwordx4 v198, s[68:69]
	s_add_u32 m0, s76, 0x1e000
	s_nop 0
	global_load_lds_dwordx4 v199, s[68:69]
	s_add_u32 m0, s76, 0x20000
	s_nop 0
	global_load_lds_dwordx4 v196, s[70:71]
	s_add_u32 m0, s76, 0x22000
	s_nop 0
	global_load_lds_dwordx4 v197, s[70:71]
	s_add_u32 s68, s68, 0x80
	s_addc_u32 s69, s69, 0
	s_add_u32 s70, s70, 0x80
	s_addc_u32 s71, s71, 0
	v_add_u32_e32 v170, s39, v244
	global_load_dwordx4 v[122:125], v170, s[14:15]
	v_add_u32_e32 v170, s40, v244
	global_load_dwordx4 v[126:129], v170, s[14:15]
	s_waitcnt vmcnt(10)
	s_waitcnt lgkmcnt(0)
	s_barrier
	v_mfma_f32_16x16x32_bf16 v[2:5], v[146:149], v[130:133], v[2:5]
	v_mfma_f32_16x16x32_bf16 v[6:9], v[150:153], v[130:133], v[6:9]
	v_mfma_f32_16x16x32_bf16 v[10:13], v[154:157], v[130:133], v[10:13]
	v_mfma_f32_16x16x32_bf16 v[14:17], v[158:161], v[130:133], v[14:17]
	v_mfma_f32_16x16x32_bf16 v[18:21], v[146:149], v[134:137], v[18:21]
	v_mfma_f32_16x16x32_bf16 v[22:25], v[150:153], v[134:137], v[22:25]
	v_mfma_f32_16x16x32_bf16 v[26:29], v[154:157], v[134:137], v[26:29]
	v_mfma_f32_16x16x32_bf16 v[30:33], v[158:161], v[134:137], v[30:33]
	v_mfma_f32_16x16x32_bf16 v[34:37], v[146:149], v[138:141], v[34:37]
	v_mfma_f32_16x16x32_bf16 v[38:41], v[150:153], v[138:141], v[38:41]
	v_mfma_f32_16x16x32_bf16 v[42:45], v[154:157], v[138:141], v[42:45]
	v_mfma_f32_16x16x32_bf16 v[46:49], v[158:161], v[138:141], v[46:49]
	v_mfma_f32_16x16x32_bf16 v[50:53], v[146:149], v[142:145], v[50:53]
	v_mfma_f32_16x16x32_bf16 v[54:57], v[150:153], v[142:145], v[54:57]
	v_mfma_f32_16x16x32_bf16 v[58:61], v[154:157], v[142:145], v[58:61]
	v_mfma_f32_16x16x32_bf16 v[62:65], v[158:161], v[142:145], v[62:65]
	v_mfma_f32_16x16x32_bf16 v[2:5], v[228:231], v[212:215], v[2:5]
	v_mfma_f32_16x16x32_bf16 v[6:9], v[232:235], v[212:215], v[6:9]
	v_mfma_f32_16x16x32_bf16 v[10:13], v[236:239], v[212:215], v[10:13]
	v_mfma_f32_16x16x32_bf16 v[14:17], v[240:243], v[212:215], v[14:17]
	v_mfma_f32_16x16x32_bf16 v[18:21], v[228:231], v[216:219], v[18:21]
	v_mfma_f32_16x16x32_bf16 v[22:25], v[232:235], v[216:219], v[22:25]
	v_mfma_f32_16x16x32_bf16 v[26:29], v[236:239], v[216:219], v[26:29]
	v_mfma_f32_16x16x32_bf16 v[30:33], v[240:243], v[216:219], v[30:33]
	v_mfma_f32_16x16x32_bf16 v[34:37], v[228:231], v[220:223], v[34:37]
	v_mfma_f32_16x16x32_bf16 v[38:41], v[232:235], v[220:223], v[38:41]
	v_mfma_f32_16x16x32_bf16 v[42:45], v[236:239], v[220:223], v[42:45]
	v_mfma_f32_16x16x32_bf16 v[46:49], v[240:243], v[220:223], v[46:49]
	v_mfma_f32_16x16x32_bf16 v[50:53], v[228:231], v[224:227], v[50:53]
	v_mfma_f32_16x16x32_bf16 v[54:57], v[232:235], v[224:227], v[54:57]
	v_mfma_f32_16x16x32_bf16 v[58:61], v[236:239], v[224:227], v[58:61]
	v_mfma_f32_16x16x32_bf16 v[62:65], v[240:243], v[224:227], v[62:65]
	s_barrier
	v_add_u32_e32 v204, 0xc000, v200
	v_add_u32_e32 v205, 0xc000, v202
	ds_read_b128 v[130:133], v204 offset:0
	ds_read_b128 v[134:137], v204 offset:2048
	ds_read_b128 v[138:141], v204 offset:4096
	ds_read_b128 v[142:145], v204 offset:6144
	ds_read_b128 v[146:149], v205 offset:0
	ds_read_b128 v[150:153], v205 offset:2048
	ds_read_b128 v[154:157], v205 offset:4096
	ds_read_b128 v[158:161], v205 offset:6144
	v_add_u32_e32 v204, 0xc000, v201
	v_add_u32_e32 v205, 0xc000, v203
	ds_read_b128 v[212:215], v204 offset:0
	ds_read_b128 v[216:219], v204 offset:2048
	ds_read_b128 v[220:223], v204 offset:4096
	ds_read_b128 v[224:227], v204 offset:6144
	ds_read_b128 v[228:231], v205 offset:0
	ds_read_b128 v[232:235], v205 offset:2048
	ds_read_b128 v[236:239], v205 offset:4096
	ds_read_b128 v[240:243], v205 offset:6144
	s_add_u32 m0, s76, 0x0
	s_nop 0
	global_load_lds_dwordx4 v196, s[68:69]
	s_add_u32 m0, s76, 0x2000
	s_nop 0
	global_load_lds_dwordx4 v197, s[68:69]
	s_add_u32 m0, s76, 0x4000
	s_nop 0
	global_load_lds_dwordx4 v198, s[68:69]
	s_add_u32 m0, s76, 0x6000
	s_nop 0
	global_load_lds_dwordx4 v199, s[68:69]
	s_add_u32 m0, s76, 0x8000
	s_nop 0
	global_load_lds_dwordx4 v196, s[70:71]
	s_add_u32 m0, s76, 0xa000
	s_nop 0
	global_load_lds_dwordx4 v197, s[70:71]
	s_add_u32 s68, s68, 0x80
	s_addc_u32 s69, s69, 0
	s_add_u32 s70, s70, 0x80
	s_addc_u32 s71, s71, 0
	s_waitcnt vmcnt(8)
	s_waitcnt lgkmcnt(0)
	s_barrier
	v_mfma_f32_16x16x32_bf16 v[2:5], v[146:149], v[130:133], v[2:5]
	v_mfma_f32_16x16x32_bf16 v[6:9], v[150:153], v[130:133], v[6:9]
	v_mfma_f32_16x16x32_bf16 v[10:13], v[154:157], v[130:133], v[10:13]
	v_mfma_f32_16x16x32_bf16 v[14:17], v[158:161], v[130:133], v[14:17]
	v_mfma_f32_16x16x32_bf16 v[18:21], v[146:149], v[134:137], v[18:21]
	v_mfma_f32_16x16x32_bf16 v[22:25], v[150:153], v[134:137], v[22:25]
	v_mfma_f32_16x16x32_bf16 v[26:29], v[154:157], v[134:137], v[26:29]
	v_mfma_f32_16x16x32_bf16 v[30:33], v[158:161], v[134:137], v[30:33]
	v_mfma_f32_16x16x32_bf16 v[34:37], v[146:149], v[138:141], v[34:37]
	v_mfma_f32_16x16x32_bf16 v[38:41], v[150:153], v[138:141], v[38:41]
	v_mfma_f32_16x16x32_bf16 v[42:45], v[154:157], v[138:141], v[42:45]
	v_mfma_f32_16x16x32_bf16 v[46:49], v[158:161], v[138:141], v[46:49]
	v_mfma_f32_16x16x32_bf16 v[50:53], v[146:149], v[142:145], v[50:53]
	v_mfma_f32_16x16x32_bf16 v[54:57], v[150:153], v[142:145], v[54:57]
	v_mfma_f32_16x16x32_bf16 v[58:61], v[154:157], v[142:145], v[58:61]
	v_mfma_f32_16x16x32_bf16 v[62:65], v[158:161], v[142:145], v[62:65]
	v_mfma_f32_16x16x32_bf16 v[2:5], v[228:231], v[212:215], v[2:5]
	v_mfma_f32_16x16x32_bf16 v[6:9], v[232:235], v[212:215], v[6:9]
	v_mfma_f32_16x16x32_bf16 v[10:13], v[236:239], v[212:215], v[10:13]
	v_mfma_f32_16x16x32_bf16 v[14:17], v[240:243], v[212:215], v[14:17]
	v_mfma_f32_16x16x32_bf16 v[18:21], v[228:231], v[216:219], v[18:21]
	v_mfma_f32_16x16x32_bf16 v[22:25], v[232:235], v[216:219], v[22:25]
	v_mfma_f32_16x16x32_bf16 v[26:29], v[236:239], v[216:219], v[26:29]
	v_mfma_f32_16x16x32_bf16 v[30:33], v[240:243], v[216:219], v[30:33]
	v_mfma_f32_16x16x32_bf16 v[34:37], v[228:231], v[220:223], v[34:37]
	v_mfma_f32_16x16x32_bf16 v[38:41], v[232:235], v[220:223], v[38:41]
	v_mfma_f32_16x16x32_bf16 v[42:45], v[236:239], v[220:223], v[42:45]
	v_mfma_f32_16x16x32_bf16 v[46:49], v[240:243], v[220:223], v[46:49]
	v_mfma_f32_16x16x32_bf16 v[50:53], v[228:231], v[224:227], v[50:53]
	v_mfma_f32_16x16x32_bf16 v[54:57], v[232:235], v[224:227], v[54:57]
	v_mfma_f32_16x16x32_bf16 v[58:61], v[236:239], v[224:227], v[58:61]
	v_mfma_f32_16x16x32_bf16 v[62:65], v[240:243], v[224:227], v[62:65]
	s_barrier
	v_add_u32_e32 v204, 0x18000, v200
	v_add_u32_e32 v205, 0x18000, v202
	ds_read_b128 v[130:133], v204 offset:0
	ds_read_b128 v[134:137], v204 offset:2048
	ds_read_b128 v[138:141], v204 offset:4096
	ds_read_b128 v[142:145], v204 offset:6144
	ds_read_b128 v[146:149], v205 offset:0
	ds_read_b128 v[150:153], v205 offset:2048
	ds_read_b128 v[154:157], v205 offset:4096
	ds_read_b128 v[158:161], v205 offset:6144
	v_add_u32_e32 v204, 0x18000, v201
	v_add_u32_e32 v205, 0x18000, v203
	ds_read_b128 v[212:215], v204 offset:0
	ds_read_b128 v[216:219], v204 offset:2048
	ds_read_b128 v[220:223], v204 offset:4096
	ds_read_b128 v[224:227], v204 offset:6144
	ds_read_b128 v[228:231], v205 offset:0
	ds_read_b128 v[232:235], v205 offset:2048
	ds_read_b128 v[236:239], v205 offset:4096
	ds_read_b128 v[240:243], v205 offset:6144
	s_add_u32 m0, s76, 0xc000
	s_nop 0
	global_load_lds_dwordx4 v196, s[68:69]
	s_add_u32 m0, s76, 0xe000
	s_nop 0
	global_load_lds_dwordx4 v197, s[68:69]
	s_add_u32 m0, s76, 0x10000
	s_nop 0
	global_load_lds_dwordx4 v198, s[68:69]
	s_add_u32 m0, s76, 0x12000
	s_nop 0
	global_load_lds_dwordx4 v199, s[68:69]
	s_add_u32 m0, s76, 0x14000
	s_nop 0
	global_load_lds_dwordx4 v196, s[70:71]
	s_add_u32 m0, s76, 0x16000
	s_nop 0
	global_load_lds_dwordx4 v197, s[70:71]
	s_add_u32 s68, s68, 0x80
	s_addc_u32 s69, s69, 0
	s_add_u32 s70, s70, 0x80
	s_addc_u32 s71, s71, 0
	s_waitcnt vmcnt(6)
	s_waitcnt lgkmcnt(0)
	s_barrier
	v_mfma_f32_16x16x32_bf16 v[2:5], v[146:149], v[130:133], v[2:5]
	v_mfma_f32_16x16x32_bf16 v[6:9], v[150:153], v[130:133], v[6:9]
	v_mfma_f32_16x16x32_bf16 v[10:13], v[154:157], v[130:133], v[10:13]
	v_mfma_f32_16x16x32_bf16 v[14:17], v[158:161], v[130:133], v[14:17]
	v_mfma_f32_16x16x32_bf16 v[18:21], v[146:149], v[134:137], v[18:21]
	v_mfma_f32_16x16x32_bf16 v[22:25], v[150:153], v[134:137], v[22:25]
	v_mfma_f32_16x16x32_bf16 v[26:29], v[154:157], v[134:137], v[26:29]
	v_mfma_f32_16x16x32_bf16 v[30:33], v[158:161], v[134:137], v[30:33]
	v_mfma_f32_16x16x32_bf16 v[34:37], v[146:149], v[138:141], v[34:37]
	v_mfma_f32_16x16x32_bf16 v[38:41], v[150:153], v[138:141], v[38:41]
	v_mfma_f32_16x16x32_bf16 v[42:45], v[154:157], v[138:141], v[42:45]
	v_mfma_f32_16x16x32_bf16 v[46:49], v[158:161], v[138:141], v[46:49]
	v_mfma_f32_16x16x32_bf16 v[50:53], v[146:149], v[142:145], v[50:53]
	v_mfma_f32_16x16x32_bf16 v[54:57], v[150:153], v[142:145], v[54:57]
	v_mfma_f32_16x16x32_bf16 v[58:61], v[154:157], v[142:145], v[58:61]
	v_mfma_f32_16x16x32_bf16 v[62:65], v[158:161], v[142:145], v[62:65]
	v_mfma_f32_16x16x32_bf16 v[2:5], v[228:231], v[212:215], v[2:5]
	v_mfma_f32_16x16x32_bf16 v[6:9], v[232:235], v[212:215], v[6:9]
	v_mfma_f32_16x16x32_bf16 v[10:13], v[236:239], v[212:215], v[10:13]
	v_mfma_f32_16x16x32_bf16 v[14:17], v[240:243], v[212:215], v[14:17]
	v_mfma_f32_16x16x32_bf16 v[18:21], v[228:231], v[216:219], v[18:21]
	v_mfma_f32_16x16x32_bf16 v[22:25], v[232:235], v[216:219], v[22:25]
	v_mfma_f32_16x16x32_bf16 v[26:29], v[236:239], v[216:219], v[26:29]
	v_mfma_f32_16x16x32_bf16 v[30:33], v[240:243], v[216:219], v[30:33]
	v_mfma_f32_16x16x32_bf16 v[34:37], v[228:231], v[220:223], v[34:37]
	v_mfma_f32_16x16x32_bf16 v[38:41], v[232:235], v[220:223], v[38:41]
	v_mfma_f32_16x16x32_bf16 v[42:45], v[236:239], v[220:223], v[42:45]
	v_mfma_f32_16x16x32_bf16 v[46:49], v[240:243], v[220:223], v[46:49]
	v_mfma_f32_16x16x32_bf16 v[50:53], v[228:231], v[224:227], v[50:53]
	v_mfma_f32_16x16x32_bf16 v[54:57], v[232:235], v[224:227], v[54:57]
	v_mfma_f32_16x16x32_bf16 v[58:61], v[236:239], v[224:227], v[58:61]
	v_mfma_f32_16x16x32_bf16 v[62:65], v[240:243], v[224:227], v[62:65]
	s_barrier
	v_add_u32_e32 v204, 0x0, v200
	v_add_u32_e32 v205, 0x0, v202
	ds_read_b128 v[130:133], v204 offset:0
	ds_read_b128 v[134:137], v204 offset:2048
	ds_read_b128 v[138:141], v204 offset:4096
	ds_read_b128 v[142:145], v204 offset:6144
	ds_read_b128 v[146:149], v205 offset:0
	ds_read_b128 v[150:153], v205 offset:2048
	ds_read_b128 v[154:157], v205 offset:4096
	ds_read_b128 v[158:161], v205 offset:6144
	v_add_u32_e32 v204, 0x0, v201
	v_add_u32_e32 v205, 0x0, v203
	ds_read_b128 v[212:215], v204 offset:0
	ds_read_b128 v[216:219], v204 offset:2048
	ds_read_b128 v[220:223], v204 offset:4096
	ds_read_b128 v[224:227], v204 offset:6144
	ds_read_b128 v[228:231], v205 offset:0
	ds_read_b128 v[232:235], v205 offset:2048
	ds_read_b128 v[236:239], v205 offset:4096
	ds_read_b128 v[240:243], v205 offset:6144
	s_add_u32 m0, s76, 0x18000
	s_nop 0
	global_load_lds_dwordx4 v196, s[68:69]
	s_add_u32 m0, s76, 0x1a000
	s_nop 0
	global_load_lds_dwordx4 v197, s[68:69]
	s_add_u32 m0, s76, 0x1c000
	s_nop 0
	global_load_lds_dwordx4 v198, s[68:69]
	s_add_u32 m0, s76, 0x1e000
	s_nop 0
	global_load_lds_dwordx4 v199, s[68:69]
	s_add_u32 m0, s76, 0x20000
	s_nop 0
	global_load_lds_dwordx4 v196, s[70:71]
	s_add_u32 m0, s76, 0x22000
	s_nop 0
	global_load_lds_dwordx4 v197, s[70:71]
	s_add_u32 s68, s68, 0x80
	s_addc_u32 s69, s69, 0
	s_add_u32 s70, s70, 0x80
	s_addc_u32 s71, s71, 0
	s_waitcnt vmcnt(6)
	s_waitcnt lgkmcnt(0)
	s_barrier
	v_mfma_f32_16x16x32_bf16 v[2:5], v[146:149], v[130:133], v[2:5]
	v_mfma_f32_16x16x32_bf16 v[6:9], v[150:153], v[130:133], v[6:9]
	v_mfma_f32_16x16x32_bf16 v[10:13], v[154:157], v[130:133], v[10:13]
	v_mfma_f32_16x16x32_bf16 v[14:17], v[158:161], v[130:133], v[14:17]
	v_mfma_f32_16x16x32_bf16 v[18:21], v[146:149], v[134:137], v[18:21]
	v_mfma_f32_16x16x32_bf16 v[22:25], v[150:153], v[134:137], v[22:25]
	v_mfma_f32_16x16x32_bf16 v[26:29], v[154:157], v[134:137], v[26:29]
	v_mfma_f32_16x16x32_bf16 v[30:33], v[158:161], v[134:137], v[30:33]
	v_mfma_f32_16x16x32_bf16 v[34:37], v[146:149], v[138:141], v[34:37]
	v_mfma_f32_16x16x32_bf16 v[38:41], v[150:153], v[138:141], v[38:41]
	v_mfma_f32_16x16x32_bf16 v[42:45], v[154:157], v[138:141], v[42:45]
	v_mfma_f32_16x16x32_bf16 v[46:49], v[158:161], v[138:141], v[46:49]
	v_mfma_f32_16x16x32_bf16 v[50:53], v[146:149], v[142:145], v[50:53]
	v_mfma_f32_16x16x32_bf16 v[54:57], v[150:153], v[142:145], v[54:57]
	v_mfma_f32_16x16x32_bf16 v[58:61], v[154:157], v[142:145], v[58:61]
	v_mfma_f32_16x16x32_bf16 v[62:65], v[158:161], v[142:145], v[62:65]
	v_mfma_f32_16x16x32_bf16 v[2:5], v[228:231], v[212:215], v[2:5]
	v_mfma_f32_16x16x32_bf16 v[6:9], v[232:235], v[212:215], v[6:9]
	v_mfma_f32_16x16x32_bf16 v[10:13], v[236:239], v[212:215], v[10:13]
	v_mfma_f32_16x16x32_bf16 v[14:17], v[240:243], v[212:215], v[14:17]
	v_mfma_f32_16x16x32_bf16 v[18:21], v[228:231], v[216:219], v[18:21]
	v_mfma_f32_16x16x32_bf16 v[22:25], v[232:235], v[216:219], v[22:25]
	v_mfma_f32_16x16x32_bf16 v[26:29], v[236:239], v[216:219], v[26:29]
	v_mfma_f32_16x16x32_bf16 v[30:33], v[240:243], v[216:219], v[30:33]
	v_mfma_f32_16x16x32_bf16 v[34:37], v[228:231], v[220:223], v[34:37]
	v_mfma_f32_16x16x32_bf16 v[38:41], v[232:235], v[220:223], v[38:41]
	v_mfma_f32_16x16x32_bf16 v[42:45], v[236:239], v[220:223], v[42:45]
	v_mfma_f32_16x16x32_bf16 v[46:49], v[240:243], v[220:223], v[46:49]
	v_mfma_f32_16x16x32_bf16 v[50:53], v[228:231], v[224:227], v[50:53]
	v_mfma_f32_16x16x32_bf16 v[54:57], v[232:235], v[224:227], v[54:57]
	v_mfma_f32_16x16x32_bf16 v[58:61], v[236:239], v[224:227], v[58:61]
	v_mfma_f32_16x16x32_bf16 v[62:65], v[240:243], v[224:227], v[62:65]
	s_barrier
	v_add_u32_e32 v204, 0xc000, v200
	v_add_u32_e32 v205, 0xc000, v202
	ds_read_b128 v[130:133], v204 offset:0
	ds_read_b128 v[134:137], v204 offset:2048
	ds_read_b128 v[138:141], v204 offset:4096
	ds_read_b128 v[142:145], v204 offset:6144
	ds_read_b128 v[146:149], v205 offset:0
	ds_read_b128 v[150:153], v205 offset:2048
	ds_read_b128 v[154:157], v205 offset:4096
	ds_read_b128 v[158:161], v205 offset:6144
	v_add_u32_e32 v204, 0xc000, v201
	v_add_u32_e32 v205, 0xc000, v203
	ds_read_b128 v[212:215], v204 offset:0
	ds_read_b128 v[216:219], v204 offset:2048
	ds_read_b128 v[220:223], v204 offset:4096
	ds_read_b128 v[224:227], v204 offset:6144
	ds_read_b128 v[228:231], v205 offset:0
	ds_read_b128 v[232:235], v205 offset:2048
	ds_read_b128 v[236:239], v205 offset:4096
	ds_read_b128 v[240:243], v205 offset:6144
	s_add_u32 m0, s76, 0x0
	s_nop 0
	global_load_lds_dwordx4 v196, s[68:69]
	s_add_u32 m0, s76, 0x2000
	s_nop 0
	global_load_lds_dwordx4 v197, s[68:69]
	s_add_u32 m0, s76, 0x4000
	s_nop 0
	global_load_lds_dwordx4 v198, s[68:69]
	s_add_u32 m0, s76, 0x6000
	s_nop 0
	global_load_lds_dwordx4 v199, s[68:69]
	s_add_u32 m0, s76, 0x8000
	s_nop 0
	global_load_lds_dwordx4 v196, s[70:71]
	s_add_u32 m0, s76, 0xa000
	s_nop 0
	global_load_lds_dwordx4 v197, s[70:71]
	s_add_u32 s68, s68, 0x80
	s_addc_u32 s69, s69, 0
	s_add_u32 s70, s70, 0x80
	s_addc_u32 s71, s71, 0
	s_waitcnt vmcnt(6)
	s_waitcnt lgkmcnt(0)
	s_barrier
	v_mfma_f32_16x16x32_bf16 v[2:5], v[146:149], v[130:133], v[2:5]
	v_mfma_f32_16x16x32_bf16 v[6:9], v[150:153], v[130:133], v[6:9]
	v_mfma_f32_16x16x32_bf16 v[10:13], v[154:157], v[130:133], v[10:13]
	v_mfma_f32_16x16x32_bf16 v[14:17], v[158:161], v[130:133], v[14:17]
	v_mfma_f32_16x16x32_bf16 v[18:21], v[146:149], v[134:137], v[18:21]
	v_mfma_f32_16x16x32_bf16 v[22:25], v[150:153], v[134:137], v[22:25]
	v_mfma_f32_16x16x32_bf16 v[26:29], v[154:157], v[134:137], v[26:29]
	v_mfma_f32_16x16x32_bf16 v[30:33], v[158:161], v[134:137], v[30:33]
	v_mfma_f32_16x16x32_bf16 v[34:37], v[146:149], v[138:141], v[34:37]
	v_mfma_f32_16x16x32_bf16 v[38:41], v[150:153], v[138:141], v[38:41]
	v_mfma_f32_16x16x32_bf16 v[42:45], v[154:157], v[138:141], v[42:45]
	v_mfma_f32_16x16x32_bf16 v[46:49], v[158:161], v[138:141], v[46:49]
	v_mfma_f32_16x16x32_bf16 v[50:53], v[146:149], v[142:145], v[50:53]
	v_mfma_f32_16x16x32_bf16 v[54:57], v[150:153], v[142:145], v[54:57]
	v_mfma_f32_16x16x32_bf16 v[58:61], v[154:157], v[142:145], v[58:61]
	v_mfma_f32_16x16x32_bf16 v[62:65], v[158:161], v[142:145], v[62:65]
	v_mfma_f32_16x16x32_bf16 v[2:5], v[228:231], v[212:215], v[2:5]
	v_mfma_f32_16x16x32_bf16 v[6:9], v[232:235], v[212:215], v[6:9]
	v_mfma_f32_16x16x32_bf16 v[10:13], v[236:239], v[212:215], v[10:13]
	v_mfma_f32_16x16x32_bf16 v[14:17], v[240:243], v[212:215], v[14:17]
	v_mfma_f32_16x16x32_bf16 v[18:21], v[228:231], v[216:219], v[18:21]
	v_mfma_f32_16x16x32_bf16 v[22:25], v[232:235], v[216:219], v[22:25]
	v_mfma_f32_16x16x32_bf16 v[26:29], v[236:239], v[216:219], v[26:29]
	v_mfma_f32_16x16x32_bf16 v[30:33], v[240:243], v[216:219], v[30:33]
	v_mfma_f32_16x16x32_bf16 v[34:37], v[228:231], v[220:223], v[34:37]
	v_mfma_f32_16x16x32_bf16 v[38:41], v[232:235], v[220:223], v[38:41]
	v_mfma_f32_16x16x32_bf16 v[42:45], v[236:239], v[220:223], v[42:45]
	v_mfma_f32_16x16x32_bf16 v[46:49], v[240:243], v[220:223], v[46:49]
	v_mfma_f32_16x16x32_bf16 v[50:53], v[228:231], v[224:227], v[50:53]
	v_mfma_f32_16x16x32_bf16 v[54:57], v[232:235], v[224:227], v[54:57]
	v_mfma_f32_16x16x32_bf16 v[58:61], v[236:239], v[224:227], v[58:61]
	v_mfma_f32_16x16x32_bf16 v[62:65], v[240:243], v[224:227], v[62:65]
	s_barrier
	v_add_u32_e32 v204, 0x18000, v200
	v_add_u32_e32 v205, 0x18000, v202
	ds_read_b128 v[130:133], v204 offset:0
	ds_read_b128 v[134:137], v204 offset:2048
	ds_read_b128 v[138:141], v204 offset:4096
	ds_read_b128 v[142:145], v204 offset:6144
	ds_read_b128 v[146:149], v205 offset:0
	ds_read_b128 v[150:153], v205 offset:2048
	ds_read_b128 v[154:157], v205 offset:4096
	ds_read_b128 v[158:161], v205 offset:6144
	v_add_u32_e32 v204, 0x18000, v201
	v_add_u32_e32 v205, 0x18000, v203
	ds_read_b128 v[212:215], v204 offset:0
	ds_read_b128 v[216:219], v204 offset:2048
	ds_read_b128 v[220:223], v204 offset:4096
	ds_read_b128 v[224:227], v204 offset:6144
	ds_read_b128 v[228:231], v205 offset:0
	ds_read_b128 v[232:235], v205 offset:2048
	ds_read_b128 v[236:239], v205 offset:4096
	ds_read_b128 v[240:243], v205 offset:6144
	s_waitcnt vmcnt(0)
	s_waitcnt lgkmcnt(0)
	s_barrier
	v_mfma_f32_16x16x32_bf16 v[2:5], v[146:149], v[130:133], v[2:5]
	v_mfma_f32_16x16x32_bf16 v[6:9], v[150:153], v[130:133], v[6:9]
	v_mfma_f32_16x16x32_bf16 v[10:13], v[154:157], v[130:133], v[10:13]
	v_mfma_f32_16x16x32_bf16 v[14:17], v[158:161], v[130:133], v[14:17]
	v_mfma_f32_16x16x32_bf16 v[18:21], v[146:149], v[134:137], v[18:21]
	v_mfma_f32_16x16x32_bf16 v[22:25], v[150:153], v[134:137], v[22:25]
	v_mfma_f32_16x16x32_bf16 v[26:29], v[154:157], v[134:137], v[26:29]
	v_mfma_f32_16x16x32_bf16 v[30:33], v[158:161], v[134:137], v[30:33]
	v_mfma_f32_16x16x32_bf16 v[34:37], v[146:149], v[138:141], v[34:37]
	v_mfma_f32_16x16x32_bf16 v[38:41], v[150:153], v[138:141], v[38:41]
	v_mfma_f32_16x16x32_bf16 v[42:45], v[154:157], v[138:141], v[42:45]
	v_mfma_f32_16x16x32_bf16 v[46:49], v[158:161], v[138:141], v[46:49]
	v_mfma_f32_16x16x32_bf16 v[50:53], v[146:149], v[142:145], v[50:53]
	v_mfma_f32_16x16x32_bf16 v[54:57], v[150:153], v[142:145], v[54:57]
	v_mfma_f32_16x16x32_bf16 v[58:61], v[154:157], v[142:145], v[58:61]
	v_mfma_f32_16x16x32_bf16 v[62:65], v[158:161], v[142:145], v[62:65]
	v_mfma_f32_16x16x32_bf16 v[2:5], v[228:231], v[212:215], v[2:5]
	v_mfma_f32_16x16x32_bf16 v[6:9], v[232:235], v[212:215], v[6:9]
	v_mfma_f32_16x16x32_bf16 v[10:13], v[236:239], v[212:215], v[10:13]
	v_mfma_f32_16x16x32_bf16 v[14:17], v[240:243], v[212:215], v[14:17]
	v_mfma_f32_16x16x32_bf16 v[18:21], v[228:231], v[216:219], v[18:21]
	v_mfma_f32_16x16x32_bf16 v[22:25], v[232:235], v[216:219], v[22:25]
	v_mfma_f32_16x16x32_bf16 v[26:29], v[236:239], v[216:219], v[26:29]
	v_mfma_f32_16x16x32_bf16 v[30:33], v[240:243], v[216:219], v[30:33]
	v_mfma_f32_16x16x32_bf16 v[34:37], v[228:231], v[220:223], v[34:37]
	v_mfma_f32_16x16x32_bf16 v[38:41], v[232:235], v[220:223], v[38:41]
	v_mfma_f32_16x16x32_bf16 v[42:45], v[236:239], v[220:223], v[42:45]
	v_mfma_f32_16x16x32_bf16 v[46:49], v[240:243], v[220:223], v[46:49]
	v_mfma_f32_16x16x32_bf16 v[50:53], v[228:231], v[224:227], v[50:53]
	v_mfma_f32_16x16x32_bf16 v[54:57], v[232:235], v[224:227], v[54:57]
	v_mfma_f32_16x16x32_bf16 v[58:61], v[236:239], v[224:227], v[58:61]
	v_mfma_f32_16x16x32_bf16 v[62:65], v[240:243], v[224:227], v[62:65]
	s_barrier
	v_add_u32_e32 v204, 0x0, v200
	v_add_u32_e32 v205, 0x0, v202
	ds_read_b128 v[130:133], v204 offset:0
	ds_read_b128 v[134:137], v204 offset:2048
	ds_read_b128 v[138:141], v204 offset:4096
	ds_read_b128 v[142:145], v204 offset:6144
	ds_read_b128 v[146:149], v205 offset:0
	ds_read_b128 v[150:153], v205 offset:2048
	ds_read_b128 v[154:157], v205 offset:4096
	ds_read_b128 v[158:161], v205 offset:6144
	v_add_u32_e32 v204, 0x0, v201
	v_add_u32_e32 v205, 0x0, v203
	ds_read_b128 v[212:215], v204 offset:0
	ds_read_b128 v[216:219], v204 offset:2048
	ds_read_b128 v[220:223], v204 offset:4096
	ds_read_b128 v[224:227], v204 offset:6144
	ds_read_b128 v[228:231], v205 offset:0
	ds_read_b128 v[232:235], v205 offset:2048
	ds_read_b128 v[236:239], v205 offset:4096
	ds_read_b128 v[240:243], v205 offset:6144
	s_waitcnt lgkmcnt(0)
	s_barrier
	v_mfma_f32_16x16x32_bf16 v[2:5], v[146:149], v[130:133], v[2:5]
	v_mfma_f32_16x16x32_bf16 v[6:9], v[150:153], v[130:133], v[6:9]
	v_mfma_f32_16x16x32_bf16 v[10:13], v[154:157], v[130:133], v[10:13]
	v_mfma_f32_16x16x32_bf16 v[14:17], v[158:161], v[130:133], v[14:17]
	v_mfma_f32_16x16x32_bf16 v[18:21], v[146:149], v[134:137], v[18:21]
	v_mfma_f32_16x16x32_bf16 v[22:25], v[150:153], v[134:137], v[22:25]
	v_mfma_f32_16x16x32_bf16 v[26:29], v[154:157], v[134:137], v[26:29]
	v_mfma_f32_16x16x32_bf16 v[30:33], v[158:161], v[134:137], v[30:33]
	v_mfma_f32_16x16x32_bf16 v[34:37], v[146:149], v[138:141], v[34:37]
	v_mfma_f32_16x16x32_bf16 v[38:41], v[150:153], v[138:141], v[38:41]
	v_mfma_f32_16x16x32_bf16 v[42:45], v[154:157], v[138:141], v[42:45]
	v_mfma_f32_16x16x32_bf16 v[46:49], v[158:161], v[138:141], v[46:49]
	v_mfma_f32_16x16x32_bf16 v[50:53], v[146:149], v[142:145], v[50:53]
	v_mfma_f32_16x16x32_bf16 v[54:57], v[150:153], v[142:145], v[54:57]
	v_mfma_f32_16x16x32_bf16 v[58:61], v[154:157], v[142:145], v[58:61]
	v_mfma_f32_16x16x32_bf16 v[62:65], v[158:161], v[142:145], v[62:65]
	v_mfma_f32_16x16x32_bf16 v[2:5], v[228:231], v[212:215], v[2:5]
	v_mfma_f32_16x16x32_bf16 v[6:9], v[232:235], v[212:215], v[6:9]
	v_mfma_f32_16x16x32_bf16 v[10:13], v[236:239], v[212:215], v[10:13]
	v_mfma_f32_16x16x32_bf16 v[14:17], v[240:243], v[212:215], v[14:17]
	v_mfma_f32_16x16x32_bf16 v[18:21], v[228:231], v[216:219], v[18:21]
	v_mfma_f32_16x16x32_bf16 v[22:25], v[232:235], v[216:219], v[22:25]
	v_mfma_f32_16x16x32_bf16 v[26:29], v[236:239], v[216:219], v[26:29]
	v_mfma_f32_16x16x32_bf16 v[30:33], v[240:243], v[216:219], v[30:33]
	v_mfma_f32_16x16x32_bf16 v[34:37], v[228:231], v[220:223], v[34:37]
	v_mfma_f32_16x16x32_bf16 v[38:41], v[232:235], v[220:223], v[38:41]
	v_mfma_f32_16x16x32_bf16 v[42:45], v[236:239], v[220:223], v[42:45]
	v_mfma_f32_16x16x32_bf16 v[46:49], v[240:243], v[220:223], v[46:49]
	v_mfma_f32_16x16x32_bf16 v[50:53], v[228:231], v[224:227], v[50:53]
	v_mfma_f32_16x16x32_bf16 v[54:57], v[232:235], v[224:227], v[54:57]
	v_mfma_f32_16x16x32_bf16 v[58:61], v[236:239], v[224:227], v[58:61]
	v_mfma_f32_16x16x32_bf16 v[62:65], v[240:243], v[224:227], v[62:65]
.Lop_join:
	s_waitcnt vmcnt(0)
	s_nop 7
	s_cmp_lg_u32 s82, 0
	s_cbranch_scc1 .Lop_cvbf
	v_pk_fma_f32 v[4:5], v[4:5], v[176:177], v[68:69]
	v_pk_fma_f32 v[2:3], v[2:3], v[174:175], v[66:67]
	s_nop 0
	v_cvt_pk_bf16_f32 v2, v2, v3
	v_cvt_pk_bf16_f32 v3, v4, v5
	global_store_dwordx2 v206, v[2:3], s[74:75] offset:0
	v_pk_fma_f32 v[8:9], v[8:9], v[180:181], v[72:73]
	v_pk_fma_f32 v[6:7], v[6:7], v[178:179], v[70:71]
	s_nop 0
	v_cvt_pk_bf16_f32 v6, v6, v7
	v_cvt_pk_bf16_f32 v7, v8, v9
	global_store_dwordx2 v206, v[6:7], s[74:75] offset:32
	v_pk_fma_f32 v[12:13], v[12:13], v[184:185], v[76:77]
	v_pk_fma_f32 v[10:11], v[10:11], v[182:183], v[74:75]
	s_nop 0
	v_cvt_pk_bf16_f32 v10, v10, v11
	v_cvt_pk_bf16_f32 v11, v12, v13
	global_store_dwordx2 v206, v[10:11], s[74:75] offset:64
	v_pk_fma_f32 v[16:17], v[16:17], v[188:189], v[80:81]
	v_pk_fma_f32 v[14:15], v[14:15], v[186:187], v[78:79]
	s_nop 0
	v_cvt_pk_bf16_f32 v14, v14, v15
	v_cvt_pk_bf16_f32 v15, v16, v17
	global_store_dwordx2 v206, v[14:15], s[74:75] offset:96
	v_pk_fma_f32 v[20:21], v[20:21], v[176:177], v[84:85]
	v_pk_fma_f32 v[18:19], v[18:19], v[174:175], v[82:83]
	s_nop 0
	v_cvt_pk_bf16_f32 v18, v18, v19
	v_cvt_pk_bf16_f32 v19, v20, v21
	global_store_dwordx2 v207, v[18:19], s[74:75] offset:0
	v_pk_fma_f32 v[24:25], v[24:25], v[180:181], v[88:89]
	v_pk_fma_f32 v[22:23], v[22:23], v[178:179], v[86:87]
	s_nop 0
	v_cvt_pk_bf16_f32 v22, v22, v23
	v_cvt_pk_bf16_f32 v23, v24, v25
	global_store_dwordx2 v207, v[22:23], s[74:75] offset:32
	v_pk_fma_f32 v[28:29], v[28:29], v[184:185], v[92:93]
	v_pk_fma_f32 v[26:27], v[26:27], v[182:183], v[90:91]
	s_nop 0
	v_cvt_pk_bf16_f32 v26, v26, v27
	v_cvt_pk_bf16_f32 v27, v28, v29
	global_store_dwordx2 v207, v[26:27], s[74:75] offset:64
	v_pk_fma_f32 v[32:33], v[32:33], v[188:189], v[96:97]
	v_pk_fma_f32 v[30:31], v[30:31], v[186:187], v[94:95]
	s_nop 0
	v_cvt_pk_bf16_f32 v30, v30, v31
	v_cvt_pk_bf16_f32 v31, v32, v33
	global_store_dwordx2 v207, v[30:31], s[74:75] offset:96
	v_pk_fma_f32 v[36:37], v[36:37], v[176:177], v[100:101]
	v_pk_fma_f32 v[34:35], v[34:35], v[174:175], v[98:99]
	s_nop 0
	v_cvt_pk_bf16_f32 v34, v34, v35
	v_cvt_pk_bf16_f32 v35, v36, v37
	global_store_dwordx2 v208, v[34:35], s[74:75] offset:0
	v_pk_fma_f32 v[40:41], v[40:41], v[180:181], v[104:105]
	v_pk_fma_f32 v[38:39], v[38:39], v[178:179], v[102:103]
	s_nop 0
	v_cvt_pk_bf16_f32 v38, v38, v39
	v_cvt_pk_bf16_f32 v39, v40, v41
	global_store_dwordx2 v208, v[38:39], s[74:75] offset:32
	v_pk_fma_f32 v[44:45], v[44:45], v[184:185], v[108:109]
	v_pk_fma_f32 v[42:43], v[42:43], v[182:183], v[106:107]
	s_nop 0
	v_cvt_pk_bf16_f32 v42, v42, v43
	v_cvt_pk_bf16_f32 v43, v44, v45
	global_store_dwordx2 v208, v[42:43], s[74:75] offset:64
	v_pk_fma_f32 v[48:49], v[48:49], v[188:189], v[112:113]
	v_pk_fma_f32 v[46:47], v[46:47], v[186:187], v[110:111]
	s_nop 0
	v_cvt_pk_bf16_f32 v46, v46, v47
	v_cvt_pk_bf16_f32 v47, v48, v49
	global_store_dwordx2 v208, v[46:47], s[74:75] offset:96
	v_pk_fma_f32 v[52:53], v[52:53], v[176:177], v[116:117]
	v_pk_fma_f32 v[50:51], v[50:51], v[174:175], v[114:115]
	s_nop 0
	v_cvt_pk_bf16_f32 v50, v50, v51
	v_cvt_pk_bf16_f32 v51, v52, v53
	global_store_dwordx2 v209, v[50:51], s[74:75] offset:0
	v_pk_fma_f32 v[56:57], v[56:57], v[180:181], v[120:121]
	v_pk_fma_f32 v[54:55], v[54:55], v[178:179], v[118:119]
	s_nop 0
	v_cvt_pk_bf16_f32 v54, v54, v55
	v_cvt_pk_bf16_f32 v55, v56, v57
	global_store_dwordx2 v209, v[54:55], s[74:75] offset:32
	v_pk_fma_f32 v[60:61], v[60:61], v[184:185], v[124:125]
	v_pk_fma_f32 v[58:59], v[58:59], v[182:183], v[122:123]
	s_nop 0
	v_cvt_pk_bf16_f32 v58, v58, v59
	v_cvt_pk_bf16_f32 v59, v60, v61
	global_store_dwordx2 v209, v[58:59], s[74:75] offset:64
	v_pk_fma_f32 v[64:65], v[64:65], v[188:189], v[128:129]
	v_pk_fma_f32 v[62:63], v[62:63], v[186:187], v[126:127]
	s_nop 0
	v_cvt_pk_bf16_f32 v62, v62, v63
	v_cvt_pk_bf16_f32 v63, v64, v65
	global_store_dwordx2 v209, v[62:63], s[74:75] offset:96
	s_branch .Lop_cvdone

.Lbr_tile:
	s_and_b32 s0, s78, 3
	s_or_b32 s0, s0, s77
	s_lshl_b32 s0, s0, 8
	s_lshr_b32 s1, s78, 2
	s_lshl_b32 s1, s1, 7
	s_mul_i32 s2, s0, 0xc00
	s_add_u32 s68, s8, s2
	s_addc_u32 s69, s9, 0
	s_mul_i32 s2, s1, 0xc00
	s_add_u32 s70, s80, s2
	s_addc_u32 s71, s81, 0
	s_mul_i32 s2, s0, 0x3400
	s_lshl_b32 s3, s1, 1
	s_add_u32 s2, s2, s3
	s_add_u32 s2, s2, 0x1c00
	s_add_u32 s72, s4, s2
	s_addc_u32 s73, s5, 0
	s_lshl_b32 s2, s0, 11
	s_add_u32 s2, s2, s3
	s_add_u32 s74, s10, s2
	s_addc_u32 s75, s11, 0
	s_add_u32 m0, s76, 0x0
	s_nop 0
	global_load_lds_dwordx4 v196, s[68:69]
	s_add_u32 m0, s76, 0x2000
	s_nop 0
	global_load_lds_dwordx4 v197, s[68:69]
	s_add_u32 m0, s76, 0x4000
	s_nop 0
	global_load_lds_dwordx4 v198, s[68:69]
	s_add_u32 m0, s76, 0x6000
	s_nop 0
	global_load_lds_dwordx4 v199, s[68:69]
	s_add_u32 m0, s76, 0x8000
	s_nop 0
	global_load_lds_dwordx4 v196, s[70:71]
	s_add_u32 m0, s76, 0xa000
	s_nop 0
	global_load_lds_dwordx4 v197, s[70:71]
	s_add_u32 s68, s68, 0x80
	s_addc_u32 s69, s69, 0
	s_add_u32 s70, s70, 0x80
	s_addc_u32 s71, s71, 0
	s_add_u32 m0, s76, 0xc000
	s_nop 0
	global_load_lds_dwordx4 v196, s[68:69]
	s_add_u32 m0, s76, 0xe000
	s_nop 0
	global_load_lds_dwordx4 v197, s[68:69]
	s_add_u32 m0, s76, 0x10000
	s_nop 0
	global_load_lds_dwordx4 v198, s[68:69]
	s_add_u32 m0, s76, 0x12000
	s_nop 0
	global_load_lds_dwordx4 v199, s[68:69]
	s_add_u32 m0, s76, 0x14000
	s_nop 0
	global_load_lds_dwordx4 v196, s[70:71]
	s_add_u32 m0, s76, 0x16000
	s_nop 0
	global_load_lds_dwordx4 v197, s[70:71]
	s_add_u32 s68, s68, 0x80
	s_addc_u32 s69, s69, 0
	s_add_u32 s70, s70, 0x80
	s_addc_u32 s71, s71, 0
	v_mov_b32_e32 v66, 0
	v_mov_b32_e32 v67, 0
	v_mov_b32_e32 v68, 0
	v_mov_b32_e32 v69, 0
	v_mov_b32_e32 v70, 0
	v_mov_b32_e32 v71, 0
	v_mov_b32_e32 v72, 0
	v_mov_b32_e32 v73, 0
	v_mov_b32_e32 v74, 0
	v_mov_b32_e32 v75, 0
	v_mov_b32_e32 v76, 0
	v_mov_b32_e32 v77, 0
	v_mov_b32_e32 v78, 0
	v_mov_b32_e32 v79, 0
	v_mov_b32_e32 v80, 0
	v_mov_b32_e32 v81, 0
	v_mov_b32_e32 v82, 0
	v_mov_b32_e32 v83, 0
	v_mov_b32_e32 v84, 0
	v_mov_b32_e32 v85, 0
	v_mov_b32_e32 v86, 0
	v_mov_b32_e32 v87, 0
	v_mov_b32_e32 v88, 0
	v_mov_b32_e32 v89, 0
	v_mov_b32_e32 v90, 0
	v_mov_b32_e32 v91, 0
	v_mov_b32_e32 v92, 0
	v_mov_b32_e32 v93, 0
	v_mov_b32_e32 v94, 0
	v_mov_b32_e32 v95, 0
	v_mov_b32_e32 v96, 0
	v_mov_b32_e32 v97, 0
	v_mov_b32_e32 v98, 0
	v_mov_b32_e32 v99, 0
	v_mov_b32_e32 v100, 0
	v_mov_b32_e32 v101, 0
	v_mov_b32_e32 v102, 0
	v_mov_b32_e32 v103, 0
	v_mov_b32_e32 v104, 0
	v_mov_b32_e32 v105, 0
	v_mov_b32_e32 v106, 0
	v_mov_b32_e32 v107, 0
	v_mov_b32_e32 v108, 0
	v_mov_b32_e32 v109, 0
	v_mov_b32_e32 v110, 0
	v_mov_b32_e32 v111, 0
	v_mov_b32_e32 v112, 0
	v_mov_b32_e32 v113, 0
	v_mov_b32_e32 v114, 0
	v_mov_b32_e32 v115, 0
	v_mov_b32_e32 v116, 0
	v_mov_b32_e32 v117, 0
	v_mov_b32_e32 v118, 0
	v_mov_b32_e32 v119, 0
	v_mov_b32_e32 v120, 0
	v_mov_b32_e32 v121, 0
	v_mov_b32_e32 v122, 0
	v_mov_b32_e32 v123, 0
	v_mov_b32_e32 v124, 0
	v_mov_b32_e32 v125, 0
	v_mov_b32_e32 v126, 0
	v_mov_b32_e32 v127, 0
	v_mov_b32_e32 v128, 0
	v_mov_b32_e32 v129, 0
	s_waitcnt vmcnt(6)
	s_barrier
	s_cmp_ge_u32 s76, 0x1000
	s_cbranch_scc1 .Lbr_streamB
	v_add_u32_e32 v204, 0x0, v200
	v_add_u32_e32 v205, 0x0, v202
	ds_read_b128 v[130:133], v204 offset:0
	ds_read_b128 v[134:137], v204 offset:2048
	ds_read_b128 v[138:141], v204 offset:4096
	ds_read_b128 v[142:145], v204 offset:6144
	ds_read_b128 v[146:149], v205 offset:0
	ds_read_b128 v[150:153], v205 offset:2048
	ds_read_b128 v[154:157], v205 offset:4096
	ds_read_b128 v[158:161], v205 offset:6144
	v_add_u32_e32 v204, 0x0, v201
	v_add_u32_e32 v205, 0x0, v203
	ds_read_b128 v[212:215], v204 offset:0
	ds_read_b128 v[216:219], v204 offset:2048
	ds_read_b128 v[220:223], v204 offset:4096
	ds_read_b128 v[224:227], v204 offset:6144
	ds_read_b128 v[228:231], v205 offset:0
	ds_read_b128 v[232:235], v205 offset:2048
	ds_read_b128 v[236:239], v205 offset:4096
	ds_read_b128 v[240:243], v205 offset:6144
	s_add_u32 m0, s76, 0x18000
	s_nop 0
	global_load_lds_dwordx4 v196, s[68:69]
	s_add_u32 m0, s76, 0x1a000
	s_nop 0
	global_load_lds_dwordx4 v197, s[68:69]
	s_add_u32 m0, s76, 0x1c000
	s_nop 0
	global_load_lds_dwordx4 v198, s[68:69]
	s_add_u32 m0, s76, 0x1e000
	s_nop 0
	global_load_lds_dwordx4 v199, s[68:69]
	s_add_u32 m0, s76, 0x20000
	s_nop 0
	global_load_lds_dwordx4 v196, s[70:71]
	s_add_u32 m0, s76, 0x22000
	s_nop 0
	global_load_lds_dwordx4 v197, s[70:71]
	s_add_u32 s68, s68, 0x80
	s_addc_u32 s69, s69, 0
	s_add_u32 s70, s70, 0x80
	s_addc_u32 s71, s71, 0
	global_load_dwordx2 v[174:175], v206, s[72:73] offset:0
	global_load_dwordx2 v[176:177], v206, s[72:73] offset:32
	global_load_dwordx2 v[178:179], v206, s[72:73] offset:64
	global_load_dwordx2 v[180:181], v206, s[72:73] offset:96
	global_load_dwordx2 v[182:183], v207, s[72:73] offset:0
	global_load_dwordx2 v[184:185], v207, s[72:73] offset:32
	s_waitcnt lgkmcnt(0)
	s_barrier
	v_mfma_f32_16x16x32_bf16 v[2:5], v[146:149], v[130:133], 0
	v_mfma_f32_16x16x32_bf16 v[6:9], v[150:153], v[130:133], 0
	v_mfma_f32_16x16x32_bf16 v[10:13], v[154:157], v[130:133], 0
	v_mfma_f32_16x16x32_bf16 v[14:17], v[158:161], v[130:133], 0
	v_mfma_f32_16x16x32_bf16 v[18:21], v[146:149], v[134:137], 0
	v_mfma_f32_16x16x32_bf16 v[22:25], v[150:153], v[134:137], 0
	v_mfma_f32_16x16x32_bf16 v[26:29], v[154:157], v[134:137], 0
	v_mfma_f32_16x16x32_bf16 v[30:33], v[158:161], v[134:137], 0
	v_mfma_f32_16x16x32_bf16 v[34:37], v[146:149], v[138:141], 0
	v_mfma_f32_16x16x32_bf16 v[38:41], v[150:153], v[138:141], 0
	v_mfma_f32_16x16x32_bf16 v[42:45], v[154:157], v[138:141], 0
	v_mfma_f32_16x16x32_bf16 v[46:49], v[158:161], v[138:141], 0
	v_mfma_f32_16x16x32_bf16 v[50:53], v[146:149], v[142:145], 0
	v_mfma_f32_16x16x32_bf16 v[54:57], v[150:153], v[142:145], 0
	v_mfma_f32_16x16x32_bf16 v[58:61], v[154:157], v[142:145], 0
	v_mfma_f32_16x16x32_bf16 v[62:65], v[158:161], v[142:145], 0
	v_mfma_f32_16x16x32_bf16 v[2:5], v[228:231], v[212:215], v[2:5]
	v_mfma_f32_16x16x32_bf16 v[6:9], v[232:235], v[212:215], v[6:9]
	v_mfma_f32_16x16x32_bf16 v[10:13], v[236:239], v[212:215], v[10:13]
	v_mfma_f32_16x16x32_bf16 v[14:17], v[240:243], v[212:215], v[14:17]
	v_mfma_f32_16x16x32_bf16 v[18:21], v[228:231], v[216:219], v[18:21]
	v_mfma_f32_16x16x32_bf16 v[22:25], v[232:235], v[216:219], v[22:25]
	v_mfma_f32_16x16x32_bf16 v[26:29], v[236:239], v[216:219], v[26:29]
	v_mfma_f32_16x16x32_bf16 v[30:33], v[240:243], v[216:219], v[30:33]
	v_mfma_f32_16x16x32_bf16 v[34:37], v[228:231], v[220:223], v[34:37]
	v_mfma_f32_16x16x32_bf16 v[38:41], v[232:235], v[220:223], v[38:41]
	v_mfma_f32_16x16x32_bf16 v[42:45], v[236:239], v[220:223], v[42:45]
	v_mfma_f32_16x16x32_bf16 v[46:49], v[240:243], v[220:223], v[46:49]
	v_mfma_f32_16x16x32_bf16 v[50:53], v[228:231], v[224:227], v[50:53]
	v_mfma_f32_16x16x32_bf16 v[54:57], v[232:235], v[224:227], v[54:57]
	v_mfma_f32_16x16x32_bf16 v[58:61], v[236:239], v[224:227], v[58:61]
	v_mfma_f32_16x16x32_bf16 v[62:65], v[240:243], v[224:227], v[62:65]
	s_waitcnt vmcnt(12)
	s_barrier
	v_add_u32_e32 v204, 0xc000, v200
	v_add_u32_e32 v205, 0xc000, v202
	ds_read_b128 v[130:133], v204 offset:0
	ds_read_b128 v[134:137], v204 offset:2048
	ds_read_b128 v[138:141], v204 offset:4096
	ds_read_b128 v[142:145], v204 offset:6144
	ds_read_b128 v[146:149], v205 offset:0
	ds_read_b128 v[150:153], v205 offset:2048
	ds_read_b128 v[154:157], v205 offset:4096
	ds_read_b128 v[158:161], v205 offset:6144
	v_add_u32_e32 v204, 0xc000, v201
	v_add_u32_e32 v205, 0xc000, v203
	ds_read_b128 v[212:215], v204 offset:0
	ds_read_b128 v[216:219], v204 offset:2048
	ds_read_b128 v[220:223], v204 offset:4096
	ds_read_b128 v[224:227], v204 offset:6144
	ds_read_b128 v[228:231], v205 offset:0
	ds_read_b128 v[232:235], v205 offset:2048
	ds_read_b128 v[236:239], v205 offset:4096
	ds_read_b128 v[240:243], v205 offset:6144
	s_add_u32 m0, s76, 0x0
	s_nop 0
	global_load_lds_dwordx4 v196, s[68:69]
	s_add_u32 m0, s76, 0x2000
	s_nop 0
	global_load_lds_dwordx4 v197, s[68:69]
	s_add_u32 m0, s76, 0x4000
	s_nop 0
	global_load_lds_dwordx4 v198, s[68:69]
	s_add_u32 m0, s76, 0x6000
	s_nop 0
	global_load_lds_dwordx4 v199, s[68:69]
	s_add_u32 m0, s76, 0x8000
	s_nop 0
	global_load_lds_dwordx4 v196, s[70:71]
	s_add_u32 m0, s76, 0xa000
	s_nop 0
	global_load_lds_dwordx4 v197, s[70:71]
	s_add_u32 s68, s68, 0x80
	s_addc_u32 s69, s69, 0
	s_add_u32 s70, s70, 0x80
	s_addc_u32 s71, s71, 0
	global_load_dwordx2 v[186:187], v207, s[72:73] offset:64
	global_load_dwordx2 v[188:189], v207, s[72:73] offset:96
	global_load_dwordx2 v[190:191], v208, s[72:73] offset:0
	global_load_dwordx2 v[192:193], v208, s[72:73] offset:32
	global_load_dwordx2 v[244:245], v208, s[72:73] offset:64
	global_load_dwordx2 v[246:247], v208, s[72:73] offset:96
	s_waitcnt lgkmcnt(0)
	s_barrier
	v_mfma_f32_16x16x32_bf16 v[2:5], v[146:149], v[130:133], v[2:5]
	v_mfma_f32_16x16x32_bf16 v[6:9], v[150:153], v[130:133], v[6:9]
	v_mfma_f32_16x16x32_bf16 v[10:13], v[154:157], v[130:133], v[10:13]
	v_mfma_f32_16x16x32_bf16 v[14:17], v[158:161], v[130:133], v[14:17]
	v_mfma_f32_16x16x32_bf16 v[18:21], v[146:149], v[134:137], v[18:21]
	v_mfma_f32_16x16x32_bf16 v[22:25], v[150:153], v[134:137], v[22:25]
	v_mfma_f32_16x16x32_bf16 v[26:29], v[154:157], v[134:137], v[26:29]
	v_mfma_f32_16x16x32_bf16 v[30:33], v[158:161], v[134:137], v[30:33]
	v_mfma_f32_16x16x32_bf16 v[34:37], v[146:149], v[138:141], v[34:37]
	v_mfma_f32_16x16x32_bf16 v[38:41], v[150:153], v[138:141], v[38:41]
	v_mfma_f32_16x16x32_bf16 v[42:45], v[154:157], v[138:141], v[42:45]
	v_mfma_f32_16x16x32_bf16 v[46:49], v[158:161], v[138:141], v[46:49]
	v_mfma_f32_16x16x32_bf16 v[50:53], v[146:149], v[142:145], v[50:53]
	v_mfma_f32_16x16x32_bf16 v[54:57], v[150:153], v[142:145], v[54:57]
	v_mfma_f32_16x16x32_bf16 v[58:61], v[154:157], v[142:145], v[58:61]
	v_mfma_f32_16x16x32_bf16 v[62:65], v[158:161], v[142:145], v[62:65]
	v_mfma_f32_16x16x32_bf16 v[2:5], v[228:231], v[212:215], v[2:5]
	v_mfma_f32_16x16x32_bf16 v[6:9], v[232:235], v[212:215], v[6:9]
	v_mfma_f32_16x16x32_bf16 v[10:13], v[236:239], v[212:215], v[10:13]
	v_mfma_f32_16x16x32_bf16 v[14:17], v[240:243], v[212:215], v[14:17]
	v_mfma_f32_16x16x32_bf16 v[18:21], v[228:231], v[216:219], v[18:21]
	v_mfma_f32_16x16x32_bf16 v[22:25], v[232:235], v[216:219], v[22:25]
	v_mfma_f32_16x16x32_bf16 v[26:29], v[236:239], v[216:219], v[26:29]
	v_mfma_f32_16x16x32_bf16 v[30:33], v[240:243], v[216:219], v[30:33]
	v_mfma_f32_16x16x32_bf16 v[34:37], v[228:231], v[220:223], v[34:37]
	v_mfma_f32_16x16x32_bf16 v[38:41], v[232:235], v[220:223], v[38:41]
	v_mfma_f32_16x16x32_bf16 v[42:45], v[236:239], v[220:223], v[42:45]
	v_mfma_f32_16x16x32_bf16 v[46:49], v[240:243], v[220:223], v[46:49]
	v_mfma_f32_16x16x32_bf16 v[50:53], v[228:231], v[224:227], v[50:53]
	v_mfma_f32_16x16x32_bf16 v[54:57], v[232:235], v[224:227], v[54:57]
	v_mfma_f32_16x16x32_bf16 v[58:61], v[236:239], v[224:227], v[58:61]
	v_mfma_f32_16x16x32_bf16 v[62:65], v[240:243], v[224:227], v[62:65]
	s_waitcnt vmcnt(18)
	s_barrier
	v_add_u32_e32 v204, 0x18000, v200
	v_add_u32_e32 v205, 0x18000, v202
	ds_read_b128 v[130:133], v204 offset:0
	ds_read_b128 v[134:137], v204 offset:2048
	ds_read_b128 v[138:141], v204 offset:4096
	ds_read_b128 v[142:145], v204 offset:6144
	ds_read_b128 v[146:149], v205 offset:0
	ds_read_b128 v[150:153], v205 offset:2048
	ds_read_b128 v[154:157], v205 offset:4096
	ds_read_b128 v[158:161], v205 offset:6144
	v_add_u32_e32 v204, 0x18000, v201
	v_add_u32_e32 v205, 0x18000, v203
	ds_read_b128 v[212:215], v204 offset:0
	ds_read_b128 v[216:219], v204 offset:2048
	ds_read_b128 v[220:223], v204 offset:4096
	ds_read_b128 v[224:227], v204 offset:6144
	ds_read_b128 v[228:231], v205 offset:0
	ds_read_b128 v[232:235], v205 offset:2048
	ds_read_b128 v[236:239], v205 offset:4096
	ds_read_b128 v[240:243], v205 offset:6144
	s_add_u32 m0, s76, 0xc000
	s_nop 0
	global_load_lds_dwordx4 v196, s[68:69]
	s_add_u32 m0, s76, 0xe000
	s_nop 0
	global_load_lds_dwordx4 v197, s[68:69]
	s_add_u32 m0, s76, 0x10000
	s_nop 0
	global_load_lds_dwordx4 v198, s[68:69]
	s_add_u32 m0, s76, 0x12000
	s_nop 0
	global_load_lds_dwordx4 v199, s[68:69]
	s_add_u32 m0, s76, 0x14000
	s_nop 0
	global_load_lds_dwordx4 v196, s[70:71]
	s_add_u32 m0, s76, 0x16000
	s_nop 0
	global_load_lds_dwordx4 v197, s[70:71]
	s_add_u32 s68, s68, 0x80
	s_addc_u32 s69, s69, 0
	s_add_u32 s70, s70, 0x80
	s_addc_u32 s71, s71, 0
	global_load_dwordx2 v[248:249], v209, s[72:73] offset:0
	global_load_dwordx2 v[250:251], v209, s[72:73] offset:32
	global_load_dwordx2 v[166:167], v209, s[72:73] offset:64
	global_load_dwordx2 v[194:195], v209, s[72:73] offset:96
	s_add_u32 s72, s72, 0x800
	s_addc_u32 s73, s73, 0
	s_waitcnt lgkmcnt(0)
	s_barrier
	v_mfma_f32_16x16x32_bf16 v[2:5], v[146:149], v[130:133], v[2:5]
	v_mfma_f32_16x16x32_bf16 v[6:9], v[150:153], v[130:133], v[6:9]
	v_mfma_f32_16x16x32_bf16 v[10:13], v[154:157], v[130:133], v[10:13]
	v_mfma_f32_16x16x32_bf16 v[14:17], v[158:161], v[130:133], v[14:17]
	v_mfma_f32_16x16x32_bf16 v[18:21], v[146:149], v[134:137], v[18:21]
	v_mfma_f32_16x16x32_bf16 v[22:25], v[150:153], v[134:137], v[22:25]
	v_mfma_f32_16x16x32_bf16 v[26:29], v[154:157], v[134:137], v[26:29]
	v_mfma_f32_16x16x32_bf16 v[30:33], v[158:161], v[134:137], v[30:33]
	v_mfma_f32_16x16x32_bf16 v[34:37], v[146:149], v[138:141], v[34:37]
	v_mfma_f32_16x16x32_bf16 v[38:41], v[150:153], v[138:141], v[38:41]
	v_mfma_f32_16x16x32_bf16 v[42:45], v[154:157], v[138:141], v[42:45]
	v_mfma_f32_16x16x32_bf16 v[46:49], v[158:161], v[138:141], v[46:49]
	v_mfma_f32_16x16x32_bf16 v[50:53], v[146:149], v[142:145], v[50:53]
	v_mfma_f32_16x16x32_bf16 v[54:57], v[150:153], v[142:145], v[54:57]
	v_mfma_f32_16x16x32_bf16 v[58:61], v[154:157], v[142:145], v[58:61]
	v_mfma_f32_16x16x32_bf16 v[62:65], v[158:161], v[142:145], v[62:65]
	v_mfma_f32_16x16x32_bf16 v[2:5], v[228:231], v[212:215], v[2:5]
	v_mfma_f32_16x16x32_bf16 v[6:9], v[232:235], v[212:215], v[6:9]
	v_mfma_f32_16x16x32_bf16 v[10:13], v[236:239], v[212:215], v[10:13]
	v_mfma_f32_16x16x32_bf16 v[14:17], v[240:243], v[212:215], v[14:17]
	v_mfma_f32_16x16x32_bf16 v[18:21], v[228:231], v[216:219], v[18:21]
	v_mfma_f32_16x16x32_bf16 v[22:25], v[232:235], v[216:219], v[22:25]
	v_mfma_f32_16x16x32_bf16 v[26:29], v[236:239], v[216:219], v[26:29]
	v_mfma_f32_16x16x32_bf16 v[30:33], v[240:243], v[216:219], v[30:33]
	v_mfma_f32_16x16x32_bf16 v[34:37], v[228:231], v[220:223], v[34:37]
	v_mfma_f32_16x16x32_bf16 v[38:41], v[232:235], v[220:223], v[38:41]
	v_mfma_f32_16x16x32_bf16 v[42:45], v[236:239], v[220:223], v[42:45]
	v_mfma_f32_16x16x32_bf16 v[46:49], v[240:243], v[220:223], v[46:49]
	v_mfma_f32_16x16x32_bf16 v[50:53], v[228:231], v[224:227], v[50:53]
	v_mfma_f32_16x16x32_bf16 v[54:57], v[232:235], v[224:227], v[54:57]
	v_mfma_f32_16x16x32_bf16 v[58:61], v[236:239], v[224:227], v[58:61]
	v_mfma_f32_16x16x32_bf16 v[62:65], v[240:243], v[224:227], v[62:65]
	s_waitcnt vmcnt(16)
	s_barrier
	v_add_u32_e32 v204, 0x0, v200
	v_add_u32_e32 v205, 0x0, v202
	ds_read_b128 v[130:133], v204 offset:0
	ds_read_b128 v[134:137], v204 offset:2048
	ds_read_b128 v[138:141], v204 offset:4096
	ds_read_b128 v[142:145], v204 offset:6144
	ds_read_b128 v[146:149], v205 offset:0
	ds_read_b128 v[150:153], v205 offset:2048
	ds_read_b128 v[154:157], v205 offset:4096
	ds_read_b128 v[158:161], v205 offset:6144
	v_add_u32_e32 v204, 0x0, v201
	v_add_u32_e32 v205, 0x0, v203
	ds_read_b128 v[212:215], v204 offset:0
	ds_read_b128 v[216:219], v204 offset:2048
	ds_read_b128 v[220:223], v204 offset:4096
	ds_read_b128 v[224:227], v204 offset:6144
	ds_read_b128 v[228:231], v205 offset:0
	ds_read_b128 v[232:235], v205 offset:2048
	ds_read_b128 v[236:239], v205 offset:4096
	ds_read_b128 v[240:243], v205 offset:6144
	s_add_u32 m0, s76, 0x18000
	s_nop 0
	global_load_lds_dwordx4 v196, s[68:69]
	s_add_u32 m0, s76, 0x1a000
	s_nop 0
	global_load_lds_dwordx4 v197, s[68:69]
	s_add_u32 m0, s76, 0x1c000
	s_nop 0
	global_load_lds_dwordx4 v198, s[68:69]
	s_add_u32 m0, s76, 0x1e000
	s_nop 0
	global_load_lds_dwordx4 v199, s[68:69]
	s_add_u32 m0, s76, 0x20000
	s_nop 0
	global_load_lds_dwordx4 v196, s[70:71]
	s_add_u32 m0, s76, 0x22000
	s_nop 0
	global_load_lds_dwordx4 v197, s[70:71]
	s_add_u32 s68, s68, 0x80
	s_addc_u32 s69, s69, 0
	s_add_u32 s70, s70, 0x80
	s_addc_u32 s71, s71, 0
	s_waitcnt lgkmcnt(0)
	s_barrier
	v_mfma_f32_16x16x32_bf16 v[2:5], v[146:149], v[130:133], v[2:5]
	v_mfma_f32_16x16x32_bf16 v[6:9], v[150:153], v[130:133], v[6:9]
	v_mfma_f32_16x16x32_bf16 v[10:13], v[154:157], v[130:133], v[10:13]
	v_mfma_f32_16x16x32_bf16 v[14:17], v[158:161], v[130:133], v[14:17]
	v_mfma_f32_16x16x32_bf16 v[18:21], v[146:149], v[134:137], v[18:21]
	v_mfma_f32_16x16x32_bf16 v[22:25], v[150:153], v[134:137], v[22:25]
	v_mfma_f32_16x16x32_bf16 v[26:29], v[154:157], v[134:137], v[26:29]
	v_mfma_f32_16x16x32_bf16 v[30:33], v[158:161], v[134:137], v[30:33]
	v_mfma_f32_16x16x32_bf16 v[34:37], v[146:149], v[138:141], v[34:37]
	v_mfma_f32_16x16x32_bf16 v[38:41], v[150:153], v[138:141], v[38:41]
	v_mfma_f32_16x16x32_bf16 v[42:45], v[154:157], v[138:141], v[42:45]
	v_mfma_f32_16x16x32_bf16 v[46:49], v[158:161], v[138:141], v[46:49]
	v_mfma_f32_16x16x32_bf16 v[50:53], v[146:149], v[142:145], v[50:53]
	v_mfma_f32_16x16x32_bf16 v[54:57], v[150:153], v[142:145], v[54:57]
	v_mfma_f32_16x16x32_bf16 v[58:61], v[154:157], v[142:145], v[58:61]
	v_mfma_f32_16x16x32_bf16 v[62:65], v[158:161], v[142:145], v[62:65]
	v_mfma_f32_16x16x32_bf16 v[2:5], v[228:231], v[212:215], v[2:5]
	v_mfma_f32_16x16x32_bf16 v[6:9], v[232:235], v[212:215], v[6:9]
	v_mfma_f32_16x16x32_bf16 v[10:13], v[236:239], v[212:215], v[10:13]
	v_mfma_f32_16x16x32_bf16 v[14:17], v[240:243], v[212:215], v[14:17]
	v_mfma_f32_16x16x32_bf16 v[18:21], v[228:231], v[216:219], v[18:21]
	v_mfma_f32_16x16x32_bf16 v[22:25], v[232:235], v[216:219], v[22:25]
	v_mfma_f32_16x16x32_bf16 v[26:29], v[236:239], v[216:219], v[26:29]
	v_mfma_f32_16x16x32_bf16 v[30:33], v[240:243], v[216:219], v[30:33]
	v_mfma_f32_16x16x32_bf16 v[34:37], v[228:231], v[220:223], v[34:37]
	v_mfma_f32_16x16x32_bf16 v[38:41], v[232:235], v[220:223], v[38:41]
	v_mfma_f32_16x16x32_bf16 v[42:45], v[236:239], v[220:223], v[42:45]
	v_mfma_f32_16x16x32_bf16 v[46:49], v[240:243], v[220:223], v[46:49]
	v_mfma_f32_16x16x32_bf16 v[50:53], v[228:231], v[224:227], v[50:53]
	v_mfma_f32_16x16x32_bf16 v[54:57], v[232:235], v[224:227], v[54:57]
	v_mfma_f32_16x16x32_bf16 v[58:61], v[236:239], v[224:227], v[58:61]
	v_mfma_f32_16x16x32_bf16 v[62:65], v[240:243], v[224:227], v[62:65]
	s_waitcnt vmcnt(10)
	s_barrier
	v_add_u32_e32 v204, 0xc000, v200
	v_add_u32_e32 v205, 0xc000, v202
	ds_read_b128 v[130:133], v204 offset:0
	ds_read_b128 v[134:137], v204 offset:2048
	ds_read_b128 v[138:141], v204 offset:4096
	ds_read_b128 v[142:145], v204 offset:6144
	ds_read_b128 v[146:149], v205 offset:0
	ds_read_b128 v[150:153], v205 offset:2048
	ds_read_b128 v[154:157], v205 offset:4096
	ds_read_b128 v[158:161], v205 offset:6144
	v_add_u32_e32 v204, 0xc000, v201
	v_add_u32_e32 v205, 0xc000, v203
	ds_read_b128 v[212:215], v204 offset:0
	ds_read_b128 v[216:219], v204 offset:2048
	ds_read_b128 v[220:223], v204 offset:4096
	ds_read_b128 v[224:227], v204 offset:6144
	ds_read_b128 v[228:231], v205 offset:0
	ds_read_b128 v[232:235], v205 offset:2048
	ds_read_b128 v[236:239], v205 offset:4096
	ds_read_b128 v[240:243], v205 offset:6144
	s_add_u32 m0, s76, 0x0
	s_nop 0
	global_load_lds_dwordx4 v196, s[68:69]
	s_add_u32 m0, s76, 0x2000
	s_nop 0
	global_load_lds_dwordx4 v197, s[68:69]
	s_add_u32 m0, s76, 0x4000
	s_nop 0
	global_load_lds_dwordx4 v198, s[68:69]
	s_add_u32 m0, s76, 0x6000
	s_nop 0
	global_load_lds_dwordx4 v199, s[68:69]
	s_add_u32 m0, s76, 0x8000
	s_nop 0
	global_load_lds_dwordx4 v196, s[70:71]
	s_add_u32 m0, s76, 0xa000
	s_nop 0
	global_load_lds_dwordx4 v197, s[70:71]
	s_add_u32 s68, s68, 0x80
	s_addc_u32 s69, s69, 0
	s_add_u32 s70, s70, 0x80
	s_addc_u32 s71, s71, 0
	s_waitcnt lgkmcnt(0)
	s_barrier
	v_mfma_f32_16x16x32_bf16 v[2:5], v[146:149], v[130:133], v[2:5]
	v_mfma_f32_16x16x32_bf16 v[6:9], v[150:153], v[130:133], v[6:9]
	v_mfma_f32_16x16x32_bf16 v[10:13], v[154:157], v[130:133], v[10:13]
	v_mfma_f32_16x16x32_bf16 v[14:17], v[158:161], v[130:133], v[14:17]
	v_mfma_f32_16x16x32_bf16 v[18:21], v[146:149], v[134:137], v[18:21]
	v_mfma_f32_16x16x32_bf16 v[22:25], v[150:153], v[134:137], v[22:25]
	v_mfma_f32_16x16x32_bf16 v[26:29], v[154:157], v[134:137], v[26:29]
	v_mfma_f32_16x16x32_bf16 v[30:33], v[158:161], v[134:137], v[30:33]
	v_mfma_f32_16x16x32_bf16 v[34:37], v[146:149], v[138:141], v[34:37]
	v_mfma_f32_16x16x32_bf16 v[38:41], v[150:153], v[138:141], v[38:41]
	v_mfma_f32_16x16x32_bf16 v[42:45], v[154:157], v[138:141], v[42:45]
	v_mfma_f32_16x16x32_bf16 v[46:49], v[158:161], v[138:141], v[46:49]
	v_mfma_f32_16x16x32_bf16 v[50:53], v[146:149], v[142:145], v[50:53]
	v_mfma_f32_16x16x32_bf16 v[54:57], v[150:153], v[142:145], v[54:57]
	v_mfma_f32_16x16x32_bf16 v[58:61], v[154:157], v[142:145], v[58:61]
	v_mfma_f32_16x16x32_bf16 v[62:65], v[158:161], v[142:145], v[62:65]
	v_mfma_f32_16x16x32_bf16 v[2:5], v[228:231], v[212:215], v[2:5]
	v_mfma_f32_16x16x32_bf16 v[6:9], v[232:235], v[212:215], v[6:9]
	v_mfma_f32_16x16x32_bf16 v[10:13], v[236:239], v[212:215], v[10:13]
	v_mfma_f32_16x16x32_bf16 v[14:17], v[240:243], v[212:215], v[14:17]
	v_mfma_f32_16x16x32_bf16 v[18:21], v[228:231], v[216:219], v[18:21]
	v_mfma_f32_16x16x32_bf16 v[22:25], v[232:235], v[216:219], v[22:25]
	v_mfma_f32_16x16x32_bf16 v[26:29], v[236:239], v[216:219], v[26:29]
	v_mfma_f32_16x16x32_bf16 v[30:33], v[240:243], v[216:219], v[30:33]
	v_mfma_f32_16x16x32_bf16 v[34:37], v[228:231], v[220:223], v[34:37]
	v_mfma_f32_16x16x32_bf16 v[38:41], v[232:235], v[220:223], v[38:41]
	v_mfma_f32_16x16x32_bf16 v[42:45], v[236:239], v[220:223], v[42:45]
	v_mfma_f32_16x16x32_bf16 v[46:49], v[240:243], v[220:223], v[46:49]
	v_mfma_f32_16x16x32_bf16 v[50:53], v[228:231], v[224:227], v[50:53]
	v_mfma_f32_16x16x32_bf16 v[54:57], v[232:235], v[224:227], v[54:57]
	v_mfma_f32_16x16x32_bf16 v[58:61], v[236:239], v[224:227], v[58:61]
	v_mfma_f32_16x16x32_bf16 v[62:65], v[240:243], v[224:227], v[62:65]
	s_waitcnt vmcnt(6)
	s_barrier
	v_add_u32_e32 v204, 0x18000, v200
	v_add_u32_e32 v205, 0x18000, v202
	ds_read_b128 v[130:133], v204 offset:0
	ds_read_b128 v[134:137], v204 offset:2048
	ds_read_b128 v[138:141], v204 offset:4096
	ds_read_b128 v[142:145], v204 offset:6144
	ds_read_b128 v[146:149], v205 offset:0
	ds_read_b128 v[150:153], v205 offset:2048
	ds_read_b128 v[154:157], v205 offset:4096
	ds_read_b128 v[158:161], v205 offset:6144
	v_add_u32_e32 v204, 0x18000, v201
	v_add_u32_e32 v205, 0x18000, v203
	ds_read_b128 v[212:215], v204 offset:0
	ds_read_b128 v[216:219], v204 offset:2048
	ds_read_b128 v[220:223], v204 offset:4096
	ds_read_b128 v[224:227], v204 offset:6144
	ds_read_b128 v[228:231], v205 offset:0
	ds_read_b128 v[232:235], v205 offset:2048
	ds_read_b128 v[236:239], v205 offset:4096
	ds_read_b128 v[240:243], v205 offset:6144
	s_add_u32 m0, s76, 0xc000
	s_nop 0
	global_load_lds_dwordx4 v196, s[68:69]
	s_add_u32 m0, s76, 0xe000
	s_nop 0
	global_load_lds_dwordx4 v197, s[68:69]
	s_add_u32 m0, s76, 0x10000
	s_nop 0
	global_load_lds_dwordx4 v198, s[68:69]
	s_add_u32 m0, s76, 0x12000
	s_nop 0
	global_load_lds_dwordx4 v199, s[68:69]
	s_add_u32 m0, s76, 0x14000
	s_nop 0
	global_load_lds_dwordx4 v196, s[70:71]
	s_add_u32 m0, s76, 0x16000
	s_nop 0
	global_load_lds_dwordx4 v197, s[70:71]
	s_add_u32 s68, s68, 0x80
	s_addc_u32 s69, s69, 0
	s_add_u32 s70, s70, 0x80
	s_addc_u32 s71, s71, 0
	s_waitcnt lgkmcnt(0)
	s_barrier
	v_mfma_f32_16x16x32_bf16 v[2:5], v[146:149], v[130:133], v[2:5]
	v_mfma_f32_16x16x32_bf16 v[6:9], v[150:153], v[130:133], v[6:9]
	v_mfma_f32_16x16x32_bf16 v[10:13], v[154:157], v[130:133], v[10:13]
	v_mfma_f32_16x16x32_bf16 v[14:17], v[158:161], v[130:133], v[14:17]
	v_mfma_f32_16x16x32_bf16 v[18:21], v[146:149], v[134:137], v[18:21]
	v_mfma_f32_16x16x32_bf16 v[22:25], v[150:153], v[134:137], v[22:25]
	v_mfma_f32_16x16x32_bf16 v[26:29], v[154:157], v[134:137], v[26:29]
	v_mfma_f32_16x16x32_bf16 v[30:33], v[158:161], v[134:137], v[30:33]
	v_mfma_f32_16x16x32_bf16 v[34:37], v[146:149], v[138:141], v[34:37]
	v_mfma_f32_16x16x32_bf16 v[38:41], v[150:153], v[138:141], v[38:41]
	v_mfma_f32_16x16x32_bf16 v[42:45], v[154:157], v[138:141], v[42:45]
	v_mfma_f32_16x16x32_bf16 v[46:49], v[158:161], v[138:141], v[46:49]
	v_mfma_f32_16x16x32_bf16 v[50:53], v[146:149], v[142:145], v[50:53]
	v_mfma_f32_16x16x32_bf16 v[54:57], v[150:153], v[142:145], v[54:57]
	v_mfma_f32_16x16x32_bf16 v[58:61], v[154:157], v[142:145], v[58:61]
	v_mfma_f32_16x16x32_bf16 v[62:65], v[158:161], v[142:145], v[62:65]
	v_mfma_f32_16x16x32_bf16 v[2:5], v[228:231], v[212:215], v[2:5]
	v_mfma_f32_16x16x32_bf16 v[6:9], v[232:235], v[212:215], v[6:9]
	v_mfma_f32_16x16x32_bf16 v[10:13], v[236:239], v[212:215], v[10:13]
	v_mfma_f32_16x16x32_bf16 v[14:17], v[240:243], v[212:215], v[14:17]
	v_mfma_f32_16x16x32_bf16 v[18:21], v[228:231], v[216:219], v[18:21]
	v_mfma_f32_16x16x32_bf16 v[22:25], v[232:235], v[216:219], v[22:25]
	v_mfma_f32_16x16x32_bf16 v[26:29], v[236:239], v[216:219], v[26:29]
	v_mfma_f32_16x16x32_bf16 v[30:33], v[240:243], v[216:219], v[30:33]
	v_mfma_f32_16x16x32_bf16 v[34:37], v[228:231], v[220:223], v[34:37]
	v_mfma_f32_16x16x32_bf16 v[38:41], v[232:235], v[220:223], v[38:41]
	v_mfma_f32_16x16x32_bf16 v[42:45], v[236:239], v[220:223], v[42:45]
	v_mfma_f32_16x16x32_bf16 v[46:49], v[240:243], v[220:223], v[46:49]
	v_mfma_f32_16x16x32_bf16 v[50:53], v[228:231], v[224:227], v[50:53]
	v_mfma_f32_16x16x32_bf16 v[54:57], v[232:235], v[224:227], v[54:57]
	v_mfma_f32_16x16x32_bf16 v[58:61], v[236:239], v[224:227], v[58:61]
	v_mfma_f32_16x16x32_bf16 v[62:65], v[240:243], v[224:227], v[62:65]
	s_waitcnt vmcnt(6)
	s_barrier
	v_add_u32_e32 v204, 0x0, v200
	v_add_u32_e32 v205, 0x0, v202
	ds_read_b128 v[130:133], v204 offset:0
	ds_read_b128 v[134:137], v204 offset:2048
	ds_read_b128 v[138:141], v204 offset:4096
	ds_read_b128 v[142:145], v204 offset:6144
	ds_read_b128 v[146:149], v205 offset:0
	ds_read_b128 v[150:153], v205 offset:2048
	ds_read_b128 v[154:157], v205 offset:4096
	ds_read_b128 v[158:161], v205 offset:6144
	v_add_u32_e32 v204, 0x0, v201
	v_add_u32_e32 v205, 0x0, v203
	ds_read_b128 v[212:215], v204 offset:0
	ds_read_b128 v[216:219], v204 offset:2048
	ds_read_b128 v[220:223], v204 offset:4096
	ds_read_b128 v[224:227], v204 offset:6144
	ds_read_b128 v[228:231], v205 offset:0
	ds_read_b128 v[232:235], v205 offset:2048
	ds_read_b128 v[236:239], v205 offset:4096
	ds_read_b128 v[240:243], v205 offset:6144
	s_add_u32 m0, s76, 0x18000
	s_nop 0
	global_load_lds_dwordx4 v196, s[68:69]
	s_add_u32 m0, s76, 0x1a000
	s_nop 0
	global_load_lds_dwordx4 v197, s[68:69]
	s_add_u32 m0, s76, 0x1c000
	s_nop 0
	global_load_lds_dwordx4 v198, s[68:69]
	s_add_u32 m0, s76, 0x1e000
	s_nop 0
	global_load_lds_dwordx4 v199, s[68:69]
	s_add_u32 m0, s76, 0x20000
	s_nop 0
	global_load_lds_dwordx4 v196, s[70:71]
	s_add_u32 m0, s76, 0x22000
	s_nop 0
	global_load_lds_dwordx4 v197, s[70:71]
	s_add_u32 s68, s68, 0x80
	s_addc_u32 s69, s69, 0
	s_add_u32 s70, s70, 0x80
	s_addc_u32 s71, s71, 0
	s_waitcnt lgkmcnt(0)
	s_barrier
	v_mfma_f32_16x16x32_bf16 v[2:5], v[146:149], v[130:133], v[2:5]
	v_mfma_f32_16x16x32_bf16 v[6:9], v[150:153], v[130:133], v[6:9]
	v_mfma_f32_16x16x32_bf16 v[10:13], v[154:157], v[130:133], v[10:13]
	v_mfma_f32_16x16x32_bf16 v[14:17], v[158:161], v[130:133], v[14:17]
	v_mfma_f32_16x16x32_bf16 v[18:21], v[146:149], v[134:137], v[18:21]
	v_mfma_f32_16x16x32_bf16 v[22:25], v[150:153], v[134:137], v[22:25]
	v_mfma_f32_16x16x32_bf16 v[26:29], v[154:157], v[134:137], v[26:29]
	v_mfma_f32_16x16x32_bf16 v[30:33], v[158:161], v[134:137], v[30:33]
	v_mfma_f32_16x16x32_bf16 v[34:37], v[146:149], v[138:141], v[34:37]
	v_mfma_f32_16x16x32_bf16 v[38:41], v[150:153], v[138:141], v[38:41]
	v_mfma_f32_16x16x32_bf16 v[42:45], v[154:157], v[138:141], v[42:45]
	v_mfma_f32_16x16x32_bf16 v[46:49], v[158:161], v[138:141], v[46:49]
	v_mfma_f32_16x16x32_bf16 v[50:53], v[146:149], v[142:145], v[50:53]
	v_mfma_f32_16x16x32_bf16 v[54:57], v[150:153], v[142:145], v[54:57]
	v_mfma_f32_16x16x32_bf16 v[58:61], v[154:157], v[142:145], v[58:61]
	v_mfma_f32_16x16x32_bf16 v[62:65], v[158:161], v[142:145], v[62:65]
	v_mfma_f32_16x16x32_bf16 v[2:5], v[228:231], v[212:215], v[2:5]
	v_mfma_f32_16x16x32_bf16 v[6:9], v[232:235], v[212:215], v[6:9]
	v_mfma_f32_16x16x32_bf16 v[10:13], v[236:239], v[212:215], v[10:13]
	v_mfma_f32_16x16x32_bf16 v[14:17], v[240:243], v[212:215], v[14:17]
	v_mfma_f32_16x16x32_bf16 v[18:21], v[228:231], v[216:219], v[18:21]
	v_mfma_f32_16x16x32_bf16 v[22:25], v[232:235], v[216:219], v[22:25]
	v_mfma_f32_16x16x32_bf16 v[26:29], v[236:239], v[216:219], v[26:29]
	v_mfma_f32_16x16x32_bf16 v[30:33], v[240:243], v[216:219], v[30:33]
	v_mfma_f32_16x16x32_bf16 v[34:37], v[228:231], v[220:223], v[34:37]
	v_mfma_f32_16x16x32_bf16 v[38:41], v[232:235], v[220:223], v[38:41]
	v_mfma_f32_16x16x32_bf16 v[42:45], v[236:239], v[220:223], v[42:45]
	v_mfma_f32_16x16x32_bf16 v[46:49], v[240:243], v[220:223], v[46:49]
	v_mfma_f32_16x16x32_bf16 v[50:53], v[228:231], v[224:227], v[50:53]
	v_mfma_f32_16x16x32_bf16 v[54:57], v[232:235], v[224:227], v[54:57]
	v_mfma_f32_16x16x32_bf16 v[58:61], v[236:239], v[224:227], v[58:61]
	v_mfma_f32_16x16x32_bf16 v[62:65], v[240:243], v[224:227], v[62:65]
	s_waitcnt vmcnt(6)
	s_barrier
	v_add_u32_e32 v204, 0xc000, v200
	v_add_u32_e32 v205, 0xc000, v202
	ds_read_b128 v[130:133], v204 offset:0
	ds_read_b128 v[134:137], v204 offset:2048
	ds_read_b128 v[138:141], v204 offset:4096
	ds_read_b128 v[142:145], v204 offset:6144
	ds_read_b128 v[146:149], v205 offset:0
	ds_read_b128 v[150:153], v205 offset:2048
	ds_read_b128 v[154:157], v205 offset:4096
	ds_read_b128 v[158:161], v205 offset:6144
	v_add_u32_e32 v204, 0xc000, v201
	v_add_u32_e32 v205, 0xc000, v203
	ds_read_b128 v[212:215], v204 offset:0
	ds_read_b128 v[216:219], v204 offset:2048
	ds_read_b128 v[220:223], v204 offset:4096
	ds_read_b128 v[224:227], v204 offset:6144
	ds_read_b128 v[228:231], v205 offset:0
	ds_read_b128 v[232:235], v205 offset:2048
	ds_read_b128 v[236:239], v205 offset:4096
	ds_read_b128 v[240:243], v205 offset:6144
	s_add_u32 m0, s76, 0x0
	s_nop 0
	global_load_lds_dwordx4 v196, s[68:69]
	s_add_u32 m0, s76, 0x2000
	s_nop 0
	global_load_lds_dwordx4 v197, s[68:69]
	s_add_u32 m0, s76, 0x4000
	s_nop 0
	global_load_lds_dwordx4 v198, s[68:69]
	s_add_u32 m0, s76, 0x6000
	s_nop 0
	global_load_lds_dwordx4 v199, s[68:69]
	s_add_u32 m0, s76, 0x8000
	s_nop 0
	global_load_lds_dwordx4 v196, s[70:71]
	s_add_u32 m0, s76, 0xa000
	s_nop 0
	global_load_lds_dwordx4 v197, s[70:71]
	s_add_u32 s68, s68, 0x80
	s_addc_u32 s69, s69, 0
	s_add_u32 s70, s70, 0x80
	s_addc_u32 s71, s71, 0
	s_waitcnt lgkmcnt(0)
	s_barrier
	v_mfma_f32_16x16x32_bf16 v[2:5], v[146:149], v[130:133], v[2:5]
	v_mfma_f32_16x16x32_bf16 v[6:9], v[150:153], v[130:133], v[6:9]
	v_mfma_f32_16x16x32_bf16 v[10:13], v[154:157], v[130:133], v[10:13]
	v_mfma_f32_16x16x32_bf16 v[14:17], v[158:161], v[130:133], v[14:17]
	v_mfma_f32_16x16x32_bf16 v[18:21], v[146:149], v[134:137], v[18:21]
	v_mfma_f32_16x16x32_bf16 v[22:25], v[150:153], v[134:137], v[22:25]
	v_mfma_f32_16x16x32_bf16 v[26:29], v[154:157], v[134:137], v[26:29]
	v_mfma_f32_16x16x32_bf16 v[30:33], v[158:161], v[134:137], v[30:33]
	v_mfma_f32_16x16x32_bf16 v[34:37], v[146:149], v[138:141], v[34:37]
	v_mfma_f32_16x16x32_bf16 v[38:41], v[150:153], v[138:141], v[38:41]
	v_mfma_f32_16x16x32_bf16 v[42:45], v[154:157], v[138:141], v[42:45]
	v_mfma_f32_16x16x32_bf16 v[46:49], v[158:161], v[138:141], v[46:49]
	v_mfma_f32_16x16x32_bf16 v[50:53], v[146:149], v[142:145], v[50:53]
	v_mfma_f32_16x16x32_bf16 v[54:57], v[150:153], v[142:145], v[54:57]
	v_mfma_f32_16x16x32_bf16 v[58:61], v[154:157], v[142:145], v[58:61]
	v_mfma_f32_16x16x32_bf16 v[62:65], v[158:161], v[142:145], v[62:65]
	v_mfma_f32_16x16x32_bf16 v[2:5], v[228:231], v[212:215], v[2:5]
	v_mfma_f32_16x16x32_bf16 v[6:9], v[232:235], v[212:215], v[6:9]
	v_mfma_f32_16x16x32_bf16 v[10:13], v[236:239], v[212:215], v[10:13]
	v_mfma_f32_16x16x32_bf16 v[14:17], v[240:243], v[212:215], v[14:17]
	v_mfma_f32_16x16x32_bf16 v[18:21], v[228:231], v[216:219], v[18:21]
	v_mfma_f32_16x16x32_bf16 v[22:25], v[232:235], v[216:219], v[22:25]
	v_mfma_f32_16x16x32_bf16 v[26:29], v[236:239], v[216:219], v[26:29]
	v_mfma_f32_16x16x32_bf16 v[30:33], v[240:243], v[216:219], v[30:33]
	v_mfma_f32_16x16x32_bf16 v[34:37], v[228:231], v[220:223], v[34:37]
	v_mfma_f32_16x16x32_bf16 v[38:41], v[232:235], v[220:223], v[38:41]
	v_mfma_f32_16x16x32_bf16 v[42:45], v[236:239], v[220:223], v[42:45]
	v_mfma_f32_16x16x32_bf16 v[46:49], v[240:243], v[220:223], v[46:49]
	v_mfma_f32_16x16x32_bf16 v[50:53], v[228:231], v[224:227], v[50:53]
	v_mfma_f32_16x16x32_bf16 v[54:57], v[232:235], v[224:227], v[54:57]
	v_mfma_f32_16x16x32_bf16 v[58:61], v[236:239], v[224:227], v[58:61]
	v_mfma_f32_16x16x32_bf16 v[62:65], v[240:243], v[224:227], v[62:65]
	s_nop 7
	v_lshlrev_b32_e32 v212, 16, v174
	v_and_b32_e32 v213, 0xffff0000, v174
	v_lshlrev_b32_e32 v214, 16, v175
	v_and_b32_e32 v215, 0xffff0000, v175
	v_pk_fma_f32 v[66:67], v[2:3], v[212:213], v[66:67]
	v_pk_fma_f32 v[68:69], v[4:5], v[214:215], v[68:69]
	v_lshlrev_b32_e32 v216, 16, v176
	v_and_b32_e32 v217, 0xffff0000, v176
	v_lshlrev_b32_e32 v218, 16, v177
	v_and_b32_e32 v219, 0xffff0000, v177
	v_pk_fma_f32 v[70:71], v[6:7], v[216:217], v[70:71]
	v_pk_fma_f32 v[72:73], v[8:9], v[218:219], v[72:73]
	v_lshlrev_b32_e32 v220, 16, v178
	v_and_b32_e32 v221, 0xffff0000, v178
	v_lshlrev_b32_e32 v222, 16, v179
	v_and_b32_e32 v223, 0xffff0000, v179
	v_pk_fma_f32 v[74:75], v[10:11], v[220:221], v[74:75]
	v_pk_fma_f32 v[76:77], v[12:13], v[222:223], v[76:77]
	v_lshlrev_b32_e32 v224, 16, v180
	v_and_b32_e32 v225, 0xffff0000, v180
	v_lshlrev_b32_e32 v226, 16, v181
	v_and_b32_e32 v227, 0xffff0000, v181
	v_pk_fma_f32 v[78:79], v[14:15], v[224:225], v[78:79]
	v_pk_fma_f32 v[80:81], v[16:17], v[226:227], v[80:81]
	v_lshlrev_b32_e32 v228, 16, v182
	v_and_b32_e32 v229, 0xffff0000, v182
	v_lshlrev_b32_e32 v230, 16, v183
	v_and_b32_e32 v231, 0xffff0000, v183
	v_pk_fma_f32 v[82:83], v[18:19], v[228:229], v[82:83]
	v_pk_fma_f32 v[84:85], v[20:21], v[230:231], v[84:85]
	v_lshlrev_b32_e32 v232, 16, v184
	v_and_b32_e32 v233, 0xffff0000, v184
	v_lshlrev_b32_e32 v234, 16, v185
	v_and_b32_e32 v235, 0xffff0000, v185
	v_pk_fma_f32 v[86:87], v[22:23], v[232:233], v[86:87]
	v_pk_fma_f32 v[88:89], v[24:25], v[234:235], v[88:89]
	v_lshlrev_b32_e32 v236, 16, v186
	v_and_b32_e32 v237, 0xffff0000, v186
	v_lshlrev_b32_e32 v238, 16, v187
	v_and_b32_e32 v239, 0xffff0000, v187
	v_pk_fma_f32 v[90:91], v[26:27], v[236:237], v[90:91]
	v_pk_fma_f32 v[92:93], v[28:29], v[238:239], v[92:93]
	v_lshlrev_b32_e32 v240, 16, v188
	v_and_b32_e32 v241, 0xffff0000, v188
	v_lshlrev_b32_e32 v242, 16, v189
	v_and_b32_e32 v243, 0xffff0000, v189
	v_pk_fma_f32 v[94:95], v[30:31], v[240:241], v[94:95]
	v_pk_fma_f32 v[96:97], v[32:33], v[242:243], v[96:97]
	v_lshlrev_b32_e32 v212, 16, v190
	v_and_b32_e32 v213, 0xffff0000, v190
	v_lshlrev_b32_e32 v214, 16, v191
	v_and_b32_e32 v215, 0xffff0000, v191
	v_pk_fma_f32 v[98:99], v[34:35], v[212:213], v[98:99]
	v_pk_fma_f32 v[100:101], v[36:37], v[214:215], v[100:101]
	v_lshlrev_b32_e32 v216, 16, v192
	v_and_b32_e32 v217, 0xffff0000, v192
	v_lshlrev_b32_e32 v218, 16, v193
	v_and_b32_e32 v219, 0xffff0000, v193
	v_pk_fma_f32 v[102:103], v[38:39], v[216:217], v[102:103]
	v_pk_fma_f32 v[104:105], v[40:41], v[218:219], v[104:105]
	v_lshlrev_b32_e32 v220, 16, v244
	v_and_b32_e32 v221, 0xffff0000, v244
	v_lshlrev_b32_e32 v222, 16, v245
	v_and_b32_e32 v223, 0xffff0000, v245
	v_pk_fma_f32 v[106:107], v[42:43], v[220:221], v[106:107]
	v_pk_fma_f32 v[108:109], v[44:45], v[222:223], v[108:109]
	v_lshlrev_b32_e32 v224, 16, v246
	v_and_b32_e32 v225, 0xffff0000, v246
	v_lshlrev_b32_e32 v226, 16, v247
	v_and_b32_e32 v227, 0xffff0000, v247
	v_pk_fma_f32 v[110:111], v[46:47], v[224:225], v[110:111]
	v_pk_fma_f32 v[112:113], v[48:49], v[226:227], v[112:113]
	v_lshlrev_b32_e32 v228, 16, v248
	v_and_b32_e32 v229, 0xffff0000, v248
	v_lshlrev_b32_e32 v230, 16, v249
	v_and_b32_e32 v231, 0xffff0000, v249
	v_pk_fma_f32 v[114:115], v[50:51], v[228:229], v[114:115]
	v_pk_fma_f32 v[116:117], v[52:53], v[230:231], v[116:117]
	v_lshlrev_b32_e32 v232, 16, v250
	v_and_b32_e32 v233, 0xffff0000, v250
	v_lshlrev_b32_e32 v234, 16, v251
	v_and_b32_e32 v235, 0xffff0000, v251
	v_pk_fma_f32 v[118:119], v[54:55], v[232:233], v[118:119]
	v_pk_fma_f32 v[120:121], v[56:57], v[234:235], v[120:121]
	v_lshlrev_b32_e32 v236, 16, v166
	v_and_b32_e32 v237, 0xffff0000, v166
	v_lshlrev_b32_e32 v238, 16, v167
	v_and_b32_e32 v239, 0xffff0000, v167
	v_pk_fma_f32 v[122:123], v[58:59], v[236:237], v[122:123]
	v_pk_fma_f32 v[124:125], v[60:61], v[238:239], v[124:125]
	v_lshlrev_b32_e32 v240, 16, v194
	v_and_b32_e32 v241, 0xffff0000, v194
	v_lshlrev_b32_e32 v242, 16, v195
	v_and_b32_e32 v243, 0xffff0000, v195
	v_pk_fma_f32 v[126:127], v[62:63], v[240:241], v[126:127]
	v_pk_fma_f32 v[128:129], v[64:65], v[242:243], v[128:129]
	s_waitcnt vmcnt(6)
	s_barrier
	v_add_u32_e32 v204, 0x18000, v200
	v_add_u32_e32 v205, 0x18000, v202
	ds_read_b128 v[130:133], v204 offset:0
	ds_read_b128 v[134:137], v204 offset:2048
	ds_read_b128 v[138:141], v204 offset:4096
	ds_read_b128 v[142:145], v204 offset:6144
	ds_read_b128 v[146:149], v205 offset:0
	ds_read_b128 v[150:153], v205 offset:2048
	ds_read_b128 v[154:157], v205 offset:4096
	ds_read_b128 v[158:161], v205 offset:6144
	v_add_u32_e32 v204, 0x18000, v201
	v_add_u32_e32 v205, 0x18000, v203
	ds_read_b128 v[212:215], v204 offset:0
	ds_read_b128 v[216:219], v204 offset:2048
	ds_read_b128 v[220:223], v204 offset:4096
	ds_read_b128 v[224:227], v204 offset:6144
	ds_read_b128 v[228:231], v205 offset:0
	ds_read_b128 v[232:235], v205 offset:2048
	ds_read_b128 v[236:239], v205 offset:4096
	ds_read_b128 v[240:243], v205 offset:6144
	s_add_u32 m0, s76, 0xc000
	s_nop 0
	global_load_lds_dwordx4 v196, s[68:69]
	s_add_u32 m0, s76, 0xe000
	s_nop 0
	global_load_lds_dwordx4 v197, s[68:69]
	s_add_u32 m0, s76, 0x10000
	s_nop 0
	global_load_lds_dwordx4 v198, s[68:69]
	s_add_u32 m0, s76, 0x12000
	s_nop 0
	global_load_lds_dwordx4 v199, s[68:69]
	s_add_u32 m0, s76, 0x14000
	s_nop 0
	global_load_lds_dwordx4 v196, s[70:71]
	s_add_u32 m0, s76, 0x16000
	s_nop 0
	global_load_lds_dwordx4 v197, s[70:71]
	s_add_u32 s68, s68, 0x80
	s_addc_u32 s69, s69, 0
	s_add_u32 s70, s70, 0x80
	s_addc_u32 s71, s71, 0
	global_load_dwordx2 v[174:175], v206, s[72:73] offset:0
	global_load_dwordx2 v[176:177], v206, s[72:73] offset:32
	global_load_dwordx2 v[178:179], v206, s[72:73] offset:64
	global_load_dwordx2 v[180:181], v206, s[72:73] offset:96
	global_load_dwordx2 v[182:183], v207, s[72:73] offset:0
	global_load_dwordx2 v[184:185], v207, s[72:73] offset:32
	s_waitcnt lgkmcnt(0)
	s_barrier
	v_mfma_f32_16x16x32_bf16 v[2:5], v[146:149], v[130:133], 0
	v_mfma_f32_16x16x32_bf16 v[6:9], v[150:153], v[130:133], 0
	v_mfma_f32_16x16x32_bf16 v[10:13], v[154:157], v[130:133], 0
	v_mfma_f32_16x16x32_bf16 v[14:17], v[158:161], v[130:133], 0
	v_mfma_f32_16x16x32_bf16 v[18:21], v[146:149], v[134:137], 0
	v_mfma_f32_16x16x32_bf16 v[22:25], v[150:153], v[134:137], 0
	v_mfma_f32_16x16x32_bf16 v[26:29], v[154:157], v[134:137], 0
	v_mfma_f32_16x16x32_bf16 v[30:33], v[158:161], v[134:137], 0
	v_mfma_f32_16x16x32_bf16 v[34:37], v[146:149], v[138:141], 0
	v_mfma_f32_16x16x32_bf16 v[38:41], v[150:153], v[138:141], 0
	v_mfma_f32_16x16x32_bf16 v[42:45], v[154:157], v[138:141], 0
	v_mfma_f32_16x16x32_bf16 v[46:49], v[158:161], v[138:141], 0
	v_mfma_f32_16x16x32_bf16 v[50:53], v[146:149], v[142:145], 0
	v_mfma_f32_16x16x32_bf16 v[54:57], v[150:153], v[142:145], 0
	v_mfma_f32_16x16x32_bf16 v[58:61], v[154:157], v[142:145], 0
	v_mfma_f32_16x16x32_bf16 v[62:65], v[158:161], v[142:145], 0
	v_mfma_f32_16x16x32_bf16 v[2:5], v[228:231], v[212:215], v[2:5]
	v_mfma_f32_16x16x32_bf16 v[6:9], v[232:235], v[212:215], v[6:9]
	v_mfma_f32_16x16x32_bf16 v[10:13], v[236:239], v[212:215], v[10:13]
	v_mfma_f32_16x16x32_bf16 v[14:17], v[240:243], v[212:215], v[14:17]
	v_mfma_f32_16x16x32_bf16 v[18:21], v[228:231], v[216:219], v[18:21]
	v_mfma_f32_16x16x32_bf16 v[22:25], v[232:235], v[216:219], v[22:25]
	v_mfma_f32_16x16x32_bf16 v[26:29], v[236:239], v[216:219], v[26:29]
	v_mfma_f32_16x16x32_bf16 v[30:33], v[240:243], v[216:219], v[30:33]
	v_mfma_f32_16x16x32_bf16 v[34:37], v[228:231], v[220:223], v[34:37]
	v_mfma_f32_16x16x32_bf16 v[38:41], v[232:235], v[220:223], v[38:41]
	v_mfma_f32_16x16x32_bf16 v[42:45], v[236:239], v[220:223], v[42:45]
	v_mfma_f32_16x16x32_bf16 v[46:49], v[240:243], v[220:223], v[46:49]
	v_mfma_f32_16x16x32_bf16 v[50:53], v[228:231], v[224:227], v[50:53]
	v_mfma_f32_16x16x32_bf16 v[54:57], v[232:235], v[224:227], v[54:57]
	v_mfma_f32_16x16x32_bf16 v[58:61], v[236:239], v[224:227], v[58:61]
	v_mfma_f32_16x16x32_bf16 v[62:65], v[240:243], v[224:227], v[62:65]
	s_waitcnt vmcnt(12)
	s_barrier
	v_add_u32_e32 v204, 0x0, v200
	v_add_u32_e32 v205, 0x0, v202
	ds_read_b128 v[130:133], v204 offset:0
	ds_read_b128 v[134:137], v204 offset:2048
	ds_read_b128 v[138:141], v204 offset:4096
	ds_read_b128 v[142:145], v204 offset:6144
	ds_read_b128 v[146:149], v205 offset:0
	ds_read_b128 v[150:153], v205 offset:2048
	ds_read_b128 v[154:157], v205 offset:4096
	ds_read_b128 v[158:161], v205 offset:6144
	v_add_u32_e32 v204, 0x0, v201
	v_add_u32_e32 v205, 0x0, v203
	ds_read_b128 v[212:215], v204 offset:0
	ds_read_b128 v[216:219], v204 offset:2048
	ds_read_b128 v[220:223], v204 offset:4096
	ds_read_b128 v[224:227], v204 offset:6144
	ds_read_b128 v[228:231], v205 offset:0
	ds_read_b128 v[232:235], v205 offset:2048
	ds_read_b128 v[236:239], v205 offset:4096
	ds_read_b128 v[240:243], v205 offset:6144
	s_add_u32 m0, s76, 0x18000
	s_nop 0
	global_load_lds_dwordx4 v196, s[68:69]
	s_add_u32 m0, s76, 0x1a000
	s_nop 0
	global_load_lds_dwordx4 v197, s[68:69]
	s_add_u32 m0, s76, 0x1c000
	s_nop 0
	global_load_lds_dwordx4 v198, s[68:69]
	s_add_u32 m0, s76, 0x1e000
	s_nop 0
	global_load_lds_dwordx4 v199, s[68:69]
	s_add_u32 m0, s76, 0x20000
	s_nop 0
	global_load_lds_dwordx4 v196, s[70:71]
	s_add_u32 m0, s76, 0x22000
	s_nop 0
	global_load_lds_dwordx4 v197, s[70:71]
	s_add_u32 s68, s68, 0x80
	s_addc_u32 s69, s69, 0
	s_add_u32 s70, s70, 0x80
	s_addc_u32 s71, s71, 0
	global_load_dwordx2 v[186:187], v207, s[72:73] offset:64
	global_load_dwordx2 v[188:189], v207, s[72:73] offset:96
	global_load_dwordx2 v[190:191], v208, s[72:73] offset:0
	global_load_dwordx2 v[192:193], v208, s[72:73] offset:32
	global_load_dwordx2 v[244:245], v208, s[72:73] offset:64
	global_load_dwordx2 v[246:247], v208, s[72:73] offset:96
	s_waitcnt lgkmcnt(0)
	s_barrier
	v_mfma_f32_16x16x32_bf16 v[2:5], v[146:149], v[130:133], v[2:5]
	v_mfma_f32_16x16x32_bf16 v[6:9], v[150:153], v[130:133], v[6:9]
	v_mfma_f32_16x16x32_bf16 v[10:13], v[154:157], v[130:133], v[10:13]
	v_mfma_f32_16x16x32_bf16 v[14:17], v[158:161], v[130:133], v[14:17]
	v_mfma_f32_16x16x32_bf16 v[18:21], v[146:149], v[134:137], v[18:21]
	v_mfma_f32_16x16x32_bf16 v[22:25], v[150:153], v[134:137], v[22:25]
	v_mfma_f32_16x16x32_bf16 v[26:29], v[154:157], v[134:137], v[26:29]
	v_mfma_f32_16x16x32_bf16 v[30:33], v[158:161], v[134:137], v[30:33]
	v_mfma_f32_16x16x32_bf16 v[34:37], v[146:149], v[138:141], v[34:37]
	v_mfma_f32_16x16x32_bf16 v[38:41], v[150:153], v[138:141], v[38:41]
	v_mfma_f32_16x16x32_bf16 v[42:45], v[154:157], v[138:141], v[42:45]
	v_mfma_f32_16x16x32_bf16 v[46:49], v[158:161], v[138:141], v[46:49]
	v_mfma_f32_16x16x32_bf16 v[50:53], v[146:149], v[142:145], v[50:53]
	v_mfma_f32_16x16x32_bf16 v[54:57], v[150:153], v[142:145], v[54:57]
	v_mfma_f32_16x16x32_bf16 v[58:61], v[154:157], v[142:145], v[58:61]
	v_mfma_f32_16x16x32_bf16 v[62:65], v[158:161], v[142:145], v[62:65]
	v_mfma_f32_16x16x32_bf16 v[2:5], v[228:231], v[212:215], v[2:5]
	v_mfma_f32_16x16x32_bf16 v[6:9], v[232:235], v[212:215], v[6:9]
	v_mfma_f32_16x16x32_bf16 v[10:13], v[236:239], v[212:215], v[10:13]
	v_mfma_f32_16x16x32_bf16 v[14:17], v[240:243], v[212:215], v[14:17]
	v_mfma_f32_16x16x32_bf16 v[18:21], v[228:231], v[216:219], v[18:21]
	v_mfma_f32_16x16x32_bf16 v[22:25], v[232:235], v[216:219], v[22:25]
	v_mfma_f32_16x16x32_bf16 v[26:29], v[236:239], v[216:219], v[26:29]
	v_mfma_f32_16x16x32_bf16 v[30:33], v[240:243], v[216:219], v[30:33]
	v_mfma_f32_16x16x32_bf16 v[34:37], v[228:231], v[220:223], v[34:37]
	v_mfma_f32_16x16x32_bf16 v[38:41], v[232:235], v[220:223], v[38:41]
	v_mfma_f32_16x16x32_bf16 v[42:45], v[236:239], v[220:223], v[42:45]
	v_mfma_f32_16x16x32_bf16 v[46:49], v[240:243], v[220:223], v[46:49]
	v_mfma_f32_16x16x32_bf16 v[50:53], v[228:231], v[224:227], v[50:53]
	v_mfma_f32_16x16x32_bf16 v[54:57], v[232:235], v[224:227], v[54:57]
	v_mfma_f32_16x16x32_bf16 v[58:61], v[236:239], v[224:227], v[58:61]
	v_mfma_f32_16x16x32_bf16 v[62:65], v[240:243], v[224:227], v[62:65]
	s_waitcnt vmcnt(18)
	s_barrier
	v_add_u32_e32 v204, 0xc000, v200
	v_add_u32_e32 v205, 0xc000, v202
	ds_read_b128 v[130:133], v204 offset:0
	ds_read_b128 v[134:137], v204 offset:2048
	ds_read_b128 v[138:141], v204 offset:4096
	ds_read_b128 v[142:145], v204 offset:6144
	ds_read_b128 v[146:149], v205 offset:0
	ds_read_b128 v[150:153], v205 offset:2048
	ds_read_b128 v[154:157], v205 offset:4096
	ds_read_b128 v[158:161], v205 offset:6144
	v_add_u32_e32 v204, 0xc000, v201
	v_add_u32_e32 v205, 0xc000, v203
	ds_read_b128 v[212:215], v204 offset:0
	ds_read_b128 v[216:219], v204 offset:2048
	ds_read_b128 v[220:223], v204 offset:4096
	ds_read_b128 v[224:227], v204 offset:6144
	ds_read_b128 v[228:231], v205 offset:0
	ds_read_b128 v[232:235], v205 offset:2048
	ds_read_b128 v[236:239], v205 offset:4096
	ds_read_b128 v[240:243], v205 offset:6144
	s_add_u32 m0, s76, 0x0
	s_nop 0
	global_load_lds_dwordx4 v196, s[68:69]
	s_add_u32 m0, s76, 0x2000
	s_nop 0
	global_load_lds_dwordx4 v197, s[68:69]
	s_add_u32 m0, s76, 0x4000
	s_nop 0
	global_load_lds_dwordx4 v198, s[68:69]
	s_add_u32 m0, s76, 0x6000
	s_nop 0
	global_load_lds_dwordx4 v199, s[68:69]
	s_add_u32 m0, s76, 0x8000
	s_nop 0
	global_load_lds_dwordx4 v196, s[70:71]
	s_add_u32 m0, s76, 0xa000
	s_nop 0
	global_load_lds_dwordx4 v197, s[70:71]
	s_add_u32 s68, s68, 0x80
	s_addc_u32 s69, s69, 0
	s_add_u32 s70, s70, 0x80
	s_addc_u32 s71, s71, 0
	global_load_dwordx2 v[248:249], v209, s[72:73] offset:0
	global_load_dwordx2 v[250:251], v209, s[72:73] offset:32
	global_load_dwordx2 v[166:167], v209, s[72:73] offset:64
	global_load_dwordx2 v[194:195], v209, s[72:73] offset:96
	s_add_u32 s72, s72, 0x800
	s_addc_u32 s73, s73, 0
	s_waitcnt lgkmcnt(0)
	s_barrier
	v_mfma_f32_16x16x32_bf16 v[2:5], v[146:149], v[130:133], v[2:5]
	v_mfma_f32_16x16x32_bf16 v[6:9], v[150:153], v[130:133], v[6:9]
	v_mfma_f32_16x16x32_bf16 v[10:13], v[154:157], v[130:133], v[10:13]
	v_mfma_f32_16x16x32_bf16 v[14:17], v[158:161], v[130:133], v[14:17]
	v_mfma_f32_16x16x32_bf16 v[18:21], v[146:149], v[134:137], v[18:21]
	v_mfma_f32_16x16x32_bf16 v[22:25], v[150:153], v[134:137], v[22:25]
	v_mfma_f32_16x16x32_bf16 v[26:29], v[154:157], v[134:137], v[26:29]
	v_mfma_f32_16x16x32_bf16 v[30:33], v[158:161], v[134:137], v[30:33]
	v_mfma_f32_16x16x32_bf16 v[34:37], v[146:149], v[138:141], v[34:37]
	v_mfma_f32_16x16x32_bf16 v[38:41], v[150:153], v[138:141], v[38:41]
	v_mfma_f32_16x16x32_bf16 v[42:45], v[154:157], v[138:141], v[42:45]
	v_mfma_f32_16x16x32_bf16 v[46:49], v[158:161], v[138:141], v[46:49]
	v_mfma_f32_16x16x32_bf16 v[50:53], v[146:149], v[142:145], v[50:53]
	v_mfma_f32_16x16x32_bf16 v[54:57], v[150:153], v[142:145], v[54:57]
	v_mfma_f32_16x16x32_bf16 v[58:61], v[154:157], v[142:145], v[58:61]
	v_mfma_f32_16x16x32_bf16 v[62:65], v[158:161], v[142:145], v[62:65]
	v_mfma_f32_16x16x32_bf16 v[2:5], v[228:231], v[212:215], v[2:5]
	v_mfma_f32_16x16x32_bf16 v[6:9], v[232:235], v[212:215], v[6:9]
	v_mfma_f32_16x16x32_bf16 v[10:13], v[236:239], v[212:215], v[10:13]
	v_mfma_f32_16x16x32_bf16 v[14:17], v[240:243], v[212:215], v[14:17]
	v_mfma_f32_16x16x32_bf16 v[18:21], v[228:231], v[216:219], v[18:21]
	v_mfma_f32_16x16x32_bf16 v[22:25], v[232:235], v[216:219], v[22:25]
	v_mfma_f32_16x16x32_bf16 v[26:29], v[236:239], v[216:219], v[26:29]
	v_mfma_f32_16x16x32_bf16 v[30:33], v[240:243], v[216:219], v[30:33]
	v_mfma_f32_16x16x32_bf16 v[34:37], v[228:231], v[220:223], v[34:37]
	v_mfma_f32_16x16x32_bf16 v[38:41], v[232:235], v[220:223], v[38:41]
	v_mfma_f32_16x16x32_bf16 v[42:45], v[236:239], v[220:223], v[42:45]
	v_mfma_f32_16x16x32_bf16 v[46:49], v[240:243], v[220:223], v[46:49]
	v_mfma_f32_16x16x32_bf16 v[50:53], v[228:231], v[224:227], v[50:53]
	v_mfma_f32_16x16x32_bf16 v[54:57], v[232:235], v[224:227], v[54:57]
	v_mfma_f32_16x16x32_bf16 v[58:61], v[236:239], v[224:227], v[58:61]
	v_mfma_f32_16x16x32_bf16 v[62:65], v[240:243], v[224:227], v[62:65]
	s_waitcnt vmcnt(16)
	s_barrier
	v_add_u32_e32 v204, 0x18000, v200
	v_add_u32_e32 v205, 0x18000, v202
	ds_read_b128 v[130:133], v204 offset:0
	ds_read_b128 v[134:137], v204 offset:2048
	ds_read_b128 v[138:141], v204 offset:4096
	ds_read_b128 v[142:145], v204 offset:6144
	ds_read_b128 v[146:149], v205 offset:0
	ds_read_b128 v[150:153], v205 offset:2048
	ds_read_b128 v[154:157], v205 offset:4096
	ds_read_b128 v[158:161], v205 offset:6144
	v_add_u32_e32 v204, 0x18000, v201
	v_add_u32_e32 v205, 0x18000, v203
	ds_read_b128 v[212:215], v204 offset:0
	ds_read_b128 v[216:219], v204 offset:2048
	ds_read_b128 v[220:223], v204 offset:4096
	ds_read_b128 v[224:227], v204 offset:6144
	ds_read_b128 v[228:231], v205 offset:0
	ds_read_b128 v[232:235], v205 offset:2048
	ds_read_b128 v[236:239], v205 offset:4096
	ds_read_b128 v[240:243], v205 offset:6144
	s_add_u32 m0, s76, 0xc000
	s_nop 0
	global_load_lds_dwordx4 v196, s[68:69]
	s_add_u32 m0, s76, 0xe000
	s_nop 0
	global_load_lds_dwordx4 v197, s[68:69]
	s_add_u32 m0, s76, 0x10000
	s_nop 0
	global_load_lds_dwordx4 v198, s[68:69]
	s_add_u32 m0, s76, 0x12000
	s_nop 0
	global_load_lds_dwordx4 v199, s[68:69]
	s_add_u32 m0, s76, 0x14000
	s_nop 0
	global_load_lds_dwordx4 v196, s[70:71]
	s_add_u32 m0, s76, 0x16000
	s_nop 0
	global_load_lds_dwordx4 v197, s[70:71]
	s_add_u32 s68, s68, 0x80
	s_addc_u32 s69, s69, 0
	s_add_u32 s70, s70, 0x80
	s_addc_u32 s71, s71, 0
	s_waitcnt lgkmcnt(0)
	s_barrier
	v_mfma_f32_16x16x32_bf16 v[2:5], v[146:149], v[130:133], v[2:5]
	v_mfma_f32_16x16x32_bf16 v[6:9], v[150:153], v[130:133], v[6:9]
	v_mfma_f32_16x16x32_bf16 v[10:13], v[154:157], v[130:133], v[10:13]
	v_mfma_f32_16x16x32_bf16 v[14:17], v[158:161], v[130:133], v[14:17]
	v_mfma_f32_16x16x32_bf16 v[18:21], v[146:149], v[134:137], v[18:21]
	v_mfma_f32_16x16x32_bf16 v[22:25], v[150:153], v[134:137], v[22:25]
	v_mfma_f32_16x16x32_bf16 v[26:29], v[154:157], v[134:137], v[26:29]
	v_mfma_f32_16x16x32_bf16 v[30:33], v[158:161], v[134:137], v[30:33]
	v_mfma_f32_16x16x32_bf16 v[34:37], v[146:149], v[138:141], v[34:37]
	v_mfma_f32_16x16x32_bf16 v[38:41], v[150:153], v[138:141], v[38:41]
	v_mfma_f32_16x16x32_bf16 v[42:45], v[154:157], v[138:141], v[42:45]
	v_mfma_f32_16x16x32_bf16 v[46:49], v[158:161], v[138:141], v[46:49]
	v_mfma_f32_16x16x32_bf16 v[50:53], v[146:149], v[142:145], v[50:53]
	v_mfma_f32_16x16x32_bf16 v[54:57], v[150:153], v[142:145], v[54:57]
	v_mfma_f32_16x16x32_bf16 v[58:61], v[154:157], v[142:145], v[58:61]
	v_mfma_f32_16x16x32_bf16 v[62:65], v[158:161], v[142:145], v[62:65]
	v_mfma_f32_16x16x32_bf16 v[2:5], v[228:231], v[212:215], v[2:5]
	v_mfma_f32_16x16x32_bf16 v[6:9], v[232:235], v[212:215], v[6:9]
	v_mfma_f32_16x16x32_bf16 v[10:13], v[236:239], v[212:215], v[10:13]
	v_mfma_f32_16x16x32_bf16 v[14:17], v[240:243], v[212:215], v[14:17]
	v_mfma_f32_16x16x32_bf16 v[18:21], v[228:231], v[216:219], v[18:21]
	v_mfma_f32_16x16x32_bf16 v[22:25], v[232:235], v[216:219], v[22:25]
	v_mfma_f32_16x16x32_bf16 v[26:29], v[236:239], v[216:219], v[26:29]
	v_mfma_f32_16x16x32_bf16 v[30:33], v[240:243], v[216:219], v[30:33]
	v_mfma_f32_16x16x32_bf16 v[34:37], v[228:231], v[220:223], v[34:37]
	v_mfma_f32_16x16x32_bf16 v[38:41], v[232:235], v[220:223], v[38:41]
	v_mfma_f32_16x16x32_bf16 v[42:45], v[236:239], v[220:223], v[42:45]
	v_mfma_f32_16x16x32_bf16 v[46:49], v[240:243], v[220:223], v[46:49]
	v_mfma_f32_16x16x32_bf16 v[50:53], v[228:231], v[224:227], v[50:53]
	v_mfma_f32_16x16x32_bf16 v[54:57], v[232:235], v[224:227], v[54:57]
	v_mfma_f32_16x16x32_bf16 v[58:61], v[236:239], v[224:227], v[58:61]
	v_mfma_f32_16x16x32_bf16 v[62:65], v[240:243], v[224:227], v[62:65]
	s_waitcnt vmcnt(10)
	s_barrier
	v_add_u32_e32 v204, 0x0, v200
	v_add_u32_e32 v205, 0x0, v202
	ds_read_b128 v[130:133], v204 offset:0
	ds_read_b128 v[134:137], v204 offset:2048
	ds_read_b128 v[138:141], v204 offset:4096
	ds_read_b128 v[142:145], v204 offset:6144
	ds_read_b128 v[146:149], v205 offset:0
	ds_read_b128 v[150:153], v205 offset:2048
	ds_read_b128 v[154:157], v205 offset:4096
	ds_read_b128 v[158:161], v205 offset:6144
	v_add_u32_e32 v204, 0x0, v201
	v_add_u32_e32 v205, 0x0, v203
	ds_read_b128 v[212:215], v204 offset:0
	ds_read_b128 v[216:219], v204 offset:2048
	ds_read_b128 v[220:223], v204 offset:4096
	ds_read_b128 v[224:227], v204 offset:6144
	ds_read_b128 v[228:231], v205 offset:0
	ds_read_b128 v[232:235], v205 offset:2048
	ds_read_b128 v[236:239], v205 offset:4096
	ds_read_b128 v[240:243], v205 offset:6144
	s_add_u32 m0, s76, 0x18000
	s_nop 0
	global_load_lds_dwordx4 v196, s[68:69]
	s_add_u32 m0, s76, 0x1a000
	s_nop 0
	global_load_lds_dwordx4 v197, s[68:69]
	s_add_u32 m0, s76, 0x1c000
	s_nop 0
	global_load_lds_dwordx4 v198, s[68:69]
	s_add_u32 m0, s76, 0x1e000
	s_nop 0
	global_load_lds_dwordx4 v199, s[68:69]
	s_add_u32 m0, s76, 0x20000
	s_nop 0
	global_load_lds_dwordx4 v196, s[70:71]
	s_add_u32 m0, s76, 0x22000
	s_nop 0
	global_load_lds_dwordx4 v197, s[70:71]
	s_add_u32 s68, s68, 0x80
	s_addc_u32 s69, s69, 0
	s_add_u32 s70, s70, 0x80
	s_addc_u32 s71, s71, 0
	s_waitcnt lgkmcnt(0)
	s_barrier
	v_mfma_f32_16x16x32_bf16 v[2:5], v[146:149], v[130:133], v[2:5]
	v_mfma_f32_16x16x32_bf16 v[6:9], v[150:153], v[130:133], v[6:9]
	v_mfma_f32_16x16x32_bf16 v[10:13], v[154:157], v[130:133], v[10:13]
	v_mfma_f32_16x16x32_bf16 v[14:17], v[158:161], v[130:133], v[14:17]
	v_mfma_f32_16x16x32_bf16 v[18:21], v[146:149], v[134:137], v[18:21]
	v_mfma_f32_16x16x32_bf16 v[22:25], v[150:153], v[134:137], v[22:25]
	v_mfma_f32_16x16x32_bf16 v[26:29], v[154:157], v[134:137], v[26:29]
	v_mfma_f32_16x16x32_bf16 v[30:33], v[158:161], v[134:137], v[30:33]
	v_mfma_f32_16x16x32_bf16 v[34:37], v[146:149], v[138:141], v[34:37]
	v_mfma_f32_16x16x32_bf16 v[38:41], v[150:153], v[138:141], v[38:41]
	v_mfma_f32_16x16x32_bf16 v[42:45], v[154:157], v[138:141], v[42:45]
	v_mfma_f32_16x16x32_bf16 v[46:49], v[158:161], v[138:141], v[46:49]
	v_mfma_f32_16x16x32_bf16 v[50:53], v[146:149], v[142:145], v[50:53]
	v_mfma_f32_16x16x32_bf16 v[54:57], v[150:153], v[142:145], v[54:57]
	v_mfma_f32_16x16x32_bf16 v[58:61], v[154:157], v[142:145], v[58:61]
	v_mfma_f32_16x16x32_bf16 v[62:65], v[158:161], v[142:145], v[62:65]
	v_mfma_f32_16x16x32_bf16 v[2:5], v[228:231], v[212:215], v[2:5]
	v_mfma_f32_16x16x32_bf16 v[6:9], v[232:235], v[212:215], v[6:9]
	v_mfma_f32_16x16x32_bf16 v[10:13], v[236:239], v[212:215], v[10:13]
	v_mfma_f32_16x16x32_bf16 v[14:17], v[240:243], v[212:215], v[14:17]
	v_mfma_f32_16x16x32_bf16 v[18:21], v[228:231], v[216:219], v[18:21]
	v_mfma_f32_16x16x32_bf16 v[22:25], v[232:235], v[216:219], v[22:25]
	v_mfma_f32_16x16x32_bf16 v[26:29], v[236:239], v[216:219], v[26:29]
	v_mfma_f32_16x16x32_bf16 v[30:33], v[240:243], v[216:219], v[30:33]
	v_mfma_f32_16x16x32_bf16 v[34:37], v[228:231], v[220:223], v[34:37]
	v_mfma_f32_16x16x32_bf16 v[38:41], v[232:235], v[220:223], v[38:41]
	v_mfma_f32_16x16x32_bf16 v[42:45], v[236:239], v[220:223], v[42:45]
	v_mfma_f32_16x16x32_bf16 v[46:49], v[240:243], v[220:223], v[46:49]
	v_mfma_f32_16x16x32_bf16 v[50:53], v[228:231], v[224:227], v[50:53]
	v_mfma_f32_16x16x32_bf16 v[54:57], v[232:235], v[224:227], v[54:57]
	v_mfma_f32_16x16x32_bf16 v[58:61], v[236:239], v[224:227], v[58:61]
	v_mfma_f32_16x16x32_bf16 v[62:65], v[240:243], v[224:227], v[62:65]
	s_waitcnt vmcnt(6)
	s_barrier
	v_add_u32_e32 v204, 0xc000, v200
	v_add_u32_e32 v205, 0xc000, v202
	ds_read_b128 v[130:133], v204 offset:0
	ds_read_b128 v[134:137], v204 offset:2048
	ds_read_b128 v[138:141], v204 offset:4096
	ds_read_b128 v[142:145], v204 offset:6144
	ds_read_b128 v[146:149], v205 offset:0
	ds_read_b128 v[150:153], v205 offset:2048
	ds_read_b128 v[154:157], v205 offset:4096
	ds_read_b128 v[158:161], v205 offset:6144
	v_add_u32_e32 v204, 0xc000, v201
	v_add_u32_e32 v205, 0xc000, v203
	ds_read_b128 v[212:215], v204 offset:0
	ds_read_b128 v[216:219], v204 offset:2048
	ds_read_b128 v[220:223], v204 offset:4096
	ds_read_b128 v[224:227], v204 offset:6144
	ds_read_b128 v[228:231], v205 offset:0
	ds_read_b128 v[232:235], v205 offset:2048
	ds_read_b128 v[236:239], v205 offset:4096
	ds_read_b128 v[240:243], v205 offset:6144
	s_add_u32 m0, s76, 0x0
	s_nop 0
	global_load_lds_dwordx4 v196, s[68:69]
	s_add_u32 m0, s76, 0x2000
	s_nop 0
	global_load_lds_dwordx4 v197, s[68:69]
	s_add_u32 m0, s76, 0x4000
	s_nop 0
	global_load_lds_dwordx4 v198, s[68:69]
	s_add_u32 m0, s76, 0x6000
	s_nop 0
	global_load_lds_dwordx4 v199, s[68:69]
	s_add_u32 m0, s76, 0x8000
	s_nop 0
	global_load_lds_dwordx4 v196, s[70:71]
	s_add_u32 m0, s76, 0xa000
	s_nop 0
	global_load_lds_dwordx4 v197, s[70:71]
	s_add_u32 s68, s68, 0x80
	s_addc_u32 s69, s69, 0
	s_add_u32 s70, s70, 0x80
	s_addc_u32 s71, s71, 0
	s_waitcnt lgkmcnt(0)
	s_barrier
	v_mfma_f32_16x16x32_bf16 v[2:5], v[146:149], v[130:133], v[2:5]
	v_mfma_f32_16x16x32_bf16 v[6:9], v[150:153], v[130:133], v[6:9]
	v_mfma_f32_16x16x32_bf16 v[10:13], v[154:157], v[130:133], v[10:13]
	v_mfma_f32_16x16x32_bf16 v[14:17], v[158:161], v[130:133], v[14:17]
	v_mfma_f32_16x16x32_bf16 v[18:21], v[146:149], v[134:137], v[18:21]
	v_mfma_f32_16x16x32_bf16 v[22:25], v[150:153], v[134:137], v[22:25]
	v_mfma_f32_16x16x32_bf16 v[26:29], v[154:157], v[134:137], v[26:29]
	v_mfma_f32_16x16x32_bf16 v[30:33], v[158:161], v[134:137], v[30:33]
	v_mfma_f32_16x16x32_bf16 v[34:37], v[146:149], v[138:141], v[34:37]
	v_mfma_f32_16x16x32_bf16 v[38:41], v[150:153], v[138:141], v[38:41]
	v_mfma_f32_16x16x32_bf16 v[42:45], v[154:157], v[138:141], v[42:45]
	v_mfma_f32_16x16x32_bf16 v[46:49], v[158:161], v[138:141], v[46:49]
	v_mfma_f32_16x16x32_bf16 v[50:53], v[146:149], v[142:145], v[50:53]
	v_mfma_f32_16x16x32_bf16 v[54:57], v[150:153], v[142:145], v[54:57]
	v_mfma_f32_16x16x32_bf16 v[58:61], v[154:157], v[142:145], v[58:61]
	v_mfma_f32_16x16x32_bf16 v[62:65], v[158:161], v[142:145], v[62:65]
	v_mfma_f32_16x16x32_bf16 v[2:5], v[228:231], v[212:215], v[2:5]
	v_mfma_f32_16x16x32_bf16 v[6:9], v[232:235], v[212:215], v[6:9]
	v_mfma_f32_16x16x32_bf16 v[10:13], v[236:239], v[212:215], v[10:13]
	v_mfma_f32_16x16x32_bf16 v[14:17], v[240:243], v[212:215], v[14:17]
	v_mfma_f32_16x16x32_bf16 v[18:21], v[228:231], v[216:219], v[18:21]
	v_mfma_f32_16x16x32_bf16 v[22:25], v[232:235], v[216:219], v[22:25]
	v_mfma_f32_16x16x32_bf16 v[26:29], v[236:239], v[216:219], v[26:29]
	v_mfma_f32_16x16x32_bf16 v[30:33], v[240:243], v[216:219], v[30:33]
	v_mfma_f32_16x16x32_bf16 v[34:37], v[228:231], v[220:223], v[34:37]
	v_mfma_f32_16x16x32_bf16 v[38:41], v[232:235], v[220:223], v[38:41]
	v_mfma_f32_16x16x32_bf16 v[42:45], v[236:239], v[220:223], v[42:45]
	v_mfma_f32_16x16x32_bf16 v[46:49], v[240:243], v[220:223], v[46:49]
	v_mfma_f32_16x16x32_bf16 v[50:53], v[228:231], v[224:227], v[50:53]
	v_mfma_f32_16x16x32_bf16 v[54:57], v[232:235], v[224:227], v[54:57]
	v_mfma_f32_16x16x32_bf16 v[58:61], v[236:239], v[224:227], v[58:61]
	v_mfma_f32_16x16x32_bf16 v[62:65], v[240:243], v[224:227], v[62:65]
	s_waitcnt vmcnt(6)
	s_barrier
	v_add_u32_e32 v204, 0x18000, v200
	v_add_u32_e32 v205, 0x18000, v202
	ds_read_b128 v[130:133], v204 offset:0
	ds_read_b128 v[134:137], v204 offset:2048
	ds_read_b128 v[138:141], v204 offset:4096
	ds_read_b128 v[142:145], v204 offset:6144
	ds_read_b128 v[146:149], v205 offset:0
	ds_read_b128 v[150:153], v205 offset:2048
	ds_read_b128 v[154:157], v205 offset:4096
	ds_read_b128 v[158:161], v205 offset:6144
	v_add_u32_e32 v204, 0x18000, v201
	v_add_u32_e32 v205, 0x18000, v203
	ds_read_b128 v[212:215], v204 offset:0
	ds_read_b128 v[216:219], v204 offset:2048
	ds_read_b128 v[220:223], v204 offset:4096
	ds_read_b128 v[224:227], v204 offset:6144
	ds_read_b128 v[228:231], v205 offset:0
	ds_read_b128 v[232:235], v205 offset:2048
	ds_read_b128 v[236:239], v205 offset:4096
	ds_read_b128 v[240:243], v205 offset:6144
	s_add_u32 m0, s76, 0xc000
	s_nop 0
	global_load_lds_dwordx4 v196, s[68:69]
	s_add_u32 m0, s76, 0xe000
	s_nop 0
	global_load_lds_dwordx4 v197, s[68:69]
	s_add_u32 m0, s76, 0x10000
	s_nop 0
	global_load_lds_dwordx4 v198, s[68:69]
	s_add_u32 m0, s76, 0x12000
	s_nop 0
	global_load_lds_dwordx4 v199, s[68:69]
	s_add_u32 m0, s76, 0x14000
	s_nop 0
	global_load_lds_dwordx4 v196, s[70:71]
	s_add_u32 m0, s76, 0x16000
	s_nop 0
	global_load_lds_dwordx4 v197, s[70:71]
	s_add_u32 s68, s68, 0x80
	s_addc_u32 s69, s69, 0
	s_add_u32 s70, s70, 0x80
	s_addc_u32 s71, s71, 0
	s_waitcnt lgkmcnt(0)
	s_barrier
	v_mfma_f32_16x16x32_bf16 v[2:5], v[146:149], v[130:133], v[2:5]
	v_mfma_f32_16x16x32_bf16 v[6:9], v[150:153], v[130:133], v[6:9]
	v_mfma_f32_16x16x32_bf16 v[10:13], v[154:157], v[130:133], v[10:13]
	v_mfma_f32_16x16x32_bf16 v[14:17], v[158:161], v[130:133], v[14:17]
	v_mfma_f32_16x16x32_bf16 v[18:21], v[146:149], v[134:137], v[18:21]
	v_mfma_f32_16x16x32_bf16 v[22:25], v[150:153], v[134:137], v[22:25]
	v_mfma_f32_16x16x32_bf16 v[26:29], v[154:157], v[134:137], v[26:29]
	v_mfma_f32_16x16x32_bf16 v[30:33], v[158:161], v[134:137], v[30:33]
	v_mfma_f32_16x16x32_bf16 v[34:37], v[146:149], v[138:141], v[34:37]
	v_mfma_f32_16x16x32_bf16 v[38:41], v[150:153], v[138:141], v[38:41]
	v_mfma_f32_16x16x32_bf16 v[42:45], v[154:157], v[138:141], v[42:45]
	v_mfma_f32_16x16x32_bf16 v[46:49], v[158:161], v[138:141], v[46:49]
	v_mfma_f32_16x16x32_bf16 v[50:53], v[146:149], v[142:145], v[50:53]
	v_mfma_f32_16x16x32_bf16 v[54:57], v[150:153], v[142:145], v[54:57]
	v_mfma_f32_16x16x32_bf16 v[58:61], v[154:157], v[142:145], v[58:61]
	v_mfma_f32_16x16x32_bf16 v[62:65], v[158:161], v[142:145], v[62:65]
	v_mfma_f32_16x16x32_bf16 v[2:5], v[228:231], v[212:215], v[2:5]
	v_mfma_f32_16x16x32_bf16 v[6:9], v[232:235], v[212:215], v[6:9]
	v_mfma_f32_16x16x32_bf16 v[10:13], v[236:239], v[212:215], v[10:13]
	v_mfma_f32_16x16x32_bf16 v[14:17], v[240:243], v[212:215], v[14:17]
	v_mfma_f32_16x16x32_bf16 v[18:21], v[228:231], v[216:219], v[18:21]
	v_mfma_f32_16x16x32_bf16 v[22:25], v[232:235], v[216:219], v[22:25]
	v_mfma_f32_16x16x32_bf16 v[26:29], v[236:239], v[216:219], v[26:29]
	v_mfma_f32_16x16x32_bf16 v[30:33], v[240:243], v[216:219], v[30:33]
	v_mfma_f32_16x16x32_bf16 v[34:37], v[228:231], v[220:223], v[34:37]
	v_mfma_f32_16x16x32_bf16 v[38:41], v[232:235], v[220:223], v[38:41]
	v_mfma_f32_16x16x32_bf16 v[42:45], v[236:239], v[220:223], v[42:45]
	v_mfma_f32_16x16x32_bf16 v[46:49], v[240:243], v[220:223], v[46:49]
	v_mfma_f32_16x16x32_bf16 v[50:53], v[228:231], v[224:227], v[50:53]
	v_mfma_f32_16x16x32_bf16 v[54:57], v[232:235], v[224:227], v[54:57]
	v_mfma_f32_16x16x32_bf16 v[58:61], v[236:239], v[224:227], v[58:61]
	v_mfma_f32_16x16x32_bf16 v[62:65], v[240:243], v[224:227], v[62:65]
	s_waitcnt vmcnt(6)
	s_barrier
	v_add_u32_e32 v204, 0x0, v200
	v_add_u32_e32 v205, 0x0, v202
	ds_read_b128 v[130:133], v204 offset:0
	ds_read_b128 v[134:137], v204 offset:2048
	ds_read_b128 v[138:141], v204 offset:4096
	ds_read_b128 v[142:145], v204 offset:6144
	ds_read_b128 v[146:149], v205 offset:0
	ds_read_b128 v[150:153], v205 offset:2048
	ds_read_b128 v[154:157], v205 offset:4096
	ds_read_b128 v[158:161], v205 offset:6144
	v_add_u32_e32 v204, 0x0, v201
	v_add_u32_e32 v205, 0x0, v203
	ds_read_b128 v[212:215], v204 offset:0
	ds_read_b128 v[216:219], v204 offset:2048
	ds_read_b128 v[220:223], v204 offset:4096
	ds_read_b128 v[224:227], v204 offset:6144
	ds_read_b128 v[228:231], v205 offset:0
	ds_read_b128 v[232:235], v205 offset:2048
	ds_read_b128 v[236:239], v205 offset:4096
	ds_read_b128 v[240:243], v205 offset:6144
	s_add_u32 m0, s76, 0x18000
	s_nop 0
	global_load_lds_dwordx4 v196, s[68:69]
	s_add_u32 m0, s76, 0x1a000
	s_nop 0
	global_load_lds_dwordx4 v197, s[68:69]
	s_add_u32 m0, s76, 0x1c000
	s_nop 0
	global_load_lds_dwordx4 v198, s[68:69]
	s_add_u32 m0, s76, 0x1e000
	s_nop 0
	global_load_lds_dwordx4 v199, s[68:69]
	s_add_u32 m0, s76, 0x20000
	s_nop 0
	global_load_lds_dwordx4 v196, s[70:71]
	s_add_u32 m0, s76, 0x22000
	s_nop 0
	global_load_lds_dwordx4 v197, s[70:71]
	s_add_u32 s68, s68, 0x80
	s_addc_u32 s69, s69, 0
	s_add_u32 s70, s70, 0x80
	s_addc_u32 s71, s71, 0
	s_waitcnt lgkmcnt(0)
	s_barrier
	v_mfma_f32_16x16x32_bf16 v[2:5], v[146:149], v[130:133], v[2:5]
	v_mfma_f32_16x16x32_bf16 v[6:9], v[150:153], v[130:133], v[6:9]
	v_mfma_f32_16x16x32_bf16 v[10:13], v[154:157], v[130:133], v[10:13]
	v_mfma_f32_16x16x32_bf16 v[14:17], v[158:161], v[130:133], v[14:17]
	v_mfma_f32_16x16x32_bf16 v[18:21], v[146:149], v[134:137], v[18:21]
	v_mfma_f32_16x16x32_bf16 v[22:25], v[150:153], v[134:137], v[22:25]
	v_mfma_f32_16x16x32_bf16 v[26:29], v[154:157], v[134:137], v[26:29]
	v_mfma_f32_16x16x32_bf16 v[30:33], v[158:161], v[134:137], v[30:33]
	v_mfma_f32_16x16x32_bf16 v[34:37], v[146:149], v[138:141], v[34:37]
	v_mfma_f32_16x16x32_bf16 v[38:41], v[150:153], v[138:141], v[38:41]
	v_mfma_f32_16x16x32_bf16 v[42:45], v[154:157], v[138:141], v[42:45]
	v_mfma_f32_16x16x32_bf16 v[46:49], v[158:161], v[138:141], v[46:49]
	v_mfma_f32_16x16x32_bf16 v[50:53], v[146:149], v[142:145], v[50:53]
	v_mfma_f32_16x16x32_bf16 v[54:57], v[150:153], v[142:145], v[54:57]
	v_mfma_f32_16x16x32_bf16 v[58:61], v[154:157], v[142:145], v[58:61]
	v_mfma_f32_16x16x32_bf16 v[62:65], v[158:161], v[142:145], v[62:65]
	v_mfma_f32_16x16x32_bf16 v[2:5], v[228:231], v[212:215], v[2:5]
	v_mfma_f32_16x16x32_bf16 v[6:9], v[232:235], v[212:215], v[6:9]
	v_mfma_f32_16x16x32_bf16 v[10:13], v[236:239], v[212:215], v[10:13]
	v_mfma_f32_16x16x32_bf16 v[14:17], v[240:243], v[212:215], v[14:17]
	v_mfma_f32_16x16x32_bf16 v[18:21], v[228:231], v[216:219], v[18:21]
	v_mfma_f32_16x16x32_bf16 v[22:25], v[232:235], v[216:219], v[22:25]
	v_mfma_f32_16x16x32_bf16 v[26:29], v[236:239], v[216:219], v[26:29]
	v_mfma_f32_16x16x32_bf16 v[30:33], v[240:243], v[216:219], v[30:33]
	v_mfma_f32_16x16x32_bf16 v[34:37], v[228:231], v[220:223], v[34:37]
	v_mfma_f32_16x16x32_bf16 v[38:41], v[232:235], v[220:223], v[38:41]
	v_mfma_f32_16x16x32_bf16 v[42:45], v[236:239], v[220:223], v[42:45]
	v_mfma_f32_16x16x32_bf16 v[46:49], v[240:243], v[220:223], v[46:49]
	v_mfma_f32_16x16x32_bf16 v[50:53], v[228:231], v[224:227], v[50:53]
	v_mfma_f32_16x16x32_bf16 v[54:57], v[232:235], v[224:227], v[54:57]
	v_mfma_f32_16x16x32_bf16 v[58:61], v[236:239], v[224:227], v[58:61]
	v_mfma_f32_16x16x32_bf16 v[62:65], v[240:243], v[224:227], v[62:65]
	s_nop 7
	v_lshlrev_b32_e32 v212, 16, v174
	v_and_b32_e32 v213, 0xffff0000, v174
	v_lshlrev_b32_e32 v214, 16, v175
	v_and_b32_e32 v215, 0xffff0000, v175
	v_pk_fma_f32 v[66:67], v[2:3], v[212:213], v[66:67]
	v_pk_fma_f32 v[68:69], v[4:5], v[214:215], v[68:69]
	v_lshlrev_b32_e32 v216, 16, v176
	v_and_b32_e32 v217, 0xffff0000, v176
	v_lshlrev_b32_e32 v218, 16, v177
	v_and_b32_e32 v219, 0xffff0000, v177
	v_pk_fma_f32 v[70:71], v[6:7], v[216:217], v[70:71]
	v_pk_fma_f32 v[72:73], v[8:9], v[218:219], v[72:73]
	v_lshlrev_b32_e32 v220, 16, v178
	v_and_b32_e32 v221, 0xffff0000, v178
	v_lshlrev_b32_e32 v222, 16, v179
	v_and_b32_e32 v223, 0xffff0000, v179
	v_pk_fma_f32 v[74:75], v[10:11], v[220:221], v[74:75]
	v_pk_fma_f32 v[76:77], v[12:13], v[222:223], v[76:77]
	v_lshlrev_b32_e32 v224, 16, v180
	v_and_b32_e32 v225, 0xffff0000, v180
	v_lshlrev_b32_e32 v226, 16, v181
	v_and_b32_e32 v227, 0xffff0000, v181
	v_pk_fma_f32 v[78:79], v[14:15], v[224:225], v[78:79]
	v_pk_fma_f32 v[80:81], v[16:17], v[226:227], v[80:81]
	v_lshlrev_b32_e32 v228, 16, v182
	v_and_b32_e32 v229, 0xffff0000, v182
	v_lshlrev_b32_e32 v230, 16, v183
	v_and_b32_e32 v231, 0xffff0000, v183
	v_pk_fma_f32 v[82:83], v[18:19], v[228:229], v[82:83]
	v_pk_fma_f32 v[84:85], v[20:21], v[230:231], v[84:85]
	v_lshlrev_b32_e32 v232, 16, v184
	v_and_b32_e32 v233, 0xffff0000, v184
	v_lshlrev_b32_e32 v234, 16, v185
	v_and_b32_e32 v235, 0xffff0000, v185
	v_pk_fma_f32 v[86:87], v[22:23], v[232:233], v[86:87]
	v_pk_fma_f32 v[88:89], v[24:25], v[234:235], v[88:89]
	v_lshlrev_b32_e32 v236, 16, v186
	v_and_b32_e32 v237, 0xffff0000, v186
	v_lshlrev_b32_e32 v238, 16, v187
	v_and_b32_e32 v239, 0xffff0000, v187
	v_pk_fma_f32 v[90:91], v[26:27], v[236:237], v[90:91]
	v_pk_fma_f32 v[92:93], v[28:29], v[238:239], v[92:93]
	v_lshlrev_b32_e32 v240, 16, v188
	v_and_b32_e32 v241, 0xffff0000, v188
	v_lshlrev_b32_e32 v242, 16, v189
	v_and_b32_e32 v243, 0xffff0000, v189
	v_pk_fma_f32 v[94:95], v[30:31], v[240:241], v[94:95]
	v_pk_fma_f32 v[96:97], v[32:33], v[242:243], v[96:97]
	v_lshlrev_b32_e32 v212, 16, v190
	v_and_b32_e32 v213, 0xffff0000, v190
	v_lshlrev_b32_e32 v214, 16, v191
	v_and_b32_e32 v215, 0xffff0000, v191
	v_pk_fma_f32 v[98:99], v[34:35], v[212:213], v[98:99]
	v_pk_fma_f32 v[100:101], v[36:37], v[214:215], v[100:101]
	v_lshlrev_b32_e32 v216, 16, v192
	v_and_b32_e32 v217, 0xffff0000, v192
	v_lshlrev_b32_e32 v218, 16, v193
	v_and_b32_e32 v219, 0xffff0000, v193
	v_pk_fma_f32 v[102:103], v[38:39], v[216:217], v[102:103]
	v_pk_fma_f32 v[104:105], v[40:41], v[218:219], v[104:105]
	v_lshlrev_b32_e32 v220, 16, v244
	v_and_b32_e32 v221, 0xffff0000, v244
	v_lshlrev_b32_e32 v222, 16, v245
	v_and_b32_e32 v223, 0xffff0000, v245
	v_pk_fma_f32 v[106:107], v[42:43], v[220:221], v[106:107]
	v_pk_fma_f32 v[108:109], v[44:45], v[222:223], v[108:109]
	v_lshlrev_b32_e32 v224, 16, v246
	v_and_b32_e32 v225, 0xffff0000, v246
	v_lshlrev_b32_e32 v226, 16, v247
	v_and_b32_e32 v227, 0xffff0000, v247
	v_pk_fma_f32 v[110:111], v[46:47], v[224:225], v[110:111]
	v_pk_fma_f32 v[112:113], v[48:49], v[226:227], v[112:113]
	v_lshlrev_b32_e32 v228, 16, v248
	v_and_b32_e32 v229, 0xffff0000, v248
	v_lshlrev_b32_e32 v230, 16, v249
	v_and_b32_e32 v231, 0xffff0000, v249
	v_pk_fma_f32 v[114:115], v[50:51], v[228:229], v[114:115]
	v_pk_fma_f32 v[116:117], v[52:53], v[230:231], v[116:117]
	v_lshlrev_b32_e32 v232, 16, v250
	v_and_b32_e32 v233, 0xffff0000, v250
	v_lshlrev_b32_e32 v234, 16, v251
	v_and_b32_e32 v235, 0xffff0000, v251
	v_pk_fma_f32 v[118:119], v[54:55], v[232:233], v[118:119]
	v_pk_fma_f32 v[120:121], v[56:57], v[234:235], v[120:121]
	v_lshlrev_b32_e32 v236, 16, v166
	v_and_b32_e32 v237, 0xffff0000, v166
	v_lshlrev_b32_e32 v238, 16, v167
	v_and_b32_e32 v239, 0xffff0000, v167
	v_pk_fma_f32 v[122:123], v[58:59], v[236:237], v[122:123]
	v_pk_fma_f32 v[124:125], v[60:61], v[238:239], v[124:125]
	v_lshlrev_b32_e32 v240, 16, v194
	v_and_b32_e32 v241, 0xffff0000, v194
	v_lshlrev_b32_e32 v242, 16, v195
	v_and_b32_e32 v243, 0xffff0000, v195
	v_pk_fma_f32 v[126:127], v[62:63], v[240:241], v[126:127]
	v_pk_fma_f32 v[128:129], v[64:65], v[242:243], v[128:129]
	s_waitcnt vmcnt(6)
	s_barrier
	v_add_u32_e32 v204, 0xc000, v200
	v_add_u32_e32 v205, 0xc000, v202
	ds_read_b128 v[130:133], v204 offset:0
	ds_read_b128 v[134:137], v204 offset:2048
	ds_read_b128 v[138:141], v204 offset:4096
	ds_read_b128 v[142:145], v204 offset:6144
	ds_read_b128 v[146:149], v205 offset:0
	ds_read_b128 v[150:153], v205 offset:2048
	ds_read_b128 v[154:157], v205 offset:4096
	ds_read_b128 v[158:161], v205 offset:6144
	v_add_u32_e32 v204, 0xc000, v201
	v_add_u32_e32 v205, 0xc000, v203
	ds_read_b128 v[212:215], v204 offset:0
	ds_read_b128 v[216:219], v204 offset:2048
	ds_read_b128 v[220:223], v204 offset:4096
	ds_read_b128 v[224:227], v204 offset:6144
	ds_read_b128 v[228:231], v205 offset:0
	ds_read_b128 v[232:235], v205 offset:2048
	ds_read_b128 v[236:239], v205 offset:4096
	ds_read_b128 v[240:243], v205 offset:6144
	s_add_u32 m0, s76, 0x0
	s_nop 0
	global_load_lds_dwordx4 v196, s[68:69]
	s_add_u32 m0, s76, 0x2000
	s_nop 0
	global_load_lds_dwordx4 v197, s[68:69]
	s_add_u32 m0, s76, 0x4000
	s_nop 0
	global_load_lds_dwordx4 v198, s[68:69]
	s_add_u32 m0, s76, 0x6000
	s_nop 0
	global_load_lds_dwordx4 v199, s[68:69]
	s_add_u32 m0, s76, 0x8000
	s_nop 0
	global_load_lds_dwordx4 v196, s[70:71]
	s_add_u32 m0, s76, 0xa000
	s_nop 0
	global_load_lds_dwordx4 v197, s[70:71]
	s_add_u32 s68, s68, 0x80
	s_addc_u32 s69, s69, 0
	s_add_u32 s70, s70, 0x80
	s_addc_u32 s71, s71, 0
	global_load_dwordx2 v[174:175], v206, s[72:73] offset:0
	global_load_dwordx2 v[176:177], v206, s[72:73] offset:32
	global_load_dwordx2 v[178:179], v206, s[72:73] offset:64
	global_load_dwordx2 v[180:181], v206, s[72:73] offset:96
	global_load_dwordx2 v[182:183], v207, s[72:73] offset:0
	global_load_dwordx2 v[184:185], v207, s[72:73] offset:32
	s_waitcnt lgkmcnt(0)
	s_barrier
	v_mfma_f32_16x16x32_bf16 v[2:5], v[146:149], v[130:133], 0
	v_mfma_f32_16x16x32_bf16 v[6:9], v[150:153], v[130:133], 0
	v_mfma_f32_16x16x32_bf16 v[10:13], v[154:157], v[130:133], 0
	v_mfma_f32_16x16x32_bf16 v[14:17], v[158:161], v[130:133], 0
	v_mfma_f32_16x16x32_bf16 v[18:21], v[146:149], v[134:137], 0
	v_mfma_f32_16x16x32_bf16 v[22:25], v[150:153], v[134:137], 0
	v_mfma_f32_16x16x32_bf16 v[26:29], v[154:157], v[134:137], 0
	v_mfma_f32_16x16x32_bf16 v[30:33], v[158:161], v[134:137], 0
	v_mfma_f32_16x16x32_bf16 v[34:37], v[146:149], v[138:141], 0
	v_mfma_f32_16x16x32_bf16 v[38:41], v[150:153], v[138:141], 0
	v_mfma_f32_16x16x32_bf16 v[42:45], v[154:157], v[138:141], 0
	v_mfma_f32_16x16x32_bf16 v[46:49], v[158:161], v[138:141], 0
	v_mfma_f32_16x16x32_bf16 v[50:53], v[146:149], v[142:145], 0
	v_mfma_f32_16x16x32_bf16 v[54:57], v[150:153], v[142:145], 0
	v_mfma_f32_16x16x32_bf16 v[58:61], v[154:157], v[142:145], 0
	v_mfma_f32_16x16x32_bf16 v[62:65], v[158:161], v[142:145], 0
	v_mfma_f32_16x16x32_bf16 v[2:5], v[228:231], v[212:215], v[2:5]
	v_mfma_f32_16x16x32_bf16 v[6:9], v[232:235], v[212:215], v[6:9]
	v_mfma_f32_16x16x32_bf16 v[10:13], v[236:239], v[212:215], v[10:13]
	v_mfma_f32_16x16x32_bf16 v[14:17], v[240:243], v[212:215], v[14:17]
	v_mfma_f32_16x16x32_bf16 v[18:21], v[228:231], v[216:219], v[18:21]
	v_mfma_f32_16x16x32_bf16 v[22:25], v[232:235], v[216:219], v[22:25]
	v_mfma_f32_16x16x32_bf16 v[26:29], v[236:239], v[216:219], v[26:29]
	v_mfma_f32_16x16x32_bf16 v[30:33], v[240:243], v[216:219], v[30:33]
	v_mfma_f32_16x16x32_bf16 v[34:37], v[228:231], v[220:223], v[34:37]
	v_mfma_f32_16x16x32_bf16 v[38:41], v[232:235], v[220:223], v[38:41]
	v_mfma_f32_16x16x32_bf16 v[42:45], v[236:239], v[220:223], v[42:45]
	v_mfma_f32_16x16x32_bf16 v[46:49], v[240:243], v[220:223], v[46:49]
	v_mfma_f32_16x16x32_bf16 v[50:53], v[228:231], v[224:227], v[50:53]
	v_mfma_f32_16x16x32_bf16 v[54:57], v[232:235], v[224:227], v[54:57]
	v_mfma_f32_16x16x32_bf16 v[58:61], v[236:239], v[224:227], v[58:61]
	v_mfma_f32_16x16x32_bf16 v[62:65], v[240:243], v[224:227], v[62:65]
	s_waitcnt vmcnt(12)
	s_barrier
	v_add_u32_e32 v204, 0x18000, v200
	v_add_u32_e32 v205, 0x18000, v202
	ds_read_b128 v[130:133], v204 offset:0
	ds_read_b128 v[134:137], v204 offset:2048
	ds_read_b128 v[138:141], v204 offset:4096
	ds_read_b128 v[142:145], v204 offset:6144
	ds_read_b128 v[146:149], v205 offset:0
	ds_read_b128 v[150:153], v205 offset:2048
	ds_read_b128 v[154:157], v205 offset:4096
	ds_read_b128 v[158:161], v205 offset:6144
	v_add_u32_e32 v204, 0x18000, v201
	v_add_u32_e32 v205, 0x18000, v203
	ds_read_b128 v[212:215], v204 offset:0
	ds_read_b128 v[216:219], v204 offset:2048
	ds_read_b128 v[220:223], v204 offset:4096
	ds_read_b128 v[224:227], v204 offset:6144
	ds_read_b128 v[228:231], v205 offset:0
	ds_read_b128 v[232:235], v205 offset:2048
	ds_read_b128 v[236:239], v205 offset:4096
	ds_read_b128 v[240:243], v205 offset:6144
	s_add_u32 m0, s76, 0xc000
	s_nop 0
	global_load_lds_dwordx4 v196, s[68:69]
	s_add_u32 m0, s76, 0xe000
	s_nop 0
	global_load_lds_dwordx4 v197, s[68:69]
	s_add_u32 m0, s76, 0x10000
	s_nop 0
	global_load_lds_dwordx4 v198, s[68:69]
	s_add_u32 m0, s76, 0x12000
	s_nop 0
	global_load_lds_dwordx4 v199, s[68:69]
	s_add_u32 m0, s76, 0x14000
	s_nop 0
	global_load_lds_dwordx4 v196, s[70:71]
	s_add_u32 m0, s76, 0x16000
	s_nop 0
	global_load_lds_dwordx4 v197, s[70:71]
	s_add_u32 s68, s68, 0x80
	s_addc_u32 s69, s69, 0
	s_add_u32 s70, s70, 0x80
	s_addc_u32 s71, s71, 0
	global_load_dwordx2 v[186:187], v207, s[72:73] offset:64
	global_load_dwordx2 v[188:189], v207, s[72:73] offset:96
	global_load_dwordx2 v[190:191], v208, s[72:73] offset:0
	global_load_dwordx2 v[192:193], v208, s[72:73] offset:32
	global_load_dwordx2 v[244:245], v208, s[72:73] offset:64
	global_load_dwordx2 v[246:247], v208, s[72:73] offset:96
	s_waitcnt lgkmcnt(0)
	s_barrier
	v_mfma_f32_16x16x32_bf16 v[2:5], v[146:149], v[130:133], v[2:5]
	v_mfma_f32_16x16x32_bf16 v[6:9], v[150:153], v[130:133], v[6:9]
	v_mfma_f32_16x16x32_bf16 v[10:13], v[154:157], v[130:133], v[10:13]
	v_mfma_f32_16x16x32_bf16 v[14:17], v[158:161], v[130:133], v[14:17]
	v_mfma_f32_16x16x32_bf16 v[18:21], v[146:149], v[134:137], v[18:21]
	v_mfma_f32_16x16x32_bf16 v[22:25], v[150:153], v[134:137], v[22:25]
	v_mfma_f32_16x16x32_bf16 v[26:29], v[154:157], v[134:137], v[26:29]
	v_mfma_f32_16x16x32_bf16 v[30:33], v[158:161], v[134:137], v[30:33]
	v_mfma_f32_16x16x32_bf16 v[34:37], v[146:149], v[138:141], v[34:37]
	v_mfma_f32_16x16x32_bf16 v[38:41], v[150:153], v[138:141], v[38:41]
	v_mfma_f32_16x16x32_bf16 v[42:45], v[154:157], v[138:141], v[42:45]
	v_mfma_f32_16x16x32_bf16 v[46:49], v[158:161], v[138:141], v[46:49]
	v_mfma_f32_16x16x32_bf16 v[50:53], v[146:149], v[142:145], v[50:53]
	v_mfma_f32_16x16x32_bf16 v[54:57], v[150:153], v[142:145], v[54:57]
	v_mfma_f32_16x16x32_bf16 v[58:61], v[154:157], v[142:145], v[58:61]
	v_mfma_f32_16x16x32_bf16 v[62:65], v[158:161], v[142:145], v[62:65]
	v_mfma_f32_16x16x32_bf16 v[2:5], v[228:231], v[212:215], v[2:5]
	v_mfma_f32_16x16x32_bf16 v[6:9], v[232:235], v[212:215], v[6:9]
	v_mfma_f32_16x16x32_bf16 v[10:13], v[236:239], v[212:215], v[10:13]
	v_mfma_f32_16x16x32_bf16 v[14:17], v[240:243], v[212:215], v[14:17]
	v_mfma_f32_16x16x32_bf16 v[18:21], v[228:231], v[216:219], v[18:21]
	v_mfma_f32_16x16x32_bf16 v[22:25], v[232:235], v[216:219], v[22:25]
	v_mfma_f32_16x16x32_bf16 v[26:29], v[236:239], v[216:219], v[26:29]
	v_mfma_f32_16x16x32_bf16 v[30:33], v[240:243], v[216:219], v[30:33]
	v_mfma_f32_16x16x32_bf16 v[34:37], v[228:231], v[220:223], v[34:37]
	v_mfma_f32_16x16x32_bf16 v[38:41], v[232:235], v[220:223], v[38:41]
	v_mfma_f32_16x16x32_bf16 v[42:45], v[236:239], v[220:223], v[42:45]
	v_mfma_f32_16x16x32_bf16 v[46:49], v[240:243], v[220:223], v[46:49]
	v_mfma_f32_16x16x32_bf16 v[50:53], v[228:231], v[224:227], v[50:53]
	v_mfma_f32_16x16x32_bf16 v[54:57], v[232:235], v[224:227], v[54:57]
	v_mfma_f32_16x16x32_bf16 v[58:61], v[236:239], v[224:227], v[58:61]
	v_mfma_f32_16x16x32_bf16 v[62:65], v[240:243], v[224:227], v[62:65]
	s_waitcnt vmcnt(18)
	s_barrier
	v_add_u32_e32 v204, 0x0, v200
	v_add_u32_e32 v205, 0x0, v202
	ds_read_b128 v[130:133], v204 offset:0
	ds_read_b128 v[134:137], v204 offset:2048
	ds_read_b128 v[138:141], v204 offset:4096
	ds_read_b128 v[142:145], v204 offset:6144
	ds_read_b128 v[146:149], v205 offset:0
	ds_read_b128 v[150:153], v205 offset:2048
	ds_read_b128 v[154:157], v205 offset:4096
	ds_read_b128 v[158:161], v205 offset:6144
	v_add_u32_e32 v204, 0x0, v201
	v_add_u32_e32 v205, 0x0, v203
	ds_read_b128 v[212:215], v204 offset:0
	ds_read_b128 v[216:219], v204 offset:2048
	ds_read_b128 v[220:223], v204 offset:4096
	ds_read_b128 v[224:227], v204 offset:6144
	ds_read_b128 v[228:231], v205 offset:0
	ds_read_b128 v[232:235], v205 offset:2048
	ds_read_b128 v[236:239], v205 offset:4096
	ds_read_b128 v[240:243], v205 offset:6144
	s_add_u32 m0, s76, 0x18000
	s_nop 0
	global_load_lds_dwordx4 v196, s[68:69]
	s_add_u32 m0, s76, 0x1a000
	s_nop 0
	global_load_lds_dwordx4 v197, s[68:69]
	s_add_u32 m0, s76, 0x1c000
	s_nop 0
	global_load_lds_dwordx4 v198, s[68:69]
	s_add_u32 m0, s76, 0x1e000
	s_nop 0
	global_load_lds_dwordx4 v199, s[68:69]
	s_add_u32 m0, s76, 0x20000
	s_nop 0
	global_load_lds_dwordx4 v196, s[70:71]
	s_add_u32 m0, s76, 0x22000
	s_nop 0
	global_load_lds_dwordx4 v197, s[70:71]
	s_add_u32 s68, s68, 0x80
	s_addc_u32 s69, s69, 0
	s_add_u32 s70, s70, 0x80
	s_addc_u32 s71, s71, 0
	global_load_dwordx2 v[248:249], v209, s[72:73] offset:0
	global_load_dwordx2 v[250:251], v209, s[72:73] offset:32
	global_load_dwordx2 v[166:167], v209, s[72:73] offset:64
	global_load_dwordx2 v[194:195], v209, s[72:73] offset:96
	s_add_u32 s72, s72, 0x800
	s_addc_u32 s73, s73, 0
	s_waitcnt lgkmcnt(0)
	s_barrier
	v_mfma_f32_16x16x32_bf16 v[2:5], v[146:149], v[130:133], v[2:5]
	v_mfma_f32_16x16x32_bf16 v[6:9], v[150:153], v[130:133], v[6:9]
	v_mfma_f32_16x16x32_bf16 v[10:13], v[154:157], v[130:133], v[10:13]
	v_mfma_f32_16x16x32_bf16 v[14:17], v[158:161], v[130:133], v[14:17]
	v_mfma_f32_16x16x32_bf16 v[18:21], v[146:149], v[134:137], v[18:21]
	v_mfma_f32_16x16x32_bf16 v[22:25], v[150:153], v[134:137], v[22:25]
	v_mfma_f32_16x16x32_bf16 v[26:29], v[154:157], v[134:137], v[26:29]
	v_mfma_f32_16x16x32_bf16 v[30:33], v[158:161], v[134:137], v[30:33]
	v_mfma_f32_16x16x32_bf16 v[34:37], v[146:149], v[138:141], v[34:37]
	v_mfma_f32_16x16x32_bf16 v[38:41], v[150:153], v[138:141], v[38:41]
	v_mfma_f32_16x16x32_bf16 v[42:45], v[154:157], v[138:141], v[42:45]
	v_mfma_f32_16x16x32_bf16 v[46:49], v[158:161], v[138:141], v[46:49]
	v_mfma_f32_16x16x32_bf16 v[50:53], v[146:149], v[142:145], v[50:53]
	v_mfma_f32_16x16x32_bf16 v[54:57], v[150:153], v[142:145], v[54:57]
	v_mfma_f32_16x16x32_bf16 v[58:61], v[154:157], v[142:145], v[58:61]
	v_mfma_f32_16x16x32_bf16 v[62:65], v[158:161], v[142:145], v[62:65]
	v_mfma_f32_16x16x32_bf16 v[2:5], v[228:231], v[212:215], v[2:5]
	v_mfma_f32_16x16x32_bf16 v[6:9], v[232:235], v[212:215], v[6:9]
	v_mfma_f32_16x16x32_bf16 v[10:13], v[236:239], v[212:215], v[10:13]
	v_mfma_f32_16x16x32_bf16 v[14:17], v[240:243], v[212:215], v[14:17]
	v_mfma_f32_16x16x32_bf16 v[18:21], v[228:231], v[216:219], v[18:21]
	v_mfma_f32_16x16x32_bf16 v[22:25], v[232:235], v[216:219], v[22:25]
	v_mfma_f32_16x16x32_bf16 v[26:29], v[236:239], v[216:219], v[26:29]
	v_mfma_f32_16x16x32_bf16 v[30:33], v[240:243], v[216:219], v[30:33]
	v_mfma_f32_16x16x32_bf16 v[34:37], v[228:231], v[220:223], v[34:37]
	v_mfma_f32_16x16x32_bf16 v[38:41], v[232:235], v[220:223], v[38:41]
	v_mfma_f32_16x16x32_bf16 v[42:45], v[236:239], v[220:223], v[42:45]
	v_mfma_f32_16x16x32_bf16 v[46:49], v[240:243], v[220:223], v[46:49]
	v_mfma_f32_16x16x32_bf16 v[50:53], v[228:231], v[224:227], v[50:53]
	v_mfma_f32_16x16x32_bf16 v[54:57], v[232:235], v[224:227], v[54:57]
	v_mfma_f32_16x16x32_bf16 v[58:61], v[236:239], v[224:227], v[58:61]
	v_mfma_f32_16x16x32_bf16 v[62:65], v[240:243], v[224:227], v[62:65]
	s_waitcnt vmcnt(16)
	s_barrier
	v_add_u32_e32 v204, 0xc000, v200
	v_add_u32_e32 v205, 0xc000, v202
	ds_read_b128 v[130:133], v204 offset:0
	ds_read_b128 v[134:137], v204 offset:2048
	ds_read_b128 v[138:141], v204 offset:4096
	ds_read_b128 v[142:145], v204 offset:6144
	ds_read_b128 v[146:149], v205 offset:0
	ds_read_b128 v[150:153], v205 offset:2048
	ds_read_b128 v[154:157], v205 offset:4096
	ds_read_b128 v[158:161], v205 offset:6144
	v_add_u32_e32 v204, 0xc000, v201
	v_add_u32_e32 v205, 0xc000, v203
	ds_read_b128 v[212:215], v204 offset:0
	ds_read_b128 v[216:219], v204 offset:2048
	ds_read_b128 v[220:223], v204 offset:4096
	ds_read_b128 v[224:227], v204 offset:6144
	ds_read_b128 v[228:231], v205 offset:0
	ds_read_b128 v[232:235], v205 offset:2048
	ds_read_b128 v[236:239], v205 offset:4096
	ds_read_b128 v[240:243], v205 offset:6144
	s_add_u32 m0, s76, 0x0
	s_nop 0
	global_load_lds_dwordx4 v196, s[68:69]
	s_add_u32 m0, s76, 0x2000
	s_nop 0
	global_load_lds_dwordx4 v197, s[68:69]
	s_add_u32 m0, s76, 0x4000
	s_nop 0
	global_load_lds_dwordx4 v198, s[68:69]
	s_add_u32 m0, s76, 0x6000
	s_nop 0
	global_load_lds_dwordx4 v199, s[68:69]
	s_add_u32 m0, s76, 0x8000
	s_nop 0
	global_load_lds_dwordx4 v196, s[70:71]
	s_add_u32 m0, s76, 0xa000
	s_nop 0
	global_load_lds_dwordx4 v197, s[70:71]
	s_add_u32 s68, s68, 0x80
	s_addc_u32 s69, s69, 0
	s_add_u32 s70, s70, 0x80
	s_addc_u32 s71, s71, 0
	s_waitcnt lgkmcnt(0)
	s_barrier
	v_mfma_f32_16x16x32_bf16 v[2:5], v[146:149], v[130:133], v[2:5]
	v_mfma_f32_16x16x32_bf16 v[6:9], v[150:153], v[130:133], v[6:9]
	v_mfma_f32_16x16x32_bf16 v[10:13], v[154:157], v[130:133], v[10:13]
	v_mfma_f32_16x16x32_bf16 v[14:17], v[158:161], v[130:133], v[14:17]
	v_mfma_f32_16x16x32_bf16 v[18:21], v[146:149], v[134:137], v[18:21]
	v_mfma_f32_16x16x32_bf16 v[22:25], v[150:153], v[134:137], v[22:25]
	v_mfma_f32_16x16x32_bf16 v[26:29], v[154:157], v[134:137], v[26:29]
	v_mfma_f32_16x16x32_bf16 v[30:33], v[158:161], v[134:137], v[30:33]
	v_mfma_f32_16x16x32_bf16 v[34:37], v[146:149], v[138:141], v[34:37]
	v_mfma_f32_16x16x32_bf16 v[38:41], v[150:153], v[138:141], v[38:41]
	v_mfma_f32_16x16x32_bf16 v[42:45], v[154:157], v[138:141], v[42:45]
	v_mfma_f32_16x16x32_bf16 v[46:49], v[158:161], v[138:141], v[46:49]
	v_mfma_f32_16x16x32_bf16 v[50:53], v[146:149], v[142:145], v[50:53]
	v_mfma_f32_16x16x32_bf16 v[54:57], v[150:153], v[142:145], v[54:57]
	v_mfma_f32_16x16x32_bf16 v[58:61], v[154:157], v[142:145], v[58:61]
	v_mfma_f32_16x16x32_bf16 v[62:65], v[158:161], v[142:145], v[62:65]
	v_mfma_f32_16x16x32_bf16 v[2:5], v[228:231], v[212:215], v[2:5]
	v_mfma_f32_16x16x32_bf16 v[6:9], v[232:235], v[212:215], v[6:9]
	v_mfma_f32_16x16x32_bf16 v[10:13], v[236:239], v[212:215], v[10:13]
	v_mfma_f32_16x16x32_bf16 v[14:17], v[240:243], v[212:215], v[14:17]
	v_mfma_f32_16x16x32_bf16 v[18:21], v[228:231], v[216:219], v[18:21]
	v_mfma_f32_16x16x32_bf16 v[22:25], v[232:235], v[216:219], v[22:25]
	v_mfma_f32_16x16x32_bf16 v[26:29], v[236:239], v[216:219], v[26:29]
	v_mfma_f32_16x16x32_bf16 v[30:33], v[240:243], v[216:219], v[30:33]
	v_mfma_f32_16x16x32_bf16 v[34:37], v[228:231], v[220:223], v[34:37]
	v_mfma_f32_16x16x32_bf16 v[38:41], v[232:235], v[220:223], v[38:41]
	v_mfma_f32_16x16x32_bf16 v[42:45], v[236:239], v[220:223], v[42:45]
	v_mfma_f32_16x16x32_bf16 v[46:49], v[240:243], v[220:223], v[46:49]
	v_mfma_f32_16x16x32_bf16 v[50:53], v[228:231], v[224:227], v[50:53]
	v_mfma_f32_16x16x32_bf16 v[54:57], v[232:235], v[224:227], v[54:57]
	v_mfma_f32_16x16x32_bf16 v[58:61], v[236:239], v[224:227], v[58:61]
	v_mfma_f32_16x16x32_bf16 v[62:65], v[240:243], v[224:227], v[62:65]
	s_waitcnt vmcnt(10)
	s_barrier
	v_add_u32_e32 v204, 0x18000, v200
	v_add_u32_e32 v205, 0x18000, v202
	ds_read_b128 v[130:133], v204 offset:0
	ds_read_b128 v[134:137], v204 offset:2048
	ds_read_b128 v[138:141], v204 offset:4096
	ds_read_b128 v[142:145], v204 offset:6144
	ds_read_b128 v[146:149], v205 offset:0
	ds_read_b128 v[150:153], v205 offset:2048
	ds_read_b128 v[154:157], v205 offset:4096
	ds_read_b128 v[158:161], v205 offset:6144
	v_add_u32_e32 v204, 0x18000, v201
	v_add_u32_e32 v205, 0x18000, v203
	ds_read_b128 v[212:215], v204 offset:0
	ds_read_b128 v[216:219], v204 offset:2048
	ds_read_b128 v[220:223], v204 offset:4096
	ds_read_b128 v[224:227], v204 offset:6144
	ds_read_b128 v[228:231], v205 offset:0
	ds_read_b128 v[232:235], v205 offset:2048
	ds_read_b128 v[236:239], v205 offset:4096
	ds_read_b128 v[240:243], v205 offset:6144
	s_add_u32 m0, s76, 0xc000
	s_nop 0
	global_load_lds_dwordx4 v196, s[68:69]
	s_add_u32 m0, s76, 0xe000
	s_nop 0
	global_load_lds_dwordx4 v197, s[68:69]
	s_add_u32 m0, s76, 0x10000
	s_nop 0
	global_load_lds_dwordx4 v198, s[68:69]
	s_add_u32 m0, s76, 0x12000
	s_nop 0
	global_load_lds_dwordx4 v199, s[68:69]
	s_add_u32 m0, s76, 0x14000
	s_nop 0
	global_load_lds_dwordx4 v196, s[70:71]
	s_add_u32 m0, s76, 0x16000
	s_nop 0
	global_load_lds_dwordx4 v197, s[70:71]
	s_add_u32 s68, s68, 0x80
	s_addc_u32 s69, s69, 0
	s_add_u32 s70, s70, 0x80
	s_addc_u32 s71, s71, 0
	s_waitcnt lgkmcnt(0)
	s_barrier
	v_mfma_f32_16x16x32_bf16 v[2:5], v[146:149], v[130:133], v[2:5]
	v_mfma_f32_16x16x32_bf16 v[6:9], v[150:153], v[130:133], v[6:9]
	v_mfma_f32_16x16x32_bf16 v[10:13], v[154:157], v[130:133], v[10:13]
	v_mfma_f32_16x16x32_bf16 v[14:17], v[158:161], v[130:133], v[14:17]
	v_mfma_f32_16x16x32_bf16 v[18:21], v[146:149], v[134:137], v[18:21]
	v_mfma_f32_16x16x32_bf16 v[22:25], v[150:153], v[134:137], v[22:25]
	v_mfma_f32_16x16x32_bf16 v[26:29], v[154:157], v[134:137], v[26:29]
	v_mfma_f32_16x16x32_bf16 v[30:33], v[158:161], v[134:137], v[30:33]
	v_mfma_f32_16x16x32_bf16 v[34:37], v[146:149], v[138:141], v[34:37]
	v_mfma_f32_16x16x32_bf16 v[38:41], v[150:153], v[138:141], v[38:41]
	v_mfma_f32_16x16x32_bf16 v[42:45], v[154:157], v[138:141], v[42:45]
	v_mfma_f32_16x16x32_bf16 v[46:49], v[158:161], v[138:141], v[46:49]
	v_mfma_f32_16x16x32_bf16 v[50:53], v[146:149], v[142:145], v[50:53]
	v_mfma_f32_16x16x32_bf16 v[54:57], v[150:153], v[142:145], v[54:57]
	v_mfma_f32_16x16x32_bf16 v[58:61], v[154:157], v[142:145], v[58:61]
	v_mfma_f32_16x16x32_bf16 v[62:65], v[158:161], v[142:145], v[62:65]
	v_mfma_f32_16x16x32_bf16 v[2:5], v[228:231], v[212:215], v[2:5]
	v_mfma_f32_16x16x32_bf16 v[6:9], v[232:235], v[212:215], v[6:9]
	v_mfma_f32_16x16x32_bf16 v[10:13], v[236:239], v[212:215], v[10:13]
	v_mfma_f32_16x16x32_bf16 v[14:17], v[240:243], v[212:215], v[14:17]
	v_mfma_f32_16x16x32_bf16 v[18:21], v[228:231], v[216:219], v[18:21]
	v_mfma_f32_16x16x32_bf16 v[22:25], v[232:235], v[216:219], v[22:25]
	v_mfma_f32_16x16x32_bf16 v[26:29], v[236:239], v[216:219], v[26:29]
	v_mfma_f32_16x16x32_bf16 v[30:33], v[240:243], v[216:219], v[30:33]
	v_mfma_f32_16x16x32_bf16 v[34:37], v[228:231], v[220:223], v[34:37]
	v_mfma_f32_16x16x32_bf16 v[38:41], v[232:235], v[220:223], v[38:41]
	v_mfma_f32_16x16x32_bf16 v[42:45], v[236:239], v[220:223], v[42:45]
	v_mfma_f32_16x16x32_bf16 v[46:49], v[240:243], v[220:223], v[46:49]
	v_mfma_f32_16x16x32_bf16 v[50:53], v[228:231], v[224:227], v[50:53]
	v_mfma_f32_16x16x32_bf16 v[54:57], v[232:235], v[224:227], v[54:57]
	v_mfma_f32_16x16x32_bf16 v[58:61], v[236:239], v[224:227], v[58:61]
	v_mfma_f32_16x16x32_bf16 v[62:65], v[240:243], v[224:227], v[62:65]
	s_waitcnt vmcnt(6)
	s_barrier
	v_add_u32_e32 v204, 0x0, v200
	v_add_u32_e32 v205, 0x0, v202
	ds_read_b128 v[130:133], v204 offset:0
	ds_read_b128 v[134:137], v204 offset:2048
	ds_read_b128 v[138:141], v204 offset:4096
	ds_read_b128 v[142:145], v204 offset:6144
	ds_read_b128 v[146:149], v205 offset:0
	ds_read_b128 v[150:153], v205 offset:2048
	ds_read_b128 v[154:157], v205 offset:4096
	ds_read_b128 v[158:161], v205 offset:6144
	v_add_u32_e32 v204, 0x0, v201
	v_add_u32_e32 v205, 0x0, v203
	ds_read_b128 v[212:215], v204 offset:0
	ds_read_b128 v[216:219], v204 offset:2048
	ds_read_b128 v[220:223], v204 offset:4096
	ds_read_b128 v[224:227], v204 offset:6144
	ds_read_b128 v[228:231], v205 offset:0
	ds_read_b128 v[232:235], v205 offset:2048
	ds_read_b128 v[236:239], v205 offset:4096
	ds_read_b128 v[240:243], v205 offset:6144
	s_add_u32 m0, s76, 0x18000
	s_nop 0
	global_load_lds_dwordx4 v196, s[68:69]
	s_add_u32 m0, s76, 0x1a000
	s_nop 0
	global_load_lds_dwordx4 v197, s[68:69]
	s_add_u32 m0, s76, 0x1c000
	s_nop 0
	global_load_lds_dwordx4 v198, s[68:69]
	s_add_u32 m0, s76, 0x1e000
	s_nop 0
	global_load_lds_dwordx4 v199, s[68:69]
	s_add_u32 m0, s76, 0x20000
	s_nop 0
	global_load_lds_dwordx4 v196, s[70:71]
	s_add_u32 m0, s76, 0x22000
	s_nop 0
	global_load_lds_dwordx4 v197, s[70:71]
	s_add_u32 s68, s68, 0x80
	s_addc_u32 s69, s69, 0
	s_add_u32 s70, s70, 0x80
	s_addc_u32 s71, s71, 0
	s_waitcnt lgkmcnt(0)
	s_barrier
	v_mfma_f32_16x16x32_bf16 v[2:5], v[146:149], v[130:133], v[2:5]
	v_mfma_f32_16x16x32_bf16 v[6:9], v[150:153], v[130:133], v[6:9]
	v_mfma_f32_16x16x32_bf16 v[10:13], v[154:157], v[130:133], v[10:13]
	v_mfma_f32_16x16x32_bf16 v[14:17], v[158:161], v[130:133], v[14:17]
	v_mfma_f32_16x16x32_bf16 v[18:21], v[146:149], v[134:137], v[18:21]
	v_mfma_f32_16x16x32_bf16 v[22:25], v[150:153], v[134:137], v[22:25]
	v_mfma_f32_16x16x32_bf16 v[26:29], v[154:157], v[134:137], v[26:29]
	v_mfma_f32_16x16x32_bf16 v[30:33], v[158:161], v[134:137], v[30:33]
	v_mfma_f32_16x16x32_bf16 v[34:37], v[146:149], v[138:141], v[34:37]
	v_mfma_f32_16x16x32_bf16 v[38:41], v[150:153], v[138:141], v[38:41]
	v_mfma_f32_16x16x32_bf16 v[42:45], v[154:157], v[138:141], v[42:45]
	v_mfma_f32_16x16x32_bf16 v[46:49], v[158:161], v[138:141], v[46:49]
	v_mfma_f32_16x16x32_bf16 v[50:53], v[146:149], v[142:145], v[50:53]
	v_mfma_f32_16x16x32_bf16 v[54:57], v[150:153], v[142:145], v[54:57]
	v_mfma_f32_16x16x32_bf16 v[58:61], v[154:157], v[142:145], v[58:61]
	v_mfma_f32_16x16x32_bf16 v[62:65], v[158:161], v[142:145], v[62:65]
	v_mfma_f32_16x16x32_bf16 v[2:5], v[228:231], v[212:215], v[2:5]
	v_mfma_f32_16x16x32_bf16 v[6:9], v[232:235], v[212:215], v[6:9]
	v_mfma_f32_16x16x32_bf16 v[10:13], v[236:239], v[212:215], v[10:13]
	v_mfma_f32_16x16x32_bf16 v[14:17], v[240:243], v[212:215], v[14:17]
	v_mfma_f32_16x16x32_bf16 v[18:21], v[228:231], v[216:219], v[18:21]
	v_mfma_f32_16x16x32_bf16 v[22:25], v[232:235], v[216:219], v[22:25]
	v_mfma_f32_16x16x32_bf16 v[26:29], v[236:239], v[216:219], v[26:29]
	v_mfma_f32_16x16x32_bf16 v[30:33], v[240:243], v[216:219], v[30:33]
	v_mfma_f32_16x16x32_bf16 v[34:37], v[228:231], v[220:223], v[34:37]
	v_mfma_f32_16x16x32_bf16 v[38:41], v[232:235], v[220:223], v[38:41]
	v_mfma_f32_16x16x32_bf16 v[42:45], v[236:239], v[220:223], v[42:45]
	v_mfma_f32_16x16x32_bf16 v[46:49], v[240:243], v[220:223], v[46:49]
	v_mfma_f32_16x16x32_bf16 v[50:53], v[228:231], v[224:227], v[50:53]
	v_mfma_f32_16x16x32_bf16 v[54:57], v[232:235], v[224:227], v[54:57]
	v_mfma_f32_16x16x32_bf16 v[58:61], v[236:239], v[224:227], v[58:61]
	v_mfma_f32_16x16x32_bf16 v[62:65], v[240:243], v[224:227], v[62:65]
	s_waitcnt vmcnt(6)
	s_barrier
	v_add_u32_e32 v204, 0xc000, v200
	v_add_u32_e32 v205, 0xc000, v202
	ds_read_b128 v[130:133], v204 offset:0
	ds_read_b128 v[134:137], v204 offset:2048
	ds_read_b128 v[138:141], v204 offset:4096
	ds_read_b128 v[142:145], v204 offset:6144
	ds_read_b128 v[146:149], v205 offset:0
	ds_read_b128 v[150:153], v205 offset:2048
	ds_read_b128 v[154:157], v205 offset:4096
	ds_read_b128 v[158:161], v205 offset:6144
	v_add_u32_e32 v204, 0xc000, v201
	v_add_u32_e32 v205, 0xc000, v203
	ds_read_b128 v[212:215], v204 offset:0
	ds_read_b128 v[216:219], v204 offset:2048
	ds_read_b128 v[220:223], v204 offset:4096
	ds_read_b128 v[224:227], v204 offset:6144
	ds_read_b128 v[228:231], v205 offset:0
	ds_read_b128 v[232:235], v205 offset:2048
	ds_read_b128 v[236:239], v205 offset:4096
	ds_read_b128 v[240:243], v205 offset:6144
	s_waitcnt lgkmcnt(0)
	s_barrier
	v_mfma_f32_16x16x32_bf16 v[2:5], v[146:149], v[130:133], v[2:5]
	v_mfma_f32_16x16x32_bf16 v[6:9], v[150:153], v[130:133], v[6:9]
	v_mfma_f32_16x16x32_bf16 v[10:13], v[154:157], v[130:133], v[10:13]
	v_mfma_f32_16x16x32_bf16 v[14:17], v[158:161], v[130:133], v[14:17]
	v_mfma_f32_16x16x32_bf16 v[18:21], v[146:149], v[134:137], v[18:21]
	v_mfma_f32_16x16x32_bf16 v[22:25], v[150:153], v[134:137], v[22:25]
	v_mfma_f32_16x16x32_bf16 v[26:29], v[154:157], v[134:137], v[26:29]
	v_mfma_f32_16x16x32_bf16 v[30:33], v[158:161], v[134:137], v[30:33]
	v_mfma_f32_16x16x32_bf16 v[34:37], v[146:149], v[138:141], v[34:37]
	v_mfma_f32_16x16x32_bf16 v[38:41], v[150:153], v[138:141], v[38:41]
	v_mfma_f32_16x16x32_bf16 v[42:45], v[154:157], v[138:141], v[42:45]
	v_mfma_f32_16x16x32_bf16 v[46:49], v[158:161], v[138:141], v[46:49]
	v_mfma_f32_16x16x32_bf16 v[50:53], v[146:149], v[142:145], v[50:53]
	v_mfma_f32_16x16x32_bf16 v[54:57], v[150:153], v[142:145], v[54:57]
	v_mfma_f32_16x16x32_bf16 v[58:61], v[154:157], v[142:145], v[58:61]
	v_mfma_f32_16x16x32_bf16 v[62:65], v[158:161], v[142:145], v[62:65]
	v_mfma_f32_16x16x32_bf16 v[2:5], v[228:231], v[212:215], v[2:5]
	v_mfma_f32_16x16x32_bf16 v[6:9], v[232:235], v[212:215], v[6:9]
	v_mfma_f32_16x16x32_bf16 v[10:13], v[236:239], v[212:215], v[10:13]
	v_mfma_f32_16x16x32_bf16 v[14:17], v[240:243], v[212:215], v[14:17]
	v_mfma_f32_16x16x32_bf16 v[18:21], v[228:231], v[216:219], v[18:21]
	v_mfma_f32_16x16x32_bf16 v[22:25], v[232:235], v[216:219], v[22:25]
	v_mfma_f32_16x16x32_bf16 v[26:29], v[236:239], v[216:219], v[26:29]
	v_mfma_f32_16x16x32_bf16 v[30:33], v[240:243], v[216:219], v[30:33]
	v_mfma_f32_16x16x32_bf16 v[34:37], v[228:231], v[220:223], v[34:37]
	v_mfma_f32_16x16x32_bf16 v[38:41], v[232:235], v[220:223], v[38:41]
	v_mfma_f32_16x16x32_bf16 v[42:45], v[236:239], v[220:223], v[42:45]
	v_mfma_f32_16x16x32_bf16 v[46:49], v[240:243], v[220:223], v[46:49]
	v_mfma_f32_16x16x32_bf16 v[50:53], v[228:231], v[224:227], v[50:53]
	v_mfma_f32_16x16x32_bf16 v[54:57], v[232:235], v[224:227], v[54:57]
	v_mfma_f32_16x16x32_bf16 v[58:61], v[236:239], v[224:227], v[58:61]
	v_mfma_f32_16x16x32_bf16 v[62:65], v[240:243], v[224:227], v[62:65]
	s_waitcnt vmcnt(0)
	s_barrier
	v_add_u32_e32 v204, 0x18000, v200
	v_add_u32_e32 v205, 0x18000, v202
	ds_read_b128 v[130:133], v204 offset:0
	ds_read_b128 v[134:137], v204 offset:2048
	ds_read_b128 v[138:141], v204 offset:4096
	ds_read_b128 v[142:145], v204 offset:6144
	ds_read_b128 v[146:149], v205 offset:0
	ds_read_b128 v[150:153], v205 offset:2048
	ds_read_b128 v[154:157], v205 offset:4096
	ds_read_b128 v[158:161], v205 offset:6144
	v_add_u32_e32 v204, 0x18000, v201
	v_add_u32_e32 v205, 0x18000, v203
	ds_read_b128 v[212:215], v204 offset:0
	ds_read_b128 v[216:219], v204 offset:2048
	ds_read_b128 v[220:223], v204 offset:4096
	ds_read_b128 v[224:227], v204 offset:6144
	ds_read_b128 v[228:231], v205 offset:0
	ds_read_b128 v[232:235], v205 offset:2048
	ds_read_b128 v[236:239], v205 offset:4096
	ds_read_b128 v[240:243], v205 offset:6144
	s_waitcnt lgkmcnt(0)
	s_barrier
	v_mfma_f32_16x16x32_bf16 v[2:5], v[146:149], v[130:133], v[2:5]
	v_mfma_f32_16x16x32_bf16 v[6:9], v[150:153], v[130:133], v[6:9]
	v_mfma_f32_16x16x32_bf16 v[10:13], v[154:157], v[130:133], v[10:13]
	v_mfma_f32_16x16x32_bf16 v[14:17], v[158:161], v[130:133], v[14:17]
	v_mfma_f32_16x16x32_bf16 v[18:21], v[146:149], v[134:137], v[18:21]
	v_mfma_f32_16x16x32_bf16 v[22:25], v[150:153], v[134:137], v[22:25]
	v_mfma_f32_16x16x32_bf16 v[26:29], v[154:157], v[134:137], v[26:29]
	v_mfma_f32_16x16x32_bf16 v[30:33], v[158:161], v[134:137], v[30:33]
	v_mfma_f32_16x16x32_bf16 v[34:37], v[146:149], v[138:141], v[34:37]
	v_mfma_f32_16x16x32_bf16 v[38:41], v[150:153], v[138:141], v[38:41]
	v_mfma_f32_16x16x32_bf16 v[42:45], v[154:157], v[138:141], v[42:45]
	v_mfma_f32_16x16x32_bf16 v[46:49], v[158:161], v[138:141], v[46:49]
	v_mfma_f32_16x16x32_bf16 v[50:53], v[146:149], v[142:145], v[50:53]
	v_mfma_f32_16x16x32_bf16 v[54:57], v[150:153], v[142:145], v[54:57]
	v_mfma_f32_16x16x32_bf16 v[58:61], v[154:157], v[142:145], v[58:61]
	v_mfma_f32_16x16x32_bf16 v[62:65], v[158:161], v[142:145], v[62:65]
	v_mfma_f32_16x16x32_bf16 v[2:5], v[228:231], v[212:215], v[2:5]
	v_mfma_f32_16x16x32_bf16 v[6:9], v[232:235], v[212:215], v[6:9]
	v_mfma_f32_16x16x32_bf16 v[10:13], v[236:239], v[212:215], v[10:13]
	v_mfma_f32_16x16x32_bf16 v[14:17], v[240:243], v[212:215], v[14:17]
	v_mfma_f32_16x16x32_bf16 v[18:21], v[228:231], v[216:219], v[18:21]
	v_mfma_f32_16x16x32_bf16 v[22:25], v[232:235], v[216:219], v[22:25]
	v_mfma_f32_16x16x32_bf16 v[26:29], v[236:239], v[216:219], v[26:29]
	v_mfma_f32_16x16x32_bf16 v[30:33], v[240:243], v[216:219], v[30:33]
	v_mfma_f32_16x16x32_bf16 v[34:37], v[228:231], v[220:223], v[34:37]
	v_mfma_f32_16x16x32_bf16 v[38:41], v[232:235], v[220:223], v[38:41]
	v_mfma_f32_16x16x32_bf16 v[42:45], v[236:239], v[220:223], v[42:45]
	v_mfma_f32_16x16x32_bf16 v[46:49], v[240:243], v[220:223], v[46:49]
	v_mfma_f32_16x16x32_bf16 v[50:53], v[228:231], v[224:227], v[50:53]
	v_mfma_f32_16x16x32_bf16 v[54:57], v[232:235], v[224:227], v[54:57]
	v_mfma_f32_16x16x32_bf16 v[58:61], v[236:239], v[224:227], v[58:61]
	v_mfma_f32_16x16x32_bf16 v[62:65], v[240:243], v[224:227], v[62:65]
	s_nop 7
	v_lshlrev_b32_e32 v212, 16, v174
	v_and_b32_e32 v213, 0xffff0000, v174
	v_lshlrev_b32_e32 v214, 16, v175
	v_and_b32_e32 v215, 0xffff0000, v175
	v_pk_fma_f32 v[66:67], v[2:3], v[212:213], v[66:67]
	v_pk_fma_f32 v[68:69], v[4:5], v[214:215], v[68:69]
	s_nop 0
	v_cvt_pk_bf16_f32 v66, v66, v67
	v_cvt_pk_bf16_f32 v67, v68, v69
	global_store_dwordx2 v210, v[66:67], s[74:75] offset:0
	v_lshlrev_b32_e32 v216, 16, v176
	v_and_b32_e32 v217, 0xffff0000, v176
	v_lshlrev_b32_e32 v218, 16, v177
	v_and_b32_e32 v219, 0xffff0000, v177
	v_pk_fma_f32 v[70:71], v[6:7], v[216:217], v[70:71]
	v_pk_fma_f32 v[72:73], v[8:9], v[218:219], v[72:73]
	s_nop 0
	v_cvt_pk_bf16_f32 v70, v70, v71
	v_cvt_pk_bf16_f32 v71, v72, v73
	global_store_dwordx2 v210, v[70:71], s[74:75] offset:32
	v_lshlrev_b32_e32 v220, 16, v178
	v_and_b32_e32 v221, 0xffff0000, v178
	v_lshlrev_b32_e32 v222, 16, v179
	v_and_b32_e32 v223, 0xffff0000, v179
	v_pk_fma_f32 v[74:75], v[10:11], v[220:221], v[74:75]
	v_pk_fma_f32 v[76:77], v[12:13], v[222:223], v[76:77]
	s_nop 0
	v_cvt_pk_bf16_f32 v74, v74, v75
	v_cvt_pk_bf16_f32 v75, v76, v77
	global_store_dwordx2 v210, v[74:75], s[74:75] offset:64
	v_lshlrev_b32_e32 v224, 16, v180
	v_and_b32_e32 v225, 0xffff0000, v180
	v_lshlrev_b32_e32 v226, 16, v181
	v_and_b32_e32 v227, 0xffff0000, v181
	v_pk_fma_f32 v[78:79], v[14:15], v[224:225], v[78:79]
	v_pk_fma_f32 v[80:81], v[16:17], v[226:227], v[80:81]
	s_nop 0
	v_cvt_pk_bf16_f32 v78, v78, v79
	v_cvt_pk_bf16_f32 v79, v80, v81
	global_store_dwordx2 v210, v[78:79], s[74:75] offset:96
	v_lshlrev_b32_e32 v228, 16, v182
	v_and_b32_e32 v229, 0xffff0000, v182
	v_lshlrev_b32_e32 v230, 16, v183
	v_and_b32_e32 v231, 0xffff0000, v183
	v_pk_fma_f32 v[82:83], v[18:19], v[228:229], v[82:83]
	v_pk_fma_f32 v[84:85], v[20:21], v[230:231], v[84:85]
	s_nop 0
	v_cvt_pk_bf16_f32 v82, v82, v83
	v_cvt_pk_bf16_f32 v83, v84, v85
	global_store_dwordx2 v211, v[82:83], s[74:75] offset:0
	v_lshlrev_b32_e32 v232, 16, v184
	v_and_b32_e32 v233, 0xffff0000, v184
	v_lshlrev_b32_e32 v234, 16, v185
	v_and_b32_e32 v235, 0xffff0000, v185
	v_pk_fma_f32 v[86:87], v[22:23], v[232:233], v[86:87]
	v_pk_fma_f32 v[88:89], v[24:25], v[234:235], v[88:89]
	s_nop 0
	v_cvt_pk_bf16_f32 v86, v86, v87
	v_cvt_pk_bf16_f32 v87, v88, v89
	global_store_dwordx2 v211, v[86:87], s[74:75] offset:32
	v_lshlrev_b32_e32 v236, 16, v186
	v_and_b32_e32 v237, 0xffff0000, v186
	v_lshlrev_b32_e32 v238, 16, v187
	v_and_b32_e32 v239, 0xffff0000, v187
	v_pk_fma_f32 v[90:91], v[26:27], v[236:237], v[90:91]
	v_pk_fma_f32 v[92:93], v[28:29], v[238:239], v[92:93]
	s_nop 0
	v_cvt_pk_bf16_f32 v90, v90, v91
	v_cvt_pk_bf16_f32 v91, v92, v93
	global_store_dwordx2 v211, v[90:91], s[74:75] offset:64
	v_lshlrev_b32_e32 v240, 16, v188
	v_and_b32_e32 v241, 0xffff0000, v188
	v_lshlrev_b32_e32 v242, 16, v189
	v_and_b32_e32 v243, 0xffff0000, v189
	v_pk_fma_f32 v[94:95], v[30:31], v[240:241], v[94:95]
	v_pk_fma_f32 v[96:97], v[32:33], v[242:243], v[96:97]
	s_nop 0
	v_cvt_pk_bf16_f32 v94, v94, v95
	v_cvt_pk_bf16_f32 v95, v96, v97
	global_store_dwordx2 v211, v[94:95], s[74:75] offset:96
	v_lshlrev_b32_e32 v212, 16, v190
	v_and_b32_e32 v213, 0xffff0000, v190
	v_lshlrev_b32_e32 v214, 16, v191
	v_and_b32_e32 v215, 0xffff0000, v191
	v_pk_fma_f32 v[98:99], v[34:35], v[212:213], v[98:99]
	v_pk_fma_f32 v[100:101], v[36:37], v[214:215], v[100:101]
	s_nop 0
	v_cvt_pk_bf16_f32 v98, v98, v99
	v_cvt_pk_bf16_f32 v99, v100, v101
	global_store_dwordx2 v168, v[98:99], s[74:75] offset:0
	v_lshlrev_b32_e32 v216, 16, v192
	v_and_b32_e32 v217, 0xffff0000, v192
	v_lshlrev_b32_e32 v218, 16, v193
	v_and_b32_e32 v219, 0xffff0000, v193
	v_pk_fma_f32 v[102:103], v[38:39], v[216:217], v[102:103]
	v_pk_fma_f32 v[104:105], v[40:41], v[218:219], v[104:105]
	s_nop 0
	v_cvt_pk_bf16_f32 v102, v102, v103
	v_cvt_pk_bf16_f32 v103, v104, v105
	global_store_dwordx2 v168, v[102:103], s[74:75] offset:32
	v_lshlrev_b32_e32 v220, 16, v244
	v_and_b32_e32 v221, 0xffff0000, v244
	v_lshlrev_b32_e32 v222, 16, v245
	v_and_b32_e32 v223, 0xffff0000, v245
	v_pk_fma_f32 v[106:107], v[42:43], v[220:221], v[106:107]
	v_pk_fma_f32 v[108:109], v[44:45], v[222:223], v[108:109]
	s_nop 0
	v_cvt_pk_bf16_f32 v106, v106, v107
	v_cvt_pk_bf16_f32 v107, v108, v109
	global_store_dwordx2 v168, v[106:107], s[74:75] offset:64
	v_lshlrev_b32_e32 v224, 16, v246
	v_and_b32_e32 v225, 0xffff0000, v246
	v_lshlrev_b32_e32 v226, 16, v247
	v_and_b32_e32 v227, 0xffff0000, v247
	v_pk_fma_f32 v[110:111], v[46:47], v[224:225], v[110:111]
	v_pk_fma_f32 v[112:113], v[48:49], v[226:227], v[112:113]
	s_nop 0
	v_cvt_pk_bf16_f32 v110, v110, v111
	v_cvt_pk_bf16_f32 v111, v112, v113
	global_store_dwordx2 v168, v[110:111], s[74:75] offset:96
	v_lshlrev_b32_e32 v228, 16, v248
	v_and_b32_e32 v229, 0xffff0000, v248
	v_lshlrev_b32_e32 v230, 16, v249
	v_and_b32_e32 v231, 0xffff0000, v249
	v_pk_fma_f32 v[114:115], v[50:51], v[228:229], v[114:115]
	v_pk_fma_f32 v[116:117], v[52:53], v[230:231], v[116:117]
	s_nop 0
	v_cvt_pk_bf16_f32 v114, v114, v115
	v_cvt_pk_bf16_f32 v115, v116, v117
	global_store_dwordx2 v169, v[114:115], s[74:75] offset:0
	v_lshlrev_b32_e32 v232, 16, v250
	v_and_b32_e32 v233, 0xffff0000, v250
	v_lshlrev_b32_e32 v234, 16, v251
	v_and_b32_e32 v235, 0xffff0000, v251
	v_pk_fma_f32 v[118:119], v[54:55], v[232:233], v[118:119]
	v_pk_fma_f32 v[120:121], v[56:57], v[234:235], v[120:121]
	s_nop 0
	v_cvt_pk_bf16_f32 v118, v118, v119
	v_cvt_pk_bf16_f32 v119, v120, v121
	global_store_dwordx2 v169, v[118:119], s[74:75] offset:32
	v_lshlrev_b32_e32 v236, 16, v166
	v_and_b32_e32 v237, 0xffff0000, v166
	v_lshlrev_b32_e32 v238, 16, v167
	v_and_b32_e32 v239, 0xffff0000, v167
	v_pk_fma_f32 v[122:123], v[58:59], v[236:237], v[122:123]
	v_pk_fma_f32 v[124:125], v[60:61], v[238:239], v[124:125]
	s_nop 0
	v_cvt_pk_bf16_f32 v122, v122, v123
	v_cvt_pk_bf16_f32 v123, v124, v125
	global_store_dwordx2 v169, v[122:123], s[74:75] offset:64
	v_lshlrev_b32_e32 v240, 16, v194
	v_and_b32_e32 v241, 0xffff0000, v194
	v_lshlrev_b32_e32 v242, 16, v195
	v_and_b32_e32 v243, 0xffff0000, v195
	v_pk_fma_f32 v[126:127], v[62:63], v[240:241], v[126:127]
	v_pk_fma_f32 v[128:129], v[64:65], v[242:243], v[128:129]
	s_nop 0
	v_cvt_pk_bf16_f32 v126, v126, v127
	v_cvt_pk_bf16_f32 v127, v128, v129
	global_store_dwordx2 v169, v[126:127], s[74:75] offset:96
	s_barrier
	s_branch .Lbr_join
.Lbr_streamB:
	s_barrier
	v_add_u32_e32 v204, 0x0, v200
	v_add_u32_e32 v205, 0x0, v202
	ds_read_b128 v[130:133], v204 offset:0
	ds_read_b128 v[134:137], v204 offset:2048
	ds_read_b128 v[138:141], v204 offset:4096
	ds_read_b128 v[142:145], v204 offset:6144
	ds_read_b128 v[146:149], v205 offset:0
	ds_read_b128 v[150:153], v205 offset:2048
	ds_read_b128 v[154:157], v205 offset:4096
	ds_read_b128 v[158:161], v205 offset:6144
	v_add_u32_e32 v204, 0x0, v201
	v_add_u32_e32 v205, 0x0, v203
	ds_read_b128 v[212:215], v204 offset:0
	ds_read_b128 v[216:219], v204 offset:2048
	ds_read_b128 v[220:223], v204 offset:4096
	ds_read_b128 v[224:227], v204 offset:6144
	ds_read_b128 v[228:231], v205 offset:0
	ds_read_b128 v[232:235], v205 offset:2048
	ds_read_b128 v[236:239], v205 offset:4096
	ds_read_b128 v[240:243], v205 offset:6144
	s_add_u32 m0, s76, 0x18000
	s_nop 0
	global_load_lds_dwordx4 v196, s[68:69]
	s_add_u32 m0, s76, 0x1a000
	s_nop 0
	global_load_lds_dwordx4 v197, s[68:69]
	s_add_u32 m0, s76, 0x1c000
	s_nop 0
	global_load_lds_dwordx4 v198, s[68:69]
	s_add_u32 m0, s76, 0x1e000
	s_nop 0
	global_load_lds_dwordx4 v199, s[68:69]
	s_add_u32 m0, s76, 0x20000
	s_nop 0
	global_load_lds_dwordx4 v196, s[70:71]
	s_add_u32 m0, s76, 0x22000
	s_nop 0
	global_load_lds_dwordx4 v197, s[70:71]
	s_add_u32 s68, s68, 0x80
	s_addc_u32 s69, s69, 0
	s_add_u32 s70, s70, 0x80
	s_addc_u32 s71, s71, 0
	global_load_dwordx2 v[174:175], v206, s[72:73] offset:0
	global_load_dwordx2 v[176:177], v206, s[72:73] offset:32
	global_load_dwordx2 v[178:179], v206, s[72:73] offset:64
	global_load_dwordx2 v[180:181], v206, s[72:73] offset:96
	global_load_dwordx2 v[182:183], v207, s[72:73] offset:0
	global_load_dwordx2 v[184:185], v207, s[72:73] offset:32
	s_waitcnt vmcnt(12)
	s_waitcnt lgkmcnt(0)
	s_barrier
	v_mfma_f32_16x16x32_bf16 v[2:5], v[146:149], v[130:133], 0
	v_mfma_f32_16x16x32_bf16 v[6:9], v[150:153], v[130:133], 0
	v_mfma_f32_16x16x32_bf16 v[10:13], v[154:157], v[130:133], 0
	v_mfma_f32_16x16x32_bf16 v[14:17], v[158:161], v[130:133], 0
	v_mfma_f32_16x16x32_bf16 v[18:21], v[146:149], v[134:137], 0
	v_mfma_f32_16x16x32_bf16 v[22:25], v[150:153], v[134:137], 0
	v_mfma_f32_16x16x32_bf16 v[26:29], v[154:157], v[134:137], 0
	v_mfma_f32_16x16x32_bf16 v[30:33], v[158:161], v[134:137], 0
	v_mfma_f32_16x16x32_bf16 v[34:37], v[146:149], v[138:141], 0
	v_mfma_f32_16x16x32_bf16 v[38:41], v[150:153], v[138:141], 0
	v_mfma_f32_16x16x32_bf16 v[42:45], v[154:157], v[138:141], 0
	v_mfma_f32_16x16x32_bf16 v[46:49], v[158:161], v[138:141], 0
	v_mfma_f32_16x16x32_bf16 v[50:53], v[146:149], v[142:145], 0
	v_mfma_f32_16x16x32_bf16 v[54:57], v[150:153], v[142:145], 0
	v_mfma_f32_16x16x32_bf16 v[58:61], v[154:157], v[142:145], 0
	v_mfma_f32_16x16x32_bf16 v[62:65], v[158:161], v[142:145], 0
	v_mfma_f32_16x16x32_bf16 v[2:5], v[228:231], v[212:215], v[2:5]
	v_mfma_f32_16x16x32_bf16 v[6:9], v[232:235], v[212:215], v[6:9]
	v_mfma_f32_16x16x32_bf16 v[10:13], v[236:239], v[212:215], v[10:13]
	v_mfma_f32_16x16x32_bf16 v[14:17], v[240:243], v[212:215], v[14:17]
	v_mfma_f32_16x16x32_bf16 v[18:21], v[228:231], v[216:219], v[18:21]
	v_mfma_f32_16x16x32_bf16 v[22:25], v[232:235], v[216:219], v[22:25]
	v_mfma_f32_16x16x32_bf16 v[26:29], v[236:239], v[216:219], v[26:29]
	v_mfma_f32_16x16x32_bf16 v[30:33], v[240:243], v[216:219], v[30:33]
	v_mfma_f32_16x16x32_bf16 v[34:37], v[228:231], v[220:223], v[34:37]
	v_mfma_f32_16x16x32_bf16 v[38:41], v[232:235], v[220:223], v[38:41]
	v_mfma_f32_16x16x32_bf16 v[42:45], v[236:239], v[220:223], v[42:45]
	v_mfma_f32_16x16x32_bf16 v[46:49], v[240:243], v[220:223], v[46:49]
	v_mfma_f32_16x16x32_bf16 v[50:53], v[228:231], v[224:227], v[50:53]
	v_mfma_f32_16x16x32_bf16 v[54:57], v[232:235], v[224:227], v[54:57]
	v_mfma_f32_16x16x32_bf16 v[58:61], v[236:239], v[224:227], v[58:61]
	v_mfma_f32_16x16x32_bf16 v[62:65], v[240:243], v[224:227], v[62:65]
	s_barrier
	v_add_u32_e32 v204, 0xc000, v200
	v_add_u32_e32 v205, 0xc000, v202
	ds_read_b128 v[130:133], v204 offset:0
	ds_read_b128 v[134:137], v204 offset:2048
	ds_read_b128 v[138:141], v204 offset:4096
	ds_read_b128 v[142:145], v204 offset:6144
	ds_read_b128 v[146:149], v205 offset:0
	ds_read_b128 v[150:153], v205 offset:2048
	ds_read_b128 v[154:157], v205 offset:4096
	ds_read_b128 v[158:161], v205 offset:6144
	v_add_u32_e32 v204, 0xc000, v201
	v_add_u32_e32 v205, 0xc000, v203
	ds_read_b128 v[212:215], v204 offset:0
	ds_read_b128 v[216:219], v204 offset:2048
	ds_read_b128 v[220:223], v204 offset:4096
	ds_read_b128 v[224:227], v204 offset:6144
	ds_read_b128 v[228:231], v205 offset:0
	ds_read_b128 v[232:235], v205 offset:2048
	ds_read_b128 v[236:239], v205 offset:4096
	ds_read_b128 v[240:243], v205 offset:6144
	s_add_u32 m0, s76, 0x0
	s_nop 0
	global_load_lds_dwordx4 v196, s[68:69]
	s_add_u32 m0, s76, 0x2000
	s_nop 0
	global_load_lds_dwordx4 v197, s[68:69]
	s_add_u32 m0, s76, 0x4000
	s_nop 0
	global_load_lds_dwordx4 v198, s[68:69]
	s_add_u32 m0, s76, 0x6000
	s_nop 0
	global_load_lds_dwordx4 v199, s[68:69]
	s_add_u32 m0, s76, 0x8000
	s_nop 0
	global_load_lds_dwordx4 v196, s[70:71]
	s_add_u32 m0, s76, 0xa000
	s_nop 0
	global_load_lds_dwordx4 v197, s[70:71]
	s_add_u32 s68, s68, 0x80
	s_addc_u32 s69, s69, 0
	s_add_u32 s70, s70, 0x80
	s_addc_u32 s71, s71, 0
	global_load_dwordx2 v[186:187], v207, s[72:73] offset:64
	global_load_dwordx2 v[188:189], v207, s[72:73] offset:96
	global_load_dwordx2 v[190:191], v208, s[72:73] offset:0
	global_load_dwordx2 v[192:193], v208, s[72:73] offset:32
	global_load_dwordx2 v[244:245], v208, s[72:73] offset:64
	global_load_dwordx2 v[246:247], v208, s[72:73] offset:96
	s_waitcnt vmcnt(18)
	s_waitcnt lgkmcnt(0)
	s_barrier
	v_mfma_f32_16x16x32_bf16 v[2:5], v[146:149], v[130:133], v[2:5]
	v_mfma_f32_16x16x32_bf16 v[6:9], v[150:153], v[130:133], v[6:9]
	v_mfma_f32_16x16x32_bf16 v[10:13], v[154:157], v[130:133], v[10:13]
	v_mfma_f32_16x16x32_bf16 v[14:17], v[158:161], v[130:133], v[14:17]
	v_mfma_f32_16x16x32_bf16 v[18:21], v[146:149], v[134:137], v[18:21]
	v_mfma_f32_16x16x32_bf16 v[22:25], v[150:153], v[134:137], v[22:25]
	v_mfma_f32_16x16x32_bf16 v[26:29], v[154:157], v[134:137], v[26:29]
	v_mfma_f32_16x16x32_bf16 v[30:33], v[158:161], v[134:137], v[30:33]
	v_mfma_f32_16x16x32_bf16 v[34:37], v[146:149], v[138:141], v[34:37]
	v_mfma_f32_16x16x32_bf16 v[38:41], v[150:153], v[138:141], v[38:41]
	v_mfma_f32_16x16x32_bf16 v[42:45], v[154:157], v[138:141], v[42:45]
	v_mfma_f32_16x16x32_bf16 v[46:49], v[158:161], v[138:141], v[46:49]
	v_mfma_f32_16x16x32_bf16 v[50:53], v[146:149], v[142:145], v[50:53]
	v_mfma_f32_16x16x32_bf16 v[54:57], v[150:153], v[142:145], v[54:57]
	v_mfma_f32_16x16x32_bf16 v[58:61], v[154:157], v[142:145], v[58:61]
	v_mfma_f32_16x16x32_bf16 v[62:65], v[158:161], v[142:145], v[62:65]
	v_mfma_f32_16x16x32_bf16 v[2:5], v[228:231], v[212:215], v[2:5]
	v_mfma_f32_16x16x32_bf16 v[6:9], v[232:235], v[212:215], v[6:9]
	v_mfma_f32_16x16x32_bf16 v[10:13], v[236:239], v[212:215], v[10:13]
	v_mfma_f32_16x16x32_bf16 v[14:17], v[240:243], v[212:215], v[14:17]
	v_mfma_f32_16x16x32_bf16 v[18:21], v[228:231], v[216:219], v[18:21]
	v_mfma_f32_16x16x32_bf16 v[22:25], v[232:235], v[216:219], v[22:25]
	v_mfma_f32_16x16x32_bf16 v[26:29], v[236:239], v[216:219], v[26:29]
	v_mfma_f32_16x16x32_bf16 v[30:33], v[240:243], v[216:219], v[30:33]
	v_mfma_f32_16x16x32_bf16 v[34:37], v[228:231], v[220:223], v[34:37]
	v_mfma_f32_16x16x32_bf16 v[38:41], v[232:235], v[220:223], v[38:41]
	v_mfma_f32_16x16x32_bf16 v[42:45], v[236:239], v[220:223], v[42:45]
	v_mfma_f32_16x16x32_bf16 v[46:49], v[240:243], v[220:223], v[46:49]
	v_mfma_f32_16x16x32_bf16 v[50:53], v[228:231], v[224:227], v[50:53]
	v_mfma_f32_16x16x32_bf16 v[54:57], v[232:235], v[224:227], v[54:57]
	v_mfma_f32_16x16x32_bf16 v[58:61], v[236:239], v[224:227], v[58:61]
	v_mfma_f32_16x16x32_bf16 v[62:65], v[240:243], v[224:227], v[62:65]
	s_barrier
	v_add_u32_e32 v204, 0x18000, v200
	v_add_u32_e32 v205, 0x18000, v202
	ds_read_b128 v[130:133], v204 offset:0
	ds_read_b128 v[134:137], v204 offset:2048
	ds_read_b128 v[138:141], v204 offset:4096
	ds_read_b128 v[142:145], v204 offset:6144
	ds_read_b128 v[146:149], v205 offset:0
	ds_read_b128 v[150:153], v205 offset:2048
	ds_read_b128 v[154:157], v205 offset:4096
	ds_read_b128 v[158:161], v205 offset:6144
	v_add_u32_e32 v204, 0x18000, v201
	v_add_u32_e32 v205, 0x18000, v203
	ds_read_b128 v[212:215], v204 offset:0
	ds_read_b128 v[216:219], v204 offset:2048
	ds_read_b128 v[220:223], v204 offset:4096
	ds_read_b128 v[224:227], v204 offset:6144
	ds_read_b128 v[228:231], v205 offset:0
	ds_read_b128 v[232:235], v205 offset:2048
	ds_read_b128 v[236:239], v205 offset:4096
	ds_read_b128 v[240:243], v205 offset:6144
	s_add_u32 m0, s76, 0xc000
	s_nop 0
	global_load_lds_dwordx4 v196, s[68:69]
	s_add_u32 m0, s76, 0xe000
	s_nop 0
	global_load_lds_dwordx4 v197, s[68:69]
	s_add_u32 m0, s76, 0x10000
	s_nop 0
	global_load_lds_dwordx4 v198, s[68:69]
	s_add_u32 m0, s76, 0x12000
	s_nop 0
	global_load_lds_dwordx4 v199, s[68:69]
	s_add_u32 m0, s76, 0x14000
	s_nop 0
	global_load_lds_dwordx4 v196, s[70:71]
	s_add_u32 m0, s76, 0x16000
	s_nop 0
	global_load_lds_dwordx4 v197, s[70:71]
	s_add_u32 s68, s68, 0x80
	s_addc_u32 s69, s69, 0
	s_add_u32 s70, s70, 0x80
	s_addc_u32 s71, s71, 0
	global_load_dwordx2 v[248:249], v209, s[72:73] offset:0
	global_load_dwordx2 v[250:251], v209, s[72:73] offset:32
	global_load_dwordx2 v[166:167], v209, s[72:73] offset:64
	global_load_dwordx2 v[194:195], v209, s[72:73] offset:96
	s_add_u32 s72, s72, 0x800
	s_addc_u32 s73, s73, 0
	s_waitcnt vmcnt(16)
	s_waitcnt lgkmcnt(0)
	s_barrier
	v_mfma_f32_16x16x32_bf16 v[2:5], v[146:149], v[130:133], v[2:5]
	v_mfma_f32_16x16x32_bf16 v[6:9], v[150:153], v[130:133], v[6:9]
	v_mfma_f32_16x16x32_bf16 v[10:13], v[154:157], v[130:133], v[10:13]
	v_mfma_f32_16x16x32_bf16 v[14:17], v[158:161], v[130:133], v[14:17]
	v_mfma_f32_16x16x32_bf16 v[18:21], v[146:149], v[134:137], v[18:21]
	v_mfma_f32_16x16x32_bf16 v[22:25], v[150:153], v[134:137], v[22:25]
	v_mfma_f32_16x16x32_bf16 v[26:29], v[154:157], v[134:137], v[26:29]
	v_mfma_f32_16x16x32_bf16 v[30:33], v[158:161], v[134:137], v[30:33]
	v_mfma_f32_16x16x32_bf16 v[34:37], v[146:149], v[138:141], v[34:37]
	v_mfma_f32_16x16x32_bf16 v[38:41], v[150:153], v[138:141], v[38:41]
	v_mfma_f32_16x16x32_bf16 v[42:45], v[154:157], v[138:141], v[42:45]
	v_mfma_f32_16x16x32_bf16 v[46:49], v[158:161], v[138:141], v[46:49]
	v_mfma_f32_16x16x32_bf16 v[50:53], v[146:149], v[142:145], v[50:53]
	v_mfma_f32_16x16x32_bf16 v[54:57], v[150:153], v[142:145], v[54:57]
	v_mfma_f32_16x16x32_bf16 v[58:61], v[154:157], v[142:145], v[58:61]
	v_mfma_f32_16x16x32_bf16 v[62:65], v[158:161], v[142:145], v[62:65]
	v_mfma_f32_16x16x32_bf16 v[2:5], v[228:231], v[212:215], v[2:5]
	v_mfma_f32_16x16x32_bf16 v[6:9], v[232:235], v[212:215], v[6:9]
	v_mfma_f32_16x16x32_bf16 v[10:13], v[236:239], v[212:215], v[10:13]
	v_mfma_f32_16x16x32_bf16 v[14:17], v[240:243], v[212:215], v[14:17]
	v_mfma_f32_16x16x32_bf16 v[18:21], v[228:231], v[216:219], v[18:21]
	v_mfma_f32_16x16x32_bf16 v[22:25], v[232:235], v[216:219], v[22:25]
	v_mfma_f32_16x16x32_bf16 v[26:29], v[236:239], v[216:219], v[26:29]
	v_mfma_f32_16x16x32_bf16 v[30:33], v[240:243], v[216:219], v[30:33]
	v_mfma_f32_16x16x32_bf16 v[34:37], v[228:231], v[220:223], v[34:37]
	v_mfma_f32_16x16x32_bf16 v[38:41], v[232:235], v[220:223], v[38:41]
	v_mfma_f32_16x16x32_bf16 v[42:45], v[236:239], v[220:223], v[42:45]
	v_mfma_f32_16x16x32_bf16 v[46:49], v[240:243], v[220:223], v[46:49]
	v_mfma_f32_16x16x32_bf16 v[50:53], v[228:231], v[224:227], v[50:53]
	v_mfma_f32_16x16x32_bf16 v[54:57], v[232:235], v[224:227], v[54:57]
	v_mfma_f32_16x16x32_bf16 v[58:61], v[236:239], v[224:227], v[58:61]
	v_mfma_f32_16x16x32_bf16 v[62:65], v[240:243], v[224:227], v[62:65]
	s_barrier
	v_add_u32_e32 v204, 0x0, v200
	v_add_u32_e32 v205, 0x0, v202
	ds_read_b128 v[130:133], v204 offset:0
	ds_read_b128 v[134:137], v204 offset:2048
	ds_read_b128 v[138:141], v204 offset:4096
	ds_read_b128 v[142:145], v204 offset:6144
	ds_read_b128 v[146:149], v205 offset:0
	ds_read_b128 v[150:153], v205 offset:2048
	ds_read_b128 v[154:157], v205 offset:4096
	ds_read_b128 v[158:161], v205 offset:6144
	v_add_u32_e32 v204, 0x0, v201
	v_add_u32_e32 v205, 0x0, v203
	ds_read_b128 v[212:215], v204 offset:0
	ds_read_b128 v[216:219], v204 offset:2048
	ds_read_b128 v[220:223], v204 offset:4096
	ds_read_b128 v[224:227], v204 offset:6144
	ds_read_b128 v[228:231], v205 offset:0
	ds_read_b128 v[232:235], v205 offset:2048
	ds_read_b128 v[236:239], v205 offset:4096
	ds_read_b128 v[240:243], v205 offset:6144
	s_add_u32 m0, s76, 0x18000
	s_nop 0
	global_load_lds_dwordx4 v196, s[68:69]
	s_add_u32 m0, s76, 0x1a000
	s_nop 0
	global_load_lds_dwordx4 v197, s[68:69]
	s_add_u32 m0, s76, 0x1c000
	s_nop 0
	global_load_lds_dwordx4 v198, s[68:69]
	s_add_u32 m0, s76, 0x1e000
	s_nop 0
	global_load_lds_dwordx4 v199, s[68:69]
	s_add_u32 m0, s76, 0x20000
	s_nop 0
	global_load_lds_dwordx4 v196, s[70:71]
	s_add_u32 m0, s76, 0x22000
	s_nop 0
	global_load_lds_dwordx4 v197, s[70:71]
	s_add_u32 s68, s68, 0x80
	s_addc_u32 s69, s69, 0
	s_add_u32 s70, s70, 0x80
	s_addc_u32 s71, s71, 0
	s_waitcnt vmcnt(10)
	s_waitcnt lgkmcnt(0)
	s_barrier
	v_mfma_f32_16x16x32_bf16 v[2:5], v[146:149], v[130:133], v[2:5]
	v_mfma_f32_16x16x32_bf16 v[6:9], v[150:153], v[130:133], v[6:9]
	v_mfma_f32_16x16x32_bf16 v[10:13], v[154:157], v[130:133], v[10:13]
	v_mfma_f32_16x16x32_bf16 v[14:17], v[158:161], v[130:133], v[14:17]
	v_mfma_f32_16x16x32_bf16 v[18:21], v[146:149], v[134:137], v[18:21]
	v_mfma_f32_16x16x32_bf16 v[22:25], v[150:153], v[134:137], v[22:25]
	v_mfma_f32_16x16x32_bf16 v[26:29], v[154:157], v[134:137], v[26:29]
	v_mfma_f32_16x16x32_bf16 v[30:33], v[158:161], v[134:137], v[30:33]
	v_mfma_f32_16x16x32_bf16 v[34:37], v[146:149], v[138:141], v[34:37]
	v_mfma_f32_16x16x32_bf16 v[38:41], v[150:153], v[138:141], v[38:41]
	v_mfma_f32_16x16x32_bf16 v[42:45], v[154:157], v[138:141], v[42:45]
	v_mfma_f32_16x16x32_bf16 v[46:49], v[158:161], v[138:141], v[46:49]
	v_mfma_f32_16x16x32_bf16 v[50:53], v[146:149], v[142:145], v[50:53]
	v_mfma_f32_16x16x32_bf16 v[54:57], v[150:153], v[142:145], v[54:57]
	v_mfma_f32_16x16x32_bf16 v[58:61], v[154:157], v[142:145], v[58:61]
	v_mfma_f32_16x16x32_bf16 v[62:65], v[158:161], v[142:145], v[62:65]
	v_mfma_f32_16x16x32_bf16 v[2:5], v[228:231], v[212:215], v[2:5]
	v_mfma_f32_16x16x32_bf16 v[6:9], v[232:235], v[212:215], v[6:9]
	v_mfma_f32_16x16x32_bf16 v[10:13], v[236:239], v[212:215], v[10:13]
	v_mfma_f32_16x16x32_bf16 v[14:17], v[240:243], v[212:215], v[14:17]
	v_mfma_f32_16x16x32_bf16 v[18:21], v[228:231], v[216:219], v[18:21]
	v_mfma_f32_16x16x32_bf16 v[22:25], v[232:235], v[216:219], v[22:25]
	v_mfma_f32_16x16x32_bf16 v[26:29], v[236:239], v[216:219], v[26:29]
	v_mfma_f32_16x16x32_bf16 v[30:33], v[240:243], v[216:219], v[30:33]
	v_mfma_f32_16x16x32_bf16 v[34:37], v[228:231], v[220:223], v[34:37]
	v_mfma_f32_16x16x32_bf16 v[38:41], v[232:235], v[220:223], v[38:41]
	v_mfma_f32_16x16x32_bf16 v[42:45], v[236:239], v[220:223], v[42:45]
	v_mfma_f32_16x16x32_bf16 v[46:49], v[240:243], v[220:223], v[46:49]
	v_mfma_f32_16x16x32_bf16 v[50:53], v[228:231], v[224:227], v[50:53]
	v_mfma_f32_16x16x32_bf16 v[54:57], v[232:235], v[224:227], v[54:57]
	v_mfma_f32_16x16x32_bf16 v[58:61], v[236:239], v[224:227], v[58:61]
	v_mfma_f32_16x16x32_bf16 v[62:65], v[240:243], v[224:227], v[62:65]
	s_barrier
	v_add_u32_e32 v204, 0xc000, v200
	v_add_u32_e32 v205, 0xc000, v202
	ds_read_b128 v[130:133], v204 offset:0
	ds_read_b128 v[134:137], v204 offset:2048
	ds_read_b128 v[138:141], v204 offset:4096
	ds_read_b128 v[142:145], v204 offset:6144
	ds_read_b128 v[146:149], v205 offset:0
	ds_read_b128 v[150:153], v205 offset:2048
	ds_read_b128 v[154:157], v205 offset:4096
	ds_read_b128 v[158:161], v205 offset:6144
	v_add_u32_e32 v204, 0xc000, v201
	v_add_u32_e32 v205, 0xc000, v203
	ds_read_b128 v[212:215], v204 offset:0
	ds_read_b128 v[216:219], v204 offset:2048
	ds_read_b128 v[220:223], v204 offset:4096
	ds_read_b128 v[224:227], v204 offset:6144
	ds_read_b128 v[228:231], v205 offset:0
	ds_read_b128 v[232:235], v205 offset:2048
	ds_read_b128 v[236:239], v205 offset:4096
	ds_read_b128 v[240:243], v205 offset:6144
	s_add_u32 m0, s76, 0x0
	s_nop 0
	global_load_lds_dwordx4 v196, s[68:69]
	s_add_u32 m0, s76, 0x2000
	s_nop 0
	global_load_lds_dwordx4 v197, s[68:69]
	s_add_u32 m0, s76, 0x4000
	s_nop 0
	global_load_lds_dwordx4 v198, s[68:69]
	s_add_u32 m0, s76, 0x6000
	s_nop 0
	global_load_lds_dwordx4 v199, s[68:69]
	s_add_u32 m0, s76, 0x8000
	s_nop 0
	global_load_lds_dwordx4 v196, s[70:71]
	s_add_u32 m0, s76, 0xa000
	s_nop 0
	global_load_lds_dwordx4 v197, s[70:71]
	s_add_u32 s68, s68, 0x80
	s_addc_u32 s69, s69, 0
	s_add_u32 s70, s70, 0x80
	s_addc_u32 s71, s71, 0
	s_waitcnt vmcnt(6)
	s_waitcnt lgkmcnt(0)
	s_barrier
	v_mfma_f32_16x16x32_bf16 v[2:5], v[146:149], v[130:133], v[2:5]
	v_mfma_f32_16x16x32_bf16 v[6:9], v[150:153], v[130:133], v[6:9]
	v_mfma_f32_16x16x32_bf16 v[10:13], v[154:157], v[130:133], v[10:13]
	v_mfma_f32_16x16x32_bf16 v[14:17], v[158:161], v[130:133], v[14:17]
	v_mfma_f32_16x16x32_bf16 v[18:21], v[146:149], v[134:137], v[18:21]
	v_mfma_f32_16x16x32_bf16 v[22:25], v[150:153], v[134:137], v[22:25]
	v_mfma_f32_16x16x32_bf16 v[26:29], v[154:157], v[134:137], v[26:29]
	v_mfma_f32_16x16x32_bf16 v[30:33], v[158:161], v[134:137], v[30:33]
	v_mfma_f32_16x16x32_bf16 v[34:37], v[146:149], v[138:141], v[34:37]
	v_mfma_f32_16x16x32_bf16 v[38:41], v[150:153], v[138:141], v[38:41]
	v_mfma_f32_16x16x32_bf16 v[42:45], v[154:157], v[138:141], v[42:45]
	v_mfma_f32_16x16x32_bf16 v[46:49], v[158:161], v[138:141], v[46:49]
	v_mfma_f32_16x16x32_bf16 v[50:53], v[146:149], v[142:145], v[50:53]
	v_mfma_f32_16x16x32_bf16 v[54:57], v[150:153], v[142:145], v[54:57]
	v_mfma_f32_16x16x32_bf16 v[58:61], v[154:157], v[142:145], v[58:61]
	v_mfma_f32_16x16x32_bf16 v[62:65], v[158:161], v[142:145], v[62:65]
	v_mfma_f32_16x16x32_bf16 v[2:5], v[228:231], v[212:215], v[2:5]
	v_mfma_f32_16x16x32_bf16 v[6:9], v[232:235], v[212:215], v[6:9]
	v_mfma_f32_16x16x32_bf16 v[10:13], v[236:239], v[212:215], v[10:13]
	v_mfma_f32_16x16x32_bf16 v[14:17], v[240:243], v[212:215], v[14:17]
	v_mfma_f32_16x16x32_bf16 v[18:21], v[228:231], v[216:219], v[18:21]
	v_mfma_f32_16x16x32_bf16 v[22:25], v[232:235], v[216:219], v[22:25]
	v_mfma_f32_16x16x32_bf16 v[26:29], v[236:239], v[216:219], v[26:29]
	v_mfma_f32_16x16x32_bf16 v[30:33], v[240:243], v[216:219], v[30:33]
	v_mfma_f32_16x16x32_bf16 v[34:37], v[228:231], v[220:223], v[34:37]
	v_mfma_f32_16x16x32_bf16 v[38:41], v[232:235], v[220:223], v[38:41]
	v_mfma_f32_16x16x32_bf16 v[42:45], v[236:239], v[220:223], v[42:45]
	v_mfma_f32_16x16x32_bf16 v[46:49], v[240:243], v[220:223], v[46:49]
	v_mfma_f32_16x16x32_bf16 v[50:53], v[228:231], v[224:227], v[50:53]
	v_mfma_f32_16x16x32_bf16 v[54:57], v[232:235], v[224:227], v[54:57]
	v_mfma_f32_16x16x32_bf16 v[58:61], v[236:239], v[224:227], v[58:61]
	v_mfma_f32_16x16x32_bf16 v[62:65], v[240:243], v[224:227], v[62:65]
	s_barrier
	v_add_u32_e32 v204, 0x18000, v200
	v_add_u32_e32 v205, 0x18000, v202
	ds_read_b128 v[130:133], v204 offset:0
	ds_read_b128 v[134:137], v204 offset:2048
	ds_read_b128 v[138:141], v204 offset:4096
	ds_read_b128 v[142:145], v204 offset:6144
	ds_read_b128 v[146:149], v205 offset:0
	ds_read_b128 v[150:153], v205 offset:2048
	ds_read_b128 v[154:157], v205 offset:4096
	ds_read_b128 v[158:161], v205 offset:6144
	v_add_u32_e32 v204, 0x18000, v201
	v_add_u32_e32 v205, 0x18000, v203
	ds_read_b128 v[212:215], v204 offset:0
	ds_read_b128 v[216:219], v204 offset:2048
	ds_read_b128 v[220:223], v204 offset:4096
	ds_read_b128 v[224:227], v204 offset:6144
	ds_read_b128 v[228:231], v205 offset:0
	ds_read_b128 v[232:235], v205 offset:2048
	ds_read_b128 v[236:239], v205 offset:4096
	ds_read_b128 v[240:243], v205 offset:6144
	s_add_u32 m0, s76, 0xc000
	s_nop 0
	global_load_lds_dwordx4 v196, s[68:69]
	s_add_u32 m0, s76, 0xe000
	s_nop 0
	global_load_lds_dwordx4 v197, s[68:69]
	s_add_u32 m0, s76, 0x10000
	s_nop 0
	global_load_lds_dwordx4 v198, s[68:69]
	s_add_u32 m0, s76, 0x12000
	s_nop 0
	global_load_lds_dwordx4 v199, s[68:69]
	s_add_u32 m0, s76, 0x14000
	s_nop 0
	global_load_lds_dwordx4 v196, s[70:71]
	s_add_u32 m0, s76, 0x16000
	s_nop 0
	global_load_lds_dwordx4 v197, s[70:71]
	s_add_u32 s68, s68, 0x80
	s_addc_u32 s69, s69, 0
	s_add_u32 s70, s70, 0x80
	s_addc_u32 s71, s71, 0
	s_waitcnt vmcnt(6)
	s_waitcnt lgkmcnt(0)
	s_barrier
	v_mfma_f32_16x16x32_bf16 v[2:5], v[146:149], v[130:133], v[2:5]
	v_mfma_f32_16x16x32_bf16 v[6:9], v[150:153], v[130:133], v[6:9]
	v_mfma_f32_16x16x32_bf16 v[10:13], v[154:157], v[130:133], v[10:13]
	v_mfma_f32_16x16x32_bf16 v[14:17], v[158:161], v[130:133], v[14:17]
	v_mfma_f32_16x16x32_bf16 v[18:21], v[146:149], v[134:137], v[18:21]
	v_mfma_f32_16x16x32_bf16 v[22:25], v[150:153], v[134:137], v[22:25]
	v_mfma_f32_16x16x32_bf16 v[26:29], v[154:157], v[134:137], v[26:29]
	v_mfma_f32_16x16x32_bf16 v[30:33], v[158:161], v[134:137], v[30:33]
	v_mfma_f32_16x16x32_bf16 v[34:37], v[146:149], v[138:141], v[34:37]
	v_mfma_f32_16x16x32_bf16 v[38:41], v[150:153], v[138:141], v[38:41]
	v_mfma_f32_16x16x32_bf16 v[42:45], v[154:157], v[138:141], v[42:45]
	v_mfma_f32_16x16x32_bf16 v[46:49], v[158:161], v[138:141], v[46:49]
	v_mfma_f32_16x16x32_bf16 v[50:53], v[146:149], v[142:145], v[50:53]
	v_mfma_f32_16x16x32_bf16 v[54:57], v[150:153], v[142:145], v[54:57]
	v_mfma_f32_16x16x32_bf16 v[58:61], v[154:157], v[142:145], v[58:61]
	v_mfma_f32_16x16x32_bf16 v[62:65], v[158:161], v[142:145], v[62:65]
	v_mfma_f32_16x16x32_bf16 v[2:5], v[228:231], v[212:215], v[2:5]
	v_mfma_f32_16x16x32_bf16 v[6:9], v[232:235], v[212:215], v[6:9]
	v_mfma_f32_16x16x32_bf16 v[10:13], v[236:239], v[212:215], v[10:13]
	v_mfma_f32_16x16x32_bf16 v[14:17], v[240:243], v[212:215], v[14:17]
	v_mfma_f32_16x16x32_bf16 v[18:21], v[228:231], v[216:219], v[18:21]
	v_mfma_f32_16x16x32_bf16 v[22:25], v[232:235], v[216:219], v[22:25]
	v_mfma_f32_16x16x32_bf16 v[26:29], v[236:239], v[216:219], v[26:29]
	v_mfma_f32_16x16x32_bf16 v[30:33], v[240:243], v[216:219], v[30:33]
	v_mfma_f32_16x16x32_bf16 v[34:37], v[228:231], v[220:223], v[34:37]
	v_mfma_f32_16x16x32_bf16 v[38:41], v[232:235], v[220:223], v[38:41]
	v_mfma_f32_16x16x32_bf16 v[42:45], v[236:239], v[220:223], v[42:45]
	v_mfma_f32_16x16x32_bf16 v[46:49], v[240:243], v[220:223], v[46:49]
	v_mfma_f32_16x16x32_bf16 v[50:53], v[228:231], v[224:227], v[50:53]
	v_mfma_f32_16x16x32_bf16 v[54:57], v[232:235], v[224:227], v[54:57]
	v_mfma_f32_16x16x32_bf16 v[58:61], v[236:239], v[224:227], v[58:61]
	v_mfma_f32_16x16x32_bf16 v[62:65], v[240:243], v[224:227], v[62:65]
	s_barrier
	v_add_u32_e32 v204, 0x0, v200
	v_add_u32_e32 v205, 0x0, v202
	ds_read_b128 v[130:133], v204 offset:0
	ds_read_b128 v[134:137], v204 offset:2048
	ds_read_b128 v[138:141], v204 offset:4096
	ds_read_b128 v[142:145], v204 offset:6144
	ds_read_b128 v[146:149], v205 offset:0
	ds_read_b128 v[150:153], v205 offset:2048
	ds_read_b128 v[154:157], v205 offset:4096
	ds_read_b128 v[158:161], v205 offset:6144
	v_add_u32_e32 v204, 0x0, v201
	v_add_u32_e32 v205, 0x0, v203
	ds_read_b128 v[212:215], v204 offset:0
	ds_read_b128 v[216:219], v204 offset:2048
	ds_read_b128 v[220:223], v204 offset:4096
	ds_read_b128 v[224:227], v204 offset:6144
	ds_read_b128 v[228:231], v205 offset:0
	ds_read_b128 v[232:235], v205 offset:2048
	ds_read_b128 v[236:239], v205 offset:4096
	ds_read_b128 v[240:243], v205 offset:6144
	s_add_u32 m0, s76, 0x18000
	s_nop 0
	global_load_lds_dwordx4 v196, s[68:69]
	s_add_u32 m0, s76, 0x1a000
	s_nop 0
	global_load_lds_dwordx4 v197, s[68:69]
	s_add_u32 m0, s76, 0x1c000
	s_nop 0
	global_load_lds_dwordx4 v198, s[68:69]
	s_add_u32 m0, s76, 0x1e000
	s_nop 0
	global_load_lds_dwordx4 v199, s[68:69]
	s_add_u32 m0, s76, 0x20000
	s_nop 0
	global_load_lds_dwordx4 v196, s[70:71]
	s_add_u32 m0, s76, 0x22000
	s_nop 0
	global_load_lds_dwordx4 v197, s[70:71]
	s_add_u32 s68, s68, 0x80
	s_addc_u32 s69, s69, 0
	s_add_u32 s70, s70, 0x80
	s_addc_u32 s71, s71, 0
	s_waitcnt vmcnt(6)
	s_waitcnt lgkmcnt(0)
	s_barrier
	v_mfma_f32_16x16x32_bf16 v[2:5], v[146:149], v[130:133], v[2:5]
	v_mfma_f32_16x16x32_bf16 v[6:9], v[150:153], v[130:133], v[6:9]
	v_mfma_f32_16x16x32_bf16 v[10:13], v[154:157], v[130:133], v[10:13]
	v_mfma_f32_16x16x32_bf16 v[14:17], v[158:161], v[130:133], v[14:17]
	v_mfma_f32_16x16x32_bf16 v[18:21], v[146:149], v[134:137], v[18:21]
	v_mfma_f32_16x16x32_bf16 v[22:25], v[150:153], v[134:137], v[22:25]
	v_mfma_f32_16x16x32_bf16 v[26:29], v[154:157], v[134:137], v[26:29]
	v_mfma_f32_16x16x32_bf16 v[30:33], v[158:161], v[134:137], v[30:33]
	v_mfma_f32_16x16x32_bf16 v[34:37], v[146:149], v[138:141], v[34:37]
	v_mfma_f32_16x16x32_bf16 v[38:41], v[150:153], v[138:141], v[38:41]
	v_mfma_f32_16x16x32_bf16 v[42:45], v[154:157], v[138:141], v[42:45]
	v_mfma_f32_16x16x32_bf16 v[46:49], v[158:161], v[138:141], v[46:49]
	v_mfma_f32_16x16x32_bf16 v[50:53], v[146:149], v[142:145], v[50:53]
	v_mfma_f32_16x16x32_bf16 v[54:57], v[150:153], v[142:145], v[54:57]
	v_mfma_f32_16x16x32_bf16 v[58:61], v[154:157], v[142:145], v[58:61]
	v_mfma_f32_16x16x32_bf16 v[62:65], v[158:161], v[142:145], v[62:65]
	v_mfma_f32_16x16x32_bf16 v[2:5], v[228:231], v[212:215], v[2:5]
	v_mfma_f32_16x16x32_bf16 v[6:9], v[232:235], v[212:215], v[6:9]
	v_mfma_f32_16x16x32_bf16 v[10:13], v[236:239], v[212:215], v[10:13]
	v_mfma_f32_16x16x32_bf16 v[14:17], v[240:243], v[212:215], v[14:17]
	v_mfma_f32_16x16x32_bf16 v[18:21], v[228:231], v[216:219], v[18:21]
	v_mfma_f32_16x16x32_bf16 v[22:25], v[232:235], v[216:219], v[22:25]
	v_mfma_f32_16x16x32_bf16 v[26:29], v[236:239], v[216:219], v[26:29]
	v_mfma_f32_16x16x32_bf16 v[30:33], v[240:243], v[216:219], v[30:33]
	v_mfma_f32_16x16x32_bf16 v[34:37], v[228:231], v[220:223], v[34:37]
	v_mfma_f32_16x16x32_bf16 v[38:41], v[232:235], v[220:223], v[38:41]
	v_mfma_f32_16x16x32_bf16 v[42:45], v[236:239], v[220:223], v[42:45]
	v_mfma_f32_16x16x32_bf16 v[46:49], v[240:243], v[220:223], v[46:49]
	v_mfma_f32_16x16x32_bf16 v[50:53], v[228:231], v[224:227], v[50:53]
	v_mfma_f32_16x16x32_bf16 v[54:57], v[232:235], v[224:227], v[54:57]
	v_mfma_f32_16x16x32_bf16 v[58:61], v[236:239], v[224:227], v[58:61]
	v_mfma_f32_16x16x32_bf16 v[62:65], v[240:243], v[224:227], v[62:65]
	s_barrier
	v_add_u32_e32 v204, 0xc000, v200
	v_add_u32_e32 v205, 0xc000, v202
	ds_read_b128 v[130:133], v204 offset:0
	ds_read_b128 v[134:137], v204 offset:2048
	ds_read_b128 v[138:141], v204 offset:4096
	ds_read_b128 v[142:145], v204 offset:6144
	ds_read_b128 v[146:149], v205 offset:0
	ds_read_b128 v[150:153], v205 offset:2048
	ds_read_b128 v[154:157], v205 offset:4096
	ds_read_b128 v[158:161], v205 offset:6144
	v_add_u32_e32 v204, 0xc000, v201
	v_add_u32_e32 v205, 0xc000, v203
	ds_read_b128 v[212:215], v204 offset:0
	ds_read_b128 v[216:219], v204 offset:2048
	ds_read_b128 v[220:223], v204 offset:4096
	ds_read_b128 v[224:227], v204 offset:6144
	ds_read_b128 v[228:231], v205 offset:0
	ds_read_b128 v[232:235], v205 offset:2048
	ds_read_b128 v[236:239], v205 offset:4096
	ds_read_b128 v[240:243], v205 offset:6144
	s_add_u32 m0, s76, 0x0
	s_nop 0
	global_load_lds_dwordx4 v196, s[68:69]
	s_add_u32 m0, s76, 0x2000
	s_nop 0
	global_load_lds_dwordx4 v197, s[68:69]
	s_add_u32 m0, s76, 0x4000
	s_nop 0
	global_load_lds_dwordx4 v198, s[68:69]
	s_add_u32 m0, s76, 0x6000
	s_nop 0
	global_load_lds_dwordx4 v199, s[68:69]
	s_add_u32 m0, s76, 0x8000
	s_nop 0
	global_load_lds_dwordx4 v196, s[70:71]
	s_add_u32 m0, s76, 0xa000
	s_nop 0
	global_load_lds_dwordx4 v197, s[70:71]
	s_add_u32 s68, s68, 0x80
	s_addc_u32 s69, s69, 0
	s_add_u32 s70, s70, 0x80
	s_addc_u32 s71, s71, 0
	s_waitcnt vmcnt(6)
	s_waitcnt lgkmcnt(0)
	s_barrier
	v_mfma_f32_16x16x32_bf16 v[2:5], v[146:149], v[130:133], v[2:5]
	v_mfma_f32_16x16x32_bf16 v[6:9], v[150:153], v[130:133], v[6:9]
	v_mfma_f32_16x16x32_bf16 v[10:13], v[154:157], v[130:133], v[10:13]
	v_mfma_f32_16x16x32_bf16 v[14:17], v[158:161], v[130:133], v[14:17]
	v_mfma_f32_16x16x32_bf16 v[18:21], v[146:149], v[134:137], v[18:21]
	v_mfma_f32_16x16x32_bf16 v[22:25], v[150:153], v[134:137], v[22:25]
	v_mfma_f32_16x16x32_bf16 v[26:29], v[154:157], v[134:137], v[26:29]
	v_mfma_f32_16x16x32_bf16 v[30:33], v[158:161], v[134:137], v[30:33]
	v_mfma_f32_16x16x32_bf16 v[34:37], v[146:149], v[138:141], v[34:37]
	v_mfma_f32_16x16x32_bf16 v[38:41], v[150:153], v[138:141], v[38:41]
	v_mfma_f32_16x16x32_bf16 v[42:45], v[154:157], v[138:141], v[42:45]
	v_mfma_f32_16x16x32_bf16 v[46:49], v[158:161], v[138:141], v[46:49]
	v_mfma_f32_16x16x32_bf16 v[50:53], v[146:149], v[142:145], v[50:53]
	v_mfma_f32_16x16x32_bf16 v[54:57], v[150:153], v[142:145], v[54:57]
	v_mfma_f32_16x16x32_bf16 v[58:61], v[154:157], v[142:145], v[58:61]
	v_mfma_f32_16x16x32_bf16 v[62:65], v[158:161], v[142:145], v[62:65]
	v_mfma_f32_16x16x32_bf16 v[2:5], v[228:231], v[212:215], v[2:5]
	v_mfma_f32_16x16x32_bf16 v[6:9], v[232:235], v[212:215], v[6:9]
	v_mfma_f32_16x16x32_bf16 v[10:13], v[236:239], v[212:215], v[10:13]
	v_mfma_f32_16x16x32_bf16 v[14:17], v[240:243], v[212:215], v[14:17]
	v_mfma_f32_16x16x32_bf16 v[18:21], v[228:231], v[216:219], v[18:21]
	v_mfma_f32_16x16x32_bf16 v[22:25], v[232:235], v[216:219], v[22:25]
	v_mfma_f32_16x16x32_bf16 v[26:29], v[236:239], v[216:219], v[26:29]
	v_mfma_f32_16x16x32_bf16 v[30:33], v[240:243], v[216:219], v[30:33]
	v_mfma_f32_16x16x32_bf16 v[34:37], v[228:231], v[220:223], v[34:37]
	v_mfma_f32_16x16x32_bf16 v[38:41], v[232:235], v[220:223], v[38:41]
	v_mfma_f32_16x16x32_bf16 v[42:45], v[236:239], v[220:223], v[42:45]
	v_mfma_f32_16x16x32_bf16 v[46:49], v[240:243], v[220:223], v[46:49]
	v_mfma_f32_16x16x32_bf16 v[50:53], v[228:231], v[224:227], v[50:53]
	v_mfma_f32_16x16x32_bf16 v[54:57], v[232:235], v[224:227], v[54:57]
	v_mfma_f32_16x16x32_bf16 v[58:61], v[236:239], v[224:227], v[58:61]
	v_mfma_f32_16x16x32_bf16 v[62:65], v[240:243], v[224:227], v[62:65]
	s_nop 7
	v_lshlrev_b32_e32 v212, 16, v174
	v_and_b32_e32 v213, 0xffff0000, v174
	v_lshlrev_b32_e32 v214, 16, v175
	v_and_b32_e32 v215, 0xffff0000, v175
	v_pk_fma_f32 v[66:67], v[2:3], v[212:213], v[66:67]
	v_pk_fma_f32 v[68:69], v[4:5], v[214:215], v[68:69]
	v_lshlrev_b32_e32 v216, 16, v176
	v_and_b32_e32 v217, 0xffff0000, v176
	v_lshlrev_b32_e32 v218, 16, v177
	v_and_b32_e32 v219, 0xffff0000, v177
	v_pk_fma_f32 v[70:71], v[6:7], v[216:217], v[70:71]
	v_pk_fma_f32 v[72:73], v[8:9], v[218:219], v[72:73]
	v_lshlrev_b32_e32 v220, 16, v178
	v_and_b32_e32 v221, 0xffff0000, v178
	v_lshlrev_b32_e32 v222, 16, v179
	v_and_b32_e32 v223, 0xffff0000, v179
	v_pk_fma_f32 v[74:75], v[10:11], v[220:221], v[74:75]
	v_pk_fma_f32 v[76:77], v[12:13], v[222:223], v[76:77]
	v_lshlrev_b32_e32 v224, 16, v180
	v_and_b32_e32 v225, 0xffff0000, v180
	v_lshlrev_b32_e32 v226, 16, v181
	v_and_b32_e32 v227, 0xffff0000, v181
	v_pk_fma_f32 v[78:79], v[14:15], v[224:225], v[78:79]
	v_pk_fma_f32 v[80:81], v[16:17], v[226:227], v[80:81]
	v_lshlrev_b32_e32 v228, 16, v182
	v_and_b32_e32 v229, 0xffff0000, v182
	v_lshlrev_b32_e32 v230, 16, v183
	v_and_b32_e32 v231, 0xffff0000, v183
	v_pk_fma_f32 v[82:83], v[18:19], v[228:229], v[82:83]
	v_pk_fma_f32 v[84:85], v[20:21], v[230:231], v[84:85]
	v_lshlrev_b32_e32 v232, 16, v184
	v_and_b32_e32 v233, 0xffff0000, v184
	v_lshlrev_b32_e32 v234, 16, v185
	v_and_b32_e32 v235, 0xffff0000, v185
	v_pk_fma_f32 v[86:87], v[22:23], v[232:233], v[86:87]
	v_pk_fma_f32 v[88:89], v[24:25], v[234:235], v[88:89]
	v_lshlrev_b32_e32 v236, 16, v186
	v_and_b32_e32 v237, 0xffff0000, v186
	v_lshlrev_b32_e32 v238, 16, v187
	v_and_b32_e32 v239, 0xffff0000, v187
	v_pk_fma_f32 v[90:91], v[26:27], v[236:237], v[90:91]
	v_pk_fma_f32 v[92:93], v[28:29], v[238:239], v[92:93]
	v_lshlrev_b32_e32 v240, 16, v188
	v_and_b32_e32 v241, 0xffff0000, v188
	v_lshlrev_b32_e32 v242, 16, v189
	v_and_b32_e32 v243, 0xffff0000, v189
	v_pk_fma_f32 v[94:95], v[30:31], v[240:241], v[94:95]
	v_pk_fma_f32 v[96:97], v[32:33], v[242:243], v[96:97]
	v_lshlrev_b32_e32 v212, 16, v190
	v_and_b32_e32 v213, 0xffff0000, v190
	v_lshlrev_b32_e32 v214, 16, v191
	v_and_b32_e32 v215, 0xffff0000, v191
	v_pk_fma_f32 v[98:99], v[34:35], v[212:213], v[98:99]
	v_pk_fma_f32 v[100:101], v[36:37], v[214:215], v[100:101]
	v_lshlrev_b32_e32 v216, 16, v192
	v_and_b32_e32 v217, 0xffff0000, v192
	v_lshlrev_b32_e32 v218, 16, v193
	v_and_b32_e32 v219, 0xffff0000, v193
	v_pk_fma_f32 v[102:103], v[38:39], v[216:217], v[102:103]
	v_pk_fma_f32 v[104:105], v[40:41], v[218:219], v[104:105]
	v_lshlrev_b32_e32 v220, 16, v244
	v_and_b32_e32 v221, 0xffff0000, v244
	v_lshlrev_b32_e32 v222, 16, v245
	v_and_b32_e32 v223, 0xffff0000, v245
	v_pk_fma_f32 v[106:107], v[42:43], v[220:221], v[106:107]
	v_pk_fma_f32 v[108:109], v[44:45], v[222:223], v[108:109]
	v_lshlrev_b32_e32 v224, 16, v246
	v_and_b32_e32 v225, 0xffff0000, v246
	v_lshlrev_b32_e32 v226, 16, v247
	v_and_b32_e32 v227, 0xffff0000, v247
	v_pk_fma_f32 v[110:111], v[46:47], v[224:225], v[110:111]
	v_pk_fma_f32 v[112:113], v[48:49], v[226:227], v[112:113]
	v_lshlrev_b32_e32 v228, 16, v248
	v_and_b32_e32 v229, 0xffff0000, v248
	v_lshlrev_b32_e32 v230, 16, v249
	v_and_b32_e32 v231, 0xffff0000, v249
	v_pk_fma_f32 v[114:115], v[50:51], v[228:229], v[114:115]
	v_pk_fma_f32 v[116:117], v[52:53], v[230:231], v[116:117]
	v_lshlrev_b32_e32 v232, 16, v250
	v_and_b32_e32 v233, 0xffff0000, v250
	v_lshlrev_b32_e32 v234, 16, v251
	v_and_b32_e32 v235, 0xffff0000, v251
	v_pk_fma_f32 v[118:119], v[54:55], v[232:233], v[118:119]
	v_pk_fma_f32 v[120:121], v[56:57], v[234:235], v[120:121]
	v_lshlrev_b32_e32 v236, 16, v166
	v_and_b32_e32 v237, 0xffff0000, v166
	v_lshlrev_b32_e32 v238, 16, v167
	v_and_b32_e32 v239, 0xffff0000, v167
	v_pk_fma_f32 v[122:123], v[58:59], v[236:237], v[122:123]
	v_pk_fma_f32 v[124:125], v[60:61], v[238:239], v[124:125]
	v_lshlrev_b32_e32 v240, 16, v194
	v_and_b32_e32 v241, 0xffff0000, v194
	v_lshlrev_b32_e32 v242, 16, v195
	v_and_b32_e32 v243, 0xffff0000, v195
	v_pk_fma_f32 v[126:127], v[62:63], v[240:241], v[126:127]
	v_pk_fma_f32 v[128:129], v[64:65], v[242:243], v[128:129]
	s_barrier
	v_add_u32_e32 v204, 0x18000, v200
	v_add_u32_e32 v205, 0x18000, v202
	ds_read_b128 v[130:133], v204 offset:0
	ds_read_b128 v[134:137], v204 offset:2048
	ds_read_b128 v[138:141], v204 offset:4096
	ds_read_b128 v[142:145], v204 offset:6144
	ds_read_b128 v[146:149], v205 offset:0
	ds_read_b128 v[150:153], v205 offset:2048
	ds_read_b128 v[154:157], v205 offset:4096
	ds_read_b128 v[158:161], v205 offset:6144
	v_add_u32_e32 v204, 0x18000, v201
	v_add_u32_e32 v205, 0x18000, v203
	ds_read_b128 v[212:215], v204 offset:0
	ds_read_b128 v[216:219], v204 offset:2048
	ds_read_b128 v[220:223], v204 offset:4096
	ds_read_b128 v[224:227], v204 offset:6144
	ds_read_b128 v[228:231], v205 offset:0
	ds_read_b128 v[232:235], v205 offset:2048
	ds_read_b128 v[236:239], v205 offset:4096
	ds_read_b128 v[240:243], v205 offset:6144
	s_add_u32 m0, s76, 0xc000
	s_nop 0
	global_load_lds_dwordx4 v196, s[68:69]
	s_add_u32 m0, s76, 0xe000
	s_nop 0
	global_load_lds_dwordx4 v197, s[68:69]
	s_add_u32 m0, s76, 0x10000
	s_nop 0
	global_load_lds_dwordx4 v198, s[68:69]
	s_add_u32 m0, s76, 0x12000
	s_nop 0
	global_load_lds_dwordx4 v199, s[68:69]
	s_add_u32 m0, s76, 0x14000
	s_nop 0
	global_load_lds_dwordx4 v196, s[70:71]
	s_add_u32 m0, s76, 0x16000
	s_nop 0
	global_load_lds_dwordx4 v197, s[70:71]
	s_add_u32 s68, s68, 0x80
	s_addc_u32 s69, s69, 0
	s_add_u32 s70, s70, 0x80
	s_addc_u32 s71, s71, 0
	global_load_dwordx2 v[174:175], v206, s[72:73] offset:0
	global_load_dwordx2 v[176:177], v206, s[72:73] offset:32
	global_load_dwordx2 v[178:179], v206, s[72:73] offset:64
	global_load_dwordx2 v[180:181], v206, s[72:73] offset:96
	global_load_dwordx2 v[182:183], v207, s[72:73] offset:0
	global_load_dwordx2 v[184:185], v207, s[72:73] offset:32
	s_waitcnt vmcnt(12)
	s_waitcnt lgkmcnt(0)
	s_barrier
	v_mfma_f32_16x16x32_bf16 v[2:5], v[146:149], v[130:133], 0
	v_mfma_f32_16x16x32_bf16 v[6:9], v[150:153], v[130:133], 0
	v_mfma_f32_16x16x32_bf16 v[10:13], v[154:157], v[130:133], 0
	v_mfma_f32_16x16x32_bf16 v[14:17], v[158:161], v[130:133], 0
	v_mfma_f32_16x16x32_bf16 v[18:21], v[146:149], v[134:137], 0
	v_mfma_f32_16x16x32_bf16 v[22:25], v[150:153], v[134:137], 0
	v_mfma_f32_16x16x32_bf16 v[26:29], v[154:157], v[134:137], 0
	v_mfma_f32_16x16x32_bf16 v[30:33], v[158:161], v[134:137], 0
	v_mfma_f32_16x16x32_bf16 v[34:37], v[146:149], v[138:141], 0
	v_mfma_f32_16x16x32_bf16 v[38:41], v[150:153], v[138:141], 0
	v_mfma_f32_16x16x32_bf16 v[42:45], v[154:157], v[138:141], 0
	v_mfma_f32_16x16x32_bf16 v[46:49], v[158:161], v[138:141], 0
	v_mfma_f32_16x16x32_bf16 v[50:53], v[146:149], v[142:145], 0
	v_mfma_f32_16x16x32_bf16 v[54:57], v[150:153], v[142:145], 0
	v_mfma_f32_16x16x32_bf16 v[58:61], v[154:157], v[142:145], 0
	v_mfma_f32_16x16x32_bf16 v[62:65], v[158:161], v[142:145], 0
	v_mfma_f32_16x16x32_bf16 v[2:5], v[228:231], v[212:215], v[2:5]
	v_mfma_f32_16x16x32_bf16 v[6:9], v[232:235], v[212:215], v[6:9]
	v_mfma_f32_16x16x32_bf16 v[10:13], v[236:239], v[212:215], v[10:13]
	v_mfma_f32_16x16x32_bf16 v[14:17], v[240:243], v[212:215], v[14:17]
	v_mfma_f32_16x16x32_bf16 v[18:21], v[228:231], v[216:219], v[18:21]
	v_mfma_f32_16x16x32_bf16 v[22:25], v[232:235], v[216:219], v[22:25]
	v_mfma_f32_16x16x32_bf16 v[26:29], v[236:239], v[216:219], v[26:29]
	v_mfma_f32_16x16x32_bf16 v[30:33], v[240:243], v[216:219], v[30:33]
	v_mfma_f32_16x16x32_bf16 v[34:37], v[228:231], v[220:223], v[34:37]
	v_mfma_f32_16x16x32_bf16 v[38:41], v[232:235], v[220:223], v[38:41]
	v_mfma_f32_16x16x32_bf16 v[42:45], v[236:239], v[220:223], v[42:45]
	v_mfma_f32_16x16x32_bf16 v[46:49], v[240:243], v[220:223], v[46:49]
	v_mfma_f32_16x16x32_bf16 v[50:53], v[228:231], v[224:227], v[50:53]
	v_mfma_f32_16x16x32_bf16 v[54:57], v[232:235], v[224:227], v[54:57]
	v_mfma_f32_16x16x32_bf16 v[58:61], v[236:239], v[224:227], v[58:61]
	v_mfma_f32_16x16x32_bf16 v[62:65], v[240:243], v[224:227], v[62:65]
	s_barrier
	v_add_u32_e32 v204, 0x0, v200
	v_add_u32_e32 v205, 0x0, v202
	ds_read_b128 v[130:133], v204 offset:0
	ds_read_b128 v[134:137], v204 offset:2048
	ds_read_b128 v[138:141], v204 offset:4096
	ds_read_b128 v[142:145], v204 offset:6144
	ds_read_b128 v[146:149], v205 offset:0
	ds_read_b128 v[150:153], v205 offset:2048
	ds_read_b128 v[154:157], v205 offset:4096
	ds_read_b128 v[158:161], v205 offset:6144
	v_add_u32_e32 v204, 0x0, v201
	v_add_u32_e32 v205, 0x0, v203
	ds_read_b128 v[212:215], v204 offset:0
	ds_read_b128 v[216:219], v204 offset:2048
	ds_read_b128 v[220:223], v204 offset:4096
	ds_read_b128 v[224:227], v204 offset:6144
	ds_read_b128 v[228:231], v205 offset:0
	ds_read_b128 v[232:235], v205 offset:2048
	ds_read_b128 v[236:239], v205 offset:4096
	ds_read_b128 v[240:243], v205 offset:6144
	s_add_u32 m0, s76, 0x18000
	s_nop 0
	global_load_lds_dwordx4 v196, s[68:69]
	s_add_u32 m0, s76, 0x1a000
	s_nop 0
	global_load_lds_dwordx4 v197, s[68:69]
	s_add_u32 m0, s76, 0x1c000
	s_nop 0
	global_load_lds_dwordx4 v198, s[68:69]
	s_add_u32 m0, s76, 0x1e000
	s_nop 0
	global_load_lds_dwordx4 v199, s[68:69]
	s_add_u32 m0, s76, 0x20000
	s_nop 0
	global_load_lds_dwordx4 v196, s[70:71]
	s_add_u32 m0, s76, 0x22000
	s_nop 0
	global_load_lds_dwordx4 v197, s[70:71]
	s_add_u32 s68, s68, 0x80
	s_addc_u32 s69, s69, 0
	s_add_u32 s70, s70, 0x80
	s_addc_u32 s71, s71, 0
	global_load_dwordx2 v[186:187], v207, s[72:73] offset:64
	global_load_dwordx2 v[188:189], v207, s[72:73] offset:96
	global_load_dwordx2 v[190:191], v208, s[72:73] offset:0
	global_load_dwordx2 v[192:193], v208, s[72:73] offset:32
	global_load_dwordx2 v[244:245], v208, s[72:73] offset:64
	global_load_dwordx2 v[246:247], v208, s[72:73] offset:96
	s_waitcnt vmcnt(18)
	s_waitcnt lgkmcnt(0)
	s_barrier
	v_mfma_f32_16x16x32_bf16 v[2:5], v[146:149], v[130:133], v[2:5]
	v_mfma_f32_16x16x32_bf16 v[6:9], v[150:153], v[130:133], v[6:9]
	v_mfma_f32_16x16x32_bf16 v[10:13], v[154:157], v[130:133], v[10:13]
	v_mfma_f32_16x16x32_bf16 v[14:17], v[158:161], v[130:133], v[14:17]
	v_mfma_f32_16x16x32_bf16 v[18:21], v[146:149], v[134:137], v[18:21]
	v_mfma_f32_16x16x32_bf16 v[22:25], v[150:153], v[134:137], v[22:25]
	v_mfma_f32_16x16x32_bf16 v[26:29], v[154:157], v[134:137], v[26:29]
	v_mfma_f32_16x16x32_bf16 v[30:33], v[158:161], v[134:137], v[30:33]
	v_mfma_f32_16x16x32_bf16 v[34:37], v[146:149], v[138:141], v[34:37]
	v_mfma_f32_16x16x32_bf16 v[38:41], v[150:153], v[138:141], v[38:41]
	v_mfma_f32_16x16x32_bf16 v[42:45], v[154:157], v[138:141], v[42:45]
	v_mfma_f32_16x16x32_bf16 v[46:49], v[158:161], v[138:141], v[46:49]
	v_mfma_f32_16x16x32_bf16 v[50:53], v[146:149], v[142:145], v[50:53]
	v_mfma_f32_16x16x32_bf16 v[54:57], v[150:153], v[142:145], v[54:57]
	v_mfma_f32_16x16x32_bf16 v[58:61], v[154:157], v[142:145], v[58:61]
	v_mfma_f32_16x16x32_bf16 v[62:65], v[158:161], v[142:145], v[62:65]
	v_mfma_f32_16x16x32_bf16 v[2:5], v[228:231], v[212:215], v[2:5]
	v_mfma_f32_16x16x32_bf16 v[6:9], v[232:235], v[212:215], v[6:9]
	v_mfma_f32_16x16x32_bf16 v[10:13], v[236:239], v[212:215], v[10:13]
	v_mfma_f32_16x16x32_bf16 v[14:17], v[240:243], v[212:215], v[14:17]
	v_mfma_f32_16x16x32_bf16 v[18:21], v[228:231], v[216:219], v[18:21]
	v_mfma_f32_16x16x32_bf16 v[22:25], v[232:235], v[216:219], v[22:25]
	v_mfma_f32_16x16x32_bf16 v[26:29], v[236:239], v[216:219], v[26:29]
	v_mfma_f32_16x16x32_bf16 v[30:33], v[240:243], v[216:219], v[30:33]
	v_mfma_f32_16x16x32_bf16 v[34:37], v[228:231], v[220:223], v[34:37]
	v_mfma_f32_16x16x32_bf16 v[38:41], v[232:235], v[220:223], v[38:41]
	v_mfma_f32_16x16x32_bf16 v[42:45], v[236:239], v[220:223], v[42:45]
	v_mfma_f32_16x16x32_bf16 v[46:49], v[240:243], v[220:223], v[46:49]
	v_mfma_f32_16x16x32_bf16 v[50:53], v[228:231], v[224:227], v[50:53]
	v_mfma_f32_16x16x32_bf16 v[54:57], v[232:235], v[224:227], v[54:57]
	v_mfma_f32_16x16x32_bf16 v[58:61], v[236:239], v[224:227], v[58:61]
	v_mfma_f32_16x16x32_bf16 v[62:65], v[240:243], v[224:227], v[62:65]
	s_barrier
	v_add_u32_e32 v204, 0xc000, v200
	v_add_u32_e32 v205, 0xc000, v202
	ds_read_b128 v[130:133], v204 offset:0
	ds_read_b128 v[134:137], v204 offset:2048
	ds_read_b128 v[138:141], v204 offset:4096
	ds_read_b128 v[142:145], v204 offset:6144
	ds_read_b128 v[146:149], v205 offset:0
	ds_read_b128 v[150:153], v205 offset:2048
	ds_read_b128 v[154:157], v205 offset:4096
	ds_read_b128 v[158:161], v205 offset:6144
	v_add_u32_e32 v204, 0xc000, v201
	v_add_u32_e32 v205, 0xc000, v203
	ds_read_b128 v[212:215], v204 offset:0
	ds_read_b128 v[216:219], v204 offset:2048
	ds_read_b128 v[220:223], v204 offset:4096
	ds_read_b128 v[224:227], v204 offset:6144
	ds_read_b128 v[228:231], v205 offset:0
	ds_read_b128 v[232:235], v205 offset:2048
	ds_read_b128 v[236:239], v205 offset:4096
	ds_read_b128 v[240:243], v205 offset:6144
	s_add_u32 m0, s76, 0x0
	s_nop 0
	global_load_lds_dwordx4 v196, s[68:69]
	s_add_u32 m0, s76, 0x2000
	s_nop 0
	global_load_lds_dwordx4 v197, s[68:69]
	s_add_u32 m0, s76, 0x4000
	s_nop 0
	global_load_lds_dwordx4 v198, s[68:69]
	s_add_u32 m0, s76, 0x6000
	s_nop 0
	global_load_lds_dwordx4 v199, s[68:69]
	s_add_u32 m0, s76, 0x8000
	s_nop 0
	global_load_lds_dwordx4 v196, s[70:71]
	s_add_u32 m0, s76, 0xa000
	s_nop 0
	global_load_lds_dwordx4 v197, s[70:71]
	s_add_u32 s68, s68, 0x80
	s_addc_u32 s69, s69, 0
	s_add_u32 s70, s70, 0x80
	s_addc_u32 s71, s71, 0
	global_load_dwordx2 v[248:249], v209, s[72:73] offset:0
	global_load_dwordx2 v[250:251], v209, s[72:73] offset:32
	global_load_dwordx2 v[166:167], v209, s[72:73] offset:64
	global_load_dwordx2 v[194:195], v209, s[72:73] offset:96
	s_add_u32 s72, s72, 0x800
	s_addc_u32 s73, s73, 0
	s_waitcnt vmcnt(16)
	s_waitcnt lgkmcnt(0)
	s_barrier
	v_mfma_f32_16x16x32_bf16 v[2:5], v[146:149], v[130:133], v[2:5]
	v_mfma_f32_16x16x32_bf16 v[6:9], v[150:153], v[130:133], v[6:9]
	v_mfma_f32_16x16x32_bf16 v[10:13], v[154:157], v[130:133], v[10:13]
	v_mfma_f32_16x16x32_bf16 v[14:17], v[158:161], v[130:133], v[14:17]
	v_mfma_f32_16x16x32_bf16 v[18:21], v[146:149], v[134:137], v[18:21]
	v_mfma_f32_16x16x32_bf16 v[22:25], v[150:153], v[134:137], v[22:25]
	v_mfma_f32_16x16x32_bf16 v[26:29], v[154:157], v[134:137], v[26:29]
	v_mfma_f32_16x16x32_bf16 v[30:33], v[158:161], v[134:137], v[30:33]
	v_mfma_f32_16x16x32_bf16 v[34:37], v[146:149], v[138:141], v[34:37]
	v_mfma_f32_16x16x32_bf16 v[38:41], v[150:153], v[138:141], v[38:41]
	v_mfma_f32_16x16x32_bf16 v[42:45], v[154:157], v[138:141], v[42:45]
	v_mfma_f32_16x16x32_bf16 v[46:49], v[158:161], v[138:141], v[46:49]
	v_mfma_f32_16x16x32_bf16 v[50:53], v[146:149], v[142:145], v[50:53]
	v_mfma_f32_16x16x32_bf16 v[54:57], v[150:153], v[142:145], v[54:57]
	v_mfma_f32_16x16x32_bf16 v[58:61], v[154:157], v[142:145], v[58:61]
	v_mfma_f32_16x16x32_bf16 v[62:65], v[158:161], v[142:145], v[62:65]
	v_mfma_f32_16x16x32_bf16 v[2:5], v[228:231], v[212:215], v[2:5]
	v_mfma_f32_16x16x32_bf16 v[6:9], v[232:235], v[212:215], v[6:9]
	v_mfma_f32_16x16x32_bf16 v[10:13], v[236:239], v[212:215], v[10:13]
	v_mfma_f32_16x16x32_bf16 v[14:17], v[240:243], v[212:215], v[14:17]
	v_mfma_f32_16x16x32_bf16 v[18:21], v[228:231], v[216:219], v[18:21]
	v_mfma_f32_16x16x32_bf16 v[22:25], v[232:235], v[216:219], v[22:25]
	v_mfma_f32_16x16x32_bf16 v[26:29], v[236:239], v[216:219], v[26:29]
	v_mfma_f32_16x16x32_bf16 v[30:33], v[240:243], v[216:219], v[30:33]
	v_mfma_f32_16x16x32_bf16 v[34:37], v[228:231], v[220:223], v[34:37]
	v_mfma_f32_16x16x32_bf16 v[38:41], v[232:235], v[220:223], v[38:41]
	v_mfma_f32_16x16x32_bf16 v[42:45], v[236:239], v[220:223], v[42:45]
	v_mfma_f32_16x16x32_bf16 v[46:49], v[240:243], v[220:223], v[46:49]
	v_mfma_f32_16x16x32_bf16 v[50:53], v[228:231], v[224:227], v[50:53]
	v_mfma_f32_16x16x32_bf16 v[54:57], v[232:235], v[224:227], v[54:57]
	v_mfma_f32_16x16x32_bf16 v[58:61], v[236:239], v[224:227], v[58:61]
	v_mfma_f32_16x16x32_bf16 v[62:65], v[240:243], v[224:227], v[62:65]
	s_barrier
	v_add_u32_e32 v204, 0x18000, v200
	v_add_u32_e32 v205, 0x18000, v202
	ds_read_b128 v[130:133], v204 offset:0
	ds_read_b128 v[134:137], v204 offset:2048
	ds_read_b128 v[138:141], v204 offset:4096
	ds_read_b128 v[142:145], v204 offset:6144
	ds_read_b128 v[146:149], v205 offset:0
	ds_read_b128 v[150:153], v205 offset:2048
	ds_read_b128 v[154:157], v205 offset:4096
	ds_read_b128 v[158:161], v205 offset:6144
	v_add_u32_e32 v204, 0x18000, v201
	v_add_u32_e32 v205, 0x18000, v203
	ds_read_b128 v[212:215], v204 offset:0
	ds_read_b128 v[216:219], v204 offset:2048
	ds_read_b128 v[220:223], v204 offset:4096
	ds_read_b128 v[224:227], v204 offset:6144
	ds_read_b128 v[228:231], v205 offset:0
	ds_read_b128 v[232:235], v205 offset:2048
	ds_read_b128 v[236:239], v205 offset:4096
	ds_read_b128 v[240:243], v205 offset:6144
	s_add_u32 m0, s76, 0xc000
	s_nop 0
	global_load_lds_dwordx4 v196, s[68:69]
	s_add_u32 m0, s76, 0xe000
	s_nop 0
	global_load_lds_dwordx4 v197, s[68:69]
	s_add_u32 m0, s76, 0x10000
	s_nop 0
	global_load_lds_dwordx4 v198, s[68:69]
	s_add_u32 m0, s76, 0x12000
	s_nop 0
	global_load_lds_dwordx4 v199, s[68:69]
	s_add_u32 m0, s76, 0x14000
	s_nop 0
	global_load_lds_dwordx4 v196, s[70:71]
	s_add_u32 m0, s76, 0x16000
	s_nop 0
	global_load_lds_dwordx4 v197, s[70:71]
	s_add_u32 s68, s68, 0x80
	s_addc_u32 s69, s69, 0
	s_add_u32 s70, s70, 0x80
	s_addc_u32 s71, s71, 0
	s_waitcnt vmcnt(10)
	s_waitcnt lgkmcnt(0)
	s_barrier
	v_mfma_f32_16x16x32_bf16 v[2:5], v[146:149], v[130:133], v[2:5]
	v_mfma_f32_16x16x32_bf16 v[6:9], v[150:153], v[130:133], v[6:9]
	v_mfma_f32_16x16x32_bf16 v[10:13], v[154:157], v[130:133], v[10:13]
	v_mfma_f32_16x16x32_bf16 v[14:17], v[158:161], v[130:133], v[14:17]
	v_mfma_f32_16x16x32_bf16 v[18:21], v[146:149], v[134:137], v[18:21]
	v_mfma_f32_16x16x32_bf16 v[22:25], v[150:153], v[134:137], v[22:25]
	v_mfma_f32_16x16x32_bf16 v[26:29], v[154:157], v[134:137], v[26:29]
	v_mfma_f32_16x16x32_bf16 v[30:33], v[158:161], v[134:137], v[30:33]
	v_mfma_f32_16x16x32_bf16 v[34:37], v[146:149], v[138:141], v[34:37]
	v_mfma_f32_16x16x32_bf16 v[38:41], v[150:153], v[138:141], v[38:41]
	v_mfma_f32_16x16x32_bf16 v[42:45], v[154:157], v[138:141], v[42:45]
	v_mfma_f32_16x16x32_bf16 v[46:49], v[158:161], v[138:141], v[46:49]
	v_mfma_f32_16x16x32_bf16 v[50:53], v[146:149], v[142:145], v[50:53]
	v_mfma_f32_16x16x32_bf16 v[54:57], v[150:153], v[142:145], v[54:57]
	v_mfma_f32_16x16x32_bf16 v[58:61], v[154:157], v[142:145], v[58:61]
	v_mfma_f32_16x16x32_bf16 v[62:65], v[158:161], v[142:145], v[62:65]
	v_mfma_f32_16x16x32_bf16 v[2:5], v[228:231], v[212:215], v[2:5]
	v_mfma_f32_16x16x32_bf16 v[6:9], v[232:235], v[212:215], v[6:9]
	v_mfma_f32_16x16x32_bf16 v[10:13], v[236:239], v[212:215], v[10:13]
	v_mfma_f32_16x16x32_bf16 v[14:17], v[240:243], v[212:215], v[14:17]
	v_mfma_f32_16x16x32_bf16 v[18:21], v[228:231], v[216:219], v[18:21]
	v_mfma_f32_16x16x32_bf16 v[22:25], v[232:235], v[216:219], v[22:25]
	v_mfma_f32_16x16x32_bf16 v[26:29], v[236:239], v[216:219], v[26:29]
	v_mfma_f32_16x16x32_bf16 v[30:33], v[240:243], v[216:219], v[30:33]
	v_mfma_f32_16x16x32_bf16 v[34:37], v[228:231], v[220:223], v[34:37]
	v_mfma_f32_16x16x32_bf16 v[38:41], v[232:235], v[220:223], v[38:41]
	v_mfma_f32_16x16x32_bf16 v[42:45], v[236:239], v[220:223], v[42:45]
	v_mfma_f32_16x16x32_bf16 v[46:49], v[240:243], v[220:223], v[46:49]
	v_mfma_f32_16x16x32_bf16 v[50:53], v[228:231], v[224:227], v[50:53]
	v_mfma_f32_16x16x32_bf16 v[54:57], v[232:235], v[224:227], v[54:57]
	v_mfma_f32_16x16x32_bf16 v[58:61], v[236:239], v[224:227], v[58:61]
	v_mfma_f32_16x16x32_bf16 v[62:65], v[240:243], v[224:227], v[62:65]
	s_barrier
	v_add_u32_e32 v204, 0x0, v200
	v_add_u32_e32 v205, 0x0, v202
	ds_read_b128 v[130:133], v204 offset:0
	ds_read_b128 v[134:137], v204 offset:2048
	ds_read_b128 v[138:141], v204 offset:4096
	ds_read_b128 v[142:145], v204 offset:6144
	ds_read_b128 v[146:149], v205 offset:0
	ds_read_b128 v[150:153], v205 offset:2048
	ds_read_b128 v[154:157], v205 offset:4096
	ds_read_b128 v[158:161], v205 offset:6144
	v_add_u32_e32 v204, 0x0, v201
	v_add_u32_e32 v205, 0x0, v203
	ds_read_b128 v[212:215], v204 offset:0
	ds_read_b128 v[216:219], v204 offset:2048
	ds_read_b128 v[220:223], v204 offset:4096
	ds_read_b128 v[224:227], v204 offset:6144
	ds_read_b128 v[228:231], v205 offset:0
	ds_read_b128 v[232:235], v205 offset:2048
	ds_read_b128 v[236:239], v205 offset:4096
	ds_read_b128 v[240:243], v205 offset:6144
	s_add_u32 m0, s76, 0x18000
	s_nop 0
	global_load_lds_dwordx4 v196, s[68:69]
	s_add_u32 m0, s76, 0x1a000
	s_nop 0
	global_load_lds_dwordx4 v197, s[68:69]
	s_add_u32 m0, s76, 0x1c000
	s_nop 0
	global_load_lds_dwordx4 v198, s[68:69]
	s_add_u32 m0, s76, 0x1e000
	s_nop 0
	global_load_lds_dwordx4 v199, s[68:69]
	s_add_u32 m0, s76, 0x20000
	s_nop 0
	global_load_lds_dwordx4 v196, s[70:71]
	s_add_u32 m0, s76, 0x22000
	s_nop 0
	global_load_lds_dwordx4 v197, s[70:71]
	s_add_u32 s68, s68, 0x80
	s_addc_u32 s69, s69, 0
	s_add_u32 s70, s70, 0x80
	s_addc_u32 s71, s71, 0
	s_waitcnt vmcnt(6)
	s_waitcnt lgkmcnt(0)
	s_barrier
	v_mfma_f32_16x16x32_bf16 v[2:5], v[146:149], v[130:133], v[2:5]
	v_mfma_f32_16x16x32_bf16 v[6:9], v[150:153], v[130:133], v[6:9]
	v_mfma_f32_16x16x32_bf16 v[10:13], v[154:157], v[130:133], v[10:13]
	v_mfma_f32_16x16x32_bf16 v[14:17], v[158:161], v[130:133], v[14:17]
	v_mfma_f32_16x16x32_bf16 v[18:21], v[146:149], v[134:137], v[18:21]
	v_mfma_f32_16x16x32_bf16 v[22:25], v[150:153], v[134:137], v[22:25]
	v_mfma_f32_16x16x32_bf16 v[26:29], v[154:157], v[134:137], v[26:29]
	v_mfma_f32_16x16x32_bf16 v[30:33], v[158:161], v[134:137], v[30:33]
	v_mfma_f32_16x16x32_bf16 v[34:37], v[146:149], v[138:141], v[34:37]
	v_mfma_f32_16x16x32_bf16 v[38:41], v[150:153], v[138:141], v[38:41]
	v_mfma_f32_16x16x32_bf16 v[42:45], v[154:157], v[138:141], v[42:45]
	v_mfma_f32_16x16x32_bf16 v[46:49], v[158:161], v[138:141], v[46:49]
	v_mfma_f32_16x16x32_bf16 v[50:53], v[146:149], v[142:145], v[50:53]
	v_mfma_f32_16x16x32_bf16 v[54:57], v[150:153], v[142:145], v[54:57]
	v_mfma_f32_16x16x32_bf16 v[58:61], v[154:157], v[142:145], v[58:61]
	v_mfma_f32_16x16x32_bf16 v[62:65], v[158:161], v[142:145], v[62:65]
	v_mfma_f32_16x16x32_bf16 v[2:5], v[228:231], v[212:215], v[2:5]
	v_mfma_f32_16x16x32_bf16 v[6:9], v[232:235], v[212:215], v[6:9]
	v_mfma_f32_16x16x32_bf16 v[10:13], v[236:239], v[212:215], v[10:13]
	v_mfma_f32_16x16x32_bf16 v[14:17], v[240:243], v[212:215], v[14:17]
	v_mfma_f32_16x16x32_bf16 v[18:21], v[228:231], v[216:219], v[18:21]
	v_mfma_f32_16x16x32_bf16 v[22:25], v[232:235], v[216:219], v[22:25]
	v_mfma_f32_16x16x32_bf16 v[26:29], v[236:239], v[216:219], v[26:29]
	v_mfma_f32_16x16x32_bf16 v[30:33], v[240:243], v[216:219], v[30:33]
	v_mfma_f32_16x16x32_bf16 v[34:37], v[228:231], v[220:223], v[34:37]
	v_mfma_f32_16x16x32_bf16 v[38:41], v[232:235], v[220:223], v[38:41]
	v_mfma_f32_16x16x32_bf16 v[42:45], v[236:239], v[220:223], v[42:45]
	v_mfma_f32_16x16x32_bf16 v[46:49], v[240:243], v[220:223], v[46:49]
	v_mfma_f32_16x16x32_bf16 v[50:53], v[228:231], v[224:227], v[50:53]
	v_mfma_f32_16x16x32_bf16 v[54:57], v[232:235], v[224:227], v[54:57]
	v_mfma_f32_16x16x32_bf16 v[58:61], v[236:239], v[224:227], v[58:61]
	v_mfma_f32_16x16x32_bf16 v[62:65], v[240:243], v[224:227], v[62:65]
	s_barrier
	v_add_u32_e32 v204, 0xc000, v200
	v_add_u32_e32 v205, 0xc000, v202
	ds_read_b128 v[130:133], v204 offset:0
	ds_read_b128 v[134:137], v204 offset:2048
	ds_read_b128 v[138:141], v204 offset:4096
	ds_read_b128 v[142:145], v204 offset:6144
	ds_read_b128 v[146:149], v205 offset:0
	ds_read_b128 v[150:153], v205 offset:2048
	ds_read_b128 v[154:157], v205 offset:4096
	ds_read_b128 v[158:161], v205 offset:6144
	v_add_u32_e32 v204, 0xc000, v201
	v_add_u32_e32 v205, 0xc000, v203
	ds_read_b128 v[212:215], v204 offset:0
	ds_read_b128 v[216:219], v204 offset:2048
	ds_read_b128 v[220:223], v204 offset:4096
	ds_read_b128 v[224:227], v204 offset:6144
	ds_read_b128 v[228:231], v205 offset:0
	ds_read_b128 v[232:235], v205 offset:2048
	ds_read_b128 v[236:239], v205 offset:4096
	ds_read_b128 v[240:243], v205 offset:6144
	s_add_u32 m0, s76, 0x0
	s_nop 0
	global_load_lds_dwordx4 v196, s[68:69]
	s_add_u32 m0, s76, 0x2000
	s_nop 0
	global_load_lds_dwordx4 v197, s[68:69]
	s_add_u32 m0, s76, 0x4000
	s_nop 0
	global_load_lds_dwordx4 v198, s[68:69]
	s_add_u32 m0, s76, 0x6000
	s_nop 0
	global_load_lds_dwordx4 v199, s[68:69]
	s_add_u32 m0, s76, 0x8000
	s_nop 0
	global_load_lds_dwordx4 v196, s[70:71]
	s_add_u32 m0, s76, 0xa000
	s_nop 0
	global_load_lds_dwordx4 v197, s[70:71]
	s_add_u32 s68, s68, 0x80
	s_addc_u32 s69, s69, 0
	s_add_u32 s70, s70, 0x80
	s_addc_u32 s71, s71, 0
	s_waitcnt vmcnt(6)
	s_waitcnt lgkmcnt(0)
	s_barrier
	v_mfma_f32_16x16x32_bf16 v[2:5], v[146:149], v[130:133], v[2:5]
	v_mfma_f32_16x16x32_bf16 v[6:9], v[150:153], v[130:133], v[6:9]
	v_mfma_f32_16x16x32_bf16 v[10:13], v[154:157], v[130:133], v[10:13]
	v_mfma_f32_16x16x32_bf16 v[14:17], v[158:161], v[130:133], v[14:17]
	v_mfma_f32_16x16x32_bf16 v[18:21], v[146:149], v[134:137], v[18:21]
	v_mfma_f32_16x16x32_bf16 v[22:25], v[150:153], v[134:137], v[22:25]
	v_mfma_f32_16x16x32_bf16 v[26:29], v[154:157], v[134:137], v[26:29]
	v_mfma_f32_16x16x32_bf16 v[30:33], v[158:161], v[134:137], v[30:33]
	v_mfma_f32_16x16x32_bf16 v[34:37], v[146:149], v[138:141], v[34:37]
	v_mfma_f32_16x16x32_bf16 v[38:41], v[150:153], v[138:141], v[38:41]
	v_mfma_f32_16x16x32_bf16 v[42:45], v[154:157], v[138:141], v[42:45]
	v_mfma_f32_16x16x32_bf16 v[46:49], v[158:161], v[138:141], v[46:49]
	v_mfma_f32_16x16x32_bf16 v[50:53], v[146:149], v[142:145], v[50:53]
	v_mfma_f32_16x16x32_bf16 v[54:57], v[150:153], v[142:145], v[54:57]
	v_mfma_f32_16x16x32_bf16 v[58:61], v[154:157], v[142:145], v[58:61]
	v_mfma_f32_16x16x32_bf16 v[62:65], v[158:161], v[142:145], v[62:65]
	v_mfma_f32_16x16x32_bf16 v[2:5], v[228:231], v[212:215], v[2:5]
	v_mfma_f32_16x16x32_bf16 v[6:9], v[232:235], v[212:215], v[6:9]
	v_mfma_f32_16x16x32_bf16 v[10:13], v[236:239], v[212:215], v[10:13]
	v_mfma_f32_16x16x32_bf16 v[14:17], v[240:243], v[212:215], v[14:17]
	v_mfma_f32_16x16x32_bf16 v[18:21], v[228:231], v[216:219], v[18:21]
	v_mfma_f32_16x16x32_bf16 v[22:25], v[232:235], v[216:219], v[22:25]
	v_mfma_f32_16x16x32_bf16 v[26:29], v[236:239], v[216:219], v[26:29]
	v_mfma_f32_16x16x32_bf16 v[30:33], v[240:243], v[216:219], v[30:33]
	v_mfma_f32_16x16x32_bf16 v[34:37], v[228:231], v[220:223], v[34:37]
	v_mfma_f32_16x16x32_bf16 v[38:41], v[232:235], v[220:223], v[38:41]
	v_mfma_f32_16x16x32_bf16 v[42:45], v[236:239], v[220:223], v[42:45]
	v_mfma_f32_16x16x32_bf16 v[46:49], v[240:243], v[220:223], v[46:49]
	v_mfma_f32_16x16x32_bf16 v[50:53], v[228:231], v[224:227], v[50:53]
	v_mfma_f32_16x16x32_bf16 v[54:57], v[232:235], v[224:227], v[54:57]
	v_mfma_f32_16x16x32_bf16 v[58:61], v[236:239], v[224:227], v[58:61]
	v_mfma_f32_16x16x32_bf16 v[62:65], v[240:243], v[224:227], v[62:65]
	s_barrier
	v_add_u32_e32 v204, 0x18000, v200
	v_add_u32_e32 v205, 0x18000, v202
	ds_read_b128 v[130:133], v204 offset:0
	ds_read_b128 v[134:137], v204 offset:2048
	ds_read_b128 v[138:141], v204 offset:4096
	ds_read_b128 v[142:145], v204 offset:6144
	ds_read_b128 v[146:149], v205 offset:0
	ds_read_b128 v[150:153], v205 offset:2048
	ds_read_b128 v[154:157], v205 offset:4096
	ds_read_b128 v[158:161], v205 offset:6144
	v_add_u32_e32 v204, 0x18000, v201
	v_add_u32_e32 v205, 0x18000, v203
	ds_read_b128 v[212:215], v204 offset:0
	ds_read_b128 v[216:219], v204 offset:2048
	ds_read_b128 v[220:223], v204 offset:4096
	ds_read_b128 v[224:227], v204 offset:6144
	ds_read_b128 v[228:231], v205 offset:0
	ds_read_b128 v[232:235], v205 offset:2048
	ds_read_b128 v[236:239], v205 offset:4096
	ds_read_b128 v[240:243], v205 offset:6144
	s_add_u32 m0, s76, 0xc000
	s_nop 0
	global_load_lds_dwordx4 v196, s[68:69]
	s_add_u32 m0, s76, 0xe000
	s_nop 0
	global_load_lds_dwordx4 v197, s[68:69]
	s_add_u32 m0, s76, 0x10000
	s_nop 0
	global_load_lds_dwordx4 v198, s[68:69]
	s_add_u32 m0, s76, 0x12000
	s_nop 0
	global_load_lds_dwordx4 v199, s[68:69]
	s_add_u32 m0, s76, 0x14000
	s_nop 0
	global_load_lds_dwordx4 v196, s[70:71]
	s_add_u32 m0, s76, 0x16000
	s_nop 0
	global_load_lds_dwordx4 v197, s[70:71]
	s_add_u32 s68, s68, 0x80
	s_addc_u32 s69, s69, 0
	s_add_u32 s70, s70, 0x80
	s_addc_u32 s71, s71, 0
	s_waitcnt vmcnt(6)
	s_waitcnt lgkmcnt(0)
	s_barrier
	v_mfma_f32_16x16x32_bf16 v[2:5], v[146:149], v[130:133], v[2:5]
	v_mfma_f32_16x16x32_bf16 v[6:9], v[150:153], v[130:133], v[6:9]
	v_mfma_f32_16x16x32_bf16 v[10:13], v[154:157], v[130:133], v[10:13]
	v_mfma_f32_16x16x32_bf16 v[14:17], v[158:161], v[130:133], v[14:17]
	v_mfma_f32_16x16x32_bf16 v[18:21], v[146:149], v[134:137], v[18:21]
	v_mfma_f32_16x16x32_bf16 v[22:25], v[150:153], v[134:137], v[22:25]
	v_mfma_f32_16x16x32_bf16 v[26:29], v[154:157], v[134:137], v[26:29]
	v_mfma_f32_16x16x32_bf16 v[30:33], v[158:161], v[134:137], v[30:33]
	v_mfma_f32_16x16x32_bf16 v[34:37], v[146:149], v[138:141], v[34:37]
	v_mfma_f32_16x16x32_bf16 v[38:41], v[150:153], v[138:141], v[38:41]
	v_mfma_f32_16x16x32_bf16 v[42:45], v[154:157], v[138:141], v[42:45]
	v_mfma_f32_16x16x32_bf16 v[46:49], v[158:161], v[138:141], v[46:49]
	v_mfma_f32_16x16x32_bf16 v[50:53], v[146:149], v[142:145], v[50:53]
	v_mfma_f32_16x16x32_bf16 v[54:57], v[150:153], v[142:145], v[54:57]
	v_mfma_f32_16x16x32_bf16 v[58:61], v[154:157], v[142:145], v[58:61]
	v_mfma_f32_16x16x32_bf16 v[62:65], v[158:161], v[142:145], v[62:65]
	v_mfma_f32_16x16x32_bf16 v[2:5], v[228:231], v[212:215], v[2:5]
	v_mfma_f32_16x16x32_bf16 v[6:9], v[232:235], v[212:215], v[6:9]
	v_mfma_f32_16x16x32_bf16 v[10:13], v[236:239], v[212:215], v[10:13]
	v_mfma_f32_16x16x32_bf16 v[14:17], v[240:243], v[212:215], v[14:17]
	v_mfma_f32_16x16x32_bf16 v[18:21], v[228:231], v[216:219], v[18:21]
	v_mfma_f32_16x16x32_bf16 v[22:25], v[232:235], v[216:219], v[22:25]
	v_mfma_f32_16x16x32_bf16 v[26:29], v[236:239], v[216:219], v[26:29]
	v_mfma_f32_16x16x32_bf16 v[30:33], v[240:243], v[216:219], v[30:33]
	v_mfma_f32_16x16x32_bf16 v[34:37], v[228:231], v[220:223], v[34:37]
	v_mfma_f32_16x16x32_bf16 v[38:41], v[232:235], v[220:223], v[38:41]
	v_mfma_f32_16x16x32_bf16 v[42:45], v[236:239], v[220:223], v[42:45]
	v_mfma_f32_16x16x32_bf16 v[46:49], v[240:243], v[220:223], v[46:49]
	v_mfma_f32_16x16x32_bf16 v[50:53], v[228:231], v[224:227], v[50:53]
	v_mfma_f32_16x16x32_bf16 v[54:57], v[232:235], v[224:227], v[54:57]
	v_mfma_f32_16x16x32_bf16 v[58:61], v[236:239], v[224:227], v[58:61]
	v_mfma_f32_16x16x32_bf16 v[62:65], v[240:243], v[224:227], v[62:65]
	s_barrier
	v_add_u32_e32 v204, 0x0, v200
	v_add_u32_e32 v205, 0x0, v202
	ds_read_b128 v[130:133], v204 offset:0
	ds_read_b128 v[134:137], v204 offset:2048
	ds_read_b128 v[138:141], v204 offset:4096
	ds_read_b128 v[142:145], v204 offset:6144
	ds_read_b128 v[146:149], v205 offset:0
	ds_read_b128 v[150:153], v205 offset:2048
	ds_read_b128 v[154:157], v205 offset:4096
	ds_read_b128 v[158:161], v205 offset:6144
	v_add_u32_e32 v204, 0x0, v201
	v_add_u32_e32 v205, 0x0, v203
	ds_read_b128 v[212:215], v204 offset:0
	ds_read_b128 v[216:219], v204 offset:2048
	ds_read_b128 v[220:223], v204 offset:4096
	ds_read_b128 v[224:227], v204 offset:6144
	ds_read_b128 v[228:231], v205 offset:0
	ds_read_b128 v[232:235], v205 offset:2048
	ds_read_b128 v[236:239], v205 offset:4096
	ds_read_b128 v[240:243], v205 offset:6144
	s_add_u32 m0, s76, 0x18000
	s_nop 0
	global_load_lds_dwordx4 v196, s[68:69]
	s_add_u32 m0, s76, 0x1a000
	s_nop 0
	global_load_lds_dwordx4 v197, s[68:69]
	s_add_u32 m0, s76, 0x1c000
	s_nop 0
	global_load_lds_dwordx4 v198, s[68:69]
	s_add_u32 m0, s76, 0x1e000
	s_nop 0
	global_load_lds_dwordx4 v199, s[68:69]
	s_add_u32 m0, s76, 0x20000
	s_nop 0
	global_load_lds_dwordx4 v196, s[70:71]
	s_add_u32 m0, s76, 0x22000
	s_nop 0
	global_load_lds_dwordx4 v197, s[70:71]
	s_add_u32 s68, s68, 0x80
	s_addc_u32 s69, s69, 0
	s_add_u32 s70, s70, 0x80
	s_addc_u32 s71, s71, 0
	s_waitcnt vmcnt(6)
	s_waitcnt lgkmcnt(0)
	s_barrier
	v_mfma_f32_16x16x32_bf16 v[2:5], v[146:149], v[130:133], v[2:5]
	v_mfma_f32_16x16x32_bf16 v[6:9], v[150:153], v[130:133], v[6:9]
	v_mfma_f32_16x16x32_bf16 v[10:13], v[154:157], v[130:133], v[10:13]
	v_mfma_f32_16x16x32_bf16 v[14:17], v[158:161], v[130:133], v[14:17]
	v_mfma_f32_16x16x32_bf16 v[18:21], v[146:149], v[134:137], v[18:21]
	v_mfma_f32_16x16x32_bf16 v[22:25], v[150:153], v[134:137], v[22:25]
	v_mfma_f32_16x16x32_bf16 v[26:29], v[154:157], v[134:137], v[26:29]
	v_mfma_f32_16x16x32_bf16 v[30:33], v[158:161], v[134:137], v[30:33]
	v_mfma_f32_16x16x32_bf16 v[34:37], v[146:149], v[138:141], v[34:37]
	v_mfma_f32_16x16x32_bf16 v[38:41], v[150:153], v[138:141], v[38:41]
	v_mfma_f32_16x16x32_bf16 v[42:45], v[154:157], v[138:141], v[42:45]
	v_mfma_f32_16x16x32_bf16 v[46:49], v[158:161], v[138:141], v[46:49]
	v_mfma_f32_16x16x32_bf16 v[50:53], v[146:149], v[142:145], v[50:53]
	v_mfma_f32_16x16x32_bf16 v[54:57], v[150:153], v[142:145], v[54:57]
	v_mfma_f32_16x16x32_bf16 v[58:61], v[154:157], v[142:145], v[58:61]
	v_mfma_f32_16x16x32_bf16 v[62:65], v[158:161], v[142:145], v[62:65]
	v_mfma_f32_16x16x32_bf16 v[2:5], v[228:231], v[212:215], v[2:5]
	v_mfma_f32_16x16x32_bf16 v[6:9], v[232:235], v[212:215], v[6:9]
	v_mfma_f32_16x16x32_bf16 v[10:13], v[236:239], v[212:215], v[10:13]
	v_mfma_f32_16x16x32_bf16 v[14:17], v[240:243], v[212:215], v[14:17]
	v_mfma_f32_16x16x32_bf16 v[18:21], v[228:231], v[216:219], v[18:21]
	v_mfma_f32_16x16x32_bf16 v[22:25], v[232:235], v[216:219], v[22:25]
	v_mfma_f32_16x16x32_bf16 v[26:29], v[236:239], v[216:219], v[26:29]
	v_mfma_f32_16x16x32_bf16 v[30:33], v[240:243], v[216:219], v[30:33]
	v_mfma_f32_16x16x32_bf16 v[34:37], v[228:231], v[220:223], v[34:37]
	v_mfma_f32_16x16x32_bf16 v[38:41], v[232:235], v[220:223], v[38:41]
	v_mfma_f32_16x16x32_bf16 v[42:45], v[236:239], v[220:223], v[42:45]
	v_mfma_f32_16x16x32_bf16 v[46:49], v[240:243], v[220:223], v[46:49]
	v_mfma_f32_16x16x32_bf16 v[50:53], v[228:231], v[224:227], v[50:53]
	v_mfma_f32_16x16x32_bf16 v[54:57], v[232:235], v[224:227], v[54:57]
	v_mfma_f32_16x16x32_bf16 v[58:61], v[236:239], v[224:227], v[58:61]
	v_mfma_f32_16x16x32_bf16 v[62:65], v[240:243], v[224:227], v[62:65]
	s_nop 7
	v_lshlrev_b32_e32 v212, 16, v174
	v_and_b32_e32 v213, 0xffff0000, v174
	v_lshlrev_b32_e32 v214, 16, v175
	v_and_b32_e32 v215, 0xffff0000, v175
	v_pk_fma_f32 v[66:67], v[2:3], v[212:213], v[66:67]
	v_pk_fma_f32 v[68:69], v[4:5], v[214:215], v[68:69]
	v_lshlrev_b32_e32 v216, 16, v176
	v_and_b32_e32 v217, 0xffff0000, v176
	v_lshlrev_b32_e32 v218, 16, v177
	v_and_b32_e32 v219, 0xffff0000, v177
	v_pk_fma_f32 v[70:71], v[6:7], v[216:217], v[70:71]
	v_pk_fma_f32 v[72:73], v[8:9], v[218:219], v[72:73]
	v_lshlrev_b32_e32 v220, 16, v178
	v_and_b32_e32 v221, 0xffff0000, v178
	v_lshlrev_b32_e32 v222, 16, v179
	v_and_b32_e32 v223, 0xffff0000, v179
	v_pk_fma_f32 v[74:75], v[10:11], v[220:221], v[74:75]
	v_pk_fma_f32 v[76:77], v[12:13], v[222:223], v[76:77]
	v_lshlrev_b32_e32 v224, 16, v180
	v_and_b32_e32 v225, 0xffff0000, v180
	v_lshlrev_b32_e32 v226, 16, v181
	v_and_b32_e32 v227, 0xffff0000, v181
	v_pk_fma_f32 v[78:79], v[14:15], v[224:225], v[78:79]
	v_pk_fma_f32 v[80:81], v[16:17], v[226:227], v[80:81]
	v_lshlrev_b32_e32 v228, 16, v182
	v_and_b32_e32 v229, 0xffff0000, v182
	v_lshlrev_b32_e32 v230, 16, v183
	v_and_b32_e32 v231, 0xffff0000, v183
	v_pk_fma_f32 v[82:83], v[18:19], v[228:229], v[82:83]
	v_pk_fma_f32 v[84:85], v[20:21], v[230:231], v[84:85]
	v_lshlrev_b32_e32 v232, 16, v184
	v_and_b32_e32 v233, 0xffff0000, v184
	v_lshlrev_b32_e32 v234, 16, v185
	v_and_b32_e32 v235, 0xffff0000, v185
	v_pk_fma_f32 v[86:87], v[22:23], v[232:233], v[86:87]
	v_pk_fma_f32 v[88:89], v[24:25], v[234:235], v[88:89]
	v_lshlrev_b32_e32 v236, 16, v186
	v_and_b32_e32 v237, 0xffff0000, v186
	v_lshlrev_b32_e32 v238, 16, v187
	v_and_b32_e32 v239, 0xffff0000, v187
	v_pk_fma_f32 v[90:91], v[26:27], v[236:237], v[90:91]
	v_pk_fma_f32 v[92:93], v[28:29], v[238:239], v[92:93]
	v_lshlrev_b32_e32 v240, 16, v188
	v_and_b32_e32 v241, 0xffff0000, v188
	v_lshlrev_b32_e32 v242, 16, v189
	v_and_b32_e32 v243, 0xffff0000, v189
	v_pk_fma_f32 v[94:95], v[30:31], v[240:241], v[94:95]
	v_pk_fma_f32 v[96:97], v[32:33], v[242:243], v[96:97]
	v_lshlrev_b32_e32 v212, 16, v190
	v_and_b32_e32 v213, 0xffff0000, v190
	v_lshlrev_b32_e32 v214, 16, v191
	v_and_b32_e32 v215, 0xffff0000, v191
	v_pk_fma_f32 v[98:99], v[34:35], v[212:213], v[98:99]
	v_pk_fma_f32 v[100:101], v[36:37], v[214:215], v[100:101]
	v_lshlrev_b32_e32 v216, 16, v192
	v_and_b32_e32 v217, 0xffff0000, v192
	v_lshlrev_b32_e32 v218, 16, v193
	v_and_b32_e32 v219, 0xffff0000, v193
	v_pk_fma_f32 v[102:103], v[38:39], v[216:217], v[102:103]
	v_pk_fma_f32 v[104:105], v[40:41], v[218:219], v[104:105]
	v_lshlrev_b32_e32 v220, 16, v244
	v_and_b32_e32 v221, 0xffff0000, v244
	v_lshlrev_b32_e32 v222, 16, v245
	v_and_b32_e32 v223, 0xffff0000, v245
	v_pk_fma_f32 v[106:107], v[42:43], v[220:221], v[106:107]
	v_pk_fma_f32 v[108:109], v[44:45], v[222:223], v[108:109]
	v_lshlrev_b32_e32 v224, 16, v246
	v_and_b32_e32 v225, 0xffff0000, v246
	v_lshlrev_b32_e32 v226, 16, v247
	v_and_b32_e32 v227, 0xffff0000, v247
	v_pk_fma_f32 v[110:111], v[46:47], v[224:225], v[110:111]
	v_pk_fma_f32 v[112:113], v[48:49], v[226:227], v[112:113]
	v_lshlrev_b32_e32 v228, 16, v248
	v_and_b32_e32 v229, 0xffff0000, v248
	v_lshlrev_b32_e32 v230, 16, v249
	v_and_b32_e32 v231, 0xffff0000, v249
	v_pk_fma_f32 v[114:115], v[50:51], v[228:229], v[114:115]
	v_pk_fma_f32 v[116:117], v[52:53], v[230:231], v[116:117]
	v_lshlrev_b32_e32 v232, 16, v250
	v_and_b32_e32 v233, 0xffff0000, v250
	v_lshlrev_b32_e32 v234, 16, v251
	v_and_b32_e32 v235, 0xffff0000, v251
	v_pk_fma_f32 v[118:119], v[54:55], v[232:233], v[118:119]
	v_pk_fma_f32 v[120:121], v[56:57], v[234:235], v[120:121]
	v_lshlrev_b32_e32 v236, 16, v166
	v_and_b32_e32 v237, 0xffff0000, v166
	v_lshlrev_b32_e32 v238, 16, v167
	v_and_b32_e32 v239, 0xffff0000, v167
	v_pk_fma_f32 v[122:123], v[58:59], v[236:237], v[122:123]
	v_pk_fma_f32 v[124:125], v[60:61], v[238:239], v[124:125]
	v_lshlrev_b32_e32 v240, 16, v194
	v_and_b32_e32 v241, 0xffff0000, v194
	v_lshlrev_b32_e32 v242, 16, v195
	v_and_b32_e32 v243, 0xffff0000, v195
	v_pk_fma_f32 v[126:127], v[62:63], v[240:241], v[126:127]
	v_pk_fma_f32 v[128:129], v[64:65], v[242:243], v[128:129]
	s_barrier
	v_add_u32_e32 v204, 0xc000, v200
	v_add_u32_e32 v205, 0xc000, v202
	ds_read_b128 v[130:133], v204 offset:0
	ds_read_b128 v[134:137], v204 offset:2048
	ds_read_b128 v[138:141], v204 offset:4096
	ds_read_b128 v[142:145], v204 offset:6144
	ds_read_b128 v[146:149], v205 offset:0
	ds_read_b128 v[150:153], v205 offset:2048
	ds_read_b128 v[154:157], v205 offset:4096
	ds_read_b128 v[158:161], v205 offset:6144
	v_add_u32_e32 v204, 0xc000, v201
	v_add_u32_e32 v205, 0xc000, v203
	ds_read_b128 v[212:215], v204 offset:0
	ds_read_b128 v[216:219], v204 offset:2048
	ds_read_b128 v[220:223], v204 offset:4096
	ds_read_b128 v[224:227], v204 offset:6144
	ds_read_b128 v[228:231], v205 offset:0
	ds_read_b128 v[232:235], v205 offset:2048
	ds_read_b128 v[236:239], v205 offset:4096
	ds_read_b128 v[240:243], v205 offset:6144
	s_add_u32 m0, s76, 0x0
	s_nop 0
	global_load_lds_dwordx4 v196, s[68:69]
	s_add_u32 m0, s76, 0x2000
	s_nop 0
	global_load_lds_dwordx4 v197, s[68:69]
	s_add_u32 m0, s76, 0x4000
	s_nop 0
	global_load_lds_dwordx4 v198, s[68:69]
	s_add_u32 m0, s76, 0x6000
	s_nop 0
	global_load_lds_dwordx4 v199, s[68:69]
	s_add_u32 m0, s76, 0x8000
	s_nop 0
	global_load_lds_dwordx4 v196, s[70:71]
	s_add_u32 m0, s76, 0xa000
	s_nop 0
	global_load_lds_dwordx4 v197, s[70:71]
	s_add_u32 s68, s68, 0x80
	s_addc_u32 s69, s69, 0
	s_add_u32 s70, s70, 0x80
	s_addc_u32 s71, s71, 0
	global_load_dwordx2 v[174:175], v206, s[72:73] offset:0
	global_load_dwordx2 v[176:177], v206, s[72:73] offset:32
	global_load_dwordx2 v[178:179], v206, s[72:73] offset:64
	global_load_dwordx2 v[180:181], v206, s[72:73] offset:96
	global_load_dwordx2 v[182:183], v207, s[72:73] offset:0
	global_load_dwordx2 v[184:185], v207, s[72:73] offset:32
	s_waitcnt vmcnt(12)
	s_waitcnt lgkmcnt(0)
	s_barrier
	v_mfma_f32_16x16x32_bf16 v[2:5], v[146:149], v[130:133], 0
	v_mfma_f32_16x16x32_bf16 v[6:9], v[150:153], v[130:133], 0
	v_mfma_f32_16x16x32_bf16 v[10:13], v[154:157], v[130:133], 0
	v_mfma_f32_16x16x32_bf16 v[14:17], v[158:161], v[130:133], 0
	v_mfma_f32_16x16x32_bf16 v[18:21], v[146:149], v[134:137], 0
	v_mfma_f32_16x16x32_bf16 v[22:25], v[150:153], v[134:137], 0
	v_mfma_f32_16x16x32_bf16 v[26:29], v[154:157], v[134:137], 0
	v_mfma_f32_16x16x32_bf16 v[30:33], v[158:161], v[134:137], 0
	v_mfma_f32_16x16x32_bf16 v[34:37], v[146:149], v[138:141], 0
	v_mfma_f32_16x16x32_bf16 v[38:41], v[150:153], v[138:141], 0
	v_mfma_f32_16x16x32_bf16 v[42:45], v[154:157], v[138:141], 0
	v_mfma_f32_16x16x32_bf16 v[46:49], v[158:161], v[138:141], 0
	v_mfma_f32_16x16x32_bf16 v[50:53], v[146:149], v[142:145], 0
	v_mfma_f32_16x16x32_bf16 v[54:57], v[150:153], v[142:145], 0
	v_mfma_f32_16x16x32_bf16 v[58:61], v[154:157], v[142:145], 0
	v_mfma_f32_16x16x32_bf16 v[62:65], v[158:161], v[142:145], 0
	v_mfma_f32_16x16x32_bf16 v[2:5], v[228:231], v[212:215], v[2:5]
	v_mfma_f32_16x16x32_bf16 v[6:9], v[232:235], v[212:215], v[6:9]
	v_mfma_f32_16x16x32_bf16 v[10:13], v[236:239], v[212:215], v[10:13]
	v_mfma_f32_16x16x32_bf16 v[14:17], v[240:243], v[212:215], v[14:17]
	v_mfma_f32_16x16x32_bf16 v[18:21], v[228:231], v[216:219], v[18:21]
	v_mfma_f32_16x16x32_bf16 v[22:25], v[232:235], v[216:219], v[22:25]
	v_mfma_f32_16x16x32_bf16 v[26:29], v[236:239], v[216:219], v[26:29]
	v_mfma_f32_16x16x32_bf16 v[30:33], v[240:243], v[216:219], v[30:33]
	v_mfma_f32_16x16x32_bf16 v[34:37], v[228:231], v[220:223], v[34:37]
	v_mfma_f32_16x16x32_bf16 v[38:41], v[232:235], v[220:223], v[38:41]
	v_mfma_f32_16x16x32_bf16 v[42:45], v[236:239], v[220:223], v[42:45]
	v_mfma_f32_16x16x32_bf16 v[46:49], v[240:243], v[220:223], v[46:49]
	v_mfma_f32_16x16x32_bf16 v[50:53], v[228:231], v[224:227], v[50:53]
	v_mfma_f32_16x16x32_bf16 v[54:57], v[232:235], v[224:227], v[54:57]
	v_mfma_f32_16x16x32_bf16 v[58:61], v[236:239], v[224:227], v[58:61]
	v_mfma_f32_16x16x32_bf16 v[62:65], v[240:243], v[224:227], v[62:65]
	s_barrier
	v_add_u32_e32 v204, 0x18000, v200
	v_add_u32_e32 v205, 0x18000, v202
	ds_read_b128 v[130:133], v204 offset:0
	ds_read_b128 v[134:137], v204 offset:2048
	ds_read_b128 v[138:141], v204 offset:4096
	ds_read_b128 v[142:145], v204 offset:6144
	ds_read_b128 v[146:149], v205 offset:0
	ds_read_b128 v[150:153], v205 offset:2048
	ds_read_b128 v[154:157], v205 offset:4096
	ds_read_b128 v[158:161], v205 offset:6144
	v_add_u32_e32 v204, 0x18000, v201
	v_add_u32_e32 v205, 0x18000, v203
	ds_read_b128 v[212:215], v204 offset:0
	ds_read_b128 v[216:219], v204 offset:2048
	ds_read_b128 v[220:223], v204 offset:4096
	ds_read_b128 v[224:227], v204 offset:6144
	ds_read_b128 v[228:231], v205 offset:0
	ds_read_b128 v[232:235], v205 offset:2048
	ds_read_b128 v[236:239], v205 offset:4096
	ds_read_b128 v[240:243], v205 offset:6144
	s_add_u32 m0, s76, 0xc000
	s_nop 0
	global_load_lds_dwordx4 v196, s[68:69]
	s_add_u32 m0, s76, 0xe000
	s_nop 0
	global_load_lds_dwordx4 v197, s[68:69]
	s_add_u32 m0, s76, 0x10000
	s_nop 0
	global_load_lds_dwordx4 v198, s[68:69]
	s_add_u32 m0, s76, 0x12000
	s_nop 0
	global_load_lds_dwordx4 v199, s[68:69]
	s_add_u32 m0, s76, 0x14000
	s_nop 0
	global_load_lds_dwordx4 v196, s[70:71]
	s_add_u32 m0, s76, 0x16000
	s_nop 0
	global_load_lds_dwordx4 v197, s[70:71]
	s_add_u32 s68, s68, 0x80
	s_addc_u32 s69, s69, 0
	s_add_u32 s70, s70, 0x80
	s_addc_u32 s71, s71, 0
	global_load_dwordx2 v[186:187], v207, s[72:73] offset:64
	global_load_dwordx2 v[188:189], v207, s[72:73] offset:96
	global_load_dwordx2 v[190:191], v208, s[72:73] offset:0
	global_load_dwordx2 v[192:193], v208, s[72:73] offset:32
	global_load_dwordx2 v[244:245], v208, s[72:73] offset:64
	global_load_dwordx2 v[246:247], v208, s[72:73] offset:96
	s_waitcnt vmcnt(18)
	s_waitcnt lgkmcnt(0)
	s_barrier
	v_mfma_f32_16x16x32_bf16 v[2:5], v[146:149], v[130:133], v[2:5]
	v_mfma_f32_16x16x32_bf16 v[6:9], v[150:153], v[130:133], v[6:9]
	v_mfma_f32_16x16x32_bf16 v[10:13], v[154:157], v[130:133], v[10:13]
	v_mfma_f32_16x16x32_bf16 v[14:17], v[158:161], v[130:133], v[14:17]
	v_mfma_f32_16x16x32_bf16 v[18:21], v[146:149], v[134:137], v[18:21]
	v_mfma_f32_16x16x32_bf16 v[22:25], v[150:153], v[134:137], v[22:25]
	v_mfma_f32_16x16x32_bf16 v[26:29], v[154:157], v[134:137], v[26:29]
	v_mfma_f32_16x16x32_bf16 v[30:33], v[158:161], v[134:137], v[30:33]
	v_mfma_f32_16x16x32_bf16 v[34:37], v[146:149], v[138:141], v[34:37]
	v_mfma_f32_16x16x32_bf16 v[38:41], v[150:153], v[138:141], v[38:41]
	v_mfma_f32_16x16x32_bf16 v[42:45], v[154:157], v[138:141], v[42:45]
	v_mfma_f32_16x16x32_bf16 v[46:49], v[158:161], v[138:141], v[46:49]
	v_mfma_f32_16x16x32_bf16 v[50:53], v[146:149], v[142:145], v[50:53]
	v_mfma_f32_16x16x32_bf16 v[54:57], v[150:153], v[142:145], v[54:57]
	v_mfma_f32_16x16x32_bf16 v[58:61], v[154:157], v[142:145], v[58:61]
	v_mfma_f32_16x16x32_bf16 v[62:65], v[158:161], v[142:145], v[62:65]
	v_mfma_f32_16x16x32_bf16 v[2:5], v[228:231], v[212:215], v[2:5]
	v_mfma_f32_16x16x32_bf16 v[6:9], v[232:235], v[212:215], v[6:9]
	v_mfma_f32_16x16x32_bf16 v[10:13], v[236:239], v[212:215], v[10:13]
	v_mfma_f32_16x16x32_bf16 v[14:17], v[240:243], v[212:215], v[14:17]
	v_mfma_f32_16x16x32_bf16 v[18:21], v[228:231], v[216:219], v[18:21]
	v_mfma_f32_16x16x32_bf16 v[22:25], v[232:235], v[216:219], v[22:25]
	v_mfma_f32_16x16x32_bf16 v[26:29], v[236:239], v[216:219], v[26:29]
	v_mfma_f32_16x16x32_bf16 v[30:33], v[240:243], v[216:219], v[30:33]
	v_mfma_f32_16x16x32_bf16 v[34:37], v[228:231], v[220:223], v[34:37]
	v_mfma_f32_16x16x32_bf16 v[38:41], v[232:235], v[220:223], v[38:41]
	v_mfma_f32_16x16x32_bf16 v[42:45], v[236:239], v[220:223], v[42:45]
	v_mfma_f32_16x16x32_bf16 v[46:49], v[240:243], v[220:223], v[46:49]
	v_mfma_f32_16x16x32_bf16 v[50:53], v[228:231], v[224:227], v[50:53]
	v_mfma_f32_16x16x32_bf16 v[54:57], v[232:235], v[224:227], v[54:57]
	v_mfma_f32_16x16x32_bf16 v[58:61], v[236:239], v[224:227], v[58:61]
	v_mfma_f32_16x16x32_bf16 v[62:65], v[240:243], v[224:227], v[62:65]
	s_barrier
	v_add_u32_e32 v204, 0x0, v200
	v_add_u32_e32 v205, 0x0, v202
	ds_read_b128 v[130:133], v204 offset:0
	ds_read_b128 v[134:137], v204 offset:2048
	ds_read_b128 v[138:141], v204 offset:4096
	ds_read_b128 v[142:145], v204 offset:6144
	ds_read_b128 v[146:149], v205 offset:0
	ds_read_b128 v[150:153], v205 offset:2048
	ds_read_b128 v[154:157], v205 offset:4096
	ds_read_b128 v[158:161], v205 offset:6144
	v_add_u32_e32 v204, 0x0, v201
	v_add_u32_e32 v205, 0x0, v203
	ds_read_b128 v[212:215], v204 offset:0
	ds_read_b128 v[216:219], v204 offset:2048
	ds_read_b128 v[220:223], v204 offset:4096
	ds_read_b128 v[224:227], v204 offset:6144
	ds_read_b128 v[228:231], v205 offset:0
	ds_read_b128 v[232:235], v205 offset:2048
	ds_read_b128 v[236:239], v205 offset:4096
	ds_read_b128 v[240:243], v205 offset:6144
	s_add_u32 m0, s76, 0x18000
	s_nop 0
	global_load_lds_dwordx4 v196, s[68:69]
	s_add_u32 m0, s76, 0x1a000
	s_nop 0
	global_load_lds_dwordx4 v197, s[68:69]
	s_add_u32 m0, s76, 0x1c000
	s_nop 0
	global_load_lds_dwordx4 v198, s[68:69]
	s_add_u32 m0, s76, 0x1e000
	s_nop 0
	global_load_lds_dwordx4 v199, s[68:69]
	s_add_u32 m0, s76, 0x20000
	s_nop 0
	global_load_lds_dwordx4 v196, s[70:71]
	s_add_u32 m0, s76, 0x22000
	s_nop 0
	global_load_lds_dwordx4 v197, s[70:71]
	s_add_u32 s68, s68, 0x80
	s_addc_u32 s69, s69, 0
	s_add_u32 s70, s70, 0x80
	s_addc_u32 s71, s71, 0
	global_load_dwordx2 v[248:249], v209, s[72:73] offset:0
	global_load_dwordx2 v[250:251], v209, s[72:73] offset:32
	global_load_dwordx2 v[166:167], v209, s[72:73] offset:64
	global_load_dwordx2 v[194:195], v209, s[72:73] offset:96
	s_add_u32 s72, s72, 0x800
	s_addc_u32 s73, s73, 0
	s_waitcnt vmcnt(16)
	s_waitcnt lgkmcnt(0)
	s_barrier
	v_mfma_f32_16x16x32_bf16 v[2:5], v[146:149], v[130:133], v[2:5]
	v_mfma_f32_16x16x32_bf16 v[6:9], v[150:153], v[130:133], v[6:9]
	v_mfma_f32_16x16x32_bf16 v[10:13], v[154:157], v[130:133], v[10:13]
	v_mfma_f32_16x16x32_bf16 v[14:17], v[158:161], v[130:133], v[14:17]
	v_mfma_f32_16x16x32_bf16 v[18:21], v[146:149], v[134:137], v[18:21]
	v_mfma_f32_16x16x32_bf16 v[22:25], v[150:153], v[134:137], v[22:25]
	v_mfma_f32_16x16x32_bf16 v[26:29], v[154:157], v[134:137], v[26:29]
	v_mfma_f32_16x16x32_bf16 v[30:33], v[158:161], v[134:137], v[30:33]
	v_mfma_f32_16x16x32_bf16 v[34:37], v[146:149], v[138:141], v[34:37]
	v_mfma_f32_16x16x32_bf16 v[38:41], v[150:153], v[138:141], v[38:41]
	v_mfma_f32_16x16x32_bf16 v[42:45], v[154:157], v[138:141], v[42:45]
	v_mfma_f32_16x16x32_bf16 v[46:49], v[158:161], v[138:141], v[46:49]
	v_mfma_f32_16x16x32_bf16 v[50:53], v[146:149], v[142:145], v[50:53]
	v_mfma_f32_16x16x32_bf16 v[54:57], v[150:153], v[142:145], v[54:57]
	v_mfma_f32_16x16x32_bf16 v[58:61], v[154:157], v[142:145], v[58:61]
	v_mfma_f32_16x16x32_bf16 v[62:65], v[158:161], v[142:145], v[62:65]
	v_mfma_f32_16x16x32_bf16 v[2:5], v[228:231], v[212:215], v[2:5]
	v_mfma_f32_16x16x32_bf16 v[6:9], v[232:235], v[212:215], v[6:9]
	v_mfma_f32_16x16x32_bf16 v[10:13], v[236:239], v[212:215], v[10:13]
	v_mfma_f32_16x16x32_bf16 v[14:17], v[240:243], v[212:215], v[14:17]
	v_mfma_f32_16x16x32_bf16 v[18:21], v[228:231], v[216:219], v[18:21]
	v_mfma_f32_16x16x32_bf16 v[22:25], v[232:235], v[216:219], v[22:25]
	v_mfma_f32_16x16x32_bf16 v[26:29], v[236:239], v[216:219], v[26:29]
	v_mfma_f32_16x16x32_bf16 v[30:33], v[240:243], v[216:219], v[30:33]
	v_mfma_f32_16x16x32_bf16 v[34:37], v[228:231], v[220:223], v[34:37]
	v_mfma_f32_16x16x32_bf16 v[38:41], v[232:235], v[220:223], v[38:41]
	v_mfma_f32_16x16x32_bf16 v[42:45], v[236:239], v[220:223], v[42:45]
	v_mfma_f32_16x16x32_bf16 v[46:49], v[240:243], v[220:223], v[46:49]
	v_mfma_f32_16x16x32_bf16 v[50:53], v[228:231], v[224:227], v[50:53]
	v_mfma_f32_16x16x32_bf16 v[54:57], v[232:235], v[224:227], v[54:57]
	v_mfma_f32_16x16x32_bf16 v[58:61], v[236:239], v[224:227], v[58:61]
	v_mfma_f32_16x16x32_bf16 v[62:65], v[240:243], v[224:227], v[62:65]
	s_barrier
	v_add_u32_e32 v204, 0xc000, v200
	v_add_u32_e32 v205, 0xc000, v202
	ds_read_b128 v[130:133], v204 offset:0
	ds_read_b128 v[134:137], v204 offset:2048
	ds_read_b128 v[138:141], v204 offset:4096
	ds_read_b128 v[142:145], v204 offset:6144
	ds_read_b128 v[146:149], v205 offset:0
	ds_read_b128 v[150:153], v205 offset:2048
	ds_read_b128 v[154:157], v205 offset:4096
	ds_read_b128 v[158:161], v205 offset:6144
	v_add_u32_e32 v204, 0xc000, v201
	v_add_u32_e32 v205, 0xc000, v203
	ds_read_b128 v[212:215], v204 offset:0
	ds_read_b128 v[216:219], v204 offset:2048
	ds_read_b128 v[220:223], v204 offset:4096
	ds_read_b128 v[224:227], v204 offset:6144
	ds_read_b128 v[228:231], v205 offset:0
	ds_read_b128 v[232:235], v205 offset:2048
	ds_read_b128 v[236:239], v205 offset:4096
	ds_read_b128 v[240:243], v205 offset:6144
	s_add_u32 m0, s76, 0x0
	s_nop 0
	global_load_lds_dwordx4 v196, s[68:69]
	s_add_u32 m0, s76, 0x2000
	s_nop 0
	global_load_lds_dwordx4 v197, s[68:69]
	s_add_u32 m0, s76, 0x4000
	s_nop 0
	global_load_lds_dwordx4 v198, s[68:69]
	s_add_u32 m0, s76, 0x6000
	s_nop 0
	global_load_lds_dwordx4 v199, s[68:69]
	s_add_u32 m0, s76, 0x8000
	s_nop 0
	global_load_lds_dwordx4 v196, s[70:71]
	s_add_u32 m0, s76, 0xa000
	s_nop 0
	global_load_lds_dwordx4 v197, s[70:71]
	s_add_u32 s68, s68, 0x80
	s_addc_u32 s69, s69, 0
	s_add_u32 s70, s70, 0x80
	s_addc_u32 s71, s71, 0
	s_waitcnt vmcnt(10)
	s_waitcnt lgkmcnt(0)
	s_barrier
	v_mfma_f32_16x16x32_bf16 v[2:5], v[146:149], v[130:133], v[2:5]
	v_mfma_f32_16x16x32_bf16 v[6:9], v[150:153], v[130:133], v[6:9]
	v_mfma_f32_16x16x32_bf16 v[10:13], v[154:157], v[130:133], v[10:13]
	v_mfma_f32_16x16x32_bf16 v[14:17], v[158:161], v[130:133], v[14:17]
	v_mfma_f32_16x16x32_bf16 v[18:21], v[146:149], v[134:137], v[18:21]
	v_mfma_f32_16x16x32_bf16 v[22:25], v[150:153], v[134:137], v[22:25]
	v_mfma_f32_16x16x32_bf16 v[26:29], v[154:157], v[134:137], v[26:29]
	v_mfma_f32_16x16x32_bf16 v[30:33], v[158:161], v[134:137], v[30:33]
	v_mfma_f32_16x16x32_bf16 v[34:37], v[146:149], v[138:141], v[34:37]
	v_mfma_f32_16x16x32_bf16 v[38:41], v[150:153], v[138:141], v[38:41]
	v_mfma_f32_16x16x32_bf16 v[42:45], v[154:157], v[138:141], v[42:45]
	v_mfma_f32_16x16x32_bf16 v[46:49], v[158:161], v[138:141], v[46:49]
	v_mfma_f32_16x16x32_bf16 v[50:53], v[146:149], v[142:145], v[50:53]
	v_mfma_f32_16x16x32_bf16 v[54:57], v[150:153], v[142:145], v[54:57]
	v_mfma_f32_16x16x32_bf16 v[58:61], v[154:157], v[142:145], v[58:61]
	v_mfma_f32_16x16x32_bf16 v[62:65], v[158:161], v[142:145], v[62:65]
	v_mfma_f32_16x16x32_bf16 v[2:5], v[228:231], v[212:215], v[2:5]
	v_mfma_f32_16x16x32_bf16 v[6:9], v[232:235], v[212:215], v[6:9]
	v_mfma_f32_16x16x32_bf16 v[10:13], v[236:239], v[212:215], v[10:13]
	v_mfma_f32_16x16x32_bf16 v[14:17], v[240:243], v[212:215], v[14:17]
	v_mfma_f32_16x16x32_bf16 v[18:21], v[228:231], v[216:219], v[18:21]
	v_mfma_f32_16x16x32_bf16 v[22:25], v[232:235], v[216:219], v[22:25]
	v_mfma_f32_16x16x32_bf16 v[26:29], v[236:239], v[216:219], v[26:29]
	v_mfma_f32_16x16x32_bf16 v[30:33], v[240:243], v[216:219], v[30:33]
	v_mfma_f32_16x16x32_bf16 v[34:37], v[228:231], v[220:223], v[34:37]
	v_mfma_f32_16x16x32_bf16 v[38:41], v[232:235], v[220:223], v[38:41]
	v_mfma_f32_16x16x32_bf16 v[42:45], v[236:239], v[220:223], v[42:45]
	v_mfma_f32_16x16x32_bf16 v[46:49], v[240:243], v[220:223], v[46:49]
	v_mfma_f32_16x16x32_bf16 v[50:53], v[228:231], v[224:227], v[50:53]
	v_mfma_f32_16x16x32_bf16 v[54:57], v[232:235], v[224:227], v[54:57]
	v_mfma_f32_16x16x32_bf16 v[58:61], v[236:239], v[224:227], v[58:61]
	v_mfma_f32_16x16x32_bf16 v[62:65], v[240:243], v[224:227], v[62:65]
	s_barrier
	v_add_u32_e32 v204, 0x18000, v200
	v_add_u32_e32 v205, 0x18000, v202
	ds_read_b128 v[130:133], v204 offset:0
	ds_read_b128 v[134:137], v204 offset:2048
	ds_read_b128 v[138:141], v204 offset:4096
	ds_read_b128 v[142:145], v204 offset:6144
	ds_read_b128 v[146:149], v205 offset:0
	ds_read_b128 v[150:153], v205 offset:2048
	ds_read_b128 v[154:157], v205 offset:4096
	ds_read_b128 v[158:161], v205 offset:6144
	v_add_u32_e32 v204, 0x18000, v201
	v_add_u32_e32 v205, 0x18000, v203
	ds_read_b128 v[212:215], v204 offset:0
	ds_read_b128 v[216:219], v204 offset:2048
	ds_read_b128 v[220:223], v204 offset:4096
	ds_read_b128 v[224:227], v204 offset:6144
	ds_read_b128 v[228:231], v205 offset:0
	ds_read_b128 v[232:235], v205 offset:2048
	ds_read_b128 v[236:239], v205 offset:4096
	ds_read_b128 v[240:243], v205 offset:6144
	s_add_u32 m0, s76, 0xc000
	s_nop 0
	global_load_lds_dwordx4 v196, s[68:69]
	s_add_u32 m0, s76, 0xe000
	s_nop 0
	global_load_lds_dwordx4 v197, s[68:69]
	s_add_u32 m0, s76, 0x10000
	s_nop 0
	global_load_lds_dwordx4 v198, s[68:69]
	s_add_u32 m0, s76, 0x12000
	s_nop 0
	global_load_lds_dwordx4 v199, s[68:69]
	s_add_u32 m0, s76, 0x14000
	s_nop 0
	global_load_lds_dwordx4 v196, s[70:71]
	s_add_u32 m0, s76, 0x16000
	s_nop 0
	global_load_lds_dwordx4 v197, s[70:71]
	s_add_u32 s68, s68, 0x80
	s_addc_u32 s69, s69, 0
	s_add_u32 s70, s70, 0x80
	s_addc_u32 s71, s71, 0
	s_waitcnt vmcnt(6)
	s_waitcnt lgkmcnt(0)
	s_barrier
	v_mfma_f32_16x16x32_bf16 v[2:5], v[146:149], v[130:133], v[2:5]
	v_mfma_f32_16x16x32_bf16 v[6:9], v[150:153], v[130:133], v[6:9]
	v_mfma_f32_16x16x32_bf16 v[10:13], v[154:157], v[130:133], v[10:13]
	v_mfma_f32_16x16x32_bf16 v[14:17], v[158:161], v[130:133], v[14:17]
	v_mfma_f32_16x16x32_bf16 v[18:21], v[146:149], v[134:137], v[18:21]
	v_mfma_f32_16x16x32_bf16 v[22:25], v[150:153], v[134:137], v[22:25]
	v_mfma_f32_16x16x32_bf16 v[26:29], v[154:157], v[134:137], v[26:29]
	v_mfma_f32_16x16x32_bf16 v[30:33], v[158:161], v[134:137], v[30:33]
	v_mfma_f32_16x16x32_bf16 v[34:37], v[146:149], v[138:141], v[34:37]
	v_mfma_f32_16x16x32_bf16 v[38:41], v[150:153], v[138:141], v[38:41]
	v_mfma_f32_16x16x32_bf16 v[42:45], v[154:157], v[138:141], v[42:45]
	v_mfma_f32_16x16x32_bf16 v[46:49], v[158:161], v[138:141], v[46:49]
	v_mfma_f32_16x16x32_bf16 v[50:53], v[146:149], v[142:145], v[50:53]
	v_mfma_f32_16x16x32_bf16 v[54:57], v[150:153], v[142:145], v[54:57]
	v_mfma_f32_16x16x32_bf16 v[58:61], v[154:157], v[142:145], v[58:61]
	v_mfma_f32_16x16x32_bf16 v[62:65], v[158:161], v[142:145], v[62:65]
	v_mfma_f32_16x16x32_bf16 v[2:5], v[228:231], v[212:215], v[2:5]
	v_mfma_f32_16x16x32_bf16 v[6:9], v[232:235], v[212:215], v[6:9]
	v_mfma_f32_16x16x32_bf16 v[10:13], v[236:239], v[212:215], v[10:13]
	v_mfma_f32_16x16x32_bf16 v[14:17], v[240:243], v[212:215], v[14:17]
	v_mfma_f32_16x16x32_bf16 v[18:21], v[228:231], v[216:219], v[18:21]
	v_mfma_f32_16x16x32_bf16 v[22:25], v[232:235], v[216:219], v[22:25]
	v_mfma_f32_16x16x32_bf16 v[26:29], v[236:239], v[216:219], v[26:29]
	v_mfma_f32_16x16x32_bf16 v[30:33], v[240:243], v[216:219], v[30:33]
	v_mfma_f32_16x16x32_bf16 v[34:37], v[228:231], v[220:223], v[34:37]
	v_mfma_f32_16x16x32_bf16 v[38:41], v[232:235], v[220:223], v[38:41]
	v_mfma_f32_16x16x32_bf16 v[42:45], v[236:239], v[220:223], v[42:45]
	v_mfma_f32_16x16x32_bf16 v[46:49], v[240:243], v[220:223], v[46:49]
	v_mfma_f32_16x16x32_bf16 v[50:53], v[228:231], v[224:227], v[50:53]
	v_mfma_f32_16x16x32_bf16 v[54:57], v[232:235], v[224:227], v[54:57]
	v_mfma_f32_16x16x32_bf16 v[58:61], v[236:239], v[224:227], v[58:61]
	v_mfma_f32_16x16x32_bf16 v[62:65], v[240:243], v[224:227], v[62:65]
	s_barrier
	v_add_u32_e32 v204, 0x0, v200
	v_add_u32_e32 v205, 0x0, v202
	ds_read_b128 v[130:133], v204 offset:0
	ds_read_b128 v[134:137], v204 offset:2048
	ds_read_b128 v[138:141], v204 offset:4096
	ds_read_b128 v[142:145], v204 offset:6144
	ds_read_b128 v[146:149], v205 offset:0
	ds_read_b128 v[150:153], v205 offset:2048
	ds_read_b128 v[154:157], v205 offset:4096
	ds_read_b128 v[158:161], v205 offset:6144
	v_add_u32_e32 v204, 0x0, v201
	v_add_u32_e32 v205, 0x0, v203
	ds_read_b128 v[212:215], v204 offset:0
	ds_read_b128 v[216:219], v204 offset:2048
	ds_read_b128 v[220:223], v204 offset:4096
	ds_read_b128 v[224:227], v204 offset:6144
	ds_read_b128 v[228:231], v205 offset:0
	ds_read_b128 v[232:235], v205 offset:2048
	ds_read_b128 v[236:239], v205 offset:4096
	ds_read_b128 v[240:243], v205 offset:6144
	s_add_u32 m0, s76, 0x18000
	s_nop 0
	global_load_lds_dwordx4 v196, s[68:69]
	s_add_u32 m0, s76, 0x1a000
	s_nop 0
	global_load_lds_dwordx4 v197, s[68:69]
	s_add_u32 m0, s76, 0x1c000
	s_nop 0
	global_load_lds_dwordx4 v198, s[68:69]
	s_add_u32 m0, s76, 0x1e000
	s_nop 0
	global_load_lds_dwordx4 v199, s[68:69]
	s_add_u32 m0, s76, 0x20000
	s_nop 0
	global_load_lds_dwordx4 v196, s[70:71]
	s_add_u32 m0, s76, 0x22000
	s_nop 0
	global_load_lds_dwordx4 v197, s[70:71]
	s_add_u32 s68, s68, 0x80
	s_addc_u32 s69, s69, 0
	s_add_u32 s70, s70, 0x80
	s_addc_u32 s71, s71, 0
	s_waitcnt vmcnt(6)
	s_waitcnt lgkmcnt(0)
	s_barrier
	v_mfma_f32_16x16x32_bf16 v[2:5], v[146:149], v[130:133], v[2:5]
	v_mfma_f32_16x16x32_bf16 v[6:9], v[150:153], v[130:133], v[6:9]
	v_mfma_f32_16x16x32_bf16 v[10:13], v[154:157], v[130:133], v[10:13]
	v_mfma_f32_16x16x32_bf16 v[14:17], v[158:161], v[130:133], v[14:17]
	v_mfma_f32_16x16x32_bf16 v[18:21], v[146:149], v[134:137], v[18:21]
	v_mfma_f32_16x16x32_bf16 v[22:25], v[150:153], v[134:137], v[22:25]
	v_mfma_f32_16x16x32_bf16 v[26:29], v[154:157], v[134:137], v[26:29]
	v_mfma_f32_16x16x32_bf16 v[30:33], v[158:161], v[134:137], v[30:33]
	v_mfma_f32_16x16x32_bf16 v[34:37], v[146:149], v[138:141], v[34:37]
	v_mfma_f32_16x16x32_bf16 v[38:41], v[150:153], v[138:141], v[38:41]
	v_mfma_f32_16x16x32_bf16 v[42:45], v[154:157], v[138:141], v[42:45]
	v_mfma_f32_16x16x32_bf16 v[46:49], v[158:161], v[138:141], v[46:49]
	v_mfma_f32_16x16x32_bf16 v[50:53], v[146:149], v[142:145], v[50:53]
	v_mfma_f32_16x16x32_bf16 v[54:57], v[150:153], v[142:145], v[54:57]
	v_mfma_f32_16x16x32_bf16 v[58:61], v[154:157], v[142:145], v[58:61]
	v_mfma_f32_16x16x32_bf16 v[62:65], v[158:161], v[142:145], v[62:65]
	v_mfma_f32_16x16x32_bf16 v[2:5], v[228:231], v[212:215], v[2:5]
	v_mfma_f32_16x16x32_bf16 v[6:9], v[232:235], v[212:215], v[6:9]
	v_mfma_f32_16x16x32_bf16 v[10:13], v[236:239], v[212:215], v[10:13]
	v_mfma_f32_16x16x32_bf16 v[14:17], v[240:243], v[212:215], v[14:17]
	v_mfma_f32_16x16x32_bf16 v[18:21], v[228:231], v[216:219], v[18:21]
	v_mfma_f32_16x16x32_bf16 v[22:25], v[232:235], v[216:219], v[22:25]
	v_mfma_f32_16x16x32_bf16 v[26:29], v[236:239], v[216:219], v[26:29]
	v_mfma_f32_16x16x32_bf16 v[30:33], v[240:243], v[216:219], v[30:33]
	v_mfma_f32_16x16x32_bf16 v[34:37], v[228:231], v[220:223], v[34:37]
	v_mfma_f32_16x16x32_bf16 v[38:41], v[232:235], v[220:223], v[38:41]
	v_mfma_f32_16x16x32_bf16 v[42:45], v[236:239], v[220:223], v[42:45]
	v_mfma_f32_16x16x32_bf16 v[46:49], v[240:243], v[220:223], v[46:49]
	v_mfma_f32_16x16x32_bf16 v[50:53], v[228:231], v[224:227], v[50:53]
	v_mfma_f32_16x16x32_bf16 v[54:57], v[232:235], v[224:227], v[54:57]
	v_mfma_f32_16x16x32_bf16 v[58:61], v[236:239], v[224:227], v[58:61]
	v_mfma_f32_16x16x32_bf16 v[62:65], v[240:243], v[224:227], v[62:65]
	s_barrier
	v_add_u32_e32 v204, 0xc000, v200
	v_add_u32_e32 v205, 0xc000, v202
	ds_read_b128 v[130:133], v204 offset:0
	ds_read_b128 v[134:137], v204 offset:2048
	ds_read_b128 v[138:141], v204 offset:4096
	ds_read_b128 v[142:145], v204 offset:6144
	ds_read_b128 v[146:149], v205 offset:0
	ds_read_b128 v[150:153], v205 offset:2048
	ds_read_b128 v[154:157], v205 offset:4096
	ds_read_b128 v[158:161], v205 offset:6144
	v_add_u32_e32 v204, 0xc000, v201
	v_add_u32_e32 v205, 0xc000, v203
	ds_read_b128 v[212:215], v204 offset:0
	ds_read_b128 v[216:219], v204 offset:2048
	ds_read_b128 v[220:223], v204 offset:4096
	ds_read_b128 v[224:227], v204 offset:6144
	ds_read_b128 v[228:231], v205 offset:0
	ds_read_b128 v[232:235], v205 offset:2048
	ds_read_b128 v[236:239], v205 offset:4096
	ds_read_b128 v[240:243], v205 offset:6144
	s_waitcnt vmcnt(0)
	s_waitcnt lgkmcnt(0)
	s_barrier
	v_mfma_f32_16x16x32_bf16 v[2:5], v[146:149], v[130:133], v[2:5]
	v_mfma_f32_16x16x32_bf16 v[6:9], v[150:153], v[130:133], v[6:9]
	v_mfma_f32_16x16x32_bf16 v[10:13], v[154:157], v[130:133], v[10:13]
	v_mfma_f32_16x16x32_bf16 v[14:17], v[158:161], v[130:133], v[14:17]
	v_mfma_f32_16x16x32_bf16 v[18:21], v[146:149], v[134:137], v[18:21]
	v_mfma_f32_16x16x32_bf16 v[22:25], v[150:153], v[134:137], v[22:25]
	v_mfma_f32_16x16x32_bf16 v[26:29], v[154:157], v[134:137], v[26:29]
	v_mfma_f32_16x16x32_bf16 v[30:33], v[158:161], v[134:137], v[30:33]
	v_mfma_f32_16x16x32_bf16 v[34:37], v[146:149], v[138:141], v[34:37]
	v_mfma_f32_16x16x32_bf16 v[38:41], v[150:153], v[138:141], v[38:41]
	v_mfma_f32_16x16x32_bf16 v[42:45], v[154:157], v[138:141], v[42:45]
	v_mfma_f32_16x16x32_bf16 v[46:49], v[158:161], v[138:141], v[46:49]
	v_mfma_f32_16x16x32_bf16 v[50:53], v[146:149], v[142:145], v[50:53]
	v_mfma_f32_16x16x32_bf16 v[54:57], v[150:153], v[142:145], v[54:57]
	v_mfma_f32_16x16x32_bf16 v[58:61], v[154:157], v[142:145], v[58:61]
	v_mfma_f32_16x16x32_bf16 v[62:65], v[158:161], v[142:145], v[62:65]
	v_mfma_f32_16x16x32_bf16 v[2:5], v[228:231], v[212:215], v[2:5]
	v_mfma_f32_16x16x32_bf16 v[6:9], v[232:235], v[212:215], v[6:9]
	v_mfma_f32_16x16x32_bf16 v[10:13], v[236:239], v[212:215], v[10:13]
	v_mfma_f32_16x16x32_bf16 v[14:17], v[240:243], v[212:215], v[14:17]
	v_mfma_f32_16x16x32_bf16 v[18:21], v[228:231], v[216:219], v[18:21]
	v_mfma_f32_16x16x32_bf16 v[22:25], v[232:235], v[216:219], v[22:25]
	v_mfma_f32_16x16x32_bf16 v[26:29], v[236:239], v[216:219], v[26:29]
	v_mfma_f32_16x16x32_bf16 v[30:33], v[240:243], v[216:219], v[30:33]
	v_mfma_f32_16x16x32_bf16 v[34:37], v[228:231], v[220:223], v[34:37]
	v_mfma_f32_16x16x32_bf16 v[38:41], v[232:235], v[220:223], v[38:41]
	v_mfma_f32_16x16x32_bf16 v[42:45], v[236:239], v[220:223], v[42:45]
	v_mfma_f32_16x16x32_bf16 v[46:49], v[240:243], v[220:223], v[46:49]
	v_mfma_f32_16x16x32_bf16 v[50:53], v[228:231], v[224:227], v[50:53]
	v_mfma_f32_16x16x32_bf16 v[54:57], v[232:235], v[224:227], v[54:57]
	v_mfma_f32_16x16x32_bf16 v[58:61], v[236:239], v[224:227], v[58:61]
	v_mfma_f32_16x16x32_bf16 v[62:65], v[240:243], v[224:227], v[62:65]
	s_barrier
	v_add_u32_e32 v204, 0x18000, v200
	v_add_u32_e32 v205, 0x18000, v202
	ds_read_b128 v[130:133], v204 offset:0
	ds_read_b128 v[134:137], v204 offset:2048
	ds_read_b128 v[138:141], v204 offset:4096
	ds_read_b128 v[142:145], v204 offset:6144
	ds_read_b128 v[146:149], v205 offset:0
	ds_read_b128 v[150:153], v205 offset:2048
	ds_read_b128 v[154:157], v205 offset:4096
	ds_read_b128 v[158:161], v205 offset:6144
	v_add_u32_e32 v204, 0x18000, v201
	v_add_u32_e32 v205, 0x18000, v203
	ds_read_b128 v[212:215], v204 offset:0
	ds_read_b128 v[216:219], v204 offset:2048
	ds_read_b128 v[220:223], v204 offset:4096
	ds_read_b128 v[224:227], v204 offset:6144
	ds_read_b128 v[228:231], v205 offset:0
	ds_read_b128 v[232:235], v205 offset:2048
	ds_read_b128 v[236:239], v205 offset:4096
	ds_read_b128 v[240:243], v205 offset:6144
	s_waitcnt lgkmcnt(0)
	s_barrier
	v_mfma_f32_16x16x32_bf16 v[2:5], v[146:149], v[130:133], v[2:5]
	v_mfma_f32_16x16x32_bf16 v[6:9], v[150:153], v[130:133], v[6:9]
	v_mfma_f32_16x16x32_bf16 v[10:13], v[154:157], v[130:133], v[10:13]
	v_mfma_f32_16x16x32_bf16 v[14:17], v[158:161], v[130:133], v[14:17]
	v_mfma_f32_16x16x32_bf16 v[18:21], v[146:149], v[134:137], v[18:21]
	v_mfma_f32_16x16x32_bf16 v[22:25], v[150:153], v[134:137], v[22:25]
	v_mfma_f32_16x16x32_bf16 v[26:29], v[154:157], v[134:137], v[26:29]
	v_mfma_f32_16x16x32_bf16 v[30:33], v[158:161], v[134:137], v[30:33]
	v_mfma_f32_16x16x32_bf16 v[34:37], v[146:149], v[138:141], v[34:37]
	v_mfma_f32_16x16x32_bf16 v[38:41], v[150:153], v[138:141], v[38:41]
	v_mfma_f32_16x16x32_bf16 v[42:45], v[154:157], v[138:141], v[42:45]
	v_mfma_f32_16x16x32_bf16 v[46:49], v[158:161], v[138:141], v[46:49]
	v_mfma_f32_16x16x32_bf16 v[50:53], v[146:149], v[142:145], v[50:53]
	v_mfma_f32_16x16x32_bf16 v[54:57], v[150:153], v[142:145], v[54:57]
	v_mfma_f32_16x16x32_bf16 v[58:61], v[154:157], v[142:145], v[58:61]
	v_mfma_f32_16x16x32_bf16 v[62:65], v[158:161], v[142:145], v[62:65]
	v_mfma_f32_16x16x32_bf16 v[2:5], v[228:231], v[212:215], v[2:5]
	v_mfma_f32_16x16x32_bf16 v[6:9], v[232:235], v[212:215], v[6:9]
	v_mfma_f32_16x16x32_bf16 v[10:13], v[236:239], v[212:215], v[10:13]
	v_mfma_f32_16x16x32_bf16 v[14:17], v[240:243], v[212:215], v[14:17]
	v_mfma_f32_16x16x32_bf16 v[18:21], v[228:231], v[216:219], v[18:21]
	v_mfma_f32_16x16x32_bf16 v[22:25], v[232:235], v[216:219], v[22:25]
	v_mfma_f32_16x16x32_bf16 v[26:29], v[236:239], v[216:219], v[26:29]
	v_mfma_f32_16x16x32_bf16 v[30:33], v[240:243], v[216:219], v[30:33]
	v_mfma_f32_16x16x32_bf16 v[34:37], v[228:231], v[220:223], v[34:37]
	v_mfma_f32_16x16x32_bf16 v[38:41], v[232:235], v[220:223], v[38:41]
	v_mfma_f32_16x16x32_bf16 v[42:45], v[236:239], v[220:223], v[42:45]
	v_mfma_f32_16x16x32_bf16 v[46:49], v[240:243], v[220:223], v[46:49]
	v_mfma_f32_16x16x32_bf16 v[50:53], v[228:231], v[224:227], v[50:53]
	v_mfma_f32_16x16x32_bf16 v[54:57], v[232:235], v[224:227], v[54:57]
	v_mfma_f32_16x16x32_bf16 v[58:61], v[236:239], v[224:227], v[58:61]
	v_mfma_f32_16x16x32_bf16 v[62:65], v[240:243], v[224:227], v[62:65]
	s_nop 7
	v_lshlrev_b32_e32 v212, 16, v174
	v_and_b32_e32 v213, 0xffff0000, v174
	v_lshlrev_b32_e32 v214, 16, v175
	v_and_b32_e32 v215, 0xffff0000, v175
	v_pk_fma_f32 v[66:67], v[2:3], v[212:213], v[66:67]
	v_pk_fma_f32 v[68:69], v[4:5], v[214:215], v[68:69]
	s_nop 0
	v_cvt_pk_bf16_f32 v66, v66, v67
	v_cvt_pk_bf16_f32 v67, v68, v69
	global_store_dwordx2 v210, v[66:67], s[74:75] offset:0
	v_lshlrev_b32_e32 v216, 16, v176
	v_and_b32_e32 v217, 0xffff0000, v176
	v_lshlrev_b32_e32 v218, 16, v177
	v_and_b32_e32 v219, 0xffff0000, v177
	v_pk_fma_f32 v[70:71], v[6:7], v[216:217], v[70:71]
	v_pk_fma_f32 v[72:73], v[8:9], v[218:219], v[72:73]
	s_nop 0
	v_cvt_pk_bf16_f32 v70, v70, v71
	v_cvt_pk_bf16_f32 v71, v72, v73
	global_store_dwordx2 v210, v[70:71], s[74:75] offset:32
	v_lshlrev_b32_e32 v220, 16, v178
	v_and_b32_e32 v221, 0xffff0000, v178
	v_lshlrev_b32_e32 v222, 16, v179
	v_and_b32_e32 v223, 0xffff0000, v179
	v_pk_fma_f32 v[74:75], v[10:11], v[220:221], v[74:75]
	v_pk_fma_f32 v[76:77], v[12:13], v[222:223], v[76:77]
	s_nop 0
	v_cvt_pk_bf16_f32 v74, v74, v75
	v_cvt_pk_bf16_f32 v75, v76, v77
	global_store_dwordx2 v210, v[74:75], s[74:75] offset:64
	v_lshlrev_b32_e32 v224, 16, v180
	v_and_b32_e32 v225, 0xffff0000, v180
	v_lshlrev_b32_e32 v226, 16, v181
	v_and_b32_e32 v227, 0xffff0000, v181
	v_pk_fma_f32 v[78:79], v[14:15], v[224:225], v[78:79]
	v_pk_fma_f32 v[80:81], v[16:17], v[226:227], v[80:81]
	s_nop 0
	v_cvt_pk_bf16_f32 v78, v78, v79
	v_cvt_pk_bf16_f32 v79, v80, v81
	global_store_dwordx2 v210, v[78:79], s[74:75] offset:96
	v_lshlrev_b32_e32 v228, 16, v182
	v_and_b32_e32 v229, 0xffff0000, v182
	v_lshlrev_b32_e32 v230, 16, v183
	v_and_b32_e32 v231, 0xffff0000, v183
	v_pk_fma_f32 v[82:83], v[18:19], v[228:229], v[82:83]
	v_pk_fma_f32 v[84:85], v[20:21], v[230:231], v[84:85]
	s_nop 0
	v_cvt_pk_bf16_f32 v82, v82, v83
	v_cvt_pk_bf16_f32 v83, v84, v85
	global_store_dwordx2 v211, v[82:83], s[74:75] offset:0
	v_lshlrev_b32_e32 v232, 16, v184
	v_and_b32_e32 v233, 0xffff0000, v184
	v_lshlrev_b32_e32 v234, 16, v185
	v_and_b32_e32 v235, 0xffff0000, v185
	v_pk_fma_f32 v[86:87], v[22:23], v[232:233], v[86:87]
	v_pk_fma_f32 v[88:89], v[24:25], v[234:235], v[88:89]
	s_nop 0
	v_cvt_pk_bf16_f32 v86, v86, v87
	v_cvt_pk_bf16_f32 v87, v88, v89
	global_store_dwordx2 v211, v[86:87], s[74:75] offset:32
	v_lshlrev_b32_e32 v236, 16, v186
	v_and_b32_e32 v237, 0xffff0000, v186
	v_lshlrev_b32_e32 v238, 16, v187
	v_and_b32_e32 v239, 0xffff0000, v187
	v_pk_fma_f32 v[90:91], v[26:27], v[236:237], v[90:91]
	v_pk_fma_f32 v[92:93], v[28:29], v[238:239], v[92:93]
	s_nop 0
	v_cvt_pk_bf16_f32 v90, v90, v91
	v_cvt_pk_bf16_f32 v91, v92, v93
	global_store_dwordx2 v211, v[90:91], s[74:75] offset:64
	v_lshlrev_b32_e32 v240, 16, v188
	v_and_b32_e32 v241, 0xffff0000, v188
	v_lshlrev_b32_e32 v242, 16, v189
	v_and_b32_e32 v243, 0xffff0000, v189
	v_pk_fma_f32 v[94:95], v[30:31], v[240:241], v[94:95]
	v_pk_fma_f32 v[96:97], v[32:33], v[242:243], v[96:97]
	s_nop 0
	v_cvt_pk_bf16_f32 v94, v94, v95
	v_cvt_pk_bf16_f32 v95, v96, v97
	global_store_dwordx2 v211, v[94:95], s[74:75] offset:96
	v_lshlrev_b32_e32 v212, 16, v190
	v_and_b32_e32 v213, 0xffff0000, v190
	v_lshlrev_b32_e32 v214, 16, v191
	v_and_b32_e32 v215, 0xffff0000, v191
	v_pk_fma_f32 v[98:99], v[34:35], v[212:213], v[98:99]
	v_pk_fma_f32 v[100:101], v[36:37], v[214:215], v[100:101]
	s_nop 0
	v_cvt_pk_bf16_f32 v98, v98, v99
	v_cvt_pk_bf16_f32 v99, v100, v101
	global_store_dwordx2 v168, v[98:99], s[74:75] offset:0
	v_lshlrev_b32_e32 v216, 16, v192
	v_and_b32_e32 v217, 0xffff0000, v192
	v_lshlrev_b32_e32 v218, 16, v193
	v_and_b32_e32 v219, 0xffff0000, v193
	v_pk_fma_f32 v[102:103], v[38:39], v[216:217], v[102:103]
	v_pk_fma_f32 v[104:105], v[40:41], v[218:219], v[104:105]
	s_nop 0
	v_cvt_pk_bf16_f32 v102, v102, v103
	v_cvt_pk_bf16_f32 v103, v104, v105
	global_store_dwordx2 v168, v[102:103], s[74:75] offset:32
	v_lshlrev_b32_e32 v220, 16, v244
	v_and_b32_e32 v221, 0xffff0000, v244
	v_lshlrev_b32_e32 v222, 16, v245
	v_and_b32_e32 v223, 0xffff0000, v245
	v_pk_fma_f32 v[106:107], v[42:43], v[220:221], v[106:107]
	v_pk_fma_f32 v[108:109], v[44:45], v[222:223], v[108:109]
	s_nop 0
	v_cvt_pk_bf16_f32 v106, v106, v107
	v_cvt_pk_bf16_f32 v107, v108, v109
	global_store_dwordx2 v168, v[106:107], s[74:75] offset:64
	v_lshlrev_b32_e32 v224, 16, v246
	v_and_b32_e32 v225, 0xffff0000, v246
	v_lshlrev_b32_e32 v226, 16, v247
	v_and_b32_e32 v227, 0xffff0000, v247
	v_pk_fma_f32 v[110:111], v[46:47], v[224:225], v[110:111]
	v_pk_fma_f32 v[112:113], v[48:49], v[226:227], v[112:113]
	s_nop 0
	v_cvt_pk_bf16_f32 v110, v110, v111
	v_cvt_pk_bf16_f32 v111, v112, v113
	global_store_dwordx2 v168, v[110:111], s[74:75] offset:96
	v_lshlrev_b32_e32 v228, 16, v248
	v_and_b32_e32 v229, 0xffff0000, v248
	v_lshlrev_b32_e32 v230, 16, v249
	v_and_b32_e32 v231, 0xffff0000, v249
	v_pk_fma_f32 v[114:115], v[50:51], v[228:229], v[114:115]
	v_pk_fma_f32 v[116:117], v[52:53], v[230:231], v[116:117]
	s_nop 0
	v_cvt_pk_bf16_f32 v114, v114, v115
	v_cvt_pk_bf16_f32 v115, v116, v117
	global_store_dwordx2 v169, v[114:115], s[74:75] offset:0
	v_lshlrev_b32_e32 v232, 16, v250
	v_and_b32_e32 v233, 0xffff0000, v250
	v_lshlrev_b32_e32 v234, 16, v251
	v_and_b32_e32 v235, 0xffff0000, v251
	v_pk_fma_f32 v[118:119], v[54:55], v[232:233], v[118:119]
	v_pk_fma_f32 v[120:121], v[56:57], v[234:235], v[120:121]
	s_nop 0
	v_cvt_pk_bf16_f32 v118, v118, v119
	v_cvt_pk_bf16_f32 v119, v120, v121
	global_store_dwordx2 v169, v[118:119], s[74:75] offset:32
	v_lshlrev_b32_e32 v236, 16, v166
	v_and_b32_e32 v237, 0xffff0000, v166
	v_lshlrev_b32_e32 v238, 16, v167
	v_and_b32_e32 v239, 0xffff0000, v167
	v_pk_fma_f32 v[122:123], v[58:59], v[236:237], v[122:123]
	v_pk_fma_f32 v[124:125], v[60:61], v[238:239], v[124:125]
	s_nop 0
	v_cvt_pk_bf16_f32 v122, v122, v123
	v_cvt_pk_bf16_f32 v123, v124, v125
	global_store_dwordx2 v169, v[122:123], s[74:75] offset:64
	v_lshlrev_b32_e32 v240, 16, v194
	v_and_b32_e32 v241, 0xffff0000, v194
	v_lshlrev_b32_e32 v242, 16, v195
	v_and_b32_e32 v243, 0xffff0000, v195
	v_pk_fma_f32 v[126:127], v[62:63], v[240:241], v[126:127]
	v_pk_fma_f32 v[128:129], v[64:65], v[242:243], v[128:129]
	s_nop 0
	v_cvt_pk_bf16_f32 v126, v126, v127
	v_cvt_pk_bf16_f32 v127, v128, v129
	global_store_dwordx2 v169, v[126:127], s[74:75] offset:96
